# E and A GEMM loops: one static priority raise for the wave half that runs one barrier behind, instead of per-segment s_setprio toggling
# speedup vs baseline: 1.0040x; 1.0040x over previous
; #define PG8_STAGE(bufoff, gbase, voff) do { _Pragma("unroll") for (int _i = 0; _i < 2; ++_i) \
;         __builtin_amdgcn_global_load_lds((const unsigned*)((const char*)(gbase) + (voff)[_i]), (LAS unsigned*)(lds + (bufoff) + ldsw + _i * 8192), 16, 0, 0); } while (0)
; #define PG8_BAR __builtin_amdgcn_s_barrier()
; template <class Epi>
; __device__ __forceinline__ void gemm_phase(LAS unsigned char* lds, const Gemm g, const StaticOrder& S, const Epi& E) {
;     int tid = threadIdx.x; asm volatile("" : "+v"(tid));
;     const int wid = __builtin_amdgcn_readfirstlane(tid >> 6), lane = tid & 63, wr = wid >> 2, wc = wid & 3, fr = lane & 15, fq = lane >> 4;
;     const int K = g.K, nt = K / BK;
;     unsigned voffA[2], voffB[2];
; #pragma unroll
;     for (int i = 0; i < 2; ++i) { int R, C; stage_rc(tid * 16 + i * 8192, R, C); const int Rb = Epi::PERM ? ((R & ~31) + perm32(R & 31)) : R;
;         voffA[i] = (unsigned)(R * K + C) * 2u; voffB[i] = (unsigned)(Rb * K + C) * 2u; }
;     const size_t kstep = (size_t)(BK * 2);
;     const size_t hstep = (size_t)HALF * K * 2;
;     const size_t tstep = 2 * hstep;
;     const unsigned ldsw = (unsigned)wid * 1024u;
;     const int aoff = lds_byte(wr * 64 + fr, fq * 8), boff = lds_byte(wc * 32 + fr, fq * 8);
;     ...
;     Unit cur, nxt; int ui = 0;
;     if (!S.next(0, cur)) return;
;     f32x4 acc[2][2][4][2];
; #pragma unroll
;     for (int a = 0; a < 2; ++a)
; #pragma unroll
;         for (int b = 0; b < 2; ++b)
; #pragma unroll
;             for (int m = 0; m < 4; ++m)
; #pragma unroll
;                 for (int n = 0; n < 2; ++n) acc[a][b][m][n] = (f32x4){0.f, 0.f, 0.f, 0.f};
;     bf16x8 At[4][2], B0[2][2], B1[2][2];
;     const char* cA = (const char*)g.A + (size_t)cur.pm * tstep; const char* cB = (const char*)g.Bt + (size_t)cur.pn * tstep;
;     PG8_STAGE(PG8_SB(0, 0), cB, voffB); PG8_STAGE(PG8_SA(0, 0), cA, voffA); PG8_STAGE(PG8_SB(0, 1), cB + hstep, voffB); PG8_STAGE(PG8_SA(0, 1), cA + hstep, voffA);
;     if (wr == 1) PG8_BAR;
.LBB0_159:
	v_readlane_b32 s4, v253, 58
	s_waitcnt vmcnt(12)
	v_mov_b32_e32 v16, v167
	v_readlane_b32 s5, v253, 59
	s_waitcnt lgkmcnt(0)
	s_barrier
	s_andn2_b64 vcc, exec, s[4:5]
	v_readfirstlane_b32 s18, v16
	s_mov_b32 s88, s96
	s_cbranch_vccnz .LBB0_175
	v_lshlrev_b32_e32 v0, 4, v16
	v_add_u32_e32 v2, 0x2000, v0
	v_ashrrev_i32_e32 v3, 31, v2
	v_lshrrev_b32_e32 v3, 22, v3
	v_add_u32_e32 v3, v2, v3
	v_ashrrev_i32_e32 v10, 10, v3
	v_mul_i32_i24_e32 v3, 0x400, v10
	v_sub_u32_e32 v2, v2, v3
	v_lshrrev_b32_e32 v3, 4, v2
	v_bitop3_b32 v2, v3, v2, 32 bitop3:0x6c
	v_ashrrev_i32_e32 v3, 31, v2
	s_add_u32 s44, s94, 0x5830000
	v_lshrrev_b32_e32 v3, 26, v3
	s_addc_u32 s45, s95, 0
	v_readlane_b32 s4, v252, 4
	v_add_u32_e32 v3, v2, v3
	v_lshlrev_b32_e32 v4, 3, v10
	v_readlane_b32 s5, v252, 5
	s_add_u32 s4, s94, s4
	v_ashrrev_i32_e32 v11, 6, v3
	v_and_b32_e32 v4, -16, v4
	s_addc_u32 s5, s95, s5
	v_add_u32_e32 v4, v11, v4
	s_add_u32 s46, s4, 0x1600000
	v_and_b32_e32 v5, 3, v11
	s_mov_b32 s4, 0x1fffe0
	v_lshrrev_b32_e32 v6, 2, v4
	v_lshlrev_b32_e32 v7, 1, v4
	v_and_b32_e32 v3, 0xc0, v3
	v_and_or_b32 v5, v4, s4, v5
	v_and_b32_e32 v6, 4, v6
	v_and_b32_e32 v7, 24, v7
	v_sub_u32_e32 v2, v2, v3
	v_or3_b32 v5, v5, v6, v7
	v_lshlrev_b32_e32 v6, 5, v10
	v_ashrrev_i16_sdwa v2, v188, sext(v2) dst_sel:DWORD dst_unused:UNUSED_PAD src0_sel:DWORD src1_sel:BYTE_0
	v_and_b32_e32 v6, 32, v6
	v_bfe_i32 v12, v2, 0, 16
	v_add_lshl_u32 v2, v6, v12, 1
	v_lshl_add_u32 v130, v5, 11, v2
	v_lshl_add_u32 v132, v4, 11, v2
	v_bfe_i32 v2, v16, 27, 1
	v_lshrrev_b32_e32 v2, 22, v2
	v_add_u32_e32 v2, v0, v2
	v_and_b32_e32 v2, 0xfffffc00, v2
	v_sub_u32_e32 v0, v0, v2
	v_lshrrev_b32_e32 v2, 4, v0
	v_ashrrev_i32_e32 v3, 31, v16
	v_bitop3_b32 v0, v2, v0, 32 bitop3:0x6c
	v_lshrrev_b32_e32 v3, 26, v3
	v_ashrrev_i32_e32 v2, 31, v0
	v_add_u32_e32 v3, v16, v3
	v_lshrrev_b32_e32 v2, 26, v2
	v_ashrrev_i32_e32 v14, 6, v3
	v_add_u32_e32 v2, v0, v2
	v_lshlrev_b32_e32 v3, 3, v14
	v_ashrrev_i32_e32 v13, 6, v2
	v_and_b32_e32 v3, -16, v3
	v_add_u32_e32 v3, v13, v3
	v_and_b32_e32 v4, 3, v13
	v_lshrrev_b32_e32 v5, 2, v3
	v_lshlrev_b32_e32 v6, 1, v3
	v_and_b32_e32 v2, 0xc0, v2
	s_addc_u32 s47, s5, 0
	s_ashr_i32 s8, s18, 6
	v_and_or_b32 v4, v3, s4, v4
	v_and_b32_e32 v5, 4, v5
	v_and_b32_e32 v6, 24, v6
	v_sub_u32_e32 v0, v0, v2
	s_ashr_i32 s9, s18, 8
	s_lshl_b32 s48, s8, 10
	v_or3_b32 v4, v4, v5, v6
	v_lshlrev_b32_e32 v5, 5, v14
	v_ashrrev_i16_sdwa v0, v188, sext(v0) dst_sel:DWORD dst_unused:UNUSED_PAD src0_sel:DWORD src1_sel:BYTE_0
	v_readlane_b32 s4, v254, 3
	v_and_b32_e32 v5, 32, v5
	v_bfe_i32 v15, v0, 0, 16
	v_readlane_b32 s5, v254, 4
	s_add_u32 s6, s46, s4
	v_add_lshl_u32 v2, v5, v15, 1
	s_addc_u32 s7, s47, s5
	s_add_i32 s49, s48, 0
	v_lshl_add_u32 v0, v4, 11, v2
	s_add_i32 m0, s49, 0x10000
	v_readlane_b32 s4, v254, 26
	global_load_lds_dwordx4 v0, s[6:7]
	s_add_i32 m0, s49, 0x12000
	v_readlane_b32 s5, v254, 27
	s_add_u32 s36, s44, s4
	v_lshl_add_u32 v134, v3, 11, v2
	global_load_lds_dwordx4 v130, s[6:7]
	s_addc_u32 s37, s45, s5
	s_mov_b32 m0, s49
	s_add_i32 s54, s49, 0x2000
	global_load_lds_dwordx4 v134, s[36:37]
	s_mov_b32 m0, s54
	s_add_u32 s4, s6, 0x40000
	global_load_lds_dwordx4 v132, s[36:37]
	s_addc_u32 s5, s7, 0
	s_add_i32 m0, s49, 0x14000
	v_mov_b32_e32 v131, v1
	global_load_lds_dwordx4 v0, s[4:5]
	s_add_i32 m0, s49, 0x16000
	v_mov_b32_e32 v135, v1
	global_load_lds_dwordx4 v130, s[4:5]
	s_add_u32 s4, s36, 0x40000
	s_addc_u32 s5, s37, 0
	s_add_i32 s55, s49, 0x4000
	s_mov_b32 m0, s55
	s_add_i32 s83, s49, 0x6000
	global_load_lds_dwordx4 v134, s[4:5]
	s_mov_b32 m0, s83
	v_mov_b32_e32 v133, v1
	global_load_lds_dwordx4 v132, s[4:5]
	v_lshl_add_u64 v[8:9], s[6:7], 0, v[0:1]
	v_lshl_add_u64 v[6:7], s[6:7], 0, v[130:131]
	v_lshl_add_u64 v[4:5], s[36:37], 0, v[134:135]
	s_cmp_lg_u32 s9, 1
	v_lshl_add_u64 v[2:3], s[36:37], 0, v[132:133]
	s_cbranch_scc1 .LBB0_162
	s_barrier
	s_setprio 1

; #define PG8_STAGE(bufoff, gbase, voff) do { _Pragma("unroll") for (int _i = 0; _i < 2; ++_i) \
;         __builtin_amdgcn_global_load_lds((const unsigned*)((const char*)(gbase) + (voff)[_i]), (LAS unsigned*)(lds + (bufoff) + ldsw + _i * 8192), 16, 0, 0); } while (0)
; #define PG8_LDA(dst, b, h) do { _Pragma("unroll") for (int m = 0; m < 4; ++m) _Pragma("unroll") for (int k = 0; k < 2; ++k) dst[m][k] = *(const LAS bf16x8*)(lds + PG8_SA(b, h) + aoff + m * 2048 + k * 1024); } while (0)
; #define PG8_LDB(dst, b, h) do { _Pragma("unroll") for (int n = 0; n < 2; ++n) _Pragma("unroll") for (int k = 0; k < 2; ++k) dst[n][k] = *(const LAS bf16x8*)(lds + PG8_SB(b, h) + boff + n * 2048 + k * 1024); } while (0)
; #define PG8_MMA(ai, bj, At, Bt) do { __builtin_amdgcn_s_setprio(1); _Pragma("unroll") for (int m = 0; m < 4; ++m) _Pragma("unroll") for (int n = 0; n < 2; ++n) _Pragma("unroll") for (int k = 0; k < 2; ++k) \
;         acc[ai][bj][m][n] = __builtin_amdgcn_mfma_f32_16x16x32_bf16(Bt[n][k], At[m][k], acc[ai][bj][m][n], 0, 0, 0); __builtin_amdgcn_s_setprio(0); } while (0)
; #define PG8_WAIT_V(n) asm volatile("s_waitcnt vmcnt(" #n ")" ::: "memory")
; #define PG8_WAIT_L(n) asm volatile("s_waitcnt lgkmcnt(" #n ")" ::: "memory")
; #define PG8_BAR __builtin_amdgcn_s_barrier()
; #define PG8_SCHED __builtin_amdgcn_sched_barrier(0)
; template <class Epi>
; __device__ __forceinline__ void gemm_phase(LAS unsigned char* lds, const Gemm g, const StaticOrder& S, const Epi& E) {
;     ...
;             const char* a1 = cA + (size_t)(t + 1) * kstep;
;             const char* a2 = last ? nA : cA + (size_t)(t + 2) * kstep; const char* b2 = last ? nB : cB + (size_t)(t + 2) * kstep;
;             const char* a3 = a2 + kstep; const char* b3 = b2 + kstep;
;             PG8_LDB(B0, 0, 0); PG8_SCHED; PG8_LDA(At, 0, 0); PG8_STAGE(PG8_SA(1, 1), a1 + hstep, voffA);
;             PG8_WAIT_L(8); PG8_BAR; PG8_WAIT_L(0); PG8_MMA(0, 0, At, B0); PG8_BAR; PG8_SCHED;
;             PG8_LDB(B1, 0, 1); PG8_STAGE(PG8_SB(0, 0), b2, voffB);
;             PG8_BAR; PG8_WAIT_L(0); PG8_MMA(0, 1, At, B1); PG8_BAR;
;             PG8_LDA(At, 0, 1); PG8_STAGE(PG8_SA(0, 0), a2, voffA);
;             PG8_BAR; PG8_WAIT_L(0); PG8_MMA(1, 0, At, B0); PG8_BAR; PG8_SCHED;
;             PG8_STAGE(PG8_SB(0, 1), b2 + hstep, voffB);
;             PG8_WAIT_V(6); PG8_BAR; PG8_MMA(1, 1, At, B1); PG8_BAR;
.LBB0_170:
	s_add_u32 s6, s36, 0xfffc0080
	s_addc_u32 s7, s37, -1
	s_add_i32 s58, 0, 0x10000
	v_add_u32_e32 v144, s58, v147
	ds_read_b128 v[140:143], v144
	ds_read_b128 v[152:155], v144 offset:1024
	ds_read_b128 v[168:171], v144 offset:2048
	ds_read_b128 v[172:175], v144 offset:3072
	s_cmp_eq_u32 s93, 12
	s_cselect_b32 s43, s11, s7
	s_cselect_b32 s42, s71, s6
	s_cselect_b32 s7, s9, s92
	s_cselect_b32 s6, s90, s91
	s_add_i32 m0, s49, 0xc000
	ds_read_b128 v[176:179], v150
	ds_read_b128 v[180:183], v150 offset:1024
	ds_read_b128 v[184:187], v150 offset:2048
	ds_read_b128 v[204:207], v150 offset:3072
	ds_read_b128 v[208:211], v150 offset:4096
	ds_read_b128 v[212:215], v150 offset:5120
	ds_read_b128 v[216:219], v150 offset:6144
	ds_read_b128 v[226:229], v150 offset:7168
	global_load_lds_dwordx4 v136, s[36:37]
	s_add_i32 m0, s49, 0xe000
	s_nop 0
	global_load_lds_dwordx4 v138, s[36:37]
	s_waitcnt lgkmcnt(8)
	s_barrier
	s_waitcnt lgkmcnt(0)
	s_waitcnt lgkmcnt(0)
	v_mfma_f32_16x16x32_bf16 v[126:129], v[140:143], v[176:179], 0
	v_mfma_f32_16x16x32_bf16 v[122:125], v[168:171], v[176:179], 0
	v_mfma_f32_16x16x32_bf16 v[110:113], v[140:143], v[184:187], 0
	v_mfma_f32_16x16x32_bf16 v[106:109], v[168:171], v[184:187], 0
	v_mfma_f32_16x16x32_bf16 v[94:97], v[140:143], v[208:211], 0
	v_mfma_f32_16x16x32_bf16 v[90:93], v[168:171], v[208:211], 0
	v_mfma_f32_16x16x32_bf16 v[78:81], v[140:143], v[216:219], 0
	v_mfma_f32_16x16x32_bf16 v[74:77], v[168:171], v[216:219], 0
	v_mfma_f32_16x16x32_bf16 v[126:129], v[152:155], v[180:183], v[126:129]
	v_mfma_f32_16x16x32_bf16 v[122:125], v[172:175], v[180:183], v[122:125]
	v_mfma_f32_16x16x32_bf16 v[110:113], v[152:155], v[204:207], v[110:113]
	v_mfma_f32_16x16x32_bf16 v[106:109], v[172:175], v[204:207], v[106:109]
	v_mfma_f32_16x16x32_bf16 v[94:97], v[152:155], v[212:215], v[94:97]
	v_mfma_f32_16x16x32_bf16 v[90:93], v[172:175], v[212:215], v[90:93]
	v_mfma_f32_16x16x32_bf16 v[78:81], v[152:155], v[226:229], v[78:81]
	v_mfma_f32_16x16x32_bf16 v[74:77], v[172:175], v[226:229], v[74:77]
	s_barrier
	s_add_i32 s70, 0, 0x14000
	v_add_u32_e32 v144, s70, v147
	s_add_i32 s58, s58, s48
	ds_read_b128 v[230:233], v144
	ds_read_b128 v[234:237], v144 offset:1024
	ds_read_b128 v[238:241], v144 offset:2048
	ds_read_b128 v[242:245], v144 offset:3072
	s_mov_b32 m0, s58
	s_nop 0
	global_load_lds_dwordx4 v0, s[6:7]
	s_add_i32 m0, s58, 0x2000
	s_nop 0
	global_load_lds_dwordx4 v130, s[6:7]
	s_barrier
	s_waitcnt lgkmcnt(0)
	s_waitcnt lgkmcnt(0)
	v_mfma_f32_16x16x32_bf16 v[118:121], v[230:233], v[176:179], 0
	v_mfma_f32_16x16x32_bf16 v[114:117], v[238:241], v[176:179], 0
	v_mfma_f32_16x16x32_bf16 v[102:105], v[230:233], v[184:187], 0
	v_mfma_f32_16x16x32_bf16 v[98:101], v[238:241], v[184:187], 0
	v_mfma_f32_16x16x32_bf16 v[86:89], v[230:233], v[208:211], 0
	v_mfma_f32_16x16x32_bf16 v[82:85], v[238:241], v[208:211], 0
	v_mfma_f32_16x16x32_bf16 v[70:73], v[230:233], v[216:219], 0
	v_mfma_f32_16x16x32_bf16 v[66:69], v[238:241], v[216:219], 0
	v_mfma_f32_16x16x32_bf16 v[118:121], v[234:237], v[180:183], v[118:121]
	v_mfma_f32_16x16x32_bf16 v[114:117], v[242:245], v[180:183], v[114:117]
	v_mfma_f32_16x16x32_bf16 v[102:105], v[234:237], v[204:207], v[102:105]
	v_mfma_f32_16x16x32_bf16 v[98:101], v[242:245], v[204:207], v[98:101]
	v_mfma_f32_16x16x32_bf16 v[86:89], v[234:237], v[212:215], v[86:89]
	v_mfma_f32_16x16x32_bf16 v[82:85], v[242:245], v[212:215], v[82:85]
	v_mfma_f32_16x16x32_bf16 v[70:73], v[234:237], v[226:229], v[70:73]
	v_mfma_f32_16x16x32_bf16 v[66:69], v[242:245], v[226:229], v[66:69]
	s_mov_b32 m0, s49
	s_add_u32 vcc_lo, s42, 0x80
	s_addc_u32 vcc_hi, s43, 0
	s_barrier
	ds_read_b128 v[176:179], v150 offset:16384
	ds_read_b128 v[180:183], v150 offset:17408
	ds_read_b128 v[184:187], v150 offset:18432
	ds_read_b128 v[204:207], v150 offset:19456
	ds_read_b128 v[208:211], v150 offset:20480
	ds_read_b128 v[212:215], v150 offset:21504
	ds_read_b128 v[216:219], v150 offset:22528
	ds_read_b128 v[226:229], v150 offset:23552
	global_load_lds_dwordx4 v134, s[42:43]
	s_mov_b32 m0, s54
	s_nop 0
	global_load_lds_dwordx4 v132, s[42:43]
	s_barrier
	s_waitcnt lgkmcnt(0)
	s_waitcnt lgkmcnt(0)
	v_mfma_f32_16x16x32_bf16 v[62:65], v[140:143], v[176:179], 0
	v_mfma_f32_16x16x32_bf16 v[58:61], v[168:171], v[176:179], 0
	v_mfma_f32_16x16x32_bf16 v[46:49], v[140:143], v[184:187], 0
	v_mfma_f32_16x16x32_bf16 v[42:45], v[168:171], v[184:187], 0
	v_mfma_f32_16x16x32_bf16 v[30:33], v[140:143], v[208:211], 0
	v_mfma_f32_16x16x32_bf16 v[26:29], v[168:171], v[208:211], 0
	v_mfma_f32_16x16x32_bf16 v[14:17], v[140:143], v[216:219], 0
	v_mfma_f32_16x16x32_bf16 v[10:13], v[168:171], v[216:219], 0
	v_mfma_f32_16x16x32_bf16 v[62:65], v[152:155], v[180:183], v[62:65]
	v_mfma_f32_16x16x32_bf16 v[58:61], v[172:175], v[180:183], v[58:61]
	v_mfma_f32_16x16x32_bf16 v[46:49], v[152:155], v[204:207], v[46:49]
	v_mfma_f32_16x16x32_bf16 v[42:45], v[172:175], v[204:207], v[42:45]
	v_mfma_f32_16x16x32_bf16 v[30:33], v[152:155], v[212:215], v[30:33]
	v_mfma_f32_16x16x32_bf16 v[26:29], v[172:175], v[212:215], v[26:29]
	v_mfma_f32_16x16x32_bf16 v[14:17], v[152:155], v[226:229], v[14:17]
	v_mfma_f32_16x16x32_bf16 v[10:13], v[172:175], v[226:229], v[10:13]
	s_barrier
	s_add_u32 s60, s6, 0x40000
	s_addc_u32 s61, s7, 0
	s_add_i32 s58, s70, s48
	s_mov_b32 m0, s58
	s_nop 0
	global_load_lds_dwordx4 v0, s[60:61]
	s_add_i32 m0, s58, 0x2000
	s_nop 0
	global_load_lds_dwordx4 v130, s[60:61]
	s_waitcnt vmcnt(6)
	s_barrier
	v_mfma_f32_16x16x32_bf16 v[54:57], v[230:233], v[176:179], 0
	v_mfma_f32_16x16x32_bf16 v[50:53], v[238:241], v[176:179], 0
	s_cmp_eq_u32 s89, 0
	s_cbranch_scc1 .LdsE_skip_0
	global_store_dwordx4 v250, v[158:161], s[4:5]
; #define PG8_STAGE(bufoff, gbase, voff) do { _Pragma("unroll") for (int _i = 0; _i < 2; ++_i) \
;         __builtin_amdgcn_global_load_lds((const unsigned*)((const char*)(gbase) + (voff)[_i]), (LAS unsigned*)(lds + (bufoff) + ldsw + _i * 8192), 16, 0, 0); } while (0)
; #define PG8_LDA(dst, b, h) do { _Pragma("unroll") for (int m = 0; m < 4; ++m) _Pragma("unroll") for (int k = 0; k < 2; ++k) dst[m][k] = *(const LAS bf16x8*)(lds + PG8_SA(b, h) + aoff + m * 2048 + k * 1024); } while (0)
; #define PG8_LDB(dst, b, h) do { _Pragma("unroll") for (int n = 0; n < 2; ++n) _Pragma("unroll") for (int k = 0; k < 2; ++k) dst[n][k] = *(const LAS bf16x8*)(lds + PG8_SB(b, h) + boff + n * 2048 + k * 1024); } while (0)
; #define PG8_MMA(ai, bj, At, Bt) do { __builtin_amdgcn_s_setprio(1); _Pragma("unroll") for (int m = 0; m < 4; ++m) _Pragma("unroll") for (int n = 0; n < 2; ++n) _Pragma("unroll") for (int k = 0; k < 2; ++k) \
;         acc[ai][bj][m][n] = __builtin_amdgcn_mfma_f32_16x16x32_bf16(Bt[n][k], At[m][k], acc[ai][bj][m][n], 0, 0, 0); __builtin_amdgcn_s_setprio(0); } while (0)
; #define PG8_WAIT_V(n) asm volatile("s_waitcnt vmcnt(" #n ")" ::: "memory")
; #define PG8_WAIT_L(n) asm volatile("s_waitcnt lgkmcnt(" #n ")" ::: "memory")
; #define PG8_BAR __builtin_amdgcn_s_barrier()
; #define PG8_SCHED __builtin_amdgcn_sched_barrier(0)
; template <class Epi>
; __device__ __forceinline__ void gemm_phase(LAS unsigned char* lds, const Gemm g, const StaticOrder& S, const Epi& E) {
;     ...
;             PG8_WAIT_V(6); PG8_BAR; PG8_MMA(1, 1, At, B1); PG8_BAR;
;             PG8_LDB(B0, 1, 0); PG8_SCHED; PG8_LDA(At, 1, 0); PG8_STAGE(PG8_SA(0, 1), a2 + hstep, voffA);
;             PG8_WAIT_L(8); PG8_BAR; PG8_WAIT_L(0); PG8_MMA(0, 0, At, B0); PG8_BAR; PG8_SCHED;
;             PG8_LDB(B1, 1, 1); PG8_STAGE(PG8_SB(1, 0), b3, voffB);
;             PG8_BAR; PG8_WAIT_L(0); PG8_MMA(0, 1, At, B1); PG8_BAR;
;             PG8_LDA(At, 1, 1); PG8_STAGE(PG8_SA(1, 0), a3, voffA);
;             PG8_BAR; PG8_WAIT_L(0); PG8_MMA(1, 0, At, B0); PG8_BAR; PG8_SCHED;
.LdsE_skip_0:
	v_mfma_f32_16x16x32_bf16 v[38:41], v[230:233], v[184:187], 0
	v_mfma_f32_16x16x32_bf16 v[34:37], v[238:241], v[184:187], 0
	v_mfma_f32_16x16x32_bf16 v[22:25], v[230:233], v[208:211], 0
	v_mfma_f32_16x16x32_bf16 v[18:21], v[238:241], v[208:211], 0
	v_mfma_f32_16x16x32_bf16 v[6:9], v[230:233], v[216:219], 0
	v_mfma_f32_16x16x32_bf16 v[2:5], v[238:241], v[216:219], 0
	v_mfma_f32_16x16x32_bf16 v[54:57], v[234:237], v[180:183], v[54:57]
	v_mfma_f32_16x16x32_bf16 v[50:53], v[242:245], v[180:183], v[50:53]
	v_mfma_f32_16x16x32_bf16 v[38:41], v[234:237], v[204:207], v[38:41]
	v_mfma_f32_16x16x32_bf16 v[34:37], v[242:245], v[204:207], v[34:37]
	v_mfma_f32_16x16x32_bf16 v[22:25], v[234:237], v[212:215], v[22:25]
	v_mfma_f32_16x16x32_bf16 v[18:21], v[242:245], v[212:215], v[18:21]
	v_mfma_f32_16x16x32_bf16 v[6:9], v[234:237], v[226:229], v[6:9]
	v_mfma_f32_16x16x32_bf16 v[2:5], v[242:245], v[226:229], v[2:5]
	s_add_i32 s58, 0, 0x18000
	v_add_u32_e32 v151, s58, v147
	s_barrier
	ds_read_b128 v[140:143], v151
	ds_read_b128 v[152:155], v151 offset:1024
	ds_read_b128 v[168:171], v151 offset:2048
	ds_read_b128 v[172:175], v151 offset:3072
	s_add_u32 s42, s42, 0x40000
	s_addc_u32 s43, s43, 0
	s_mov_b32 m0, s55
	ds_read_b128 v[176:179], v150 offset:32768
	ds_read_b128 v[180:183], v150 offset:33792
	ds_read_b128 v[184:187], v150 offset:34816
	ds_read_b128 v[204:207], v150 offset:35840
	ds_read_b128 v[208:211], v150 offset:36864
	ds_read_b128 v[212:215], v150 offset:37888
	ds_read_b128 v[216:219], v150 offset:38912
	ds_read_b128 v[226:229], v150 offset:39936
	global_load_lds_dwordx4 v134, s[42:43]
	s_mov_b32 m0, s83
	s_nop 0
	global_load_lds_dwordx4 v132, s[42:43]
	s_waitcnt lgkmcnt(8)
	s_barrier
	s_waitcnt lgkmcnt(0)
	s_waitcnt lgkmcnt(0)
	v_mfma_f32_16x16x32_bf16 v[126:129], v[140:143], v[176:179], v[126:129]
	v_mfma_f32_16x16x32_bf16 v[122:125], v[168:171], v[176:179], v[122:125]
	v_mfma_f32_16x16x32_bf16 v[110:113], v[140:143], v[184:187], v[110:113]
	v_mfma_f32_16x16x32_bf16 v[106:109], v[168:171], v[184:187], v[106:109]
	v_mfma_f32_16x16x32_bf16 v[94:97], v[140:143], v[208:211], v[94:97]
	v_mfma_f32_16x16x32_bf16 v[90:93], v[168:171], v[208:211], v[90:93]
	v_mfma_f32_16x16x32_bf16 v[78:81], v[140:143], v[216:219], v[78:81]
	v_mfma_f32_16x16x32_bf16 v[74:77], v[168:171], v[216:219], v[74:77]
	v_mfma_f32_16x16x32_bf16 v[126:129], v[152:155], v[180:183], v[126:129]
	v_mfma_f32_16x16x32_bf16 v[122:125], v[172:175], v[180:183], v[122:125]
	v_mfma_f32_16x16x32_bf16 v[110:113], v[152:155], v[204:207], v[110:113]
	v_mfma_f32_16x16x32_bf16 v[106:109], v[172:175], v[204:207], v[106:109]
	v_mfma_f32_16x16x32_bf16 v[94:97], v[152:155], v[212:215], v[94:97]
	v_mfma_f32_16x16x32_bf16 v[90:93], v[172:175], v[212:215], v[90:93]
	v_mfma_f32_16x16x32_bf16 v[78:81], v[152:155], v[226:229], v[78:81]
	v_mfma_f32_16x16x32_bf16 v[74:77], v[172:175], v[226:229], v[74:77]
	s_barrier
	s_add_i32 s42, 0, 0x1c000
	s_add_i32 s43, s58, s48
	v_add_u32_e32 v151, s42, v147
	s_add_u32 s60, s6, 0x80
	s_addc_u32 s61, s7, 0
	s_mov_b32 m0, s43
	ds_read_b128 v[230:233], v151
	ds_read_b128 v[234:237], v151 offset:1024
	ds_read_b128 v[238:241], v151 offset:2048
	ds_read_b128 v[242:245], v151 offset:3072
	global_load_lds_dwordx4 v0, s[60:61]
	s_add_i32 m0, s43, 0x2000
	s_nop 0
	global_load_lds_dwordx4 v130, s[60:61]
	s_barrier
	s_waitcnt lgkmcnt(0)
	s_waitcnt lgkmcnt(0)
	v_mfma_f32_16x16x32_bf16 v[118:121], v[230:233], v[176:179], v[118:121]
	v_mfma_f32_16x16x32_bf16 v[114:117], v[238:241], v[176:179], v[114:117]
	v_mfma_f32_16x16x32_bf16 v[102:105], v[230:233], v[184:187], v[102:105]
	v_mfma_f32_16x16x32_bf16 v[98:101], v[238:241], v[184:187], v[98:101]
	v_mfma_f32_16x16x32_bf16 v[86:89], v[230:233], v[208:211], v[86:89]
	v_mfma_f32_16x16x32_bf16 v[82:85], v[238:241], v[208:211], v[82:85]
	v_mfma_f32_16x16x32_bf16 v[70:73], v[230:233], v[216:219], v[70:73]
	v_mfma_f32_16x16x32_bf16 v[66:69], v[238:241], v[216:219], v[66:69]
	v_mfma_f32_16x16x32_bf16 v[118:121], v[234:237], v[180:183], v[118:121]
	v_mfma_f32_16x16x32_bf16 v[114:117], v[242:245], v[180:183], v[114:117]
	v_mfma_f32_16x16x32_bf16 v[102:105], v[234:237], v[204:207], v[102:105]
	v_mfma_f32_16x16x32_bf16 v[98:101], v[242:245], v[204:207], v[98:101]
	v_mfma_f32_16x16x32_bf16 v[86:89], v[234:237], v[212:215], v[86:89]
	v_mfma_f32_16x16x32_bf16 v[82:85], v[242:245], v[212:215], v[82:85]
	v_mfma_f32_16x16x32_bf16 v[70:73], v[234:237], v[226:229], v[70:73]
	v_mfma_f32_16x16x32_bf16 v[66:69], v[242:245], v[226:229], v[66:69]
	s_mov_b32 m0, s84
	s_barrier
	ds_read_b128 v[176:179], v150 offset:49152
	ds_read_b128 v[180:183], v150 offset:50176
	ds_read_b128 v[184:187], v150 offset:51200
	ds_read_b128 v[204:207], v150 offset:52224
	ds_read_b128 v[208:211], v150 offset:53248
	ds_read_b128 v[212:215], v150 offset:54272
	ds_read_b128 v[216:219], v150 offset:55296
	ds_read_b128 v[226:229], v150 offset:56320
	global_load_lds_dwordx4 v134, vcc
	s_mov_b32 m0, s85
	s_nop 0
	global_load_lds_dwordx4 v132, vcc
	s_barrier
	s_waitcnt lgkmcnt(0)
	s_waitcnt lgkmcnt(0)
	v_mfma_f32_16x16x32_bf16 v[62:65], v[140:143], v[176:179], v[62:65]
	v_mfma_f32_16x16x32_bf16 v[58:61], v[168:171], v[176:179], v[58:61]
	v_mfma_f32_16x16x32_bf16 v[46:49], v[140:143], v[184:187], v[46:49]
	v_mfma_f32_16x16x32_bf16 v[42:45], v[168:171], v[184:187], v[42:45]
	v_mfma_f32_16x16x32_bf16 v[30:33], v[140:143], v[208:211], v[30:33]
	v_mfma_f32_16x16x32_bf16 v[26:29], v[168:171], v[208:211], v[26:29]
	v_mfma_f32_16x16x32_bf16 v[14:17], v[140:143], v[216:219], v[14:17]
	v_mfma_f32_16x16x32_bf16 v[10:13], v[168:171], v[216:219], v[10:13]
	v_mfma_f32_16x16x32_bf16 v[62:65], v[152:155], v[180:183], v[62:65]
	v_mfma_f32_16x16x32_bf16 v[58:61], v[172:175], v[180:183], v[58:61]
	v_mfma_f32_16x16x32_bf16 v[46:49], v[152:155], v[204:207], v[46:49]
	v_mfma_f32_16x16x32_bf16 v[42:45], v[172:175], v[204:207], v[42:45]
	v_mfma_f32_16x16x32_bf16 v[30:33], v[152:155], v[212:215], v[30:33]
	v_mfma_f32_16x16x32_bf16 v[26:29], v[172:175], v[212:215], v[26:29]
	v_mfma_f32_16x16x32_bf16 v[14:17], v[152:155], v[226:229], v[14:17]
	v_mfma_f32_16x16x32_bf16 v[10:13], v[172:175], v[226:229], v[10:13]
	s_barrier
; #define PG8_STAGE(bufoff, gbase, voff) do { _Pragma("unroll") for (int _i = 0; _i < 2; ++_i) \
;         __builtin_amdgcn_global_load_lds((const unsigned*)((const char*)(gbase) + (voff)[_i]), (LAS unsigned*)(lds + (bufoff) + ldsw + _i * 8192), 16, 0, 0); } while (0)
; #define PG8_LDA(dst, b, h) do { _Pragma("unroll") for (int m = 0; m < 4; ++m) _Pragma("unroll") for (int k = 0; k < 2; ++k) dst[m][k] = *(const LAS bf16x8*)(lds + PG8_SA(b, h) + aoff + m * 2048 + k * 1024); } while (0)
; #define PG8_LDB(dst, b, h) do { _Pragma("unroll") for (int n = 0; n < 2; ++n) _Pragma("unroll") for (int k = 0; k < 2; ++k) dst[n][k] = *(const LAS bf16x8*)(lds + PG8_SB(b, h) + boff + n * 2048 + k * 1024); } while (0)
; #define PG8_MMA(ai, bj, At, Bt) do { __builtin_amdgcn_s_setprio(1); _Pragma("unroll") for (int m = 0; m < 4; ++m) _Pragma("unroll") for (int n = 0; n < 2; ++n) _Pragma("unroll") for (int k = 0; k < 2; ++k) \
;         acc[ai][bj][m][n] = __builtin_amdgcn_mfma_f32_16x16x32_bf16(Bt[n][k], At[m][k], acc[ai][bj][m][n], 0, 0, 0); __builtin_amdgcn_s_setprio(0); } while (0)
; #define PG8_WAIT_V(n) asm volatile("s_waitcnt vmcnt(" #n ")" ::: "memory")
; #define PG8_WAIT_L(n) asm volatile("s_waitcnt lgkmcnt(" #n ")" ::: "memory")
; #define PG8_BAR __builtin_amdgcn_s_barrier()
; #define PG8_SCHED __builtin_amdgcn_sched_barrier(0)
; template <class Epi>
; __device__ __forceinline__ void gemm_phase(LAS unsigned char* lds, const Gemm g, const StaticOrder& S, const Epi& E) {
;     ...
;             const char* a1 = cA + (size_t)(t + 1) * kstep;
;             const char* a2 = last ? nA : cA + (size_t)(t + 2) * kstep; const char* b2 = last ? nB : cB + (size_t)(t + 2) * kstep;
;             const char* a3 = a2 + kstep; const char* b3 = b2 + kstep;
;             PG8_LDB(B0, 0, 0); PG8_SCHED; PG8_LDA(At, 0, 0); PG8_STAGE(PG8_SA(1, 1), a1 + hstep, voffA);
;             PG8_WAIT_L(8); PG8_BAR; PG8_WAIT_L(0); PG8_MMA(0, 0, At, B0); PG8_BAR; PG8_SCHED;
;             PG8_LDB(B1, 0, 1); PG8_STAGE(PG8_SB(0, 0), b2, voffB);
;             PG8_BAR; PG8_WAIT_L(0); PG8_MMA(0, 1, At, B1); PG8_BAR;
;             PG8_LDA(At, 0, 1); PG8_STAGE(PG8_SA(0, 0), a2, voffA);
;             PG8_BAR; PG8_WAIT_L(0); PG8_MMA(1, 0, At, B0); PG8_BAR; PG8_SCHED;
;     ...
;             PG8_STAGE(PG8_SB(1, 1), b3 + hstep, voffB);
;             PG8_WAIT_V(6); PG8_BAR; PG8_MMA(1, 1, At, B1); PG8_BAR;
	s_add_u32 s6, s6, 0x40080
	s_addc_u32 s7, s7, 0
	s_add_i32 s42, s42, s48
	s_mov_b32 m0, s42
	s_nop 0
	global_load_lds_dwordx4 v0, s[6:7]
	s_add_i32 m0, s42, 0x2000
	s_nop 0
	global_load_lds_dwordx4 v130, s[6:7]
	s_waitcnt vmcnt(6)
	s_barrier
	v_mfma_f32_16x16x32_bf16 v[54:57], v[230:233], v[176:179], v[54:57]
	v_mfma_f32_16x16x32_bf16 v[50:53], v[238:241], v[176:179], v[50:53]
	v_mfma_f32_16x16x32_bf16 v[38:41], v[230:233], v[184:187], v[38:41]
	v_mfma_f32_16x16x32_bf16 v[34:37], v[238:241], v[184:187], v[34:37]
	v_mfma_f32_16x16x32_bf16 v[22:25], v[230:233], v[208:211], v[22:25]
	v_mfma_f32_16x16x32_bf16 v[18:21], v[238:241], v[208:211], v[18:21]
	v_mfma_f32_16x16x32_bf16 v[6:9], v[230:233], v[216:219], v[6:9]
	v_mfma_f32_16x16x32_bf16 v[2:5], v[238:241], v[216:219], v[2:5]
	v_mfma_f32_16x16x32_bf16 v[54:57], v[234:237], v[180:183], v[54:57]
	v_mfma_f32_16x16x32_bf16 v[50:53], v[242:245], v[180:183], v[50:53]
	v_mfma_f32_16x16x32_bf16 v[38:41], v[234:237], v[204:207], v[38:41]
	v_mfma_f32_16x16x32_bf16 v[34:37], v[242:245], v[204:207], v[34:37]
	v_mfma_f32_16x16x32_bf16 v[22:25], v[234:237], v[212:215], v[22:25]
	v_mfma_f32_16x16x32_bf16 v[18:21], v[242:245], v[212:215], v[18:21]
	v_mfma_f32_16x16x32_bf16 v[6:9], v[234:237], v[226:229], v[6:9]
	v_mfma_f32_16x16x32_bf16 v[2:5], v[242:245], v[226:229], v[2:5]
	s_add_i32 s93, s93, 2
	s_add_u32 s36, s36, 0x100
	s_addc_u32 s37, s37, 0
	s_add_u32 s91, s91, 0x100
	s_addc_u32 s92, s92, 0
	s_cmp_gt_u32 s93, 13
	s_barrier
	s_add_u32 s6, s36, 0xfffc0080
	s_addc_u32 s7, s37, -1
	s_add_i32 s58, 0, 0x10000
	v_add_u32_e32 v144, s58, v147
	ds_read_b128 v[140:143], v144
	ds_read_b128 v[152:155], v144 offset:1024
	ds_read_b128 v[168:171], v144 offset:2048
	ds_read_b128 v[172:175], v144 offset:3072
	s_cmp_eq_u32 s93, 12
	s_cselect_b32 s43, s11, s7
	s_cselect_b32 s42, s71, s6
	s_cselect_b32 s7, s9, s92
	s_cselect_b32 s6, s90, s91
	s_add_i32 m0, s49, 0xc000
	ds_read_b128 v[176:179], v150
	ds_read_b128 v[180:183], v150 offset:1024
	ds_read_b128 v[184:187], v150 offset:2048
	ds_read_b128 v[204:207], v150 offset:3072
	ds_read_b128 v[208:211], v150 offset:4096
	ds_read_b128 v[212:215], v150 offset:5120
	ds_read_b128 v[216:219], v150 offset:6144
	ds_read_b128 v[226:229], v150 offset:7168
	global_load_lds_dwordx4 v136, s[36:37]
	s_add_i32 m0, s49, 0xe000
	s_nop 0
	global_load_lds_dwordx4 v138, s[36:37]
	s_waitcnt lgkmcnt(8)
	s_barrier
	s_waitcnt lgkmcnt(0)
	s_waitcnt lgkmcnt(0)
	v_mfma_f32_16x16x32_bf16 v[126:129], v[140:143], v[176:179], v[126:129]
	v_mfma_f32_16x16x32_bf16 v[122:125], v[168:171], v[176:179], v[122:125]
	v_mfma_f32_16x16x32_bf16 v[110:113], v[140:143], v[184:187], v[110:113]
	v_mfma_f32_16x16x32_bf16 v[106:109], v[168:171], v[184:187], v[106:109]
	v_mfma_f32_16x16x32_bf16 v[94:97], v[140:143], v[208:211], v[94:97]
	v_mfma_f32_16x16x32_bf16 v[90:93], v[168:171], v[208:211], v[90:93]
	v_mfma_f32_16x16x32_bf16 v[78:81], v[140:143], v[216:219], v[78:81]
	v_mfma_f32_16x16x32_bf16 v[74:77], v[168:171], v[216:219], v[74:77]
	v_mfma_f32_16x16x32_bf16 v[126:129], v[152:155], v[180:183], v[126:129]
	v_mfma_f32_16x16x32_bf16 v[122:125], v[172:175], v[180:183], v[122:125]
	v_mfma_f32_16x16x32_bf16 v[110:113], v[152:155], v[204:207], v[110:113]
	v_mfma_f32_16x16x32_bf16 v[106:109], v[172:175], v[204:207], v[106:109]
	v_mfma_f32_16x16x32_bf16 v[94:97], v[152:155], v[212:215], v[94:97]
	v_mfma_f32_16x16x32_bf16 v[90:93], v[172:175], v[212:215], v[90:93]
	v_mfma_f32_16x16x32_bf16 v[78:81], v[152:155], v[226:229], v[78:81]
	v_mfma_f32_16x16x32_bf16 v[74:77], v[172:175], v[226:229], v[74:77]
	s_barrier
	s_add_i32 s70, 0, 0x14000
	v_add_u32_e32 v144, s70, v147
	s_add_i32 s58, s58, s48
	ds_read_b128 v[230:233], v144
	ds_read_b128 v[234:237], v144 offset:1024
	ds_read_b128 v[238:241], v144 offset:2048
	ds_read_b128 v[242:245], v144 offset:3072
	s_mov_b32 m0, s58
	s_nop 0
	global_load_lds_dwordx4 v0, s[6:7]
	s_add_i32 m0, s58, 0x2000
	s_nop 0
	global_load_lds_dwordx4 v130, s[6:7]
	s_barrier
	s_waitcnt lgkmcnt(0)
	s_waitcnt lgkmcnt(0)
	v_mfma_f32_16x16x32_bf16 v[118:121], v[230:233], v[176:179], v[118:121]
	v_mfma_f32_16x16x32_bf16 v[114:117], v[238:241], v[176:179], v[114:117]
	v_mfma_f32_16x16x32_bf16 v[102:105], v[230:233], v[184:187], v[102:105]
	v_mfma_f32_16x16x32_bf16 v[98:101], v[238:241], v[184:187], v[98:101]
	v_mfma_f32_16x16x32_bf16 v[86:89], v[230:233], v[208:211], v[86:89]
	v_mfma_f32_16x16x32_bf16 v[82:85], v[238:241], v[208:211], v[82:85]
	v_mfma_f32_16x16x32_bf16 v[70:73], v[230:233], v[216:219], v[70:73]
	v_mfma_f32_16x16x32_bf16 v[66:69], v[238:241], v[216:219], v[66:69]
	v_mfma_f32_16x16x32_bf16 v[118:121], v[234:237], v[180:183], v[118:121]
	v_mfma_f32_16x16x32_bf16 v[114:117], v[242:245], v[180:183], v[114:117]
	v_mfma_f32_16x16x32_bf16 v[102:105], v[234:237], v[204:207], v[102:105]
	v_mfma_f32_16x16x32_bf16 v[98:101], v[242:245], v[204:207], v[98:101]
	v_mfma_f32_16x16x32_bf16 v[86:89], v[234:237], v[212:215], v[86:89]
	v_mfma_f32_16x16x32_bf16 v[82:85], v[242:245], v[212:215], v[82:85]
	v_mfma_f32_16x16x32_bf16 v[70:73], v[234:237], v[226:229], v[70:73]
	v_mfma_f32_16x16x32_bf16 v[66:69], v[242:245], v[226:229], v[66:69]
	s_mov_b32 m0, s49
	s_add_u32 vcc_lo, s42, 0x80
	s_addc_u32 vcc_hi, s43, 0
	s_barrier
	ds_read_b128 v[176:179], v150 offset:16384
	ds_read_b128 v[180:183], v150 offset:17408
	ds_read_b128 v[184:187], v150 offset:18432
	ds_read_b128 v[204:207], v150 offset:19456
	ds_read_b128 v[208:211], v150 offset:20480
	ds_read_b128 v[212:215], v150 offset:21504
	ds_read_b128 v[216:219], v150 offset:22528
	ds_read_b128 v[226:229], v150 offset:23552
	global_load_lds_dwordx4 v134, s[42:43]
	s_mov_b32 m0, s54
	s_nop 0
	global_load_lds_dwordx4 v132, s[42:43]
	s_barrier
; #define PG8_STAGE(bufoff, gbase, voff) do { _Pragma("unroll") for (int _i = 0; _i < 2; ++_i) \
;         __builtin_amdgcn_global_load_lds((const unsigned*)((const char*)(gbase) + (voff)[_i]), (LAS unsigned*)(lds + (bufoff) + ldsw + _i * 8192), 16, 0, 0); } while (0)
; #define PG8_LDA(dst, b, h) do { _Pragma("unroll") for (int m = 0; m < 4; ++m) _Pragma("unroll") for (int k = 0; k < 2; ++k) dst[m][k] = *(const LAS bf16x8*)(lds + PG8_SA(b, h) + aoff + m * 2048 + k * 1024); } while (0)
; #define PG8_LDB(dst, b, h) do { _Pragma("unroll") for (int n = 0; n < 2; ++n) _Pragma("unroll") for (int k = 0; k < 2; ++k) dst[n][k] = *(const LAS bf16x8*)(lds + PG8_SB(b, h) + boff + n * 2048 + k * 1024); } while (0)
; #define PG8_MMA(ai, bj, At, Bt) do { __builtin_amdgcn_s_setprio(1); _Pragma("unroll") for (int m = 0; m < 4; ++m) _Pragma("unroll") for (int n = 0; n < 2; ++n) _Pragma("unroll") for (int k = 0; k < 2; ++k) \
;         acc[ai][bj][m][n] = __builtin_amdgcn_mfma_f32_16x16x32_bf16(Bt[n][k], At[m][k], acc[ai][bj][m][n], 0, 0, 0); __builtin_amdgcn_s_setprio(0); } while (0)
; #define PG8_WAIT_V(n) asm volatile("s_waitcnt vmcnt(" #n ")" ::: "memory")
; #define PG8_WAIT_L(n) asm volatile("s_waitcnt lgkmcnt(" #n ")" ::: "memory")
; #define PG8_BAR __builtin_amdgcn_s_barrier()
; #define PG8_SCHED __builtin_amdgcn_sched_barrier(0)
; template <class Epi>
; __device__ __forceinline__ void gemm_phase(LAS unsigned char* lds, const Gemm g, const StaticOrder& S, const Epi& E) {
;     ...
;             PG8_BAR; PG8_WAIT_L(0); PG8_MMA(1, 0, At, B0); PG8_BAR; PG8_SCHED;
;             PG8_STAGE(PG8_SB(0, 1), b2 + hstep, voffB);
;             PG8_WAIT_V(6); PG8_BAR; PG8_MMA(1, 1, At, B1); PG8_BAR;
;             PG8_LDB(B0, 1, 0); PG8_SCHED; PG8_LDA(At, 1, 0); PG8_STAGE(PG8_SA(0, 1), a2 + hstep, voffA);
;             PG8_WAIT_L(8); PG8_BAR; PG8_WAIT_L(0); PG8_MMA(0, 0, At, B0); PG8_BAR; PG8_SCHED;
;             PG8_LDB(B1, 1, 1); PG8_STAGE(PG8_SB(1, 0), b3, voffB);
	s_waitcnt lgkmcnt(0)
	s_waitcnt lgkmcnt(0)
	v_mfma_f32_16x16x32_bf16 v[62:65], v[140:143], v[176:179], v[62:65]
	v_mfma_f32_16x16x32_bf16 v[58:61], v[168:171], v[176:179], v[58:61]
	v_mfma_f32_16x16x32_bf16 v[46:49], v[140:143], v[184:187], v[46:49]
	v_mfma_f32_16x16x32_bf16 v[42:45], v[168:171], v[184:187], v[42:45]
	v_mfma_f32_16x16x32_bf16 v[30:33], v[140:143], v[208:211], v[30:33]
	v_mfma_f32_16x16x32_bf16 v[26:29], v[168:171], v[208:211], v[26:29]
	v_mfma_f32_16x16x32_bf16 v[14:17], v[140:143], v[216:219], v[14:17]
	v_mfma_f32_16x16x32_bf16 v[10:13], v[168:171], v[216:219], v[10:13]
	v_mfma_f32_16x16x32_bf16 v[62:65], v[152:155], v[180:183], v[62:65]
	v_mfma_f32_16x16x32_bf16 v[58:61], v[172:175], v[180:183], v[58:61]
	v_mfma_f32_16x16x32_bf16 v[46:49], v[152:155], v[204:207], v[46:49]
	v_mfma_f32_16x16x32_bf16 v[42:45], v[172:175], v[204:207], v[42:45]
	v_mfma_f32_16x16x32_bf16 v[30:33], v[152:155], v[212:215], v[30:33]
	v_mfma_f32_16x16x32_bf16 v[26:29], v[172:175], v[212:215], v[26:29]
	v_mfma_f32_16x16x32_bf16 v[14:17], v[152:155], v[226:229], v[14:17]
	v_mfma_f32_16x16x32_bf16 v[10:13], v[172:175], v[226:229], v[10:13]
	s_barrier
	s_add_u32 s60, s6, 0x40000
	s_addc_u32 s61, s7, 0
	s_add_i32 s58, s70, s48
	s_mov_b32 m0, s58
	s_nop 0
	global_load_lds_dwordx4 v0, s[60:61]
	s_add_i32 m0, s58, 0x2000
	s_nop 0
	global_load_lds_dwordx4 v130, s[60:61]
	s_waitcnt vmcnt(6)
	s_barrier
	v_mfma_f32_16x16x32_bf16 v[54:57], v[230:233], v[176:179], v[54:57]
	v_mfma_f32_16x16x32_bf16 v[50:53], v[238:241], v[176:179], v[50:53]
	s_cmp_eq_u32 s89, 0
	s_cbranch_scc1 .LdsE_skip_1
	global_store_dwordx4 v250, v[164:167], s[4:5] offset:256
	s_nop 1
	v_add_u32_e32 v250, 0x20000, v250
.LdsE_skip_1:
	v_mfma_f32_16x16x32_bf16 v[38:41], v[230:233], v[184:187], v[38:41]
	v_mfma_f32_16x16x32_bf16 v[34:37], v[238:241], v[184:187], v[34:37]
	v_mfma_f32_16x16x32_bf16 v[22:25], v[230:233], v[208:211], v[22:25]
	v_mfma_f32_16x16x32_bf16 v[18:21], v[238:241], v[208:211], v[18:21]
	v_mfma_f32_16x16x32_bf16 v[6:9], v[230:233], v[216:219], v[6:9]
	v_mfma_f32_16x16x32_bf16 v[2:5], v[238:241], v[216:219], v[2:5]
	v_mfma_f32_16x16x32_bf16 v[54:57], v[234:237], v[180:183], v[54:57]
	v_mfma_f32_16x16x32_bf16 v[50:53], v[242:245], v[180:183], v[50:53]
	v_mfma_f32_16x16x32_bf16 v[38:41], v[234:237], v[204:207], v[38:41]
	v_mfma_f32_16x16x32_bf16 v[34:37], v[242:245], v[204:207], v[34:37]
	v_mfma_f32_16x16x32_bf16 v[22:25], v[234:237], v[212:215], v[22:25]
	v_mfma_f32_16x16x32_bf16 v[18:21], v[242:245], v[212:215], v[18:21]
	v_mfma_f32_16x16x32_bf16 v[6:9], v[234:237], v[226:229], v[6:9]
	v_mfma_f32_16x16x32_bf16 v[2:5], v[242:245], v[226:229], v[2:5]
	s_add_i32 s58, 0, 0x18000
	v_add_u32_e32 v151, s58, v147
	s_barrier
	ds_read_b128 v[140:143], v151
	ds_read_b128 v[152:155], v151 offset:1024
	ds_read_b128 v[168:171], v151 offset:2048
	ds_read_b128 v[172:175], v151 offset:3072
	s_add_u32 s42, s42, 0x40000
	s_addc_u32 s43, s43, 0
	s_mov_b32 m0, s55
	ds_read_b128 v[176:179], v150 offset:32768
	ds_read_b128 v[180:183], v150 offset:33792
	ds_read_b128 v[184:187], v150 offset:34816
	ds_read_b128 v[204:207], v150 offset:35840
	ds_read_b128 v[208:211], v150 offset:36864
	ds_read_b128 v[212:215], v150 offset:37888
	ds_read_b128 v[216:219], v150 offset:38912
	ds_read_b128 v[226:229], v150 offset:39936
	global_load_lds_dwordx4 v134, s[42:43]
	s_mov_b32 m0, s83
	s_nop 0
	global_load_lds_dwordx4 v132, s[42:43]
	s_waitcnt lgkmcnt(8)
	s_barrier
	s_waitcnt lgkmcnt(0)
	s_waitcnt lgkmcnt(0)
	v_mfma_f32_16x16x32_bf16 v[126:129], v[140:143], v[176:179], v[126:129]
	v_mfma_f32_16x16x32_bf16 v[122:125], v[168:171], v[176:179], v[122:125]
	v_mfma_f32_16x16x32_bf16 v[110:113], v[140:143], v[184:187], v[110:113]
	v_mfma_f32_16x16x32_bf16 v[106:109], v[168:171], v[184:187], v[106:109]
	v_mfma_f32_16x16x32_bf16 v[94:97], v[140:143], v[208:211], v[94:97]
	v_mfma_f32_16x16x32_bf16 v[90:93], v[168:171], v[208:211], v[90:93]
	v_mfma_f32_16x16x32_bf16 v[78:81], v[140:143], v[216:219], v[78:81]
	v_mfma_f32_16x16x32_bf16 v[74:77], v[168:171], v[216:219], v[74:77]
	v_mfma_f32_16x16x32_bf16 v[126:129], v[152:155], v[180:183], v[126:129]
	v_mfma_f32_16x16x32_bf16 v[122:125], v[172:175], v[180:183], v[122:125]
	v_mfma_f32_16x16x32_bf16 v[110:113], v[152:155], v[204:207], v[110:113]
	v_mfma_f32_16x16x32_bf16 v[106:109], v[172:175], v[204:207], v[106:109]
	v_mfma_f32_16x16x32_bf16 v[94:97], v[152:155], v[212:215], v[94:97]
	v_mfma_f32_16x16x32_bf16 v[90:93], v[172:175], v[212:215], v[90:93]
	v_mfma_f32_16x16x32_bf16 v[78:81], v[152:155], v[226:229], v[78:81]
	v_mfma_f32_16x16x32_bf16 v[74:77], v[172:175], v[226:229], v[74:77]
	s_barrier
	s_add_i32 s42, 0, 0x1c000
	s_add_i32 s43, s58, s48
	v_add_u32_e32 v151, s42, v147
	s_add_u32 s60, s6, 0x80
	s_addc_u32 s61, s7, 0
	s_mov_b32 m0, s43
	ds_read_b128 v[230:233], v151
	ds_read_b128 v[234:237], v151 offset:1024
	ds_read_b128 v[238:241], v151 offset:2048
	ds_read_b128 v[242:245], v151 offset:3072
	global_load_lds_dwordx4 v0, s[60:61]
	s_add_i32 m0, s43, 0x2000
	s_nop 0
	global_load_lds_dwordx4 v130, s[60:61]
	s_barrier
; #define PG8_STAGE(bufoff, gbase, voff) do { _Pragma("unroll") for (int _i = 0; _i < 2; ++_i) \
;         __builtin_amdgcn_global_load_lds((const unsigned*)((const char*)(gbase) + (voff)[_i]), (LAS unsigned*)(lds + (bufoff) + ldsw + _i * 8192), 16, 0, 0); } while (0)
; #define PG8_LDA(dst, b, h) do { _Pragma("unroll") for (int m = 0; m < 4; ++m) _Pragma("unroll") for (int k = 0; k < 2; ++k) dst[m][k] = *(const LAS bf16x8*)(lds + PG8_SA(b, h) + aoff + m * 2048 + k * 1024); } while (0)
; #define PG8_LDB(dst, b, h) do { _Pragma("unroll") for (int n = 0; n < 2; ++n) _Pragma("unroll") for (int k = 0; k < 2; ++k) dst[n][k] = *(const LAS bf16x8*)(lds + PG8_SB(b, h) + boff + n * 2048 + k * 1024); } while (0)
; #define PG8_MMA(ai, bj, At, Bt) do { __builtin_amdgcn_s_setprio(1); _Pragma("unroll") for (int m = 0; m < 4; ++m) _Pragma("unroll") for (int n = 0; n < 2; ++n) _Pragma("unroll") for (int k = 0; k < 2; ++k) \
;         acc[ai][bj][m][n] = __builtin_amdgcn_mfma_f32_16x16x32_bf16(Bt[n][k], At[m][k], acc[ai][bj][m][n], 0, 0, 0); __builtin_amdgcn_s_setprio(0); } while (0)
; #define PG8_WAIT_V(n) asm volatile("s_waitcnt vmcnt(" #n ")" ::: "memory")
; #define PG8_WAIT_L(n) asm volatile("s_waitcnt lgkmcnt(" #n ")" ::: "memory")
; #define PG8_BAR __builtin_amdgcn_s_barrier()
; #define PG8_SCHED __builtin_amdgcn_sched_barrier(0)
; template <class Epi>
; __device__ __forceinline__ void gemm_phase(LAS unsigned char* lds, const Gemm g, const StaticOrder& S, const Epi& E) {
;     ...
;             const char* a1 = cA + (size_t)(t + 1) * kstep;
;             const char* a2 = last ? nA : cA + (size_t)(t + 2) * kstep; const char* b2 = last ? nB : cB + (size_t)(t + 2) * kstep;
;             const char* a3 = a2 + kstep; const char* b3 = b2 + kstep;
;             PG8_LDB(B0, 0, 0); PG8_SCHED; PG8_LDA(At, 0, 0); PG8_STAGE(PG8_SA(1, 1), a1 + hstep, voffA);
;     ...
;             PG8_BAR; PG8_WAIT_L(0); PG8_MMA(0, 1, At, B1); PG8_BAR;
;             PG8_LDA(At, 1, 1); PG8_STAGE(PG8_SA(1, 0), a3, voffA);
;             PG8_BAR; PG8_WAIT_L(0); PG8_MMA(1, 0, At, B0); PG8_BAR; PG8_SCHED;
;             PG8_STAGE(PG8_SB(1, 1), b3 + hstep, voffB);
;             PG8_WAIT_V(6); PG8_BAR; PG8_MMA(1, 1, At, B1); PG8_BAR;
	s_waitcnt lgkmcnt(0)
	s_waitcnt lgkmcnt(0)
	v_mfma_f32_16x16x32_bf16 v[118:121], v[230:233], v[176:179], v[118:121]
	v_mfma_f32_16x16x32_bf16 v[114:117], v[238:241], v[176:179], v[114:117]
	v_mfma_f32_16x16x32_bf16 v[102:105], v[230:233], v[184:187], v[102:105]
	v_mfma_f32_16x16x32_bf16 v[98:101], v[238:241], v[184:187], v[98:101]
	v_mfma_f32_16x16x32_bf16 v[86:89], v[230:233], v[208:211], v[86:89]
	v_mfma_f32_16x16x32_bf16 v[82:85], v[238:241], v[208:211], v[82:85]
	v_mfma_f32_16x16x32_bf16 v[70:73], v[230:233], v[216:219], v[70:73]
	v_mfma_f32_16x16x32_bf16 v[66:69], v[238:241], v[216:219], v[66:69]
	v_mfma_f32_16x16x32_bf16 v[118:121], v[234:237], v[180:183], v[118:121]
	v_mfma_f32_16x16x32_bf16 v[114:117], v[242:245], v[180:183], v[114:117]
	v_mfma_f32_16x16x32_bf16 v[102:105], v[234:237], v[204:207], v[102:105]
	v_mfma_f32_16x16x32_bf16 v[98:101], v[242:245], v[204:207], v[98:101]
	v_mfma_f32_16x16x32_bf16 v[86:89], v[234:237], v[212:215], v[86:89]
	v_mfma_f32_16x16x32_bf16 v[82:85], v[242:245], v[212:215], v[82:85]
	v_mfma_f32_16x16x32_bf16 v[70:73], v[234:237], v[226:229], v[70:73]
	v_mfma_f32_16x16x32_bf16 v[66:69], v[242:245], v[226:229], v[66:69]
	s_mov_b32 m0, s84
	s_barrier
	ds_read_b128 v[176:179], v150 offset:49152
	ds_read_b128 v[180:183], v150 offset:50176
	ds_read_b128 v[184:187], v150 offset:51200
	ds_read_b128 v[204:207], v150 offset:52224
	ds_read_b128 v[208:211], v150 offset:53248
	ds_read_b128 v[212:215], v150 offset:54272
	ds_read_b128 v[216:219], v150 offset:55296
	ds_read_b128 v[226:229], v150 offset:56320
	global_load_lds_dwordx4 v134, vcc
	s_mov_b32 m0, s85
	s_nop 0
	global_load_lds_dwordx4 v132, vcc
	s_barrier
	s_waitcnt lgkmcnt(0)
	s_waitcnt lgkmcnt(0)
	v_mfma_f32_16x16x32_bf16 v[62:65], v[140:143], v[176:179], v[62:65]
	v_mfma_f32_16x16x32_bf16 v[58:61], v[168:171], v[176:179], v[58:61]
	v_mfma_f32_16x16x32_bf16 v[46:49], v[140:143], v[184:187], v[46:49]
	v_mfma_f32_16x16x32_bf16 v[42:45], v[168:171], v[184:187], v[42:45]
	v_mfma_f32_16x16x32_bf16 v[30:33], v[140:143], v[208:211], v[30:33]
	v_mfma_f32_16x16x32_bf16 v[26:29], v[168:171], v[208:211], v[26:29]
	v_mfma_f32_16x16x32_bf16 v[14:17], v[140:143], v[216:219], v[14:17]
	v_mfma_f32_16x16x32_bf16 v[10:13], v[168:171], v[216:219], v[10:13]
	v_mfma_f32_16x16x32_bf16 v[62:65], v[152:155], v[180:183], v[62:65]
	v_mfma_f32_16x16x32_bf16 v[58:61], v[172:175], v[180:183], v[58:61]
	v_mfma_f32_16x16x32_bf16 v[46:49], v[152:155], v[204:207], v[46:49]
	v_mfma_f32_16x16x32_bf16 v[42:45], v[172:175], v[204:207], v[42:45]
	v_mfma_f32_16x16x32_bf16 v[30:33], v[152:155], v[212:215], v[30:33]
	v_mfma_f32_16x16x32_bf16 v[26:29], v[172:175], v[212:215], v[26:29]
	v_mfma_f32_16x16x32_bf16 v[14:17], v[152:155], v[226:229], v[14:17]
	v_mfma_f32_16x16x32_bf16 v[10:13], v[172:175], v[226:229], v[10:13]
	s_barrier
	s_add_u32 s6, s6, 0x40080
	s_addc_u32 s7, s7, 0
	s_add_i32 s42, s42, s48
	s_mov_b32 m0, s42
	s_nop 0
	global_load_lds_dwordx4 v0, s[6:7]
	s_add_i32 m0, s42, 0x2000
	s_nop 0
	global_load_lds_dwordx4 v130, s[6:7]
	s_waitcnt vmcnt(6)
	s_barrier
	v_mfma_f32_16x16x32_bf16 v[54:57], v[230:233], v[176:179], v[54:57]
	v_mfma_f32_16x16x32_bf16 v[50:53], v[238:241], v[176:179], v[50:53]
	v_mfma_f32_16x16x32_bf16 v[38:41], v[230:233], v[184:187], v[38:41]
	v_mfma_f32_16x16x32_bf16 v[34:37], v[238:241], v[184:187], v[34:37]
	v_mfma_f32_16x16x32_bf16 v[22:25], v[230:233], v[208:211], v[22:25]
	v_mfma_f32_16x16x32_bf16 v[18:21], v[238:241], v[208:211], v[18:21]
	v_mfma_f32_16x16x32_bf16 v[6:9], v[230:233], v[216:219], v[6:9]
	v_mfma_f32_16x16x32_bf16 v[2:5], v[238:241], v[216:219], v[2:5]
	v_mfma_f32_16x16x32_bf16 v[54:57], v[234:237], v[180:183], v[54:57]
	v_mfma_f32_16x16x32_bf16 v[50:53], v[242:245], v[180:183], v[50:53]
	v_mfma_f32_16x16x32_bf16 v[38:41], v[234:237], v[204:207], v[38:41]
	v_mfma_f32_16x16x32_bf16 v[34:37], v[242:245], v[204:207], v[34:37]
	v_mfma_f32_16x16x32_bf16 v[22:25], v[234:237], v[212:215], v[22:25]
	v_mfma_f32_16x16x32_bf16 v[18:21], v[242:245], v[212:215], v[18:21]
	v_mfma_f32_16x16x32_bf16 v[6:9], v[234:237], v[226:229], v[6:9]
	v_mfma_f32_16x16x32_bf16 v[2:5], v[242:245], v[226:229], v[2:5]
	s_add_i32 s93, s93, 2
	s_add_u32 s36, s36, 0x100
	s_addc_u32 s37, s37, 0
	s_add_u32 s91, s91, 0x100
	s_addc_u32 s92, s92, 0
	s_cmp_gt_u32 s93, 13
	s_barrier
	s_add_u32 s6, s36, 0xfffc0080
	s_addc_u32 s7, s37, -1
	s_add_i32 s58, 0, 0x10000
	v_add_u32_e32 v144, s58, v147
	ds_read_b128 v[140:143], v144
	ds_read_b128 v[152:155], v144 offset:1024
	ds_read_b128 v[168:171], v144 offset:2048
	ds_read_b128 v[172:175], v144 offset:3072
	s_cmp_eq_u32 s93, 12
	s_cselect_b32 s43, s11, s7
	s_cselect_b32 s42, s71, s6
	s_cselect_b32 s7, s9, s92
	s_cselect_b32 s6, s90, s91
	s_add_i32 m0, s49, 0xc000
	ds_read_b128 v[176:179], v150
	ds_read_b128 v[180:183], v150 offset:1024
	ds_read_b128 v[184:187], v150 offset:2048
	ds_read_b128 v[204:207], v150 offset:3072
	ds_read_b128 v[208:211], v150 offset:4096
	ds_read_b128 v[212:215], v150 offset:5120
	ds_read_b128 v[216:219], v150 offset:6144
	ds_read_b128 v[226:229], v150 offset:7168
	global_load_lds_dwordx4 v136, s[36:37]
	s_add_i32 m0, s49, 0xe000
	s_nop 0
	global_load_lds_dwordx4 v138, s[36:37]
	s_waitcnt lgkmcnt(8)
	s_barrier
; #define PG8_STAGE(bufoff, gbase, voff) do { _Pragma("unroll") for (int _i = 0; _i < 2; ++_i) \
;         __builtin_amdgcn_global_load_lds((const unsigned*)((const char*)(gbase) + (voff)[_i]), (LAS unsigned*)(lds + (bufoff) + ldsw + _i * 8192), 16, 0, 0); } while (0)
; #define PG8_LDA(dst, b, h) do { _Pragma("unroll") for (int m = 0; m < 4; ++m) _Pragma("unroll") for (int k = 0; k < 2; ++k) dst[m][k] = *(const LAS bf16x8*)(lds + PG8_SA(b, h) + aoff + m * 2048 + k * 1024); } while (0)
; #define PG8_LDB(dst, b, h) do { _Pragma("unroll") for (int n = 0; n < 2; ++n) _Pragma("unroll") for (int k = 0; k < 2; ++k) dst[n][k] = *(const LAS bf16x8*)(lds + PG8_SB(b, h) + boff + n * 2048 + k * 1024); } while (0)
; #define PG8_MMA(ai, bj, At, Bt) do { __builtin_amdgcn_s_setprio(1); _Pragma("unroll") for (int m = 0; m < 4; ++m) _Pragma("unroll") for (int n = 0; n < 2; ++n) _Pragma("unroll") for (int k = 0; k < 2; ++k) \
;         acc[ai][bj][m][n] = __builtin_amdgcn_mfma_f32_16x16x32_bf16(Bt[n][k], At[m][k], acc[ai][bj][m][n], 0, 0, 0); __builtin_amdgcn_s_setprio(0); } while (0)
; #define PG8_WAIT_V(n) asm volatile("s_waitcnt vmcnt(" #n ")" ::: "memory")
; #define PG8_WAIT_L(n) asm volatile("s_waitcnt lgkmcnt(" #n ")" ::: "memory")
; #define PG8_BAR __builtin_amdgcn_s_barrier()
; #define PG8_SCHED __builtin_amdgcn_sched_barrier(0)
; template <class Epi>
; __device__ __forceinline__ void gemm_phase(LAS unsigned char* lds, const Gemm g, const StaticOrder& S, const Epi& E) {
;     ...
;             PG8_WAIT_L(8); PG8_BAR; PG8_WAIT_L(0); PG8_MMA(0, 0, At, B0); PG8_BAR; PG8_SCHED;
;             PG8_LDB(B1, 0, 1); PG8_STAGE(PG8_SB(0, 0), b2, voffB);
;             PG8_BAR; PG8_WAIT_L(0); PG8_MMA(0, 1, At, B1); PG8_BAR;
;             PG8_LDA(At, 0, 1); PG8_STAGE(PG8_SA(0, 0), a2, voffA);
;             PG8_BAR; PG8_WAIT_L(0); PG8_MMA(1, 0, At, B0); PG8_BAR; PG8_SCHED;
;             PG8_STAGE(PG8_SB(0, 1), b2 + hstep, voffB);
;             PG8_WAIT_V(6); PG8_BAR; PG8_MMA(1, 1, At, B1); PG8_BAR;
	s_waitcnt lgkmcnt(0)
	s_waitcnt lgkmcnt(0)
	v_mfma_f32_16x16x32_bf16 v[126:129], v[140:143], v[176:179], v[126:129]
	v_mfma_f32_16x16x32_bf16 v[122:125], v[168:171], v[176:179], v[122:125]
	v_mfma_f32_16x16x32_bf16 v[110:113], v[140:143], v[184:187], v[110:113]
	v_mfma_f32_16x16x32_bf16 v[106:109], v[168:171], v[184:187], v[106:109]
	v_mfma_f32_16x16x32_bf16 v[94:97], v[140:143], v[208:211], v[94:97]
	v_mfma_f32_16x16x32_bf16 v[90:93], v[168:171], v[208:211], v[90:93]
	v_mfma_f32_16x16x32_bf16 v[78:81], v[140:143], v[216:219], v[78:81]
	v_mfma_f32_16x16x32_bf16 v[74:77], v[168:171], v[216:219], v[74:77]
	v_mfma_f32_16x16x32_bf16 v[126:129], v[152:155], v[180:183], v[126:129]
	v_mfma_f32_16x16x32_bf16 v[122:125], v[172:175], v[180:183], v[122:125]
	v_mfma_f32_16x16x32_bf16 v[110:113], v[152:155], v[204:207], v[110:113]
	v_mfma_f32_16x16x32_bf16 v[106:109], v[172:175], v[204:207], v[106:109]
	v_mfma_f32_16x16x32_bf16 v[94:97], v[152:155], v[212:215], v[94:97]
	v_mfma_f32_16x16x32_bf16 v[90:93], v[172:175], v[212:215], v[90:93]
	v_mfma_f32_16x16x32_bf16 v[78:81], v[152:155], v[226:229], v[78:81]
	v_mfma_f32_16x16x32_bf16 v[74:77], v[172:175], v[226:229], v[74:77]
	s_barrier
	s_add_i32 s70, 0, 0x14000
	v_add_u32_e32 v144, s70, v147
	s_add_i32 s58, s58, s48
	ds_read_b128 v[230:233], v144
	ds_read_b128 v[234:237], v144 offset:1024
	ds_read_b128 v[238:241], v144 offset:2048
	ds_read_b128 v[242:245], v144 offset:3072
	s_mov_b32 m0, s58
	s_nop 0
	global_load_lds_dwordx4 v0, s[6:7]
	s_add_i32 m0, s58, 0x2000
	s_nop 0
	global_load_lds_dwordx4 v130, s[6:7]
	s_barrier
	s_waitcnt lgkmcnt(0)
	s_waitcnt lgkmcnt(0)
	v_mfma_f32_16x16x32_bf16 v[118:121], v[230:233], v[176:179], v[118:121]
	v_mfma_f32_16x16x32_bf16 v[114:117], v[238:241], v[176:179], v[114:117]
	v_mfma_f32_16x16x32_bf16 v[102:105], v[230:233], v[184:187], v[102:105]
	v_mfma_f32_16x16x32_bf16 v[98:101], v[238:241], v[184:187], v[98:101]
	v_mfma_f32_16x16x32_bf16 v[86:89], v[230:233], v[208:211], v[86:89]
	v_mfma_f32_16x16x32_bf16 v[82:85], v[238:241], v[208:211], v[82:85]
	v_mfma_f32_16x16x32_bf16 v[70:73], v[230:233], v[216:219], v[70:73]
	v_mfma_f32_16x16x32_bf16 v[66:69], v[238:241], v[216:219], v[66:69]
	v_mfma_f32_16x16x32_bf16 v[118:121], v[234:237], v[180:183], v[118:121]
	v_mfma_f32_16x16x32_bf16 v[114:117], v[242:245], v[180:183], v[114:117]
	v_mfma_f32_16x16x32_bf16 v[102:105], v[234:237], v[204:207], v[102:105]
	v_mfma_f32_16x16x32_bf16 v[98:101], v[242:245], v[204:207], v[98:101]
	v_mfma_f32_16x16x32_bf16 v[86:89], v[234:237], v[212:215], v[86:89]
	v_mfma_f32_16x16x32_bf16 v[82:85], v[242:245], v[212:215], v[82:85]
	v_mfma_f32_16x16x32_bf16 v[70:73], v[234:237], v[226:229], v[70:73]
	v_mfma_f32_16x16x32_bf16 v[66:69], v[242:245], v[226:229], v[66:69]
	s_mov_b32 m0, s49
	s_add_u32 vcc_lo, s42, 0x80
	s_addc_u32 vcc_hi, s43, 0
	s_barrier
	ds_read_b128 v[176:179], v150 offset:16384
	ds_read_b128 v[180:183], v150 offset:17408
	ds_read_b128 v[184:187], v150 offset:18432
	ds_read_b128 v[204:207], v150 offset:19456
	ds_read_b128 v[208:211], v150 offset:20480
	ds_read_b128 v[212:215], v150 offset:21504
	ds_read_b128 v[216:219], v150 offset:22528
	ds_read_b128 v[226:229], v150 offset:23552
	global_load_lds_dwordx4 v134, s[42:43]
	s_mov_b32 m0, s54
	s_nop 0
	global_load_lds_dwordx4 v132, s[42:43]
	s_barrier
	s_waitcnt lgkmcnt(0)
	s_waitcnt lgkmcnt(0)
	v_mfma_f32_16x16x32_bf16 v[62:65], v[140:143], v[176:179], v[62:65]
	v_mfma_f32_16x16x32_bf16 v[58:61], v[168:171], v[176:179], v[58:61]
	v_mfma_f32_16x16x32_bf16 v[46:49], v[140:143], v[184:187], v[46:49]
	v_mfma_f32_16x16x32_bf16 v[42:45], v[168:171], v[184:187], v[42:45]
	v_mfma_f32_16x16x32_bf16 v[30:33], v[140:143], v[208:211], v[30:33]
	v_mfma_f32_16x16x32_bf16 v[26:29], v[168:171], v[208:211], v[26:29]
	v_mfma_f32_16x16x32_bf16 v[14:17], v[140:143], v[216:219], v[14:17]
	v_mfma_f32_16x16x32_bf16 v[10:13], v[168:171], v[216:219], v[10:13]
	v_mfma_f32_16x16x32_bf16 v[62:65], v[152:155], v[180:183], v[62:65]
	v_mfma_f32_16x16x32_bf16 v[58:61], v[172:175], v[180:183], v[58:61]
	v_mfma_f32_16x16x32_bf16 v[46:49], v[152:155], v[204:207], v[46:49]
	v_mfma_f32_16x16x32_bf16 v[42:45], v[172:175], v[204:207], v[42:45]
	v_mfma_f32_16x16x32_bf16 v[30:33], v[152:155], v[212:215], v[30:33]
	v_mfma_f32_16x16x32_bf16 v[26:29], v[172:175], v[212:215], v[26:29]
	v_mfma_f32_16x16x32_bf16 v[14:17], v[152:155], v[226:229], v[14:17]
	v_mfma_f32_16x16x32_bf16 v[10:13], v[172:175], v[226:229], v[10:13]
	s_barrier
	s_add_u32 s60, s6, 0x40000
	s_addc_u32 s61, s7, 0
	s_add_i32 s58, s70, s48
	s_mov_b32 m0, s58
	s_nop 0
	global_load_lds_dwordx4 v0, s[60:61]
	s_add_i32 m0, s58, 0x2000
	s_nop 0
	global_load_lds_dwordx4 v130, s[60:61]
	s_waitcnt vmcnt(6)
	s_barrier
	v_mfma_f32_16x16x32_bf16 v[54:57], v[230:233], v[176:179], v[54:57]
	v_mfma_f32_16x16x32_bf16 v[50:53], v[238:241], v[176:179], v[50:53]
	s_cmp_eq_u32 s89, 0
	s_cbranch_scc1 .LdsE_skip_2
	global_store_dwordx4 v250, v[188:191], s[4:5]
; #define PG8_STAGE(bufoff, gbase, voff) do { _Pragma("unroll") for (int _i = 0; _i < 2; ++_i) \
;         __builtin_amdgcn_global_load_lds((const unsigned*)((const char*)(gbase) + (voff)[_i]), (LAS unsigned*)(lds + (bufoff) + ldsw + _i * 8192), 16, 0, 0); } while (0)
; #define PG8_LDA(dst, b, h) do { _Pragma("unroll") for (int m = 0; m < 4; ++m) _Pragma("unroll") for (int k = 0; k < 2; ++k) dst[m][k] = *(const LAS bf16x8*)(lds + PG8_SA(b, h) + aoff + m * 2048 + k * 1024); } while (0)
; #define PG8_LDB(dst, b, h) do { _Pragma("unroll") for (int n = 0; n < 2; ++n) _Pragma("unroll") for (int k = 0; k < 2; ++k) dst[n][k] = *(const LAS bf16x8*)(lds + PG8_SB(b, h) + boff + n * 2048 + k * 1024); } while (0)
; #define PG8_MMA(ai, bj, At, Bt) do { __builtin_amdgcn_s_setprio(1); _Pragma("unroll") for (int m = 0; m < 4; ++m) _Pragma("unroll") for (int n = 0; n < 2; ++n) _Pragma("unroll") for (int k = 0; k < 2; ++k) \
;         acc[ai][bj][m][n] = __builtin_amdgcn_mfma_f32_16x16x32_bf16(Bt[n][k], At[m][k], acc[ai][bj][m][n], 0, 0, 0); __builtin_amdgcn_s_setprio(0); } while (0)
; #define PG8_WAIT_V(n) asm volatile("s_waitcnt vmcnt(" #n ")" ::: "memory")
; #define PG8_WAIT_L(n) asm volatile("s_waitcnt lgkmcnt(" #n ")" ::: "memory")
; #define PG8_BAR __builtin_amdgcn_s_barrier()
; #define PG8_SCHED __builtin_amdgcn_sched_barrier(0)
; template <class Epi>
; __device__ __forceinline__ void gemm_phase(LAS unsigned char* lds, const Gemm g, const StaticOrder& S, const Epi& E) {
;     ...
;             PG8_WAIT_V(6); PG8_BAR; PG8_MMA(1, 1, At, B1); PG8_BAR;
;             PG8_LDB(B0, 1, 0); PG8_SCHED; PG8_LDA(At, 1, 0); PG8_STAGE(PG8_SA(0, 1), a2 + hstep, voffA);
;             PG8_WAIT_L(8); PG8_BAR; PG8_WAIT_L(0); PG8_MMA(0, 0, At, B0); PG8_BAR; PG8_SCHED;
;             PG8_LDB(B1, 1, 1); PG8_STAGE(PG8_SB(1, 0), b3, voffB);
;             PG8_BAR; PG8_WAIT_L(0); PG8_MMA(0, 1, At, B1); PG8_BAR;
;             PG8_LDA(At, 1, 1); PG8_STAGE(PG8_SA(1, 0), a3, voffA);
;             PG8_BAR; PG8_WAIT_L(0); PG8_MMA(1, 0, At, B0); PG8_BAR; PG8_SCHED;
.LdsE_skip_2:
	v_mfma_f32_16x16x32_bf16 v[38:41], v[230:233], v[184:187], v[38:41]
	v_mfma_f32_16x16x32_bf16 v[34:37], v[238:241], v[184:187], v[34:37]
	v_mfma_f32_16x16x32_bf16 v[22:25], v[230:233], v[208:211], v[22:25]
	v_mfma_f32_16x16x32_bf16 v[18:21], v[238:241], v[208:211], v[18:21]
	v_mfma_f32_16x16x32_bf16 v[6:9], v[230:233], v[216:219], v[6:9]
	v_mfma_f32_16x16x32_bf16 v[2:5], v[238:241], v[216:219], v[2:5]
	v_mfma_f32_16x16x32_bf16 v[54:57], v[234:237], v[180:183], v[54:57]
	v_mfma_f32_16x16x32_bf16 v[50:53], v[242:245], v[180:183], v[50:53]
	v_mfma_f32_16x16x32_bf16 v[38:41], v[234:237], v[204:207], v[38:41]
	v_mfma_f32_16x16x32_bf16 v[34:37], v[242:245], v[204:207], v[34:37]
	v_mfma_f32_16x16x32_bf16 v[22:25], v[234:237], v[212:215], v[22:25]
	v_mfma_f32_16x16x32_bf16 v[18:21], v[242:245], v[212:215], v[18:21]
	v_mfma_f32_16x16x32_bf16 v[6:9], v[234:237], v[226:229], v[6:9]
	v_mfma_f32_16x16x32_bf16 v[2:5], v[242:245], v[226:229], v[2:5]
	s_add_i32 s58, 0, 0x18000
	v_add_u32_e32 v151, s58, v147
	s_barrier
	ds_read_b128 v[140:143], v151
	ds_read_b128 v[152:155], v151 offset:1024
	ds_read_b128 v[168:171], v151 offset:2048
	ds_read_b128 v[172:175], v151 offset:3072
	s_add_u32 s42, s42, 0x40000
	s_addc_u32 s43, s43, 0
	s_mov_b32 m0, s55
	ds_read_b128 v[176:179], v150 offset:32768
	ds_read_b128 v[180:183], v150 offset:33792
	ds_read_b128 v[184:187], v150 offset:34816
	ds_read_b128 v[204:207], v150 offset:35840
	ds_read_b128 v[208:211], v150 offset:36864
	ds_read_b128 v[212:215], v150 offset:37888
	ds_read_b128 v[216:219], v150 offset:38912
	ds_read_b128 v[226:229], v150 offset:39936
	global_load_lds_dwordx4 v134, s[42:43]
	s_mov_b32 m0, s83
	s_nop 0
	global_load_lds_dwordx4 v132, s[42:43]
	s_waitcnt lgkmcnt(8)
	s_barrier
	s_waitcnt lgkmcnt(0)
	s_waitcnt lgkmcnt(0)
	v_mfma_f32_16x16x32_bf16 v[126:129], v[140:143], v[176:179], v[126:129]
	v_mfma_f32_16x16x32_bf16 v[122:125], v[168:171], v[176:179], v[122:125]
	v_mfma_f32_16x16x32_bf16 v[110:113], v[140:143], v[184:187], v[110:113]
	v_mfma_f32_16x16x32_bf16 v[106:109], v[168:171], v[184:187], v[106:109]
	v_mfma_f32_16x16x32_bf16 v[94:97], v[140:143], v[208:211], v[94:97]
	v_mfma_f32_16x16x32_bf16 v[90:93], v[168:171], v[208:211], v[90:93]
	v_mfma_f32_16x16x32_bf16 v[78:81], v[140:143], v[216:219], v[78:81]
	v_mfma_f32_16x16x32_bf16 v[74:77], v[168:171], v[216:219], v[74:77]
	v_mfma_f32_16x16x32_bf16 v[126:129], v[152:155], v[180:183], v[126:129]
	v_mfma_f32_16x16x32_bf16 v[122:125], v[172:175], v[180:183], v[122:125]
	v_mfma_f32_16x16x32_bf16 v[110:113], v[152:155], v[204:207], v[110:113]
	v_mfma_f32_16x16x32_bf16 v[106:109], v[172:175], v[204:207], v[106:109]
	v_mfma_f32_16x16x32_bf16 v[94:97], v[152:155], v[212:215], v[94:97]
	v_mfma_f32_16x16x32_bf16 v[90:93], v[172:175], v[212:215], v[90:93]
	v_mfma_f32_16x16x32_bf16 v[78:81], v[152:155], v[226:229], v[78:81]
	v_mfma_f32_16x16x32_bf16 v[74:77], v[172:175], v[226:229], v[74:77]
	s_barrier
	s_add_i32 s42, 0, 0x1c000
	s_add_i32 s43, s58, s48
	v_add_u32_e32 v151, s42, v147
	s_add_u32 s60, s6, 0x80
	s_addc_u32 s61, s7, 0
	s_mov_b32 m0, s43
	ds_read_b128 v[230:233], v151
	ds_read_b128 v[234:237], v151 offset:1024
	ds_read_b128 v[238:241], v151 offset:2048
	ds_read_b128 v[242:245], v151 offset:3072
	global_load_lds_dwordx4 v0, s[60:61]
	s_add_i32 m0, s43, 0x2000
	s_nop 0
	global_load_lds_dwordx4 v130, s[60:61]
	s_barrier
	s_waitcnt lgkmcnt(0)
	s_waitcnt lgkmcnt(0)
	v_mfma_f32_16x16x32_bf16 v[118:121], v[230:233], v[176:179], v[118:121]
	v_mfma_f32_16x16x32_bf16 v[114:117], v[238:241], v[176:179], v[114:117]
	v_mfma_f32_16x16x32_bf16 v[102:105], v[230:233], v[184:187], v[102:105]
	v_mfma_f32_16x16x32_bf16 v[98:101], v[238:241], v[184:187], v[98:101]
	v_mfma_f32_16x16x32_bf16 v[86:89], v[230:233], v[208:211], v[86:89]
	v_mfma_f32_16x16x32_bf16 v[82:85], v[238:241], v[208:211], v[82:85]
	v_mfma_f32_16x16x32_bf16 v[70:73], v[230:233], v[216:219], v[70:73]
	v_mfma_f32_16x16x32_bf16 v[66:69], v[238:241], v[216:219], v[66:69]
	v_mfma_f32_16x16x32_bf16 v[118:121], v[234:237], v[180:183], v[118:121]
	v_mfma_f32_16x16x32_bf16 v[114:117], v[242:245], v[180:183], v[114:117]
	v_mfma_f32_16x16x32_bf16 v[102:105], v[234:237], v[204:207], v[102:105]
	v_mfma_f32_16x16x32_bf16 v[98:101], v[242:245], v[204:207], v[98:101]
	v_mfma_f32_16x16x32_bf16 v[86:89], v[234:237], v[212:215], v[86:89]
	v_mfma_f32_16x16x32_bf16 v[82:85], v[242:245], v[212:215], v[82:85]
	v_mfma_f32_16x16x32_bf16 v[70:73], v[234:237], v[226:229], v[70:73]
	v_mfma_f32_16x16x32_bf16 v[66:69], v[242:245], v[226:229], v[66:69]
	s_mov_b32 m0, s84
	s_barrier
	ds_read_b128 v[176:179], v150 offset:49152
	ds_read_b128 v[180:183], v150 offset:50176
	ds_read_b128 v[184:187], v150 offset:51200
	ds_read_b128 v[204:207], v150 offset:52224
	ds_read_b128 v[208:211], v150 offset:53248
	ds_read_b128 v[212:215], v150 offset:54272
	ds_read_b128 v[216:219], v150 offset:55296
	ds_read_b128 v[226:229], v150 offset:56320
	global_load_lds_dwordx4 v134, vcc
	s_mov_b32 m0, s85
	s_nop 0
	global_load_lds_dwordx4 v132, vcc
	s_barrier
	s_waitcnt lgkmcnt(0)
	s_waitcnt lgkmcnt(0)
	v_mfma_f32_16x16x32_bf16 v[62:65], v[140:143], v[176:179], v[62:65]
	v_mfma_f32_16x16x32_bf16 v[58:61], v[168:171], v[176:179], v[58:61]
	v_mfma_f32_16x16x32_bf16 v[46:49], v[140:143], v[184:187], v[46:49]
	v_mfma_f32_16x16x32_bf16 v[42:45], v[168:171], v[184:187], v[42:45]
	v_mfma_f32_16x16x32_bf16 v[30:33], v[140:143], v[208:211], v[30:33]
	v_mfma_f32_16x16x32_bf16 v[26:29], v[168:171], v[208:211], v[26:29]
	v_mfma_f32_16x16x32_bf16 v[14:17], v[140:143], v[216:219], v[14:17]
	v_mfma_f32_16x16x32_bf16 v[10:13], v[168:171], v[216:219], v[10:13]
	v_mfma_f32_16x16x32_bf16 v[62:65], v[152:155], v[180:183], v[62:65]
	v_mfma_f32_16x16x32_bf16 v[58:61], v[172:175], v[180:183], v[58:61]
	v_mfma_f32_16x16x32_bf16 v[46:49], v[152:155], v[204:207], v[46:49]
	v_mfma_f32_16x16x32_bf16 v[42:45], v[172:175], v[204:207], v[42:45]
	v_mfma_f32_16x16x32_bf16 v[30:33], v[152:155], v[212:215], v[30:33]
	v_mfma_f32_16x16x32_bf16 v[26:29], v[172:175], v[212:215], v[26:29]
	v_mfma_f32_16x16x32_bf16 v[14:17], v[152:155], v[226:229], v[14:17]
	v_mfma_f32_16x16x32_bf16 v[10:13], v[172:175], v[226:229], v[10:13]
	s_barrier
; template <class Epi>
; __device__ __forceinline__ void gemm_phase(LAS unsigned char* lds, const Gemm g, const StaticOrder& S, const Epi& E) {
;     ...
;         for (int t = 0; t < nt; t += 2) {
;             if constexpr (Epi::MIDSCALE) {
;                 if (t == 4 || t == 8) {
;                     float f[2][4];
; #pragma unroll
;                     for (int ai = 0; ai < 2; ++ai)
; #pragma unroll
;                         for (int m = 0; m < 4; ++m) f[ai][m] = E.rstab[ui * 256 + wr * 64 + fr + ai * HALF + m * 16];
;                     asm volatile("s_waitcnt lgkmcnt(0)" ::: "memory");
; #pragma unroll
;                     for (int ai = 0; ai < 2; ++ai)
; #pragma unroll
;                         for (int m = 0; m < 4; ++m) { const float ff = (t == 4) ? __builtin_amdgcn_rcpf(f[ai][m]) : f[ai][m];
; #pragma unroll
;                             for (int bj = 0; bj < 2; ++bj)
; #pragma unroll
;                                 for (int n = 0; n < 2; ++n) acc[ai][bj][m][n] = acc[ai][bj][m][n] * ff; }
;                 }
;             }
;             const bool last = (t == nt - 2);
;             const char* a1 = cA + (size_t)(t + 1) * kstep;
;             const char* a2 = last ? nA : cA + (size_t)(t + 2) * kstep; const char* b2 = last ? nB : cB + (size_t)(t + 2) * kstep;
;             const char* a3 = a2 + kstep; const char* b3 = b2 + kstep;
;             PG8_LDB(B0, 0, 0); PG8_SCHED; PG8_LDA(At, 0, 0); PG8_STAGE(PG8_SA(1, 1), a1 + hstep, voffA);
;             PG8_WAIT_L(8); PG8_BAR; PG8_WAIT_L(0); PG8_MMA(0, 0, At, B0); PG8_BAR; PG8_SCHED;
;             PG8_LDB(B1, 0, 1); PG8_STAGE(PG8_SB(0, 0), b2, voffB);
;             PG8_BAR; PG8_WAIT_L(0); PG8_MMA(0, 1, At, B1); PG8_BAR;
;             PG8_LDA(At, 0, 1); PG8_STAGE(PG8_SA(0, 0), a2, voffA);
;             PG8_BAR; PG8_WAIT_L(0); PG8_MMA(1, 0, At, B0); PG8_BAR; PG8_SCHED;
;             PG8_STAGE(PG8_SB(0, 1), b2 + hstep, voffB);
;             PG8_WAIT_V(6); PG8_BAR; PG8_MMA(1, 1, At, B1); PG8_BAR;
;             PG8_LDB(B0, 1, 0); PG8_SCHED; PG8_LDA(At, 1, 0); PG8_STAGE(PG8_SA(0, 1), a2 + hstep, voffA);
;             PG8_WAIT_L(8); PG8_BAR; PG8_WAIT_L(0); PG8_MMA(0, 0, At, B0); PG8_BAR; PG8_SCHED;
;             PG8_LDB(B1, 1, 1); PG8_STAGE(PG8_SB(1, 0), b3, voffB);
;             PG8_BAR; PG8_WAIT_L(0); PG8_MMA(0, 1, At, B1); PG8_BAR;
;             PG8_LDA(At, 1, 1); PG8_STAGE(PG8_SA(1, 0), a3, voffA);
	s_add_u32 s6, s6, 0x40080
	s_addc_u32 s7, s7, 0
	s_add_i32 s42, s42, s48
	s_mov_b32 m0, s42
	s_nop 0
	global_load_lds_dwordx4 v0, s[6:7]
	s_add_i32 m0, s42, 0x2000
	s_nop 0
	global_load_lds_dwordx4 v130, s[6:7]
	s_waitcnt vmcnt(6)
	s_barrier
	v_mfma_f32_16x16x32_bf16 v[54:57], v[230:233], v[176:179], v[54:57]
	v_mfma_f32_16x16x32_bf16 v[50:53], v[238:241], v[176:179], v[50:53]
	v_mfma_f32_16x16x32_bf16 v[38:41], v[230:233], v[184:187], v[38:41]
	v_mfma_f32_16x16x32_bf16 v[34:37], v[238:241], v[184:187], v[34:37]
	v_mfma_f32_16x16x32_bf16 v[22:25], v[230:233], v[208:211], v[22:25]
	v_mfma_f32_16x16x32_bf16 v[18:21], v[238:241], v[208:211], v[18:21]
	v_mfma_f32_16x16x32_bf16 v[6:9], v[230:233], v[216:219], v[6:9]
	v_mfma_f32_16x16x32_bf16 v[2:5], v[238:241], v[216:219], v[2:5]
	v_mfma_f32_16x16x32_bf16 v[54:57], v[234:237], v[180:183], v[54:57]
	v_mfma_f32_16x16x32_bf16 v[50:53], v[242:245], v[180:183], v[50:53]
	v_mfma_f32_16x16x32_bf16 v[38:41], v[234:237], v[204:207], v[38:41]
	v_mfma_f32_16x16x32_bf16 v[34:37], v[242:245], v[204:207], v[34:37]
	v_mfma_f32_16x16x32_bf16 v[22:25], v[234:237], v[212:215], v[22:25]
	v_mfma_f32_16x16x32_bf16 v[18:21], v[242:245], v[212:215], v[18:21]
	v_mfma_f32_16x16x32_bf16 v[6:9], v[234:237], v[226:229], v[6:9]
	v_mfma_f32_16x16x32_bf16 v[2:5], v[242:245], v[226:229], v[2:5]
	s_add_i32 s93, s93, 2
	s_add_u32 s36, s36, 0x100
	s_addc_u32 s37, s37, 0
	s_add_u32 s91, s91, 0x100
	s_addc_u32 s92, s92, 0
	s_cmp_gt_u32 s93, 13
	s_barrier
	s_add_u32 s6, s36, 0xfffc0080
	s_addc_u32 s7, s37, -1
	s_add_i32 s58, 0, 0x10000
	v_add_u32_e32 v144, s58, v147
	ds_read_b128 v[140:143], v144
	ds_read_b128 v[152:155], v144 offset:1024
	ds_read_b128 v[168:171], v144 offset:2048
	ds_read_b128 v[172:175], v144 offset:3072
	s_cmp_eq_u32 s93, 12
	s_cselect_b32 s43, s11, s7
	s_cselect_b32 s42, s71, s6
	s_cselect_b32 s7, s9, s92
	s_cselect_b32 s6, s90, s91
	s_add_i32 m0, s49, 0xc000
	ds_read_b128 v[176:179], v150
	ds_read_b128 v[180:183], v150 offset:1024
	ds_read_b128 v[184:187], v150 offset:2048
	ds_read_b128 v[204:207], v150 offset:3072
	ds_read_b128 v[208:211], v150 offset:4096
	ds_read_b128 v[212:215], v150 offset:5120
	ds_read_b128 v[216:219], v150 offset:6144
	ds_read_b128 v[226:229], v150 offset:7168
	global_load_lds_dwordx4 v136, s[36:37]
	s_add_i32 m0, s49, 0xe000
	s_nop 0
	global_load_lds_dwordx4 v138, s[36:37]
	s_waitcnt lgkmcnt(8)
	s_barrier
	s_waitcnt lgkmcnt(0)
	s_waitcnt lgkmcnt(0)
	v_mfma_f32_16x16x32_bf16 v[126:129], v[140:143], v[176:179], v[126:129]
	v_mfma_f32_16x16x32_bf16 v[122:125], v[168:171], v[176:179], v[122:125]
	v_mfma_f32_16x16x32_bf16 v[110:113], v[140:143], v[184:187], v[110:113]
	v_mfma_f32_16x16x32_bf16 v[106:109], v[168:171], v[184:187], v[106:109]
	v_mfma_f32_16x16x32_bf16 v[94:97], v[140:143], v[208:211], v[94:97]
	v_mfma_f32_16x16x32_bf16 v[90:93], v[168:171], v[208:211], v[90:93]
	v_mfma_f32_16x16x32_bf16 v[78:81], v[140:143], v[216:219], v[78:81]
	v_mfma_f32_16x16x32_bf16 v[74:77], v[168:171], v[216:219], v[74:77]
	v_mfma_f32_16x16x32_bf16 v[126:129], v[152:155], v[180:183], v[126:129]
	v_mfma_f32_16x16x32_bf16 v[122:125], v[172:175], v[180:183], v[122:125]
	v_mfma_f32_16x16x32_bf16 v[110:113], v[152:155], v[204:207], v[110:113]
	v_mfma_f32_16x16x32_bf16 v[106:109], v[172:175], v[204:207], v[106:109]
	v_mfma_f32_16x16x32_bf16 v[94:97], v[152:155], v[212:215], v[94:97]
	v_mfma_f32_16x16x32_bf16 v[90:93], v[172:175], v[212:215], v[90:93]
	v_mfma_f32_16x16x32_bf16 v[78:81], v[152:155], v[226:229], v[78:81]
	v_mfma_f32_16x16x32_bf16 v[74:77], v[172:175], v[226:229], v[74:77]
	s_barrier
	s_add_i32 s70, 0, 0x14000
	v_add_u32_e32 v144, s70, v147
	s_add_i32 s58, s58, s48
	ds_read_b128 v[230:233], v144
	ds_read_b128 v[234:237], v144 offset:1024
	ds_read_b128 v[238:241], v144 offset:2048
	ds_read_b128 v[242:245], v144 offset:3072
	s_mov_b32 m0, s58
	s_nop 0
	global_load_lds_dwordx4 v0, s[6:7]
	s_add_i32 m0, s58, 0x2000
	s_nop 0
	global_load_lds_dwordx4 v130, s[6:7]
	s_barrier
	s_waitcnt lgkmcnt(0)
	s_waitcnt lgkmcnt(0)
	v_mfma_f32_16x16x32_bf16 v[118:121], v[230:233], v[176:179], v[118:121]
	v_mfma_f32_16x16x32_bf16 v[114:117], v[238:241], v[176:179], v[114:117]
	v_mfma_f32_16x16x32_bf16 v[102:105], v[230:233], v[184:187], v[102:105]
	v_mfma_f32_16x16x32_bf16 v[98:101], v[238:241], v[184:187], v[98:101]
	v_mfma_f32_16x16x32_bf16 v[86:89], v[230:233], v[208:211], v[86:89]
	v_mfma_f32_16x16x32_bf16 v[82:85], v[238:241], v[208:211], v[82:85]
	v_mfma_f32_16x16x32_bf16 v[70:73], v[230:233], v[216:219], v[70:73]
	v_mfma_f32_16x16x32_bf16 v[66:69], v[238:241], v[216:219], v[66:69]
	v_mfma_f32_16x16x32_bf16 v[118:121], v[234:237], v[180:183], v[118:121]
	v_mfma_f32_16x16x32_bf16 v[114:117], v[242:245], v[180:183], v[114:117]
	v_mfma_f32_16x16x32_bf16 v[102:105], v[234:237], v[204:207], v[102:105]
	v_mfma_f32_16x16x32_bf16 v[98:101], v[242:245], v[204:207], v[98:101]
	v_mfma_f32_16x16x32_bf16 v[86:89], v[234:237], v[212:215], v[86:89]
	v_mfma_f32_16x16x32_bf16 v[82:85], v[242:245], v[212:215], v[82:85]
	v_mfma_f32_16x16x32_bf16 v[70:73], v[234:237], v[226:229], v[70:73]
	v_mfma_f32_16x16x32_bf16 v[66:69], v[242:245], v[226:229], v[66:69]
	s_mov_b32 m0, s49
	s_add_u32 vcc_lo, s42, 0x80
	s_addc_u32 vcc_hi, s43, 0
	s_barrier
	ds_read_b128 v[176:179], v150 offset:16384
	ds_read_b128 v[180:183], v150 offset:17408
	ds_read_b128 v[184:187], v150 offset:18432
	ds_read_b128 v[204:207], v150 offset:19456
	ds_read_b128 v[208:211], v150 offset:20480
	ds_read_b128 v[212:215], v150 offset:21504
	ds_read_b128 v[216:219], v150 offset:22528
	ds_read_b128 v[226:229], v150 offset:23552
	global_load_lds_dwordx4 v134, s[42:43]
	s_mov_b32 m0, s54
	s_nop 0
	global_load_lds_dwordx4 v132, s[42:43]
	s_barrier
; #define PG8_STAGE(bufoff, gbase, voff) do { _Pragma("unroll") for (int _i = 0; _i < 2; ++_i) \
;         __builtin_amdgcn_global_load_lds((const unsigned*)((const char*)(gbase) + (voff)[_i]), (LAS unsigned*)(lds + (bufoff) + ldsw + _i * 8192), 16, 0, 0); } while (0)
; #define PG8_LDA(dst, b, h) do { _Pragma("unroll") for (int m = 0; m < 4; ++m) _Pragma("unroll") for (int k = 0; k < 2; ++k) dst[m][k] = *(const LAS bf16x8*)(lds + PG8_SA(b, h) + aoff + m * 2048 + k * 1024); } while (0)
; #define PG8_LDB(dst, b, h) do { _Pragma("unroll") for (int n = 0; n < 2; ++n) _Pragma("unroll") for (int k = 0; k < 2; ++k) dst[n][k] = *(const LAS bf16x8*)(lds + PG8_SB(b, h) + boff + n * 2048 + k * 1024); } while (0)
; #define PG8_WAIT_V(n) asm volatile("s_waitcnt vmcnt(" #n ")" ::: "memory")
;     __device__ __forceinline__ void operator()(const f32x4 (&acc)[2][2][4][2], const Unit& u, int ui, int wr, int wc, int fr, int fq) const {
;     ...
;                     *(u32x4*)(rowp + bj * HALF) = w;
; template <class Epi>
; __device__ __forceinline__ void gemm_phase(LAS unsigned char* lds, const Gemm g, const StaticOrder& S, const Epi& E) {
;     ...
;             PG8_LDB(B0, 0, 0); PG8_SCHED; PG8_LDA(At, 0, 0); PG8_STAGE(PG8_SA(1, 1), a1 + hstep, voffA);
;             PG8_WAIT_L(8); PG8_BAR; PG8_WAIT_L(0); PG8_MMA(0, 0, At, B0); PG8_BAR; PG8_SCHED;
;             PG8_LDB(B1, 0, 1); PG8_STAGE(PG8_SB(0, 0), b2, voffB);
;             PG8_BAR; PG8_WAIT_L(0); PG8_MMA(0, 1, At, B1); PG8_BAR;
;             PG8_LDA(At, 0, 1); PG8_STAGE(PG8_SA(0, 0), a2, voffA);
;             PG8_BAR; PG8_WAIT_L(0); PG8_MMA(1, 0, At, B0); PG8_BAR; PG8_SCHED;
;             PG8_STAGE(PG8_SB(0, 1), b2 + hstep, voffB);
;             PG8_WAIT_V(6); PG8_BAR; PG8_MMA(1, 1, At, B1); PG8_BAR;
;             PG8_LDB(B0, 1, 0); PG8_SCHED; PG8_LDA(At, 1, 0); PG8_STAGE(PG8_SA(0, 1), a2 + hstep, voffA);
;             PG8_WAIT_L(8); PG8_BAR; PG8_WAIT_L(0); PG8_MMA(0, 0, At, B0); PG8_BAR; PG8_SCHED;
;             PG8_LDB(B1, 1, 1); PG8_STAGE(PG8_SB(1, 0), b3, voffB);
;             PG8_BAR; PG8_WAIT_L(0); PG8_MMA(0, 1, At, B1); PG8_BAR;
;             PG8_LDA(At, 1, 1); PG8_STAGE(PG8_SA(1, 0), a3, voffA);
;             PG8_BAR; PG8_WAIT_L(0); PG8_MMA(1, 0, At, B0); PG8_BAR; PG8_SCHED;
;             PG8_STAGE(PG8_SB(1, 1), b3 + hstep, voffB);
;             PG8_WAIT_V(6); PG8_BAR; PG8_MMA(1, 1, At, B1); PG8_BAR;
	s_waitcnt lgkmcnt(0)
	s_waitcnt lgkmcnt(0)
	v_mfma_f32_16x16x32_bf16 v[62:65], v[140:143], v[176:179], v[62:65]
	v_mfma_f32_16x16x32_bf16 v[58:61], v[168:171], v[176:179], v[58:61]
	v_mfma_f32_16x16x32_bf16 v[46:49], v[140:143], v[184:187], v[46:49]
	v_mfma_f32_16x16x32_bf16 v[42:45], v[168:171], v[184:187], v[42:45]
	v_mfma_f32_16x16x32_bf16 v[30:33], v[140:143], v[208:211], v[30:33]
	v_mfma_f32_16x16x32_bf16 v[26:29], v[168:171], v[208:211], v[26:29]
	v_mfma_f32_16x16x32_bf16 v[14:17], v[140:143], v[216:219], v[14:17]
	v_mfma_f32_16x16x32_bf16 v[10:13], v[168:171], v[216:219], v[10:13]
	v_mfma_f32_16x16x32_bf16 v[62:65], v[152:155], v[180:183], v[62:65]
	v_mfma_f32_16x16x32_bf16 v[58:61], v[172:175], v[180:183], v[58:61]
	v_mfma_f32_16x16x32_bf16 v[46:49], v[152:155], v[204:207], v[46:49]
	v_mfma_f32_16x16x32_bf16 v[42:45], v[172:175], v[204:207], v[42:45]
	v_mfma_f32_16x16x32_bf16 v[30:33], v[152:155], v[212:215], v[30:33]
	v_mfma_f32_16x16x32_bf16 v[26:29], v[172:175], v[212:215], v[26:29]
	v_mfma_f32_16x16x32_bf16 v[14:17], v[152:155], v[226:229], v[14:17]
	v_mfma_f32_16x16x32_bf16 v[10:13], v[172:175], v[226:229], v[10:13]
	s_barrier
	s_add_u32 s60, s6, 0x40000
	s_addc_u32 s61, s7, 0
	s_add_i32 s58, s70, s48
	s_mov_b32 m0, s58
	s_nop 0
	global_load_lds_dwordx4 v0, s[60:61]
	s_add_i32 m0, s58, 0x2000
	s_nop 0
	global_load_lds_dwordx4 v130, s[60:61]
	s_waitcnt vmcnt(6)
	s_barrier
	v_mfma_f32_16x16x32_bf16 v[54:57], v[230:233], v[176:179], v[54:57]
	v_mfma_f32_16x16x32_bf16 v[50:53], v[238:241], v[176:179], v[50:53]
	s_cmp_eq_u32 s89, 0
	s_cbranch_scc1 .LdsE_skip_3
	global_store_dwordx4 v250, v[192:195], s[4:5] offset:256
	s_nop 1
	v_add_u32_e32 v250, 0x20000, v250
.LdsE_skip_3:
	v_mfma_f32_16x16x32_bf16 v[38:41], v[230:233], v[184:187], v[38:41]
	v_mfma_f32_16x16x32_bf16 v[34:37], v[238:241], v[184:187], v[34:37]
	v_mfma_f32_16x16x32_bf16 v[22:25], v[230:233], v[208:211], v[22:25]
	v_mfma_f32_16x16x32_bf16 v[18:21], v[238:241], v[208:211], v[18:21]
	v_mfma_f32_16x16x32_bf16 v[6:9], v[230:233], v[216:219], v[6:9]
	v_mfma_f32_16x16x32_bf16 v[2:5], v[238:241], v[216:219], v[2:5]
	v_mfma_f32_16x16x32_bf16 v[54:57], v[234:237], v[180:183], v[54:57]
	v_mfma_f32_16x16x32_bf16 v[50:53], v[242:245], v[180:183], v[50:53]
	v_mfma_f32_16x16x32_bf16 v[38:41], v[234:237], v[204:207], v[38:41]
	v_mfma_f32_16x16x32_bf16 v[34:37], v[242:245], v[204:207], v[34:37]
	v_mfma_f32_16x16x32_bf16 v[22:25], v[234:237], v[212:215], v[22:25]
	v_mfma_f32_16x16x32_bf16 v[18:21], v[242:245], v[212:215], v[18:21]
	v_mfma_f32_16x16x32_bf16 v[6:9], v[234:237], v[226:229], v[6:9]
	v_mfma_f32_16x16x32_bf16 v[2:5], v[242:245], v[226:229], v[2:5]
	s_add_i32 s58, 0, 0x18000
	v_add_u32_e32 v151, s58, v147
	s_barrier
	ds_read_b128 v[140:143], v151
	ds_read_b128 v[152:155], v151 offset:1024
	ds_read_b128 v[168:171], v151 offset:2048
	ds_read_b128 v[172:175], v151 offset:3072
	s_add_u32 s42, s42, 0x40000
	s_addc_u32 s43, s43, 0
	s_mov_b32 m0, s55
	ds_read_b128 v[176:179], v150 offset:32768
	ds_read_b128 v[180:183], v150 offset:33792
	ds_read_b128 v[184:187], v150 offset:34816
	ds_read_b128 v[204:207], v150 offset:35840
	ds_read_b128 v[208:211], v150 offset:36864
	ds_read_b128 v[212:215], v150 offset:37888
	ds_read_b128 v[216:219], v150 offset:38912
	ds_read_b128 v[226:229], v150 offset:39936
	global_load_lds_dwordx4 v134, s[42:43]
	s_mov_b32 m0, s83
	s_nop 0
	global_load_lds_dwordx4 v132, s[42:43]
	s_waitcnt lgkmcnt(8)
	s_barrier
	s_waitcnt lgkmcnt(0)
	s_waitcnt lgkmcnt(0)
	v_mfma_f32_16x16x32_bf16 v[126:129], v[140:143], v[176:179], v[126:129]
	v_mfma_f32_16x16x32_bf16 v[122:125], v[168:171], v[176:179], v[122:125]
	v_mfma_f32_16x16x32_bf16 v[110:113], v[140:143], v[184:187], v[110:113]
	v_mfma_f32_16x16x32_bf16 v[106:109], v[168:171], v[184:187], v[106:109]
	v_mfma_f32_16x16x32_bf16 v[94:97], v[140:143], v[208:211], v[94:97]
	v_mfma_f32_16x16x32_bf16 v[90:93], v[168:171], v[208:211], v[90:93]
	v_mfma_f32_16x16x32_bf16 v[78:81], v[140:143], v[216:219], v[78:81]
	v_mfma_f32_16x16x32_bf16 v[74:77], v[168:171], v[216:219], v[74:77]
	v_mfma_f32_16x16x32_bf16 v[126:129], v[152:155], v[180:183], v[126:129]
	v_mfma_f32_16x16x32_bf16 v[122:125], v[172:175], v[180:183], v[122:125]
	v_mfma_f32_16x16x32_bf16 v[110:113], v[152:155], v[204:207], v[110:113]
	v_mfma_f32_16x16x32_bf16 v[106:109], v[172:175], v[204:207], v[106:109]
	v_mfma_f32_16x16x32_bf16 v[94:97], v[152:155], v[212:215], v[94:97]
	v_mfma_f32_16x16x32_bf16 v[90:93], v[172:175], v[212:215], v[90:93]
	v_mfma_f32_16x16x32_bf16 v[78:81], v[152:155], v[226:229], v[78:81]
	v_mfma_f32_16x16x32_bf16 v[74:77], v[172:175], v[226:229], v[74:77]
	s_barrier
	s_add_i32 s42, 0, 0x1c000
	s_add_i32 s43, s58, s48
	v_add_u32_e32 v151, s42, v147
	s_add_u32 s60, s6, 0x80
	s_addc_u32 s61, s7, 0
	s_mov_b32 m0, s43
	ds_read_b128 v[230:233], v151
	ds_read_b128 v[234:237], v151 offset:1024
	ds_read_b128 v[238:241], v151 offset:2048
	ds_read_b128 v[242:245], v151 offset:3072
	global_load_lds_dwordx4 v0, s[60:61]
	s_add_i32 m0, s43, 0x2000
	s_nop 0
	global_load_lds_dwordx4 v130, s[60:61]
	s_barrier
; #define PG8_STAGE(bufoff, gbase, voff) do { _Pragma("unroll") for (int _i = 0; _i < 2; ++_i) \
;         __builtin_amdgcn_global_load_lds((const unsigned*)((const char*)(gbase) + (voff)[_i]), (LAS unsigned*)(lds + (bufoff) + ldsw + _i * 8192), 16, 0, 0); } while (0)
; #define PG8_LDA(dst, b, h) do { _Pragma("unroll") for (int m = 0; m < 4; ++m) _Pragma("unroll") for (int k = 0; k < 2; ++k) dst[m][k] = *(const LAS bf16x8*)(lds + PG8_SA(b, h) + aoff + m * 2048 + k * 1024); } while (0)
; #define PG8_LDB(dst, b, h) do { _Pragma("unroll") for (int n = 0; n < 2; ++n) _Pragma("unroll") for (int k = 0; k < 2; ++k) dst[n][k] = *(const LAS bf16x8*)(lds + PG8_SB(b, h) + boff + n * 2048 + k * 1024); } while (0)
; #define PG8_WAIT_V(n) asm volatile("s_waitcnt vmcnt(" #n ")" ::: "memory")
; #define PG8_WAIT_L(n) asm volatile("s_waitcnt lgkmcnt(" #n ")" ::: "memory")
; #define PG8_BAR __builtin_amdgcn_s_barrier()
; #define PG8_SCHED __builtin_amdgcn_sched_barrier(0)
; template <class Epi>
; __device__ __forceinline__ void gemm_phase(LAS unsigned char* lds, const Gemm g, const StaticOrder& S, const Epi& E) {
;     ...
;         for (int t = 0; t < nt; t += 2) {
;     ...
;             PG8_LDB(B0, 0, 0); PG8_SCHED; PG8_LDA(At, 0, 0); PG8_STAGE(PG8_SA(1, 1), a1 + hstep, voffA);
;             PG8_WAIT_L(8); PG8_BAR; PG8_WAIT_L(0); PG8_MMA(0, 0, At, B0); PG8_BAR; PG8_SCHED;
;             PG8_LDB(B1, 0, 1); PG8_STAGE(PG8_SB(0, 0), b2, voffB);
;             PG8_BAR; PG8_WAIT_L(0); PG8_MMA(0, 1, At, B1); PG8_BAR;
;             PG8_LDA(At, 0, 1); PG8_STAGE(PG8_SA(0, 0), a2, voffA);
;             PG8_BAR; PG8_WAIT_L(0); PG8_MMA(1, 0, At, B0); PG8_BAR; PG8_SCHED;
;             PG8_STAGE(PG8_SB(0, 1), b2 + hstep, voffB);
;             PG8_WAIT_V(6); PG8_BAR; PG8_MMA(1, 1, At, B1); PG8_BAR;
;             PG8_LDB(B0, 1, 0); PG8_SCHED; PG8_LDA(At, 1, 0); PG8_STAGE(PG8_SA(0, 1), a2 + hstep, voffA);
;             PG8_WAIT_L(8); PG8_BAR; PG8_WAIT_L(0); PG8_MMA(0, 0, At, B0); PG8_BAR; PG8_SCHED;
;             PG8_LDB(B1, 1, 1); PG8_STAGE(PG8_SB(1, 0), b3, voffB);
;             PG8_BAR; PG8_WAIT_L(0); PG8_MMA(0, 1, At, B1); PG8_BAR;
;             PG8_LDA(At, 1, 1); PG8_STAGE(PG8_SA(1, 0), a3, voffA);
;             PG8_BAR; PG8_WAIT_L(0); PG8_MMA(1, 0, At, B0); PG8_BAR; PG8_SCHED;
;             PG8_STAGE(PG8_SB(1, 1), b3 + hstep, voffB);
;             PG8_WAIT_V(6); PG8_BAR; PG8_MMA(1, 1, At, B1); PG8_BAR;
	s_waitcnt lgkmcnt(0)
	s_waitcnt lgkmcnt(0)
	v_mfma_f32_16x16x32_bf16 v[118:121], v[230:233], v[176:179], v[118:121]
	v_mfma_f32_16x16x32_bf16 v[114:117], v[238:241], v[176:179], v[114:117]
	v_mfma_f32_16x16x32_bf16 v[102:105], v[230:233], v[184:187], v[102:105]
	v_mfma_f32_16x16x32_bf16 v[98:101], v[238:241], v[184:187], v[98:101]
	v_mfma_f32_16x16x32_bf16 v[86:89], v[230:233], v[208:211], v[86:89]
	v_mfma_f32_16x16x32_bf16 v[82:85], v[238:241], v[208:211], v[82:85]
	v_mfma_f32_16x16x32_bf16 v[70:73], v[230:233], v[216:219], v[70:73]
	v_mfma_f32_16x16x32_bf16 v[66:69], v[238:241], v[216:219], v[66:69]
	v_mfma_f32_16x16x32_bf16 v[118:121], v[234:237], v[180:183], v[118:121]
	v_mfma_f32_16x16x32_bf16 v[114:117], v[242:245], v[180:183], v[114:117]
	v_mfma_f32_16x16x32_bf16 v[102:105], v[234:237], v[204:207], v[102:105]
	v_mfma_f32_16x16x32_bf16 v[98:101], v[242:245], v[204:207], v[98:101]
	v_mfma_f32_16x16x32_bf16 v[86:89], v[234:237], v[212:215], v[86:89]
	v_mfma_f32_16x16x32_bf16 v[82:85], v[242:245], v[212:215], v[82:85]
	v_mfma_f32_16x16x32_bf16 v[70:73], v[234:237], v[226:229], v[70:73]
	v_mfma_f32_16x16x32_bf16 v[66:69], v[242:245], v[226:229], v[66:69]
	s_mov_b32 m0, s84
	s_barrier
	ds_read_b128 v[176:179], v150 offset:49152
	ds_read_b128 v[180:183], v150 offset:50176
	ds_read_b128 v[184:187], v150 offset:51200
	ds_read_b128 v[204:207], v150 offset:52224
	ds_read_b128 v[208:211], v150 offset:53248
	ds_read_b128 v[212:215], v150 offset:54272
	ds_read_b128 v[216:219], v150 offset:55296
	ds_read_b128 v[226:229], v150 offset:56320
	global_load_lds_dwordx4 v134, vcc
	s_mov_b32 m0, s85
	s_nop 0
	global_load_lds_dwordx4 v132, vcc
	s_barrier
	s_waitcnt lgkmcnt(0)
	s_waitcnt lgkmcnt(0)
	v_mfma_f32_16x16x32_bf16 v[62:65], v[140:143], v[176:179], v[62:65]
	v_mfma_f32_16x16x32_bf16 v[58:61], v[168:171], v[176:179], v[58:61]
	v_mfma_f32_16x16x32_bf16 v[46:49], v[140:143], v[184:187], v[46:49]
	v_mfma_f32_16x16x32_bf16 v[42:45], v[168:171], v[184:187], v[42:45]
	v_mfma_f32_16x16x32_bf16 v[30:33], v[140:143], v[208:211], v[30:33]
	v_mfma_f32_16x16x32_bf16 v[26:29], v[168:171], v[208:211], v[26:29]
	v_mfma_f32_16x16x32_bf16 v[14:17], v[140:143], v[216:219], v[14:17]
	v_mfma_f32_16x16x32_bf16 v[10:13], v[168:171], v[216:219], v[10:13]
	v_mfma_f32_16x16x32_bf16 v[62:65], v[152:155], v[180:183], v[62:65]
	v_mfma_f32_16x16x32_bf16 v[58:61], v[172:175], v[180:183], v[58:61]
	v_mfma_f32_16x16x32_bf16 v[46:49], v[152:155], v[204:207], v[46:49]
	v_mfma_f32_16x16x32_bf16 v[42:45], v[172:175], v[204:207], v[42:45]
	v_mfma_f32_16x16x32_bf16 v[30:33], v[152:155], v[212:215], v[30:33]
	v_mfma_f32_16x16x32_bf16 v[26:29], v[172:175], v[212:215], v[26:29]
	v_mfma_f32_16x16x32_bf16 v[14:17], v[152:155], v[226:229], v[14:17]
	v_mfma_f32_16x16x32_bf16 v[10:13], v[172:175], v[226:229], v[10:13]
	s_barrier
	s_add_u32 s6, s6, 0x40080
	s_addc_u32 s7, s7, 0
	s_add_i32 s42, s42, s48
	s_mov_b32 m0, s42
	s_nop 0
	global_load_lds_dwordx4 v0, s[6:7]
	s_add_i32 m0, s42, 0x2000
	s_nop 0
	global_load_lds_dwordx4 v130, s[6:7]
	s_waitcnt vmcnt(6)
	s_barrier
	v_mfma_f32_16x16x32_bf16 v[54:57], v[230:233], v[176:179], v[54:57]
	v_mfma_f32_16x16x32_bf16 v[50:53], v[238:241], v[176:179], v[50:53]
	v_mfma_f32_16x16x32_bf16 v[38:41], v[230:233], v[184:187], v[38:41]
	v_mfma_f32_16x16x32_bf16 v[34:37], v[238:241], v[184:187], v[34:37]
	v_mfma_f32_16x16x32_bf16 v[22:25], v[230:233], v[208:211], v[22:25]
	v_mfma_f32_16x16x32_bf16 v[18:21], v[238:241], v[208:211], v[18:21]
	v_mfma_f32_16x16x32_bf16 v[6:9], v[230:233], v[216:219], v[6:9]
	v_mfma_f32_16x16x32_bf16 v[2:5], v[238:241], v[216:219], v[2:5]
	v_mfma_f32_16x16x32_bf16 v[54:57], v[234:237], v[180:183], v[54:57]
	v_mfma_f32_16x16x32_bf16 v[50:53], v[242:245], v[180:183], v[50:53]
	v_mfma_f32_16x16x32_bf16 v[38:41], v[234:237], v[204:207], v[38:41]
	v_mfma_f32_16x16x32_bf16 v[34:37], v[242:245], v[204:207], v[34:37]
	v_mfma_f32_16x16x32_bf16 v[22:25], v[234:237], v[212:215], v[22:25]
	v_mfma_f32_16x16x32_bf16 v[18:21], v[242:245], v[212:215], v[18:21]
	v_mfma_f32_16x16x32_bf16 v[6:9], v[234:237], v[226:229], v[6:9]
	v_mfma_f32_16x16x32_bf16 v[2:5], v[242:245], v[226:229], v[2:5]
	s_add_i32 s93, s93, 2
	s_add_u32 s36, s36, 0x100
	s_addc_u32 s37, s37, 0
	s_add_u32 s91, s91, 0x100
	s_addc_u32 s92, s92, 0
	s_cmp_gt_u32 s93, 13
	s_barrier
	s_add_u32 s6, s36, 0xfffc0080
	s_addc_u32 s7, s37, -1
	s_add_i32 s58, 0, 0x10000
	v_add_u32_e32 v144, s58, v147
	ds_read_b128 v[140:143], v144
	ds_read_b128 v[152:155], v144 offset:1024
	ds_read_b128 v[168:171], v144 offset:2048
	ds_read_b128 v[172:175], v144 offset:3072
	s_cmp_eq_u32 s93, 12
	s_cselect_b32 s43, s11, s7
	s_cselect_b32 s42, s71, s6
	s_cselect_b32 s7, s9, s92
	s_cselect_b32 s6, s90, s91
	s_add_i32 m0, s49, 0xc000
	ds_read_b128 v[176:179], v150
	ds_read_b128 v[180:183], v150 offset:1024
	ds_read_b128 v[184:187], v150 offset:2048
	ds_read_b128 v[204:207], v150 offset:3072
	ds_read_b128 v[208:211], v150 offset:4096
	ds_read_b128 v[212:215], v150 offset:5120
	ds_read_b128 v[216:219], v150 offset:6144
	ds_read_b128 v[226:229], v150 offset:7168
	global_load_lds_dwordx4 v136, s[36:37]
	s_add_i32 m0, s49, 0xe000
	s_nop 0
	global_load_lds_dwordx4 v138, s[36:37]
	s_waitcnt lgkmcnt(8)
	s_barrier
; #define PG8_STAGE(bufoff, gbase, voff) do { _Pragma("unroll") for (int _i = 0; _i < 2; ++_i) \
;         __builtin_amdgcn_global_load_lds((const unsigned*)((const char*)(gbase) + (voff)[_i]), (LAS unsigned*)(lds + (bufoff) + ldsw + _i * 8192), 16, 0, 0); } while (0)
; #define PG8_LDA(dst, b, h) do { _Pragma("unroll") for (int m = 0; m < 4; ++m) _Pragma("unroll") for (int k = 0; k < 2; ++k) dst[m][k] = *(const LAS bf16x8*)(lds + PG8_SA(b, h) + aoff + m * 2048 + k * 1024); } while (0)
; #define PG8_LDB(dst, b, h) do { _Pragma("unroll") for (int n = 0; n < 2; ++n) _Pragma("unroll") for (int k = 0; k < 2; ++k) dst[n][k] = *(const LAS bf16x8*)(lds + PG8_SB(b, h) + boff + n * 2048 + k * 1024); } while (0)
; #define PG8_WAIT_V(n) asm volatile("s_waitcnt vmcnt(" #n ")" ::: "memory")
;     __device__ __forceinline__ void operator()(const f32x4 (&acc)[2][2][4][2], const Unit& u, int ui, int wr, int wc, int fr, int fq) const {
;     ...
;                     *(u32x4*)(rowp + bj * HALF) = w;
; template <class Epi>
; __device__ __forceinline__ void gemm_phase(LAS unsigned char* lds, const Gemm g, const StaticOrder& S, const Epi& E) {
;     ...
;             PG8_LDB(B0, 0, 0); PG8_SCHED; PG8_LDA(At, 0, 0); PG8_STAGE(PG8_SA(1, 1), a1 + hstep, voffA);
;             PG8_WAIT_L(8); PG8_BAR; PG8_WAIT_L(0); PG8_MMA(0, 0, At, B0); PG8_BAR; PG8_SCHED;
;             PG8_LDB(B1, 0, 1); PG8_STAGE(PG8_SB(0, 0), b2, voffB);
;             PG8_BAR; PG8_WAIT_L(0); PG8_MMA(0, 1, At, B1); PG8_BAR;
;             PG8_LDA(At, 0, 1); PG8_STAGE(PG8_SA(0, 0), a2, voffA);
;             PG8_BAR; PG8_WAIT_L(0); PG8_MMA(1, 0, At, B0); PG8_BAR; PG8_SCHED;
;             PG8_STAGE(PG8_SB(0, 1), b2 + hstep, voffB);
;             PG8_WAIT_V(6); PG8_BAR; PG8_MMA(1, 1, At, B1); PG8_BAR;
;             PG8_LDB(B0, 1, 0); PG8_SCHED; PG8_LDA(At, 1, 0); PG8_STAGE(PG8_SA(0, 1), a2 + hstep, voffA);
;             PG8_WAIT_L(8); PG8_BAR; PG8_WAIT_L(0); PG8_MMA(0, 0, At, B0); PG8_BAR; PG8_SCHED;
;             PG8_LDB(B1, 1, 1); PG8_STAGE(PG8_SB(1, 0), b3, voffB);
;             PG8_BAR; PG8_WAIT_L(0); PG8_MMA(0, 1, At, B1); PG8_BAR;
;             PG8_LDA(At, 1, 1); PG8_STAGE(PG8_SA(1, 0), a3, voffA);
;             PG8_BAR; PG8_WAIT_L(0); PG8_MMA(1, 0, At, B0); PG8_BAR; PG8_SCHED;
;             PG8_STAGE(PG8_SB(1, 1), b3 + hstep, voffB);
;             PG8_WAIT_V(6); PG8_BAR; PG8_MMA(1, 1, At, B1); PG8_BAR;
	s_waitcnt lgkmcnt(0)
	s_waitcnt lgkmcnt(0)
	v_mfma_f32_16x16x32_bf16 v[126:129], v[140:143], v[176:179], v[126:129]
	v_mfma_f32_16x16x32_bf16 v[122:125], v[168:171], v[176:179], v[122:125]
	v_mfma_f32_16x16x32_bf16 v[110:113], v[140:143], v[184:187], v[110:113]
	v_mfma_f32_16x16x32_bf16 v[106:109], v[168:171], v[184:187], v[106:109]
	v_mfma_f32_16x16x32_bf16 v[94:97], v[140:143], v[208:211], v[94:97]
	v_mfma_f32_16x16x32_bf16 v[90:93], v[168:171], v[208:211], v[90:93]
	v_mfma_f32_16x16x32_bf16 v[78:81], v[140:143], v[216:219], v[78:81]
	v_mfma_f32_16x16x32_bf16 v[74:77], v[168:171], v[216:219], v[74:77]
	v_mfma_f32_16x16x32_bf16 v[126:129], v[152:155], v[180:183], v[126:129]
	v_mfma_f32_16x16x32_bf16 v[122:125], v[172:175], v[180:183], v[122:125]
	v_mfma_f32_16x16x32_bf16 v[110:113], v[152:155], v[204:207], v[110:113]
	v_mfma_f32_16x16x32_bf16 v[106:109], v[172:175], v[204:207], v[106:109]
	v_mfma_f32_16x16x32_bf16 v[94:97], v[152:155], v[212:215], v[94:97]
	v_mfma_f32_16x16x32_bf16 v[90:93], v[172:175], v[212:215], v[90:93]
	v_mfma_f32_16x16x32_bf16 v[78:81], v[152:155], v[226:229], v[78:81]
	v_mfma_f32_16x16x32_bf16 v[74:77], v[172:175], v[226:229], v[74:77]
	s_barrier
	s_add_i32 s70, 0, 0x14000
	v_add_u32_e32 v144, s70, v147
	s_add_i32 s58, s58, s48
	ds_read_b128 v[230:233], v144
	ds_read_b128 v[234:237], v144 offset:1024
	ds_read_b128 v[238:241], v144 offset:2048
	ds_read_b128 v[242:245], v144 offset:3072
	s_mov_b32 m0, s58
	s_nop 0
	global_load_lds_dwordx4 v0, s[6:7]
	s_add_i32 m0, s58, 0x2000
	s_nop 0
	global_load_lds_dwordx4 v130, s[6:7]
	s_barrier
	s_waitcnt lgkmcnt(0)
	s_waitcnt lgkmcnt(0)
	v_mfma_f32_16x16x32_bf16 v[118:121], v[230:233], v[176:179], v[118:121]
	v_mfma_f32_16x16x32_bf16 v[114:117], v[238:241], v[176:179], v[114:117]
	v_mfma_f32_16x16x32_bf16 v[102:105], v[230:233], v[184:187], v[102:105]
	v_mfma_f32_16x16x32_bf16 v[98:101], v[238:241], v[184:187], v[98:101]
	v_mfma_f32_16x16x32_bf16 v[86:89], v[230:233], v[208:211], v[86:89]
	v_mfma_f32_16x16x32_bf16 v[82:85], v[238:241], v[208:211], v[82:85]
	v_mfma_f32_16x16x32_bf16 v[70:73], v[230:233], v[216:219], v[70:73]
	v_mfma_f32_16x16x32_bf16 v[66:69], v[238:241], v[216:219], v[66:69]
	v_mfma_f32_16x16x32_bf16 v[118:121], v[234:237], v[180:183], v[118:121]
	v_mfma_f32_16x16x32_bf16 v[114:117], v[242:245], v[180:183], v[114:117]
	v_mfma_f32_16x16x32_bf16 v[102:105], v[234:237], v[204:207], v[102:105]
	v_mfma_f32_16x16x32_bf16 v[98:101], v[242:245], v[204:207], v[98:101]
	v_mfma_f32_16x16x32_bf16 v[86:89], v[234:237], v[212:215], v[86:89]
	v_mfma_f32_16x16x32_bf16 v[82:85], v[242:245], v[212:215], v[82:85]
	v_mfma_f32_16x16x32_bf16 v[70:73], v[234:237], v[226:229], v[70:73]
	v_mfma_f32_16x16x32_bf16 v[66:69], v[242:245], v[226:229], v[66:69]
	s_mov_b32 m0, s49
	s_add_u32 vcc_lo, s42, 0x80
	s_addc_u32 vcc_hi, s43, 0
	s_barrier
	ds_read_b128 v[176:179], v150 offset:16384
	ds_read_b128 v[180:183], v150 offset:17408
	ds_read_b128 v[184:187], v150 offset:18432
	ds_read_b128 v[204:207], v150 offset:19456
	ds_read_b128 v[208:211], v150 offset:20480
	ds_read_b128 v[212:215], v150 offset:21504
	ds_read_b128 v[216:219], v150 offset:22528
	ds_read_b128 v[226:229], v150 offset:23552
	global_load_lds_dwordx4 v134, s[42:43]
	s_mov_b32 m0, s54
	s_nop 0
	global_load_lds_dwordx4 v132, s[42:43]
	s_barrier
	s_waitcnt lgkmcnt(0)
	s_waitcnt lgkmcnt(0)
	v_mfma_f32_16x16x32_bf16 v[62:65], v[140:143], v[176:179], v[62:65]
	v_mfma_f32_16x16x32_bf16 v[58:61], v[168:171], v[176:179], v[58:61]
	v_mfma_f32_16x16x32_bf16 v[46:49], v[140:143], v[184:187], v[46:49]
	v_mfma_f32_16x16x32_bf16 v[42:45], v[168:171], v[184:187], v[42:45]
	v_mfma_f32_16x16x32_bf16 v[30:33], v[140:143], v[208:211], v[30:33]
	v_mfma_f32_16x16x32_bf16 v[26:29], v[168:171], v[208:211], v[26:29]
	v_mfma_f32_16x16x32_bf16 v[14:17], v[140:143], v[216:219], v[14:17]
	v_mfma_f32_16x16x32_bf16 v[10:13], v[168:171], v[216:219], v[10:13]
	v_mfma_f32_16x16x32_bf16 v[62:65], v[152:155], v[180:183], v[62:65]
	v_mfma_f32_16x16x32_bf16 v[58:61], v[172:175], v[180:183], v[58:61]
	v_mfma_f32_16x16x32_bf16 v[46:49], v[152:155], v[204:207], v[46:49]
	v_mfma_f32_16x16x32_bf16 v[42:45], v[172:175], v[204:207], v[42:45]
	v_mfma_f32_16x16x32_bf16 v[30:33], v[152:155], v[212:215], v[30:33]
	v_mfma_f32_16x16x32_bf16 v[26:29], v[172:175], v[212:215], v[26:29]
	v_mfma_f32_16x16x32_bf16 v[14:17], v[152:155], v[226:229], v[14:17]
	v_mfma_f32_16x16x32_bf16 v[10:13], v[172:175], v[226:229], v[10:13]
	s_barrier
	s_add_u32 s60, s6, 0x40000
	s_addc_u32 s61, s7, 0
	s_add_i32 s58, s70, s48
	s_mov_b32 m0, s58
	s_nop 0
	global_load_lds_dwordx4 v0, s[60:61]
	s_add_i32 m0, s58, 0x2000
	s_nop 0
	global_load_lds_dwordx4 v130, s[60:61]
	s_waitcnt vmcnt(6)
	s_barrier
	v_mfma_f32_16x16x32_bf16 v[54:57], v[230:233], v[176:179], v[54:57]
	v_mfma_f32_16x16x32_bf16 v[50:53], v[238:241], v[176:179], v[50:53]
	s_cmp_eq_u32 s89, 0
	s_cbranch_scc1 .LdsE_skip_4
	global_store_dwordx4 v250, v[196:199], s[4:5]
; #define PG8_STAGE(bufoff, gbase, voff) do { _Pragma("unroll") for (int _i = 0; _i < 2; ++_i) \
;         __builtin_amdgcn_global_load_lds((const unsigned*)((const char*)(gbase) + (voff)[_i]), (LAS unsigned*)(lds + (bufoff) + ldsw + _i * 8192), 16, 0, 0); } while (0)
; #define PG8_LDA(dst, b, h) do { _Pragma("unroll") for (int m = 0; m < 4; ++m) _Pragma("unroll") for (int k = 0; k < 2; ++k) dst[m][k] = *(const LAS bf16x8*)(lds + PG8_SA(b, h) + aoff + m * 2048 + k * 1024); } while (0)
; #define PG8_LDB(dst, b, h) do { _Pragma("unroll") for (int n = 0; n < 2; ++n) _Pragma("unroll") for (int k = 0; k < 2; ++k) dst[n][k] = *(const LAS bf16x8*)(lds + PG8_SB(b, h) + boff + n * 2048 + k * 1024); } while (0)
; #define PG8_WAIT_V(n) asm volatile("s_waitcnt vmcnt(" #n ")" ::: "memory")
; #define PG8_WAIT_L(n) asm volatile("s_waitcnt lgkmcnt(" #n ")" ::: "memory")
; #define PG8_BAR __builtin_amdgcn_s_barrier()
; #define PG8_SCHED __builtin_amdgcn_sched_barrier(0)
; template <class Epi>
; __device__ __forceinline__ void gemm_phase(LAS unsigned char* lds, const Gemm g, const StaticOrder& S, const Epi& E) {
;     ...
;             PG8_LDB(B0, 0, 0); PG8_SCHED; PG8_LDA(At, 0, 0); PG8_STAGE(PG8_SA(1, 1), a1 + hstep, voffA);
;             PG8_WAIT_L(8); PG8_BAR; PG8_WAIT_L(0); PG8_MMA(0, 0, At, B0); PG8_BAR; PG8_SCHED;
;             PG8_LDB(B1, 0, 1); PG8_STAGE(PG8_SB(0, 0), b2, voffB);
;             PG8_BAR; PG8_WAIT_L(0); PG8_MMA(0, 1, At, B1); PG8_BAR;
;             PG8_LDA(At, 0, 1); PG8_STAGE(PG8_SA(0, 0), a2, voffA);
;             PG8_BAR; PG8_WAIT_L(0); PG8_MMA(1, 0, At, B0); PG8_BAR; PG8_SCHED;
;             PG8_STAGE(PG8_SB(0, 1), b2 + hstep, voffB);
;             PG8_WAIT_V(6); PG8_BAR; PG8_MMA(1, 1, At, B1); PG8_BAR;
;             PG8_LDB(B0, 1, 0); PG8_SCHED; PG8_LDA(At, 1, 0); PG8_STAGE(PG8_SA(0, 1), a2 + hstep, voffA);
;             PG8_WAIT_L(8); PG8_BAR; PG8_WAIT_L(0); PG8_MMA(0, 0, At, B0); PG8_BAR; PG8_SCHED;
;             PG8_LDB(B1, 1, 1); PG8_STAGE(PG8_SB(1, 0), b3, voffB);
;             PG8_BAR; PG8_WAIT_L(0); PG8_MMA(0, 1, At, B1); PG8_BAR;
;             PG8_LDA(At, 1, 1); PG8_STAGE(PG8_SA(1, 0), a3, voffA);
;             PG8_BAR; PG8_WAIT_L(0); PG8_MMA(1, 0, At, B0); PG8_BAR; PG8_SCHED;
;             PG8_STAGE(PG8_SB(1, 1), b3 + hstep, voffB);
;             PG8_WAIT_V(6); PG8_BAR; PG8_MMA(1, 1, At, B1); PG8_BAR;
.LdsE_skip_4:
	v_mfma_f32_16x16x32_bf16 v[38:41], v[230:233], v[184:187], v[38:41]
	v_mfma_f32_16x16x32_bf16 v[34:37], v[238:241], v[184:187], v[34:37]
	v_mfma_f32_16x16x32_bf16 v[22:25], v[230:233], v[208:211], v[22:25]
	v_mfma_f32_16x16x32_bf16 v[18:21], v[238:241], v[208:211], v[18:21]
	v_mfma_f32_16x16x32_bf16 v[6:9], v[230:233], v[216:219], v[6:9]
	v_mfma_f32_16x16x32_bf16 v[2:5], v[238:241], v[216:219], v[2:5]
	v_mfma_f32_16x16x32_bf16 v[54:57], v[234:237], v[180:183], v[54:57]
	v_mfma_f32_16x16x32_bf16 v[50:53], v[242:245], v[180:183], v[50:53]
	v_mfma_f32_16x16x32_bf16 v[38:41], v[234:237], v[204:207], v[38:41]
	v_mfma_f32_16x16x32_bf16 v[34:37], v[242:245], v[204:207], v[34:37]
	v_mfma_f32_16x16x32_bf16 v[22:25], v[234:237], v[212:215], v[22:25]
	v_mfma_f32_16x16x32_bf16 v[18:21], v[242:245], v[212:215], v[18:21]
	v_mfma_f32_16x16x32_bf16 v[6:9], v[234:237], v[226:229], v[6:9]
	v_mfma_f32_16x16x32_bf16 v[2:5], v[242:245], v[226:229], v[2:5]
	s_add_i32 s58, 0, 0x18000
	v_add_u32_e32 v151, s58, v147
	s_barrier
	ds_read_b128 v[140:143], v151
	ds_read_b128 v[152:155], v151 offset:1024
	ds_read_b128 v[168:171], v151 offset:2048
	ds_read_b128 v[172:175], v151 offset:3072
	s_add_u32 s42, s42, 0x40000
	s_addc_u32 s43, s43, 0
	s_mov_b32 m0, s55
	ds_read_b128 v[176:179], v150 offset:32768
	ds_read_b128 v[180:183], v150 offset:33792
	ds_read_b128 v[184:187], v150 offset:34816
	ds_read_b128 v[204:207], v150 offset:35840
	ds_read_b128 v[208:211], v150 offset:36864
	ds_read_b128 v[212:215], v150 offset:37888
	ds_read_b128 v[216:219], v150 offset:38912
	ds_read_b128 v[226:229], v150 offset:39936
	global_load_lds_dwordx4 v134, s[42:43]
	s_mov_b32 m0, s83
	s_nop 0
	global_load_lds_dwordx4 v132, s[42:43]
	s_waitcnt lgkmcnt(8)
	s_barrier
	s_waitcnt lgkmcnt(0)
	s_waitcnt lgkmcnt(0)
	v_mfma_f32_16x16x32_bf16 v[126:129], v[140:143], v[176:179], v[126:129]
	v_mfma_f32_16x16x32_bf16 v[122:125], v[168:171], v[176:179], v[122:125]
	v_mfma_f32_16x16x32_bf16 v[110:113], v[140:143], v[184:187], v[110:113]
	v_mfma_f32_16x16x32_bf16 v[106:109], v[168:171], v[184:187], v[106:109]
	v_mfma_f32_16x16x32_bf16 v[94:97], v[140:143], v[208:211], v[94:97]
	v_mfma_f32_16x16x32_bf16 v[90:93], v[168:171], v[208:211], v[90:93]
	v_mfma_f32_16x16x32_bf16 v[78:81], v[140:143], v[216:219], v[78:81]
	v_mfma_f32_16x16x32_bf16 v[74:77], v[168:171], v[216:219], v[74:77]
	v_mfma_f32_16x16x32_bf16 v[126:129], v[152:155], v[180:183], v[126:129]
	v_mfma_f32_16x16x32_bf16 v[122:125], v[172:175], v[180:183], v[122:125]
	v_mfma_f32_16x16x32_bf16 v[110:113], v[152:155], v[204:207], v[110:113]
	v_mfma_f32_16x16x32_bf16 v[106:109], v[172:175], v[204:207], v[106:109]
	v_mfma_f32_16x16x32_bf16 v[94:97], v[152:155], v[212:215], v[94:97]
	v_mfma_f32_16x16x32_bf16 v[90:93], v[172:175], v[212:215], v[90:93]
	v_mfma_f32_16x16x32_bf16 v[78:81], v[152:155], v[226:229], v[78:81]
	v_mfma_f32_16x16x32_bf16 v[74:77], v[172:175], v[226:229], v[74:77]
	s_barrier
	s_add_i32 s42, 0, 0x1c000
	s_add_i32 s43, s58, s48
	v_add_u32_e32 v151, s42, v147
	s_add_u32 s60, s6, 0x80
	s_addc_u32 s61, s7, 0
	s_mov_b32 m0, s43
	ds_read_b128 v[230:233], v151
	ds_read_b128 v[234:237], v151 offset:1024
	ds_read_b128 v[238:241], v151 offset:2048
	ds_read_b128 v[242:245], v151 offset:3072
	global_load_lds_dwordx4 v0, s[60:61]
	s_add_i32 m0, s43, 0x2000
	s_nop 0
	global_load_lds_dwordx4 v130, s[60:61]
	s_barrier
	s_waitcnt lgkmcnt(0)
	s_waitcnt lgkmcnt(0)
	v_mfma_f32_16x16x32_bf16 v[118:121], v[230:233], v[176:179], v[118:121]
	v_mfma_f32_16x16x32_bf16 v[114:117], v[238:241], v[176:179], v[114:117]
	v_mfma_f32_16x16x32_bf16 v[102:105], v[230:233], v[184:187], v[102:105]
	v_mfma_f32_16x16x32_bf16 v[98:101], v[238:241], v[184:187], v[98:101]
	v_mfma_f32_16x16x32_bf16 v[86:89], v[230:233], v[208:211], v[86:89]
	v_mfma_f32_16x16x32_bf16 v[82:85], v[238:241], v[208:211], v[82:85]
	v_mfma_f32_16x16x32_bf16 v[70:73], v[230:233], v[216:219], v[70:73]
	v_mfma_f32_16x16x32_bf16 v[66:69], v[238:241], v[216:219], v[66:69]
	v_mfma_f32_16x16x32_bf16 v[118:121], v[234:237], v[180:183], v[118:121]
	v_mfma_f32_16x16x32_bf16 v[114:117], v[242:245], v[180:183], v[114:117]
	v_mfma_f32_16x16x32_bf16 v[102:105], v[234:237], v[204:207], v[102:105]
	v_mfma_f32_16x16x32_bf16 v[98:101], v[242:245], v[204:207], v[98:101]
	v_mfma_f32_16x16x32_bf16 v[86:89], v[234:237], v[212:215], v[86:89]
	v_mfma_f32_16x16x32_bf16 v[82:85], v[242:245], v[212:215], v[82:85]
	v_mfma_f32_16x16x32_bf16 v[70:73], v[234:237], v[226:229], v[70:73]
	v_mfma_f32_16x16x32_bf16 v[66:69], v[242:245], v[226:229], v[66:69]
	s_mov_b32 m0, s84
	s_barrier
	ds_read_b128 v[176:179], v150 offset:49152
	ds_read_b128 v[180:183], v150 offset:50176
	ds_read_b128 v[184:187], v150 offset:51200
	ds_read_b128 v[204:207], v150 offset:52224
	ds_read_b128 v[208:211], v150 offset:53248
	ds_read_b128 v[212:215], v150 offset:54272
	ds_read_b128 v[216:219], v150 offset:55296
	ds_read_b128 v[226:229], v150 offset:56320
	global_load_lds_dwordx4 v134, vcc
	s_mov_b32 m0, s85
	s_nop 0
	global_load_lds_dwordx4 v132, vcc
	s_barrier
	s_waitcnt lgkmcnt(0)
	s_waitcnt lgkmcnt(0)
	v_mfma_f32_16x16x32_bf16 v[62:65], v[140:143], v[176:179], v[62:65]
	v_mfma_f32_16x16x32_bf16 v[58:61], v[168:171], v[176:179], v[58:61]
	v_mfma_f32_16x16x32_bf16 v[46:49], v[140:143], v[184:187], v[46:49]
	v_mfma_f32_16x16x32_bf16 v[42:45], v[168:171], v[184:187], v[42:45]
	v_mfma_f32_16x16x32_bf16 v[30:33], v[140:143], v[208:211], v[30:33]
	v_mfma_f32_16x16x32_bf16 v[26:29], v[168:171], v[208:211], v[26:29]
	v_mfma_f32_16x16x32_bf16 v[14:17], v[140:143], v[216:219], v[14:17]
	v_mfma_f32_16x16x32_bf16 v[10:13], v[168:171], v[216:219], v[10:13]
	v_mfma_f32_16x16x32_bf16 v[62:65], v[152:155], v[180:183], v[62:65]
	v_mfma_f32_16x16x32_bf16 v[58:61], v[172:175], v[180:183], v[58:61]
	v_mfma_f32_16x16x32_bf16 v[46:49], v[152:155], v[204:207], v[46:49]
	v_mfma_f32_16x16x32_bf16 v[42:45], v[172:175], v[204:207], v[42:45]
	v_mfma_f32_16x16x32_bf16 v[30:33], v[152:155], v[212:215], v[30:33]
	v_mfma_f32_16x16x32_bf16 v[26:29], v[172:175], v[212:215], v[26:29]
	v_mfma_f32_16x16x32_bf16 v[14:17], v[152:155], v[226:229], v[14:17]
	v_mfma_f32_16x16x32_bf16 v[10:13], v[172:175], v[226:229], v[10:13]
	s_barrier
; template <class Epi>
; __device__ __forceinline__ void gemm_phase(LAS unsigned char* lds, const Gemm g, const StaticOrder& S, const Epi& E) {
;     ...
;         for (int t = 0; t < nt; t += 2) {
;             if constexpr (Epi::MIDSCALE) {
;                 if (t == 4 || t == 8) {
;                     float f[2][4];
; #pragma unroll
;                     for (int ai = 0; ai < 2; ++ai)
; #pragma unroll
;                         for (int m = 0; m < 4; ++m) f[ai][m] = E.rstab[ui * 256 + wr * 64 + fr + ai * HALF + m * 16];
;                     asm volatile("s_waitcnt lgkmcnt(0)" ::: "memory");
; #pragma unroll
;                     for (int ai = 0; ai < 2; ++ai)
; #pragma unroll
;                         for (int m = 0; m < 4; ++m) { const float ff = (t == 4) ? __builtin_amdgcn_rcpf(f[ai][m]) : f[ai][m];
; #pragma unroll
;                             for (int bj = 0; bj < 2; ++bj)
; #pragma unroll
;                                 for (int n = 0; n < 2; ++n) acc[ai][bj][m][n] = acc[ai][bj][m][n] * ff; }
;                 }
;             }
;             const bool last = (t == nt - 2);
;             const char* a1 = cA + (size_t)(t + 1) * kstep;
;             const char* a2 = last ? nA : cA + (size_t)(t + 2) * kstep; const char* b2 = last ? nB : cB + (size_t)(t + 2) * kstep;
;             const char* a3 = a2 + kstep; const char* b3 = b2 + kstep;
;             PG8_LDB(B0, 0, 0); PG8_SCHED; PG8_LDA(At, 0, 0); PG8_STAGE(PG8_SA(1, 1), a1 + hstep, voffA);
;             PG8_WAIT_L(8); PG8_BAR; PG8_WAIT_L(0); PG8_MMA(0, 0, At, B0); PG8_BAR; PG8_SCHED;
;             PG8_LDB(B1, 0, 1); PG8_STAGE(PG8_SB(0, 0), b2, voffB);
;             PG8_BAR; PG8_WAIT_L(0); PG8_MMA(0, 1, At, B1); PG8_BAR;
;             PG8_LDA(At, 0, 1); PG8_STAGE(PG8_SA(0, 0), a2, voffA);
;             PG8_BAR; PG8_WAIT_L(0); PG8_MMA(1, 0, At, B0); PG8_BAR; PG8_SCHED;
;             PG8_STAGE(PG8_SB(0, 1), b2 + hstep, voffB);
;             PG8_WAIT_V(6); PG8_BAR; PG8_MMA(1, 1, At, B1); PG8_BAR;
;             PG8_LDB(B0, 1, 0); PG8_SCHED; PG8_LDA(At, 1, 0); PG8_STAGE(PG8_SA(0, 1), a2 + hstep, voffA);
;             PG8_WAIT_L(8); PG8_BAR; PG8_WAIT_L(0); PG8_MMA(0, 0, At, B0); PG8_BAR; PG8_SCHED;
;             PG8_LDB(B1, 1, 1); PG8_STAGE(PG8_SB(1, 0), b3, voffB);
;             PG8_BAR; PG8_WAIT_L(0); PG8_MMA(0, 1, At, B1); PG8_BAR;
;             PG8_LDA(At, 1, 1); PG8_STAGE(PG8_SA(1, 0), a3, voffA);
	s_add_u32 s6, s6, 0x40080
	s_addc_u32 s7, s7, 0
	s_add_i32 s42, s42, s48
	s_mov_b32 m0, s42
	s_nop 0
	global_load_lds_dwordx4 v0, s[6:7]
	s_add_i32 m0, s42, 0x2000
	s_nop 0
	global_load_lds_dwordx4 v130, s[6:7]
	s_waitcnt vmcnt(6)
	s_barrier
	v_mfma_f32_16x16x32_bf16 v[54:57], v[230:233], v[176:179], v[54:57]
	v_mfma_f32_16x16x32_bf16 v[50:53], v[238:241], v[176:179], v[50:53]
	v_mfma_f32_16x16x32_bf16 v[38:41], v[230:233], v[184:187], v[38:41]
	v_mfma_f32_16x16x32_bf16 v[34:37], v[238:241], v[184:187], v[34:37]
	v_mfma_f32_16x16x32_bf16 v[22:25], v[230:233], v[208:211], v[22:25]
	v_mfma_f32_16x16x32_bf16 v[18:21], v[238:241], v[208:211], v[18:21]
	v_mfma_f32_16x16x32_bf16 v[6:9], v[230:233], v[216:219], v[6:9]
	v_mfma_f32_16x16x32_bf16 v[2:5], v[238:241], v[216:219], v[2:5]
	v_mfma_f32_16x16x32_bf16 v[54:57], v[234:237], v[180:183], v[54:57]
	v_mfma_f32_16x16x32_bf16 v[50:53], v[242:245], v[180:183], v[50:53]
	v_mfma_f32_16x16x32_bf16 v[38:41], v[234:237], v[204:207], v[38:41]
	v_mfma_f32_16x16x32_bf16 v[34:37], v[242:245], v[204:207], v[34:37]
	v_mfma_f32_16x16x32_bf16 v[22:25], v[234:237], v[212:215], v[22:25]
	v_mfma_f32_16x16x32_bf16 v[18:21], v[242:245], v[212:215], v[18:21]
	v_mfma_f32_16x16x32_bf16 v[6:9], v[234:237], v[226:229], v[6:9]
	v_mfma_f32_16x16x32_bf16 v[2:5], v[242:245], v[226:229], v[2:5]
	s_add_i32 s93, s93, 2
	s_add_u32 s36, s36, 0x100
	s_addc_u32 s37, s37, 0
	s_add_u32 s91, s91, 0x100
	s_addc_u32 s92, s92, 0
	s_cmp_gt_u32 s93, 13
	s_barrier
	s_add_u32 s6, s36, 0xfffc0080
	s_addc_u32 s7, s37, -1
	s_add_i32 s58, 0, 0x10000
	v_add_u32_e32 v144, s58, v147
	ds_read_b128 v[140:143], v144
	ds_read_b128 v[152:155], v144 offset:1024
	ds_read_b128 v[168:171], v144 offset:2048
	ds_read_b128 v[172:175], v144 offset:3072
	s_cmp_eq_u32 s93, 12
	s_cselect_b32 s43, s11, s7
	s_cselect_b32 s42, s71, s6
	s_cselect_b32 s7, s9, s92
	s_cselect_b32 s6, s90, s91
	s_add_i32 m0, s49, 0xc000
	ds_read_b128 v[176:179], v150
	ds_read_b128 v[180:183], v150 offset:1024
	ds_read_b128 v[184:187], v150 offset:2048
	ds_read_b128 v[204:207], v150 offset:3072
	ds_read_b128 v[208:211], v150 offset:4096
	ds_read_b128 v[212:215], v150 offset:5120
	ds_read_b128 v[216:219], v150 offset:6144
	ds_read_b128 v[226:229], v150 offset:7168
	global_load_lds_dwordx4 v136, s[36:37]
	s_add_i32 m0, s49, 0xe000
	s_nop 0
	global_load_lds_dwordx4 v138, s[36:37]
	s_waitcnt lgkmcnt(8)
	s_barrier
	s_waitcnt lgkmcnt(0)
	s_waitcnt lgkmcnt(0)
	v_mfma_f32_16x16x32_bf16 v[126:129], v[140:143], v[176:179], v[126:129]
	v_mfma_f32_16x16x32_bf16 v[122:125], v[168:171], v[176:179], v[122:125]
	v_mfma_f32_16x16x32_bf16 v[110:113], v[140:143], v[184:187], v[110:113]
	v_mfma_f32_16x16x32_bf16 v[106:109], v[168:171], v[184:187], v[106:109]
	v_mfma_f32_16x16x32_bf16 v[94:97], v[140:143], v[208:211], v[94:97]
	v_mfma_f32_16x16x32_bf16 v[90:93], v[168:171], v[208:211], v[90:93]
	v_mfma_f32_16x16x32_bf16 v[78:81], v[140:143], v[216:219], v[78:81]
	v_mfma_f32_16x16x32_bf16 v[74:77], v[168:171], v[216:219], v[74:77]
	v_mfma_f32_16x16x32_bf16 v[126:129], v[152:155], v[180:183], v[126:129]
	v_mfma_f32_16x16x32_bf16 v[122:125], v[172:175], v[180:183], v[122:125]
	v_mfma_f32_16x16x32_bf16 v[110:113], v[152:155], v[204:207], v[110:113]
	v_mfma_f32_16x16x32_bf16 v[106:109], v[172:175], v[204:207], v[106:109]
	v_mfma_f32_16x16x32_bf16 v[94:97], v[152:155], v[212:215], v[94:97]
	v_mfma_f32_16x16x32_bf16 v[90:93], v[172:175], v[212:215], v[90:93]
	v_mfma_f32_16x16x32_bf16 v[78:81], v[152:155], v[226:229], v[78:81]
	v_mfma_f32_16x16x32_bf16 v[74:77], v[172:175], v[226:229], v[74:77]
	s_barrier
	s_add_i32 s70, 0, 0x14000
	v_add_u32_e32 v144, s70, v147
	s_add_i32 s58, s58, s48
	ds_read_b128 v[230:233], v144
	ds_read_b128 v[234:237], v144 offset:1024
	ds_read_b128 v[238:241], v144 offset:2048
	ds_read_b128 v[242:245], v144 offset:3072
	s_mov_b32 m0, s58
	s_nop 0
	global_load_lds_dwordx4 v0, s[6:7]
	s_add_i32 m0, s58, 0x2000
	s_nop 0
	global_load_lds_dwordx4 v130, s[6:7]
	s_barrier
	s_waitcnt lgkmcnt(0)
	s_waitcnt lgkmcnt(0)
	v_mfma_f32_16x16x32_bf16 v[118:121], v[230:233], v[176:179], v[118:121]
	v_mfma_f32_16x16x32_bf16 v[114:117], v[238:241], v[176:179], v[114:117]
	v_mfma_f32_16x16x32_bf16 v[102:105], v[230:233], v[184:187], v[102:105]
	v_mfma_f32_16x16x32_bf16 v[98:101], v[238:241], v[184:187], v[98:101]
	v_mfma_f32_16x16x32_bf16 v[86:89], v[230:233], v[208:211], v[86:89]
	v_mfma_f32_16x16x32_bf16 v[82:85], v[238:241], v[208:211], v[82:85]
	v_mfma_f32_16x16x32_bf16 v[70:73], v[230:233], v[216:219], v[70:73]
	v_mfma_f32_16x16x32_bf16 v[66:69], v[238:241], v[216:219], v[66:69]
	v_mfma_f32_16x16x32_bf16 v[118:121], v[234:237], v[180:183], v[118:121]
	v_mfma_f32_16x16x32_bf16 v[114:117], v[242:245], v[180:183], v[114:117]
	v_mfma_f32_16x16x32_bf16 v[102:105], v[234:237], v[204:207], v[102:105]
	v_mfma_f32_16x16x32_bf16 v[98:101], v[242:245], v[204:207], v[98:101]
	v_mfma_f32_16x16x32_bf16 v[86:89], v[234:237], v[212:215], v[86:89]
	v_mfma_f32_16x16x32_bf16 v[82:85], v[242:245], v[212:215], v[82:85]
	v_mfma_f32_16x16x32_bf16 v[70:73], v[234:237], v[226:229], v[70:73]
	v_mfma_f32_16x16x32_bf16 v[66:69], v[242:245], v[226:229], v[66:69]
	s_mov_b32 m0, s49
	s_add_u32 vcc_lo, s42, 0x80
	s_addc_u32 vcc_hi, s43, 0
	s_barrier
	ds_read_b128 v[176:179], v150 offset:16384
	ds_read_b128 v[180:183], v150 offset:17408
	ds_read_b128 v[184:187], v150 offset:18432
	ds_read_b128 v[204:207], v150 offset:19456
	ds_read_b128 v[208:211], v150 offset:20480
	ds_read_b128 v[212:215], v150 offset:21504
	ds_read_b128 v[216:219], v150 offset:22528
	ds_read_b128 v[226:229], v150 offset:23552
	global_load_lds_dwordx4 v134, s[42:43]
	s_mov_b32 m0, s54
	s_nop 0
	global_load_lds_dwordx4 v132, s[42:43]
	s_barrier
; #define PG8_STAGE(bufoff, gbase, voff) do { _Pragma("unroll") for (int _i = 0; _i < 2; ++_i) \
;         __builtin_amdgcn_global_load_lds((const unsigned*)((const char*)(gbase) + (voff)[_i]), (LAS unsigned*)(lds + (bufoff) + ldsw + _i * 8192), 16, 0, 0); } while (0)
; #define PG8_LDA(dst, b, h) do { _Pragma("unroll") for (int m = 0; m < 4; ++m) _Pragma("unroll") for (int k = 0; k < 2; ++k) dst[m][k] = *(const LAS bf16x8*)(lds + PG8_SA(b, h) + aoff + m * 2048 + k * 1024); } while (0)
; #define PG8_LDB(dst, b, h) do { _Pragma("unroll") for (int n = 0; n < 2; ++n) _Pragma("unroll") for (int k = 0; k < 2; ++k) dst[n][k] = *(const LAS bf16x8*)(lds + PG8_SB(b, h) + boff + n * 2048 + k * 1024); } while (0)
; #define PG8_WAIT_V(n) asm volatile("s_waitcnt vmcnt(" #n ")" ::: "memory")
;     __device__ __forceinline__ void operator()(const f32x4 (&acc)[2][2][4][2], const Unit& u, int ui, int wr, int wc, int fr, int fq) const {
;     ...
;                     *(u32x4*)(rowp + bj * HALF) = w;
; template <class Epi>
; __device__ __forceinline__ void gemm_phase(LAS unsigned char* lds, const Gemm g, const StaticOrder& S, const Epi& E) {
;     ...
;             PG8_LDB(B0, 0, 0); PG8_SCHED; PG8_LDA(At, 0, 0); PG8_STAGE(PG8_SA(1, 1), a1 + hstep, voffA);
;             PG8_WAIT_L(8); PG8_BAR; PG8_WAIT_L(0); PG8_MMA(0, 0, At, B0); PG8_BAR; PG8_SCHED;
;             PG8_LDB(B1, 0, 1); PG8_STAGE(PG8_SB(0, 0), b2, voffB);
;             PG8_BAR; PG8_WAIT_L(0); PG8_MMA(0, 1, At, B1); PG8_BAR;
;             PG8_LDA(At, 0, 1); PG8_STAGE(PG8_SA(0, 0), a2, voffA);
;             PG8_BAR; PG8_WAIT_L(0); PG8_MMA(1, 0, At, B0); PG8_BAR; PG8_SCHED;
;             PG8_STAGE(PG8_SB(0, 1), b2 + hstep, voffB);
;             PG8_WAIT_V(6); PG8_BAR; PG8_MMA(1, 1, At, B1); PG8_BAR;
;             PG8_LDB(B0, 1, 0); PG8_SCHED; PG8_LDA(At, 1, 0); PG8_STAGE(PG8_SA(0, 1), a2 + hstep, voffA);
;             PG8_WAIT_L(8); PG8_BAR; PG8_WAIT_L(0); PG8_MMA(0, 0, At, B0); PG8_BAR; PG8_SCHED;
;             PG8_LDB(B1, 1, 1); PG8_STAGE(PG8_SB(1, 0), b3, voffB);
;             PG8_BAR; PG8_WAIT_L(0); PG8_MMA(0, 1, At, B1); PG8_BAR;
;             PG8_LDA(At, 1, 1); PG8_STAGE(PG8_SA(1, 0), a3, voffA);
;             PG8_BAR; PG8_WAIT_L(0); PG8_MMA(1, 0, At, B0); PG8_BAR; PG8_SCHED;
;             PG8_STAGE(PG8_SB(1, 1), b3 + hstep, voffB);
;             PG8_WAIT_V(6); PG8_BAR; PG8_MMA(1, 1, At, B1); PG8_BAR;
	s_waitcnt lgkmcnt(0)
	s_waitcnt lgkmcnt(0)
	v_mfma_f32_16x16x32_bf16 v[62:65], v[140:143], v[176:179], v[62:65]
	v_mfma_f32_16x16x32_bf16 v[58:61], v[168:171], v[176:179], v[58:61]
	v_mfma_f32_16x16x32_bf16 v[46:49], v[140:143], v[184:187], v[46:49]
	v_mfma_f32_16x16x32_bf16 v[42:45], v[168:171], v[184:187], v[42:45]
	v_mfma_f32_16x16x32_bf16 v[30:33], v[140:143], v[208:211], v[30:33]
	v_mfma_f32_16x16x32_bf16 v[26:29], v[168:171], v[208:211], v[26:29]
	v_mfma_f32_16x16x32_bf16 v[14:17], v[140:143], v[216:219], v[14:17]
	v_mfma_f32_16x16x32_bf16 v[10:13], v[168:171], v[216:219], v[10:13]
	v_mfma_f32_16x16x32_bf16 v[62:65], v[152:155], v[180:183], v[62:65]
	v_mfma_f32_16x16x32_bf16 v[58:61], v[172:175], v[180:183], v[58:61]
	v_mfma_f32_16x16x32_bf16 v[46:49], v[152:155], v[204:207], v[46:49]
	v_mfma_f32_16x16x32_bf16 v[42:45], v[172:175], v[204:207], v[42:45]
	v_mfma_f32_16x16x32_bf16 v[30:33], v[152:155], v[212:215], v[30:33]
	v_mfma_f32_16x16x32_bf16 v[26:29], v[172:175], v[212:215], v[26:29]
	v_mfma_f32_16x16x32_bf16 v[14:17], v[152:155], v[226:229], v[14:17]
	v_mfma_f32_16x16x32_bf16 v[10:13], v[172:175], v[226:229], v[10:13]
	s_barrier
	s_add_u32 s60, s6, 0x40000
	s_addc_u32 s61, s7, 0
	s_add_i32 s58, s70, s48
	s_mov_b32 m0, s58
	s_nop 0
	global_load_lds_dwordx4 v0, s[60:61]
	s_add_i32 m0, s58, 0x2000
	s_nop 0
	global_load_lds_dwordx4 v130, s[60:61]
	s_waitcnt vmcnt(6)
	s_barrier
	v_mfma_f32_16x16x32_bf16 v[54:57], v[230:233], v[176:179], v[54:57]
	v_mfma_f32_16x16x32_bf16 v[50:53], v[238:241], v[176:179], v[50:53]
	s_cmp_eq_u32 s89, 0
	s_cbranch_scc1 .LdsE_skip_5
	global_store_dwordx4 v250, v[200:203], s[4:5] offset:256
	s_nop 1
	v_add_u32_e32 v250, 0x20000, v250
.LdsE_skip_5:
	v_mfma_f32_16x16x32_bf16 v[38:41], v[230:233], v[184:187], v[38:41]
	v_mfma_f32_16x16x32_bf16 v[34:37], v[238:241], v[184:187], v[34:37]
	v_mfma_f32_16x16x32_bf16 v[22:25], v[230:233], v[208:211], v[22:25]
	v_mfma_f32_16x16x32_bf16 v[18:21], v[238:241], v[208:211], v[18:21]
	v_mfma_f32_16x16x32_bf16 v[6:9], v[230:233], v[216:219], v[6:9]
	v_mfma_f32_16x16x32_bf16 v[2:5], v[238:241], v[216:219], v[2:5]
	v_mfma_f32_16x16x32_bf16 v[54:57], v[234:237], v[180:183], v[54:57]
	v_mfma_f32_16x16x32_bf16 v[50:53], v[242:245], v[180:183], v[50:53]
	v_mfma_f32_16x16x32_bf16 v[38:41], v[234:237], v[204:207], v[38:41]
	v_mfma_f32_16x16x32_bf16 v[34:37], v[242:245], v[204:207], v[34:37]
	v_mfma_f32_16x16x32_bf16 v[22:25], v[234:237], v[212:215], v[22:25]
	v_mfma_f32_16x16x32_bf16 v[18:21], v[242:245], v[212:215], v[18:21]
	v_mfma_f32_16x16x32_bf16 v[6:9], v[234:237], v[226:229], v[6:9]
	v_mfma_f32_16x16x32_bf16 v[2:5], v[242:245], v[226:229], v[2:5]
	s_add_i32 s58, 0, 0x18000
	v_add_u32_e32 v151, s58, v147
	s_barrier
	ds_read_b128 v[140:143], v151
	ds_read_b128 v[152:155], v151 offset:1024
	ds_read_b128 v[168:171], v151 offset:2048
	ds_read_b128 v[172:175], v151 offset:3072
	s_add_u32 s42, s42, 0x40000
	s_addc_u32 s43, s43, 0
	s_mov_b32 m0, s55
	ds_read_b128 v[176:179], v150 offset:32768
	ds_read_b128 v[180:183], v150 offset:33792
	ds_read_b128 v[184:187], v150 offset:34816
	ds_read_b128 v[204:207], v150 offset:35840
	ds_read_b128 v[208:211], v150 offset:36864
	ds_read_b128 v[212:215], v150 offset:37888
	ds_read_b128 v[216:219], v150 offset:38912
	ds_read_b128 v[226:229], v150 offset:39936
	global_load_lds_dwordx4 v134, s[42:43]
	s_mov_b32 m0, s83
	s_nop 0
	global_load_lds_dwordx4 v132, s[42:43]
	s_waitcnt lgkmcnt(8)
	s_barrier
	s_waitcnt lgkmcnt(0)
	s_waitcnt lgkmcnt(0)
	v_mfma_f32_16x16x32_bf16 v[126:129], v[140:143], v[176:179], v[126:129]
	v_mfma_f32_16x16x32_bf16 v[122:125], v[168:171], v[176:179], v[122:125]
	v_mfma_f32_16x16x32_bf16 v[110:113], v[140:143], v[184:187], v[110:113]
	v_mfma_f32_16x16x32_bf16 v[106:109], v[168:171], v[184:187], v[106:109]
	v_mfma_f32_16x16x32_bf16 v[94:97], v[140:143], v[208:211], v[94:97]
	v_mfma_f32_16x16x32_bf16 v[90:93], v[168:171], v[208:211], v[90:93]
	v_mfma_f32_16x16x32_bf16 v[78:81], v[140:143], v[216:219], v[78:81]
	v_mfma_f32_16x16x32_bf16 v[74:77], v[168:171], v[216:219], v[74:77]
	v_mfma_f32_16x16x32_bf16 v[126:129], v[152:155], v[180:183], v[126:129]
	v_mfma_f32_16x16x32_bf16 v[122:125], v[172:175], v[180:183], v[122:125]
	v_mfma_f32_16x16x32_bf16 v[110:113], v[152:155], v[204:207], v[110:113]
	v_mfma_f32_16x16x32_bf16 v[106:109], v[172:175], v[204:207], v[106:109]
	v_mfma_f32_16x16x32_bf16 v[94:97], v[152:155], v[212:215], v[94:97]
	v_mfma_f32_16x16x32_bf16 v[90:93], v[172:175], v[212:215], v[90:93]
	v_mfma_f32_16x16x32_bf16 v[78:81], v[152:155], v[226:229], v[78:81]
	v_mfma_f32_16x16x32_bf16 v[74:77], v[172:175], v[226:229], v[74:77]
	s_barrier
	s_add_i32 s42, 0, 0x1c000
	s_add_i32 s43, s58, s48
	v_add_u32_e32 v151, s42, v147
	s_add_u32 s60, s6, 0x80
	s_addc_u32 s61, s7, 0
	s_mov_b32 m0, s43
	ds_read_b128 v[230:233], v151
	ds_read_b128 v[234:237], v151 offset:1024
	ds_read_b128 v[238:241], v151 offset:2048
	ds_read_b128 v[242:245], v151 offset:3072
	global_load_lds_dwordx4 v0, s[60:61]
	s_add_i32 m0, s43, 0x2000
	s_nop 0
	global_load_lds_dwordx4 v130, s[60:61]
	s_barrier
; #define PG8_STAGE(bufoff, gbase, voff) do { _Pragma("unroll") for (int _i = 0; _i < 2; ++_i) \
;         __builtin_amdgcn_global_load_lds((const unsigned*)((const char*)(gbase) + (voff)[_i]), (LAS unsigned*)(lds + (bufoff) + ldsw + _i * 8192), 16, 0, 0); } while (0)
; #define PG8_LDA(dst, b, h) do { _Pragma("unroll") for (int m = 0; m < 4; ++m) _Pragma("unroll") for (int k = 0; k < 2; ++k) dst[m][k] = *(const LAS bf16x8*)(lds + PG8_SA(b, h) + aoff + m * 2048 + k * 1024); } while (0)
; #define PG8_LDB(dst, b, h) do { _Pragma("unroll") for (int n = 0; n < 2; ++n) _Pragma("unroll") for (int k = 0; k < 2; ++k) dst[n][k] = *(const LAS bf16x8*)(lds + PG8_SB(b, h) + boff + n * 2048 + k * 1024); } while (0)
; #define PG8_WAIT_V(n) asm volatile("s_waitcnt vmcnt(" #n ")" ::: "memory")
; #define PG8_WAIT_L(n) asm volatile("s_waitcnt lgkmcnt(" #n ")" ::: "memory")
; #define PG8_BAR __builtin_amdgcn_s_barrier()
; #define PG8_SCHED __builtin_amdgcn_sched_barrier(0)
; template <class Epi>
; __device__ __forceinline__ void gemm_phase(LAS unsigned char* lds, const Gemm g, const StaticOrder& S, const Epi& E) {
;     ...
;         for (int t = 0; t < nt; t += 2) {
;     ...
;             PG8_LDB(B0, 0, 0); PG8_SCHED; PG8_LDA(At, 0, 0); PG8_STAGE(PG8_SA(1, 1), a1 + hstep, voffA);
;             PG8_WAIT_L(8); PG8_BAR; PG8_WAIT_L(0); PG8_MMA(0, 0, At, B0); PG8_BAR; PG8_SCHED;
;             PG8_LDB(B1, 0, 1); PG8_STAGE(PG8_SB(0, 0), b2, voffB);
;             PG8_BAR; PG8_WAIT_L(0); PG8_MMA(0, 1, At, B1); PG8_BAR;
;             PG8_LDA(At, 0, 1); PG8_STAGE(PG8_SA(0, 0), a2, voffA);
;             PG8_BAR; PG8_WAIT_L(0); PG8_MMA(1, 0, At, B0); PG8_BAR; PG8_SCHED;
;             PG8_STAGE(PG8_SB(0, 1), b2 + hstep, voffB);
;             PG8_WAIT_V(6); PG8_BAR; PG8_MMA(1, 1, At, B1); PG8_BAR;
;             PG8_LDB(B0, 1, 0); PG8_SCHED; PG8_LDA(At, 1, 0); PG8_STAGE(PG8_SA(0, 1), a2 + hstep, voffA);
;             PG8_WAIT_L(8); PG8_BAR; PG8_WAIT_L(0); PG8_MMA(0, 0, At, B0); PG8_BAR; PG8_SCHED;
;             PG8_LDB(B1, 1, 1); PG8_STAGE(PG8_SB(1, 0), b3, voffB);
;             PG8_BAR; PG8_WAIT_L(0); PG8_MMA(0, 1, At, B1); PG8_BAR;
;             PG8_LDA(At, 1, 1); PG8_STAGE(PG8_SA(1, 0), a3, voffA);
;             PG8_BAR; PG8_WAIT_L(0); PG8_MMA(1, 0, At, B0); PG8_BAR; PG8_SCHED;
;             PG8_STAGE(PG8_SB(1, 1), b3 + hstep, voffB);
;             PG8_WAIT_V(6); PG8_BAR; PG8_MMA(1, 1, At, B1); PG8_BAR;
	s_waitcnt lgkmcnt(0)
	s_waitcnt lgkmcnt(0)
	v_mfma_f32_16x16x32_bf16 v[118:121], v[230:233], v[176:179], v[118:121]
	v_mfma_f32_16x16x32_bf16 v[114:117], v[238:241], v[176:179], v[114:117]
	v_mfma_f32_16x16x32_bf16 v[102:105], v[230:233], v[184:187], v[102:105]
	v_mfma_f32_16x16x32_bf16 v[98:101], v[238:241], v[184:187], v[98:101]
	v_mfma_f32_16x16x32_bf16 v[86:89], v[230:233], v[208:211], v[86:89]
	v_mfma_f32_16x16x32_bf16 v[82:85], v[238:241], v[208:211], v[82:85]
	v_mfma_f32_16x16x32_bf16 v[70:73], v[230:233], v[216:219], v[70:73]
	v_mfma_f32_16x16x32_bf16 v[66:69], v[238:241], v[216:219], v[66:69]
	v_mfma_f32_16x16x32_bf16 v[118:121], v[234:237], v[180:183], v[118:121]
	v_mfma_f32_16x16x32_bf16 v[114:117], v[242:245], v[180:183], v[114:117]
	v_mfma_f32_16x16x32_bf16 v[102:105], v[234:237], v[204:207], v[102:105]
	v_mfma_f32_16x16x32_bf16 v[98:101], v[242:245], v[204:207], v[98:101]
	v_mfma_f32_16x16x32_bf16 v[86:89], v[234:237], v[212:215], v[86:89]
	v_mfma_f32_16x16x32_bf16 v[82:85], v[242:245], v[212:215], v[82:85]
	v_mfma_f32_16x16x32_bf16 v[70:73], v[234:237], v[226:229], v[70:73]
	v_mfma_f32_16x16x32_bf16 v[66:69], v[242:245], v[226:229], v[66:69]
	s_mov_b32 m0, s84
	s_barrier
	ds_read_b128 v[176:179], v150 offset:49152
	ds_read_b128 v[180:183], v150 offset:50176
	ds_read_b128 v[184:187], v150 offset:51200
	ds_read_b128 v[204:207], v150 offset:52224
	ds_read_b128 v[208:211], v150 offset:53248
	ds_read_b128 v[212:215], v150 offset:54272
	ds_read_b128 v[216:219], v150 offset:55296
	ds_read_b128 v[226:229], v150 offset:56320
	global_load_lds_dwordx4 v134, vcc
	s_mov_b32 m0, s85
	s_nop 0
	global_load_lds_dwordx4 v132, vcc
	s_barrier
	s_waitcnt lgkmcnt(0)
	s_waitcnt lgkmcnt(0)
	v_mfma_f32_16x16x32_bf16 v[62:65], v[140:143], v[176:179], v[62:65]
	v_mfma_f32_16x16x32_bf16 v[58:61], v[168:171], v[176:179], v[58:61]
	v_mfma_f32_16x16x32_bf16 v[46:49], v[140:143], v[184:187], v[46:49]
	v_mfma_f32_16x16x32_bf16 v[42:45], v[168:171], v[184:187], v[42:45]
	v_mfma_f32_16x16x32_bf16 v[30:33], v[140:143], v[208:211], v[30:33]
	v_mfma_f32_16x16x32_bf16 v[26:29], v[168:171], v[208:211], v[26:29]
	v_mfma_f32_16x16x32_bf16 v[14:17], v[140:143], v[216:219], v[14:17]
	v_mfma_f32_16x16x32_bf16 v[10:13], v[168:171], v[216:219], v[10:13]
	v_mfma_f32_16x16x32_bf16 v[62:65], v[152:155], v[180:183], v[62:65]
	v_mfma_f32_16x16x32_bf16 v[58:61], v[172:175], v[180:183], v[58:61]
	v_mfma_f32_16x16x32_bf16 v[46:49], v[152:155], v[204:207], v[46:49]
	v_mfma_f32_16x16x32_bf16 v[42:45], v[172:175], v[204:207], v[42:45]
	v_mfma_f32_16x16x32_bf16 v[30:33], v[152:155], v[212:215], v[30:33]
	v_mfma_f32_16x16x32_bf16 v[26:29], v[172:175], v[212:215], v[26:29]
	v_mfma_f32_16x16x32_bf16 v[14:17], v[152:155], v[226:229], v[14:17]
	v_mfma_f32_16x16x32_bf16 v[10:13], v[172:175], v[226:229], v[10:13]
	s_barrier
	s_add_u32 s6, s6, 0x40080
	s_addc_u32 s7, s7, 0
	s_add_i32 s42, s42, s48
	s_mov_b32 m0, s42
	s_nop 0
	global_load_lds_dwordx4 v0, s[6:7]
	s_add_i32 m0, s42, 0x2000
	s_nop 0
	global_load_lds_dwordx4 v130, s[6:7]
	s_waitcnt vmcnt(6)
	s_barrier
	v_mfma_f32_16x16x32_bf16 v[54:57], v[230:233], v[176:179], v[54:57]
	v_mfma_f32_16x16x32_bf16 v[50:53], v[238:241], v[176:179], v[50:53]
	v_mfma_f32_16x16x32_bf16 v[38:41], v[230:233], v[184:187], v[38:41]
	v_mfma_f32_16x16x32_bf16 v[34:37], v[238:241], v[184:187], v[34:37]
	v_mfma_f32_16x16x32_bf16 v[22:25], v[230:233], v[208:211], v[22:25]
	v_mfma_f32_16x16x32_bf16 v[18:21], v[238:241], v[208:211], v[18:21]
	v_mfma_f32_16x16x32_bf16 v[6:9], v[230:233], v[216:219], v[6:9]
	v_mfma_f32_16x16x32_bf16 v[2:5], v[238:241], v[216:219], v[2:5]
	v_mfma_f32_16x16x32_bf16 v[54:57], v[234:237], v[180:183], v[54:57]
	v_mfma_f32_16x16x32_bf16 v[50:53], v[242:245], v[180:183], v[50:53]
	v_mfma_f32_16x16x32_bf16 v[38:41], v[234:237], v[204:207], v[38:41]
	v_mfma_f32_16x16x32_bf16 v[34:37], v[242:245], v[204:207], v[34:37]
	v_mfma_f32_16x16x32_bf16 v[22:25], v[234:237], v[212:215], v[22:25]
	v_mfma_f32_16x16x32_bf16 v[18:21], v[242:245], v[212:215], v[18:21]
	v_mfma_f32_16x16x32_bf16 v[6:9], v[234:237], v[226:229], v[6:9]
	v_mfma_f32_16x16x32_bf16 v[2:5], v[242:245], v[226:229], v[2:5]
	s_add_i32 s93, s93, 2
	s_add_u32 s36, s36, 0x100
	s_addc_u32 s37, s37, 0
	s_add_u32 s91, s91, 0x100
	s_addc_u32 s92, s92, 0
	s_cmp_gt_u32 s93, 13
	s_barrier
	s_add_u32 s6, s36, 0xfffc0080
	s_addc_u32 s7, s37, -1
	s_add_i32 s58, 0, 0x10000
	v_add_u32_e32 v144, s58, v147
	ds_read_b128 v[140:143], v144
	ds_read_b128 v[152:155], v144 offset:1024
	ds_read_b128 v[168:171], v144 offset:2048
	ds_read_b128 v[172:175], v144 offset:3072
	s_cmp_eq_u32 s93, 12
	s_cselect_b32 s43, s11, s7
	s_cselect_b32 s42, s71, s6
	s_cselect_b32 s7, s9, s92
	s_cselect_b32 s6, s90, s91
	s_add_i32 m0, s49, 0xc000
	ds_read_b128 v[176:179], v150
	ds_read_b128 v[180:183], v150 offset:1024
	ds_read_b128 v[184:187], v150 offset:2048
	ds_read_b128 v[204:207], v150 offset:3072
	ds_read_b128 v[208:211], v150 offset:4096
	ds_read_b128 v[212:215], v150 offset:5120
	ds_read_b128 v[216:219], v150 offset:6144
	ds_read_b128 v[226:229], v150 offset:7168
	global_load_lds_dwordx4 v136, s[36:37]
	s_add_i32 m0, s49, 0xe000
	s_nop 0
	global_load_lds_dwordx4 v138, s[36:37]
	s_waitcnt lgkmcnt(8)
	s_barrier
; #define PG8_STAGE(bufoff, gbase, voff) do { _Pragma("unroll") for (int _i = 0; _i < 2; ++_i) \
;         __builtin_amdgcn_global_load_lds((const unsigned*)((const char*)(gbase) + (voff)[_i]), (LAS unsigned*)(lds + (bufoff) + ldsw + _i * 8192), 16, 0, 0); } while (0)
; #define PG8_LDA(dst, b, h) do { _Pragma("unroll") for (int m = 0; m < 4; ++m) _Pragma("unroll") for (int k = 0; k < 2; ++k) dst[m][k] = *(const LAS bf16x8*)(lds + PG8_SA(b, h) + aoff + m * 2048 + k * 1024); } while (0)
; #define PG8_LDB(dst, b, h) do { _Pragma("unroll") for (int n = 0; n < 2; ++n) _Pragma("unroll") for (int k = 0; k < 2; ++k) dst[n][k] = *(const LAS bf16x8*)(lds + PG8_SB(b, h) + boff + n * 2048 + k * 1024); } while (0)
; #define PG8_WAIT_V(n) asm volatile("s_waitcnt vmcnt(" #n ")" ::: "memory")
;     __device__ __forceinline__ void operator()(const f32x4 (&acc)[2][2][4][2], const Unit& u, int ui, int wr, int wc, int fr, int fq) const {
;     ...
;                     *(u32x4*)(rowp + bj * HALF) = w;
; template <class Epi>
; __device__ __forceinline__ void gemm_phase(LAS unsigned char* lds, const Gemm g, const StaticOrder& S, const Epi& E) {
;     ...
;             PG8_LDB(B0, 0, 0); PG8_SCHED; PG8_LDA(At, 0, 0); PG8_STAGE(PG8_SA(1, 1), a1 + hstep, voffA);
;             PG8_WAIT_L(8); PG8_BAR; PG8_WAIT_L(0); PG8_MMA(0, 0, At, B0); PG8_BAR; PG8_SCHED;
;             PG8_LDB(B1, 0, 1); PG8_STAGE(PG8_SB(0, 0), b2, voffB);
;             PG8_BAR; PG8_WAIT_L(0); PG8_MMA(0, 1, At, B1); PG8_BAR;
;             PG8_LDA(At, 0, 1); PG8_STAGE(PG8_SA(0, 0), a2, voffA);
;             PG8_BAR; PG8_WAIT_L(0); PG8_MMA(1, 0, At, B0); PG8_BAR; PG8_SCHED;
;             PG8_STAGE(PG8_SB(0, 1), b2 + hstep, voffB);
;             PG8_WAIT_V(6); PG8_BAR; PG8_MMA(1, 1, At, B1); PG8_BAR;
;             PG8_LDB(B0, 1, 0); PG8_SCHED; PG8_LDA(At, 1, 0); PG8_STAGE(PG8_SA(0, 1), a2 + hstep, voffA);
;             PG8_WAIT_L(8); PG8_BAR; PG8_WAIT_L(0); PG8_MMA(0, 0, At, B0); PG8_BAR; PG8_SCHED;
;             PG8_LDB(B1, 1, 1); PG8_STAGE(PG8_SB(1, 0), b3, voffB);
;             PG8_BAR; PG8_WAIT_L(0); PG8_MMA(0, 1, At, B1); PG8_BAR;
;             PG8_LDA(At, 1, 1); PG8_STAGE(PG8_SA(1, 0), a3, voffA);
;             PG8_BAR; PG8_WAIT_L(0); PG8_MMA(1, 0, At, B0); PG8_BAR; PG8_SCHED;
;             PG8_STAGE(PG8_SB(1, 1), b3 + hstep, voffB);
;             PG8_WAIT_V(6); PG8_BAR; PG8_MMA(1, 1, At, B1); PG8_BAR;
	s_waitcnt lgkmcnt(0)
	s_waitcnt lgkmcnt(0)
	v_mfma_f32_16x16x32_bf16 v[126:129], v[140:143], v[176:179], v[126:129]
	v_mfma_f32_16x16x32_bf16 v[122:125], v[168:171], v[176:179], v[122:125]
	v_mfma_f32_16x16x32_bf16 v[110:113], v[140:143], v[184:187], v[110:113]
	v_mfma_f32_16x16x32_bf16 v[106:109], v[168:171], v[184:187], v[106:109]
	v_mfma_f32_16x16x32_bf16 v[94:97], v[140:143], v[208:211], v[94:97]
	v_mfma_f32_16x16x32_bf16 v[90:93], v[168:171], v[208:211], v[90:93]
	v_mfma_f32_16x16x32_bf16 v[78:81], v[140:143], v[216:219], v[78:81]
	v_mfma_f32_16x16x32_bf16 v[74:77], v[168:171], v[216:219], v[74:77]
	v_mfma_f32_16x16x32_bf16 v[126:129], v[152:155], v[180:183], v[126:129]
	v_mfma_f32_16x16x32_bf16 v[122:125], v[172:175], v[180:183], v[122:125]
	v_mfma_f32_16x16x32_bf16 v[110:113], v[152:155], v[204:207], v[110:113]
	v_mfma_f32_16x16x32_bf16 v[106:109], v[172:175], v[204:207], v[106:109]
	v_mfma_f32_16x16x32_bf16 v[94:97], v[152:155], v[212:215], v[94:97]
	v_mfma_f32_16x16x32_bf16 v[90:93], v[172:175], v[212:215], v[90:93]
	v_mfma_f32_16x16x32_bf16 v[78:81], v[152:155], v[226:229], v[78:81]
	v_mfma_f32_16x16x32_bf16 v[74:77], v[172:175], v[226:229], v[74:77]
	s_barrier
	s_add_i32 s70, 0, 0x14000
	v_add_u32_e32 v144, s70, v147
	s_add_i32 s58, s58, s48
	ds_read_b128 v[230:233], v144
	ds_read_b128 v[234:237], v144 offset:1024
	ds_read_b128 v[238:241], v144 offset:2048
	ds_read_b128 v[242:245], v144 offset:3072
	s_mov_b32 m0, s58
	s_nop 0
	global_load_lds_dwordx4 v0, s[6:7]
	s_add_i32 m0, s58, 0x2000
	s_nop 0
	global_load_lds_dwordx4 v130, s[6:7]
	s_barrier
	s_waitcnt lgkmcnt(0)
	s_waitcnt lgkmcnt(0)
	v_mfma_f32_16x16x32_bf16 v[118:121], v[230:233], v[176:179], v[118:121]
	v_mfma_f32_16x16x32_bf16 v[114:117], v[238:241], v[176:179], v[114:117]
	v_mfma_f32_16x16x32_bf16 v[102:105], v[230:233], v[184:187], v[102:105]
	v_mfma_f32_16x16x32_bf16 v[98:101], v[238:241], v[184:187], v[98:101]
	v_mfma_f32_16x16x32_bf16 v[86:89], v[230:233], v[208:211], v[86:89]
	v_mfma_f32_16x16x32_bf16 v[82:85], v[238:241], v[208:211], v[82:85]
	v_mfma_f32_16x16x32_bf16 v[70:73], v[230:233], v[216:219], v[70:73]
	v_mfma_f32_16x16x32_bf16 v[66:69], v[238:241], v[216:219], v[66:69]
	v_mfma_f32_16x16x32_bf16 v[118:121], v[234:237], v[180:183], v[118:121]
	v_mfma_f32_16x16x32_bf16 v[114:117], v[242:245], v[180:183], v[114:117]
	v_mfma_f32_16x16x32_bf16 v[102:105], v[234:237], v[204:207], v[102:105]
	v_mfma_f32_16x16x32_bf16 v[98:101], v[242:245], v[204:207], v[98:101]
	v_mfma_f32_16x16x32_bf16 v[86:89], v[234:237], v[212:215], v[86:89]
	v_mfma_f32_16x16x32_bf16 v[82:85], v[242:245], v[212:215], v[82:85]
	v_mfma_f32_16x16x32_bf16 v[70:73], v[234:237], v[226:229], v[70:73]
	v_mfma_f32_16x16x32_bf16 v[66:69], v[242:245], v[226:229], v[66:69]
	s_mov_b32 m0, s49
	s_add_u32 vcc_lo, s42, 0x80
	s_addc_u32 vcc_hi, s43, 0
	s_barrier
	ds_read_b128 v[176:179], v150 offset:16384
	ds_read_b128 v[180:183], v150 offset:17408
	ds_read_b128 v[184:187], v150 offset:18432
	ds_read_b128 v[204:207], v150 offset:19456
	ds_read_b128 v[208:211], v150 offset:20480
	ds_read_b128 v[212:215], v150 offset:21504
	ds_read_b128 v[216:219], v150 offset:22528
	ds_read_b128 v[226:229], v150 offset:23552
	global_load_lds_dwordx4 v134, s[42:43]
	s_mov_b32 m0, s54
	s_nop 0
	global_load_lds_dwordx4 v132, s[42:43]
	s_barrier
	s_waitcnt lgkmcnt(0)
	s_waitcnt lgkmcnt(0)
	v_mfma_f32_16x16x32_bf16 v[62:65], v[140:143], v[176:179], v[62:65]
	v_mfma_f32_16x16x32_bf16 v[58:61], v[168:171], v[176:179], v[58:61]
	v_mfma_f32_16x16x32_bf16 v[46:49], v[140:143], v[184:187], v[46:49]
	v_mfma_f32_16x16x32_bf16 v[42:45], v[168:171], v[184:187], v[42:45]
	v_mfma_f32_16x16x32_bf16 v[30:33], v[140:143], v[208:211], v[30:33]
	v_mfma_f32_16x16x32_bf16 v[26:29], v[168:171], v[208:211], v[26:29]
	v_mfma_f32_16x16x32_bf16 v[14:17], v[140:143], v[216:219], v[14:17]
	v_mfma_f32_16x16x32_bf16 v[10:13], v[168:171], v[216:219], v[10:13]
	v_mfma_f32_16x16x32_bf16 v[62:65], v[152:155], v[180:183], v[62:65]
	v_mfma_f32_16x16x32_bf16 v[58:61], v[172:175], v[180:183], v[58:61]
	v_mfma_f32_16x16x32_bf16 v[46:49], v[152:155], v[204:207], v[46:49]
	v_mfma_f32_16x16x32_bf16 v[42:45], v[172:175], v[204:207], v[42:45]
	v_mfma_f32_16x16x32_bf16 v[30:33], v[152:155], v[212:215], v[30:33]
	v_mfma_f32_16x16x32_bf16 v[26:29], v[172:175], v[212:215], v[26:29]
	v_mfma_f32_16x16x32_bf16 v[14:17], v[152:155], v[226:229], v[14:17]
	v_mfma_f32_16x16x32_bf16 v[10:13], v[172:175], v[226:229], v[10:13]
	s_barrier
	s_add_u32 s60, s6, 0x40000
	s_addc_u32 s61, s7, 0
	s_add_i32 s58, s70, s48
	s_mov_b32 m0, s58
	s_nop 0
	global_load_lds_dwordx4 v0, s[60:61]
	s_add_i32 m0, s58, 0x2000
	s_nop 0
	global_load_lds_dwordx4 v130, s[60:61]
	s_waitcnt vmcnt(6)
	s_barrier
	v_mfma_f32_16x16x32_bf16 v[54:57], v[230:233], v[176:179], v[54:57]
	v_mfma_f32_16x16x32_bf16 v[50:53], v[238:241], v[176:179], v[50:53]
	s_cmp_eq_u32 s89, 0
	s_cbranch_scc1 .LdsE_skip_6
	global_store_dwordx4 v250, v[222:225], s[4:5]
; #define PG8_STAGE(bufoff, gbase, voff) do { _Pragma("unroll") for (int _i = 0; _i < 2; ++_i) \
;         __builtin_amdgcn_global_load_lds((const unsigned*)((const char*)(gbase) + (voff)[_i]), (LAS unsigned*)(lds + (bufoff) + ldsw + _i * 8192), 16, 0, 0); } while (0)
; #define PG8_LDA(dst, b, h) do { _Pragma("unroll") for (int m = 0; m < 4; ++m) _Pragma("unroll") for (int k = 0; k < 2; ++k) dst[m][k] = *(const LAS bf16x8*)(lds + PG8_SA(b, h) + aoff + m * 2048 + k * 1024); } while (0)
; #define PG8_LDB(dst, b, h) do { _Pragma("unroll") for (int n = 0; n < 2; ++n) _Pragma("unroll") for (int k = 0; k < 2; ++k) dst[n][k] = *(const LAS bf16x8*)(lds + PG8_SB(b, h) + boff + n * 2048 + k * 1024); } while (0)
; #define PG8_WAIT_V(n) asm volatile("s_waitcnt vmcnt(" #n ")" ::: "memory")
; #define PG8_WAIT_L(n) asm volatile("s_waitcnt lgkmcnt(" #n ")" ::: "memory")
; #define PG8_BAR __builtin_amdgcn_s_barrier()
; #define PG8_SCHED __builtin_amdgcn_sched_barrier(0)
; template <class Epi>
; __device__ __forceinline__ void gemm_phase(LAS unsigned char* lds, const Gemm g, const StaticOrder& S, const Epi& E) {
;     ...
;             PG8_LDB(B0, 0, 0); PG8_SCHED; PG8_LDA(At, 0, 0); PG8_STAGE(PG8_SA(1, 1), a1 + hstep, voffA);
;             PG8_WAIT_L(8); PG8_BAR; PG8_WAIT_L(0); PG8_MMA(0, 0, At, B0); PG8_BAR; PG8_SCHED;
;             PG8_LDB(B1, 0, 1); PG8_STAGE(PG8_SB(0, 0), b2, voffB);
;             PG8_BAR; PG8_WAIT_L(0); PG8_MMA(0, 1, At, B1); PG8_BAR;
;             PG8_LDA(At, 0, 1); PG8_STAGE(PG8_SA(0, 0), a2, voffA);
;             PG8_BAR; PG8_WAIT_L(0); PG8_MMA(1, 0, At, B0); PG8_BAR; PG8_SCHED;
;             PG8_STAGE(PG8_SB(0, 1), b2 + hstep, voffB);
;             PG8_WAIT_V(6); PG8_BAR; PG8_MMA(1, 1, At, B1); PG8_BAR;
;             PG8_LDB(B0, 1, 0); PG8_SCHED; PG8_LDA(At, 1, 0); PG8_STAGE(PG8_SA(0, 1), a2 + hstep, voffA);
;             PG8_WAIT_L(8); PG8_BAR; PG8_WAIT_L(0); PG8_MMA(0, 0, At, B0); PG8_BAR; PG8_SCHED;
;             PG8_LDB(B1, 1, 1); PG8_STAGE(PG8_SB(1, 0), b3, voffB);
;             PG8_BAR; PG8_WAIT_L(0); PG8_MMA(0, 1, At, B1); PG8_BAR;
;             PG8_LDA(At, 1, 1); PG8_STAGE(PG8_SA(1, 0), a3, voffA);
;             PG8_BAR; PG8_WAIT_L(0); PG8_MMA(1, 0, At, B0); PG8_BAR; PG8_SCHED;
;             PG8_STAGE(PG8_SB(1, 1), b3 + hstep, voffB);
;             PG8_WAIT_V(6); PG8_BAR; PG8_MMA(1, 1, At, B1); PG8_BAR;
.LdsE_skip_6:
	v_mfma_f32_16x16x32_bf16 v[38:41], v[230:233], v[184:187], v[38:41]
	v_mfma_f32_16x16x32_bf16 v[34:37], v[238:241], v[184:187], v[34:37]
	v_mfma_f32_16x16x32_bf16 v[22:25], v[230:233], v[208:211], v[22:25]
	v_mfma_f32_16x16x32_bf16 v[18:21], v[238:241], v[208:211], v[18:21]
	v_mfma_f32_16x16x32_bf16 v[6:9], v[230:233], v[216:219], v[6:9]
	v_mfma_f32_16x16x32_bf16 v[2:5], v[238:241], v[216:219], v[2:5]
	v_mfma_f32_16x16x32_bf16 v[54:57], v[234:237], v[180:183], v[54:57]
	v_mfma_f32_16x16x32_bf16 v[50:53], v[242:245], v[180:183], v[50:53]
	v_mfma_f32_16x16x32_bf16 v[38:41], v[234:237], v[204:207], v[38:41]
	v_mfma_f32_16x16x32_bf16 v[34:37], v[242:245], v[204:207], v[34:37]
	v_mfma_f32_16x16x32_bf16 v[22:25], v[234:237], v[212:215], v[22:25]
	v_mfma_f32_16x16x32_bf16 v[18:21], v[242:245], v[212:215], v[18:21]
	v_mfma_f32_16x16x32_bf16 v[6:9], v[234:237], v[226:229], v[6:9]
	v_mfma_f32_16x16x32_bf16 v[2:5], v[242:245], v[226:229], v[2:5]
	s_add_i32 s58, 0, 0x18000
	v_add_u32_e32 v151, s58, v147
	s_barrier
	ds_read_b128 v[140:143], v151
	ds_read_b128 v[152:155], v151 offset:1024
	ds_read_b128 v[168:171], v151 offset:2048
	ds_read_b128 v[172:175], v151 offset:3072
	s_add_u32 s42, s42, 0x40000
	s_addc_u32 s43, s43, 0
	s_mov_b32 m0, s55
	ds_read_b128 v[176:179], v150 offset:32768
	ds_read_b128 v[180:183], v150 offset:33792
	ds_read_b128 v[184:187], v150 offset:34816
	ds_read_b128 v[204:207], v150 offset:35840
	ds_read_b128 v[208:211], v150 offset:36864
	ds_read_b128 v[212:215], v150 offset:37888
	ds_read_b128 v[216:219], v150 offset:38912
	ds_read_b128 v[226:229], v150 offset:39936
	global_load_lds_dwordx4 v134, s[42:43]
	s_mov_b32 m0, s83
	s_nop 0
	global_load_lds_dwordx4 v132, s[42:43]
	s_waitcnt lgkmcnt(8)
	s_barrier
	s_waitcnt lgkmcnt(0)
	s_waitcnt lgkmcnt(0)
	v_mfma_f32_16x16x32_bf16 v[126:129], v[140:143], v[176:179], v[126:129]
	v_mfma_f32_16x16x32_bf16 v[122:125], v[168:171], v[176:179], v[122:125]
	v_mfma_f32_16x16x32_bf16 v[110:113], v[140:143], v[184:187], v[110:113]
	v_mfma_f32_16x16x32_bf16 v[106:109], v[168:171], v[184:187], v[106:109]
	v_mfma_f32_16x16x32_bf16 v[94:97], v[140:143], v[208:211], v[94:97]
	v_mfma_f32_16x16x32_bf16 v[90:93], v[168:171], v[208:211], v[90:93]
	v_mfma_f32_16x16x32_bf16 v[78:81], v[140:143], v[216:219], v[78:81]
	v_mfma_f32_16x16x32_bf16 v[74:77], v[168:171], v[216:219], v[74:77]
	v_mfma_f32_16x16x32_bf16 v[126:129], v[152:155], v[180:183], v[126:129]
	v_mfma_f32_16x16x32_bf16 v[122:125], v[172:175], v[180:183], v[122:125]
	v_mfma_f32_16x16x32_bf16 v[110:113], v[152:155], v[204:207], v[110:113]
	v_mfma_f32_16x16x32_bf16 v[106:109], v[172:175], v[204:207], v[106:109]
	v_mfma_f32_16x16x32_bf16 v[94:97], v[152:155], v[212:215], v[94:97]
	v_mfma_f32_16x16x32_bf16 v[90:93], v[172:175], v[212:215], v[90:93]
	v_mfma_f32_16x16x32_bf16 v[78:81], v[152:155], v[226:229], v[78:81]
	v_mfma_f32_16x16x32_bf16 v[74:77], v[172:175], v[226:229], v[74:77]
	s_barrier
	s_add_i32 s42, 0, 0x1c000
	s_add_i32 s43, s58, s48
	v_add_u32_e32 v151, s42, v147
	s_add_u32 s60, s6, 0x80
	s_addc_u32 s61, s7, 0
	s_mov_b32 m0, s43
	ds_read_b128 v[230:233], v151
	ds_read_b128 v[234:237], v151 offset:1024
	ds_read_b128 v[238:241], v151 offset:2048
	ds_read_b128 v[242:245], v151 offset:3072
	global_load_lds_dwordx4 v0, s[60:61]
	s_add_i32 m0, s43, 0x2000
	s_nop 0
	global_load_lds_dwordx4 v130, s[60:61]
	s_barrier
	s_waitcnt lgkmcnt(0)
	s_waitcnt lgkmcnt(0)
	v_mfma_f32_16x16x32_bf16 v[118:121], v[230:233], v[176:179], v[118:121]
	v_mfma_f32_16x16x32_bf16 v[114:117], v[238:241], v[176:179], v[114:117]
	v_mfma_f32_16x16x32_bf16 v[102:105], v[230:233], v[184:187], v[102:105]
	v_mfma_f32_16x16x32_bf16 v[98:101], v[238:241], v[184:187], v[98:101]
	v_mfma_f32_16x16x32_bf16 v[86:89], v[230:233], v[208:211], v[86:89]
	v_mfma_f32_16x16x32_bf16 v[82:85], v[238:241], v[208:211], v[82:85]
	v_mfma_f32_16x16x32_bf16 v[70:73], v[230:233], v[216:219], v[70:73]
	v_mfma_f32_16x16x32_bf16 v[66:69], v[238:241], v[216:219], v[66:69]
	v_mfma_f32_16x16x32_bf16 v[118:121], v[234:237], v[180:183], v[118:121]
	v_mfma_f32_16x16x32_bf16 v[114:117], v[242:245], v[180:183], v[114:117]
	v_mfma_f32_16x16x32_bf16 v[102:105], v[234:237], v[204:207], v[102:105]
	v_mfma_f32_16x16x32_bf16 v[98:101], v[242:245], v[204:207], v[98:101]
	v_mfma_f32_16x16x32_bf16 v[86:89], v[234:237], v[212:215], v[86:89]
	v_mfma_f32_16x16x32_bf16 v[82:85], v[242:245], v[212:215], v[82:85]
	v_mfma_f32_16x16x32_bf16 v[70:73], v[234:237], v[226:229], v[70:73]
	v_mfma_f32_16x16x32_bf16 v[66:69], v[242:245], v[226:229], v[66:69]
	s_mov_b32 m0, s84
	s_barrier
	ds_read_b128 v[176:179], v150 offset:49152
	ds_read_b128 v[180:183], v150 offset:50176
	ds_read_b128 v[184:187], v150 offset:51200
	ds_read_b128 v[204:207], v150 offset:52224
	ds_read_b128 v[208:211], v150 offset:53248
	ds_read_b128 v[212:215], v150 offset:54272
	ds_read_b128 v[216:219], v150 offset:55296
	ds_read_b128 v[226:229], v150 offset:56320
	global_load_lds_dwordx4 v134, vcc
	s_mov_b32 m0, s85
	s_nop 0
	global_load_lds_dwordx4 v132, vcc
	s_barrier
	s_waitcnt lgkmcnt(0)
	s_waitcnt lgkmcnt(0)
	v_mfma_f32_16x16x32_bf16 v[62:65], v[140:143], v[176:179], v[62:65]
	v_mfma_f32_16x16x32_bf16 v[58:61], v[168:171], v[176:179], v[58:61]
	v_mfma_f32_16x16x32_bf16 v[46:49], v[140:143], v[184:187], v[46:49]
	v_mfma_f32_16x16x32_bf16 v[42:45], v[168:171], v[184:187], v[42:45]
	v_mfma_f32_16x16x32_bf16 v[30:33], v[140:143], v[208:211], v[30:33]
	v_mfma_f32_16x16x32_bf16 v[26:29], v[168:171], v[208:211], v[26:29]
	v_mfma_f32_16x16x32_bf16 v[14:17], v[140:143], v[216:219], v[14:17]
	v_mfma_f32_16x16x32_bf16 v[10:13], v[168:171], v[216:219], v[10:13]
	v_mfma_f32_16x16x32_bf16 v[62:65], v[152:155], v[180:183], v[62:65]
	v_mfma_f32_16x16x32_bf16 v[58:61], v[172:175], v[180:183], v[58:61]
	v_mfma_f32_16x16x32_bf16 v[46:49], v[152:155], v[204:207], v[46:49]
	v_mfma_f32_16x16x32_bf16 v[42:45], v[172:175], v[204:207], v[42:45]
	v_mfma_f32_16x16x32_bf16 v[30:33], v[152:155], v[212:215], v[30:33]
	v_mfma_f32_16x16x32_bf16 v[26:29], v[172:175], v[212:215], v[26:29]
	v_mfma_f32_16x16x32_bf16 v[14:17], v[152:155], v[226:229], v[14:17]
	v_mfma_f32_16x16x32_bf16 v[10:13], v[172:175], v[226:229], v[10:13]
	s_barrier
; template <class Epi>
; __device__ __forceinline__ void gemm_phase(LAS unsigned char* lds, const Gemm g, const StaticOrder& S, const Epi& E) {
;     ...
;         for (int t = 0; t < nt; t += 2) {
;             if constexpr (Epi::MIDSCALE) {
;                 if (t == 4 || t == 8) {
;                     float f[2][4];
; #pragma unroll
;                     for (int ai = 0; ai < 2; ++ai)
; #pragma unroll
;                         for (int m = 0; m < 4; ++m) f[ai][m] = E.rstab[ui * 256 + wr * 64 + fr + ai * HALF + m * 16];
;                     asm volatile("s_waitcnt lgkmcnt(0)" ::: "memory");
; #pragma unroll
;                     for (int ai = 0; ai < 2; ++ai)
; #pragma unroll
;                         for (int m = 0; m < 4; ++m) { const float ff = (t == 4) ? __builtin_amdgcn_rcpf(f[ai][m]) : f[ai][m];
; #pragma unroll
;                             for (int bj = 0; bj < 2; ++bj)
; #pragma unroll
;                                 for (int n = 0; n < 2; ++n) acc[ai][bj][m][n] = acc[ai][bj][m][n] * ff; }
;                 }
;             }
;             const bool last = (t == nt - 2);
;             const char* a1 = cA + (size_t)(t + 1) * kstep;
;             const char* a2 = last ? nA : cA + (size_t)(t + 2) * kstep; const char* b2 = last ? nB : cB + (size_t)(t + 2) * kstep;
;             const char* a3 = a2 + kstep; const char* b3 = b2 + kstep;
;             PG8_LDB(B0, 0, 0); PG8_SCHED; PG8_LDA(At, 0, 0); PG8_STAGE(PG8_SA(1, 1), a1 + hstep, voffA);
;             PG8_WAIT_L(8); PG8_BAR; PG8_WAIT_L(0); PG8_MMA(0, 0, At, B0); PG8_BAR; PG8_SCHED;
;             PG8_LDB(B1, 0, 1); PG8_STAGE(PG8_SB(0, 0), b2, voffB);
;             PG8_BAR; PG8_WAIT_L(0); PG8_MMA(0, 1, At, B1); PG8_BAR;
;             PG8_LDA(At, 0, 1); PG8_STAGE(PG8_SA(0, 0), a2, voffA);
;             PG8_BAR; PG8_WAIT_L(0); PG8_MMA(1, 0, At, B0); PG8_BAR; PG8_SCHED;
;             PG8_STAGE(PG8_SB(0, 1), b2 + hstep, voffB);
;             PG8_WAIT_V(6); PG8_BAR; PG8_MMA(1, 1, At, B1); PG8_BAR;
;             PG8_LDB(B0, 1, 0); PG8_SCHED; PG8_LDA(At, 1, 0); PG8_STAGE(PG8_SA(0, 1), a2 + hstep, voffA);
;             PG8_WAIT_L(8); PG8_BAR; PG8_WAIT_L(0); PG8_MMA(0, 0, At, B0); PG8_BAR; PG8_SCHED;
;             PG8_LDB(B1, 1, 1); PG8_STAGE(PG8_SB(1, 0), b3, voffB);
;             PG8_BAR; PG8_WAIT_L(0); PG8_MMA(0, 1, At, B1); PG8_BAR;
;             PG8_LDA(At, 1, 1); PG8_STAGE(PG8_SA(1, 0), a3, voffA);
	s_add_u32 s6, s6, 0x40080
	s_addc_u32 s7, s7, 0
	s_add_i32 s42, s42, s48
	s_mov_b32 m0, s42
	s_nop 0
	global_load_lds_dwordx4 v0, s[6:7]
	s_add_i32 m0, s42, 0x2000
	s_nop 0
	global_load_lds_dwordx4 v130, s[6:7]
	s_waitcnt vmcnt(6)
	s_barrier
	v_mfma_f32_16x16x32_bf16 v[54:57], v[230:233], v[176:179], v[54:57]
	v_mfma_f32_16x16x32_bf16 v[50:53], v[238:241], v[176:179], v[50:53]
	v_mfma_f32_16x16x32_bf16 v[38:41], v[230:233], v[184:187], v[38:41]
	v_mfma_f32_16x16x32_bf16 v[34:37], v[238:241], v[184:187], v[34:37]
	v_mfma_f32_16x16x32_bf16 v[22:25], v[230:233], v[208:211], v[22:25]
	v_mfma_f32_16x16x32_bf16 v[18:21], v[238:241], v[208:211], v[18:21]
	v_mfma_f32_16x16x32_bf16 v[6:9], v[230:233], v[216:219], v[6:9]
	v_mfma_f32_16x16x32_bf16 v[2:5], v[238:241], v[216:219], v[2:5]
	v_mfma_f32_16x16x32_bf16 v[54:57], v[234:237], v[180:183], v[54:57]
	v_mfma_f32_16x16x32_bf16 v[50:53], v[242:245], v[180:183], v[50:53]
	v_mfma_f32_16x16x32_bf16 v[38:41], v[234:237], v[204:207], v[38:41]
	v_mfma_f32_16x16x32_bf16 v[34:37], v[242:245], v[204:207], v[34:37]
	v_mfma_f32_16x16x32_bf16 v[22:25], v[234:237], v[212:215], v[22:25]
	v_mfma_f32_16x16x32_bf16 v[18:21], v[242:245], v[212:215], v[18:21]
	v_mfma_f32_16x16x32_bf16 v[6:9], v[234:237], v[226:229], v[6:9]
	v_mfma_f32_16x16x32_bf16 v[2:5], v[242:245], v[226:229], v[2:5]
	s_add_i32 s93, s93, 2
	s_add_u32 s36, s36, 0x100
	s_addc_u32 s37, s37, 0
	s_add_u32 s91, s91, 0x100
	s_addc_u32 s92, s92, 0
	s_cmp_gt_u32 s93, 13
	s_barrier
	s_add_u32 s6, s36, 0xfffc0080
	s_addc_u32 s7, s37, -1
	s_add_i32 s58, 0, 0x10000
	v_add_u32_e32 v144, s58, v147
	ds_read_b128 v[140:143], v144
	ds_read_b128 v[152:155], v144 offset:1024
	ds_read_b128 v[168:171], v144 offset:2048
	ds_read_b128 v[172:175], v144 offset:3072
	s_cmp_eq_u32 s93, 12
	s_cselect_b32 s43, s11, s7
	s_cselect_b32 s42, s71, s6
	s_cselect_b32 s7, s9, s92
	s_cselect_b32 s6, s90, s91
	s_add_i32 m0, s49, 0xc000
	ds_read_b128 v[176:179], v150
	ds_read_b128 v[180:183], v150 offset:1024
	ds_read_b128 v[184:187], v150 offset:2048
	ds_read_b128 v[204:207], v150 offset:3072
	ds_read_b128 v[208:211], v150 offset:4096
	ds_read_b128 v[212:215], v150 offset:5120
	ds_read_b128 v[216:219], v150 offset:6144
	ds_read_b128 v[226:229], v150 offset:7168
	global_load_lds_dwordx4 v136, s[36:37]
	s_add_i32 m0, s49, 0xe000
	s_nop 0
	global_load_lds_dwordx4 v138, s[36:37]
	s_waitcnt lgkmcnt(8)
	s_barrier
	s_waitcnt lgkmcnt(0)
	s_waitcnt lgkmcnt(0)
	v_mfma_f32_16x16x32_bf16 v[126:129], v[140:143], v[176:179], v[126:129]
	v_mfma_f32_16x16x32_bf16 v[122:125], v[168:171], v[176:179], v[122:125]
	v_mfma_f32_16x16x32_bf16 v[110:113], v[140:143], v[184:187], v[110:113]
	v_mfma_f32_16x16x32_bf16 v[106:109], v[168:171], v[184:187], v[106:109]
	v_mfma_f32_16x16x32_bf16 v[94:97], v[140:143], v[208:211], v[94:97]
	v_mfma_f32_16x16x32_bf16 v[90:93], v[168:171], v[208:211], v[90:93]
	v_mfma_f32_16x16x32_bf16 v[78:81], v[140:143], v[216:219], v[78:81]
	v_mfma_f32_16x16x32_bf16 v[74:77], v[168:171], v[216:219], v[74:77]
	v_mfma_f32_16x16x32_bf16 v[126:129], v[152:155], v[180:183], v[126:129]
	v_mfma_f32_16x16x32_bf16 v[122:125], v[172:175], v[180:183], v[122:125]
	v_mfma_f32_16x16x32_bf16 v[110:113], v[152:155], v[204:207], v[110:113]
	v_mfma_f32_16x16x32_bf16 v[106:109], v[172:175], v[204:207], v[106:109]
	v_mfma_f32_16x16x32_bf16 v[94:97], v[152:155], v[212:215], v[94:97]
	v_mfma_f32_16x16x32_bf16 v[90:93], v[172:175], v[212:215], v[90:93]
	v_mfma_f32_16x16x32_bf16 v[78:81], v[152:155], v[226:229], v[78:81]
	v_mfma_f32_16x16x32_bf16 v[74:77], v[172:175], v[226:229], v[74:77]
	s_barrier
	s_add_i32 s70, 0, 0x14000
	v_add_u32_e32 v144, s70, v147
	s_add_i32 s58, s58, s48
	ds_read_b128 v[230:233], v144
	ds_read_b128 v[234:237], v144 offset:1024
	ds_read_b128 v[238:241], v144 offset:2048
	ds_read_b128 v[242:245], v144 offset:3072
	s_mov_b32 m0, s58
	s_nop 0
	global_load_lds_dwordx4 v0, s[6:7]
	s_add_i32 m0, s58, 0x2000
	s_nop 0
	global_load_lds_dwordx4 v130, s[6:7]
	s_barrier
	s_waitcnt lgkmcnt(0)
	s_waitcnt lgkmcnt(0)
	v_mfma_f32_16x16x32_bf16 v[118:121], v[230:233], v[176:179], v[118:121]
	v_mfma_f32_16x16x32_bf16 v[114:117], v[238:241], v[176:179], v[114:117]
	v_mfma_f32_16x16x32_bf16 v[102:105], v[230:233], v[184:187], v[102:105]
	v_mfma_f32_16x16x32_bf16 v[98:101], v[238:241], v[184:187], v[98:101]
	v_mfma_f32_16x16x32_bf16 v[86:89], v[230:233], v[208:211], v[86:89]
	v_mfma_f32_16x16x32_bf16 v[82:85], v[238:241], v[208:211], v[82:85]
	v_mfma_f32_16x16x32_bf16 v[70:73], v[230:233], v[216:219], v[70:73]
	v_mfma_f32_16x16x32_bf16 v[66:69], v[238:241], v[216:219], v[66:69]
	v_mfma_f32_16x16x32_bf16 v[118:121], v[234:237], v[180:183], v[118:121]
	v_mfma_f32_16x16x32_bf16 v[114:117], v[242:245], v[180:183], v[114:117]
	v_mfma_f32_16x16x32_bf16 v[102:105], v[234:237], v[204:207], v[102:105]
	v_mfma_f32_16x16x32_bf16 v[98:101], v[242:245], v[204:207], v[98:101]
	v_mfma_f32_16x16x32_bf16 v[86:89], v[234:237], v[212:215], v[86:89]
	v_mfma_f32_16x16x32_bf16 v[82:85], v[242:245], v[212:215], v[82:85]
	v_mfma_f32_16x16x32_bf16 v[70:73], v[234:237], v[226:229], v[70:73]
	v_mfma_f32_16x16x32_bf16 v[66:69], v[242:245], v[226:229], v[66:69]
	s_mov_b32 m0, s49
	s_add_u32 vcc_lo, s42, 0x80
	s_addc_u32 vcc_hi, s43, 0
	s_barrier
	ds_read_b128 v[176:179], v150 offset:16384
	ds_read_b128 v[180:183], v150 offset:17408
	ds_read_b128 v[184:187], v150 offset:18432
	ds_read_b128 v[204:207], v150 offset:19456
	ds_read_b128 v[208:211], v150 offset:20480
	ds_read_b128 v[212:215], v150 offset:21504
	ds_read_b128 v[216:219], v150 offset:22528
	ds_read_b128 v[226:229], v150 offset:23552
	global_load_lds_dwordx4 v134, s[42:43]
	s_mov_b32 m0, s54
	s_nop 0
	global_load_lds_dwordx4 v132, s[42:43]
	s_barrier
; #define PG8_STAGE(bufoff, gbase, voff) do { _Pragma("unroll") for (int _i = 0; _i < 2; ++_i) \
;         __builtin_amdgcn_global_load_lds((const unsigned*)((const char*)(gbase) + (voff)[_i]), (LAS unsigned*)(lds + (bufoff) + ldsw + _i * 8192), 16, 0, 0); } while (0)
; #define PG8_LDA(dst, b, h) do { _Pragma("unroll") for (int m = 0; m < 4; ++m) _Pragma("unroll") for (int k = 0; k < 2; ++k) dst[m][k] = *(const LAS bf16x8*)(lds + PG8_SA(b, h) + aoff + m * 2048 + k * 1024); } while (0)
; #define PG8_LDB(dst, b, h) do { _Pragma("unroll") for (int n = 0; n < 2; ++n) _Pragma("unroll") for (int k = 0; k < 2; ++k) dst[n][k] = *(const LAS bf16x8*)(lds + PG8_SB(b, h) + boff + n * 2048 + k * 1024); } while (0)
; #define PG8_WAIT_V(n) asm volatile("s_waitcnt vmcnt(" #n ")" ::: "memory")
;     __device__ __forceinline__ void operator()(const f32x4 (&acc)[2][2][4][2], const Unit& u, int ui, int wr, int wc, int fr, int fq) const {
;     ...
;                     *(u32x4*)(rowp + bj * HALF) = w;
; template <class Epi>
; __device__ __forceinline__ void gemm_phase(LAS unsigned char* lds, const Gemm g, const StaticOrder& S, const Epi& E) {
;     ...
;             PG8_LDB(B0, 0, 0); PG8_SCHED; PG8_LDA(At, 0, 0); PG8_STAGE(PG8_SA(1, 1), a1 + hstep, voffA);
;             PG8_WAIT_L(8); PG8_BAR; PG8_WAIT_L(0); PG8_MMA(0, 0, At, B0); PG8_BAR; PG8_SCHED;
;             PG8_LDB(B1, 0, 1); PG8_STAGE(PG8_SB(0, 0), b2, voffB);
;             PG8_BAR; PG8_WAIT_L(0); PG8_MMA(0, 1, At, B1); PG8_BAR;
;             PG8_LDA(At, 0, 1); PG8_STAGE(PG8_SA(0, 0), a2, voffA);
;             PG8_BAR; PG8_WAIT_L(0); PG8_MMA(1, 0, At, B0); PG8_BAR; PG8_SCHED;
;             PG8_STAGE(PG8_SB(0, 1), b2 + hstep, voffB);
;             PG8_WAIT_V(6); PG8_BAR; PG8_MMA(1, 1, At, B1); PG8_BAR;
;             PG8_LDB(B0, 1, 0); PG8_SCHED; PG8_LDA(At, 1, 0); PG8_STAGE(PG8_SA(0, 1), a2 + hstep, voffA);
;             PG8_WAIT_L(8); PG8_BAR; PG8_WAIT_L(0); PG8_MMA(0, 0, At, B0); PG8_BAR; PG8_SCHED;
;             PG8_LDB(B1, 1, 1); PG8_STAGE(PG8_SB(1, 0), b3, voffB);
;             PG8_BAR; PG8_WAIT_L(0); PG8_MMA(0, 1, At, B1); PG8_BAR;
;             PG8_LDA(At, 1, 1); PG8_STAGE(PG8_SA(1, 0), a3, voffA);
;             PG8_BAR; PG8_WAIT_L(0); PG8_MMA(1, 0, At, B0); PG8_BAR; PG8_SCHED;
;             PG8_STAGE(PG8_SB(1, 1), b3 + hstep, voffB);
;             PG8_WAIT_V(6); PG8_BAR; PG8_MMA(1, 1, At, B1); PG8_BAR;
	s_waitcnt lgkmcnt(0)
	s_waitcnt lgkmcnt(0)
	v_mfma_f32_16x16x32_bf16 v[62:65], v[140:143], v[176:179], v[62:65]
	v_mfma_f32_16x16x32_bf16 v[58:61], v[168:171], v[176:179], v[58:61]
	v_mfma_f32_16x16x32_bf16 v[46:49], v[140:143], v[184:187], v[46:49]
	v_mfma_f32_16x16x32_bf16 v[42:45], v[168:171], v[184:187], v[42:45]
	v_mfma_f32_16x16x32_bf16 v[30:33], v[140:143], v[208:211], v[30:33]
	v_mfma_f32_16x16x32_bf16 v[26:29], v[168:171], v[208:211], v[26:29]
	v_mfma_f32_16x16x32_bf16 v[14:17], v[140:143], v[216:219], v[14:17]
	v_mfma_f32_16x16x32_bf16 v[10:13], v[168:171], v[216:219], v[10:13]
	v_mfma_f32_16x16x32_bf16 v[62:65], v[152:155], v[180:183], v[62:65]
	v_mfma_f32_16x16x32_bf16 v[58:61], v[172:175], v[180:183], v[58:61]
	v_mfma_f32_16x16x32_bf16 v[46:49], v[152:155], v[204:207], v[46:49]
	v_mfma_f32_16x16x32_bf16 v[42:45], v[172:175], v[204:207], v[42:45]
	v_mfma_f32_16x16x32_bf16 v[30:33], v[152:155], v[212:215], v[30:33]
	v_mfma_f32_16x16x32_bf16 v[26:29], v[172:175], v[212:215], v[26:29]
	v_mfma_f32_16x16x32_bf16 v[14:17], v[152:155], v[226:229], v[14:17]
	v_mfma_f32_16x16x32_bf16 v[10:13], v[172:175], v[226:229], v[10:13]
	s_barrier
	s_add_u32 s60, s6, 0x40000
	s_addc_u32 s61, s7, 0
	s_add_i32 s58, s70, s48
	s_mov_b32 m0, s58
	s_nop 0
	global_load_lds_dwordx4 v0, s[60:61]
	s_add_i32 m0, s58, 0x2000
	s_nop 0
	global_load_lds_dwordx4 v130, s[60:61]
	s_waitcnt vmcnt(6)
	s_barrier
	v_mfma_f32_16x16x32_bf16 v[54:57], v[230:233], v[176:179], v[54:57]
	v_mfma_f32_16x16x32_bf16 v[50:53], v[238:241], v[176:179], v[50:53]
	s_cmp_eq_u32 s89, 0
	s_cbranch_scc1 .LdsE_skip_7
	global_store_dwordx4 v250, v[246:249], s[4:5] offset:256
.LdsE_skip_7:
	v_mfma_f32_16x16x32_bf16 v[38:41], v[230:233], v[184:187], v[38:41]
	v_mfma_f32_16x16x32_bf16 v[34:37], v[238:241], v[184:187], v[34:37]
	v_mfma_f32_16x16x32_bf16 v[22:25], v[230:233], v[208:211], v[22:25]
	v_mfma_f32_16x16x32_bf16 v[18:21], v[238:241], v[208:211], v[18:21]
	v_mfma_f32_16x16x32_bf16 v[6:9], v[230:233], v[216:219], v[6:9]
	v_mfma_f32_16x16x32_bf16 v[2:5], v[238:241], v[216:219], v[2:5]
	v_mfma_f32_16x16x32_bf16 v[54:57], v[234:237], v[180:183], v[54:57]
	v_mfma_f32_16x16x32_bf16 v[50:53], v[242:245], v[180:183], v[50:53]
	v_mfma_f32_16x16x32_bf16 v[38:41], v[234:237], v[204:207], v[38:41]
	v_mfma_f32_16x16x32_bf16 v[34:37], v[242:245], v[204:207], v[34:37]
	v_mfma_f32_16x16x32_bf16 v[22:25], v[234:237], v[212:215], v[22:25]
	v_mfma_f32_16x16x32_bf16 v[18:21], v[242:245], v[212:215], v[18:21]
	v_mfma_f32_16x16x32_bf16 v[6:9], v[234:237], v[226:229], v[6:9]
	v_mfma_f32_16x16x32_bf16 v[2:5], v[242:245], v[226:229], v[2:5]
	s_add_i32 s58, 0, 0x18000
	v_add_u32_e32 v151, s58, v147
	s_barrier
	ds_read_b128 v[140:143], v151
	ds_read_b128 v[152:155], v151 offset:1024
	ds_read_b128 v[168:171], v151 offset:2048
	ds_read_b128 v[172:175], v151 offset:3072
	s_add_u32 s42, s42, 0x40000
	s_addc_u32 s43, s43, 0
	s_mov_b32 m0, s55
	ds_read_b128 v[176:179], v150 offset:32768
	ds_read_b128 v[180:183], v150 offset:33792
	ds_read_b128 v[184:187], v150 offset:34816
	ds_read_b128 v[204:207], v150 offset:35840
	ds_read_b128 v[208:211], v150 offset:36864
	ds_read_b128 v[212:215], v150 offset:37888
	ds_read_b128 v[216:219], v150 offset:38912
	ds_read_b128 v[226:229], v150 offset:39936
	global_load_lds_dwordx4 v134, s[42:43]
	s_mov_b32 m0, s83
	s_nop 0
	global_load_lds_dwordx4 v132, s[42:43]
	s_waitcnt lgkmcnt(8)
	s_barrier
	s_waitcnt lgkmcnt(0)
	s_waitcnt lgkmcnt(0)
	v_mfma_f32_16x16x32_bf16 v[126:129], v[140:143], v[176:179], v[126:129]
	v_mfma_f32_16x16x32_bf16 v[122:125], v[168:171], v[176:179], v[122:125]
	v_mfma_f32_16x16x32_bf16 v[110:113], v[140:143], v[184:187], v[110:113]
	v_mfma_f32_16x16x32_bf16 v[106:109], v[168:171], v[184:187], v[106:109]
	v_mfma_f32_16x16x32_bf16 v[94:97], v[140:143], v[208:211], v[94:97]
	v_mfma_f32_16x16x32_bf16 v[90:93], v[168:171], v[208:211], v[90:93]
	v_mfma_f32_16x16x32_bf16 v[78:81], v[140:143], v[216:219], v[78:81]
	v_mfma_f32_16x16x32_bf16 v[74:77], v[168:171], v[216:219], v[74:77]
	v_mfma_f32_16x16x32_bf16 v[126:129], v[152:155], v[180:183], v[126:129]
	v_mfma_f32_16x16x32_bf16 v[122:125], v[172:175], v[180:183], v[122:125]
	v_mfma_f32_16x16x32_bf16 v[110:113], v[152:155], v[204:207], v[110:113]
	v_mfma_f32_16x16x32_bf16 v[106:109], v[172:175], v[204:207], v[106:109]
	v_mfma_f32_16x16x32_bf16 v[94:97], v[152:155], v[212:215], v[94:97]
	v_mfma_f32_16x16x32_bf16 v[90:93], v[172:175], v[212:215], v[90:93]
	v_mfma_f32_16x16x32_bf16 v[78:81], v[152:155], v[226:229], v[78:81]
	v_mfma_f32_16x16x32_bf16 v[74:77], v[172:175], v[226:229], v[74:77]
	s_barrier
	s_add_i32 s42, 0, 0x1c000
	s_add_i32 s43, s58, s48
	v_add_u32_e32 v151, s42, v147
	s_add_u32 s60, s6, 0x80
	s_addc_u32 s61, s7, 0
	s_mov_b32 m0, s43
	ds_read_b128 v[230:233], v151
	ds_read_b128 v[234:237], v151 offset:1024
	ds_read_b128 v[238:241], v151 offset:2048
	ds_read_b128 v[242:245], v151 offset:3072
	global_load_lds_dwordx4 v0, s[60:61]
	s_add_i32 m0, s43, 0x2000
	s_nop 0
	global_load_lds_dwordx4 v130, s[60:61]
	s_barrier
; #define PG8_STAGE(bufoff, gbase, voff) do { _Pragma("unroll") for (int _i = 0; _i < 2; ++_i) \
;         __builtin_amdgcn_global_load_lds((const unsigned*)((const char*)(gbase) + (voff)[_i]), (LAS unsigned*)(lds + (bufoff) + ldsw + _i * 8192), 16, 0, 0); } while (0)
; #define PG8_LDA(dst, b, h) do { _Pragma("unroll") for (int m = 0; m < 4; ++m) _Pragma("unroll") for (int k = 0; k < 2; ++k) dst[m][k] = *(const LAS bf16x8*)(lds + PG8_SA(b, h) + aoff + m * 2048 + k * 1024); } while (0)
; #define PG8_LDB(dst, b, h) do { _Pragma("unroll") for (int n = 0; n < 2; ++n) _Pragma("unroll") for (int k = 0; k < 2; ++k) dst[n][k] = *(const LAS bf16x8*)(lds + PG8_SB(b, h) + boff + n * 2048 + k * 1024); } while (0)
; #define PG8_WAIT_V(n) asm volatile("s_waitcnt vmcnt(" #n ")" ::: "memory")
; #define PG8_WAIT_L(n) asm volatile("s_waitcnt lgkmcnt(" #n ")" ::: "memory")
; #define PG8_BAR __builtin_amdgcn_s_barrier()
; #define PG8_SCHED __builtin_amdgcn_sched_barrier(0)
; template <class Epi>
; __device__ __forceinline__ void gemm_phase(LAS unsigned char* lds, const Gemm g, const StaticOrder& S, const Epi& E) {
;     ...
;         for (int t = 0; t < nt; t += 2) {
;     ...
;             PG8_LDB(B0, 0, 0); PG8_SCHED; PG8_LDA(At, 0, 0); PG8_STAGE(PG8_SA(1, 1), a1 + hstep, voffA);
;             PG8_WAIT_L(8); PG8_BAR; PG8_WAIT_L(0); PG8_MMA(0, 0, At, B0); PG8_BAR; PG8_SCHED;
;             PG8_LDB(B1, 0, 1); PG8_STAGE(PG8_SB(0, 0), b2, voffB);
;             PG8_BAR; PG8_WAIT_L(0); PG8_MMA(0, 1, At, B1); PG8_BAR;
;             PG8_LDA(At, 0, 1); PG8_STAGE(PG8_SA(0, 0), a2, voffA);
;             PG8_BAR; PG8_WAIT_L(0); PG8_MMA(1, 0, At, B0); PG8_BAR; PG8_SCHED;
;             PG8_STAGE(PG8_SB(0, 1), b2 + hstep, voffB);
;             PG8_WAIT_V(6); PG8_BAR; PG8_MMA(1, 1, At, B1); PG8_BAR;
;             PG8_LDB(B0, 1, 0); PG8_SCHED; PG8_LDA(At, 1, 0); PG8_STAGE(PG8_SA(0, 1), a2 + hstep, voffA);
;             PG8_WAIT_L(8); PG8_BAR; PG8_WAIT_L(0); PG8_MMA(0, 0, At, B0); PG8_BAR; PG8_SCHED;
;             PG8_LDB(B1, 1, 1); PG8_STAGE(PG8_SB(1, 0), b3, voffB);
;             PG8_BAR; PG8_WAIT_L(0); PG8_MMA(0, 1, At, B1); PG8_BAR;
;             PG8_LDA(At, 1, 1); PG8_STAGE(PG8_SA(1, 0), a3, voffA);
;             PG8_BAR; PG8_WAIT_L(0); PG8_MMA(1, 0, At, B0); PG8_BAR; PG8_SCHED;
;             PG8_STAGE(PG8_SB(1, 1), b3 + hstep, voffB);
;             PG8_WAIT_V(6); PG8_BAR; PG8_MMA(1, 1, At, B1); PG8_BAR;
	s_waitcnt lgkmcnt(0)
	s_waitcnt lgkmcnt(0)
	v_mfma_f32_16x16x32_bf16 v[118:121], v[230:233], v[176:179], v[118:121]
	v_mfma_f32_16x16x32_bf16 v[114:117], v[238:241], v[176:179], v[114:117]
	v_mfma_f32_16x16x32_bf16 v[102:105], v[230:233], v[184:187], v[102:105]
	v_mfma_f32_16x16x32_bf16 v[98:101], v[238:241], v[184:187], v[98:101]
	v_mfma_f32_16x16x32_bf16 v[86:89], v[230:233], v[208:211], v[86:89]
	v_mfma_f32_16x16x32_bf16 v[82:85], v[238:241], v[208:211], v[82:85]
	v_mfma_f32_16x16x32_bf16 v[70:73], v[230:233], v[216:219], v[70:73]
	v_mfma_f32_16x16x32_bf16 v[66:69], v[238:241], v[216:219], v[66:69]
	v_mfma_f32_16x16x32_bf16 v[118:121], v[234:237], v[180:183], v[118:121]
	v_mfma_f32_16x16x32_bf16 v[114:117], v[242:245], v[180:183], v[114:117]
	v_mfma_f32_16x16x32_bf16 v[102:105], v[234:237], v[204:207], v[102:105]
	v_mfma_f32_16x16x32_bf16 v[98:101], v[242:245], v[204:207], v[98:101]
	v_mfma_f32_16x16x32_bf16 v[86:89], v[234:237], v[212:215], v[86:89]
	v_mfma_f32_16x16x32_bf16 v[82:85], v[242:245], v[212:215], v[82:85]
	v_mfma_f32_16x16x32_bf16 v[70:73], v[234:237], v[226:229], v[70:73]
	v_mfma_f32_16x16x32_bf16 v[66:69], v[242:245], v[226:229], v[66:69]
	s_mov_b32 m0, s84
	s_barrier
	ds_read_b128 v[176:179], v150 offset:49152
	ds_read_b128 v[180:183], v150 offset:50176
	ds_read_b128 v[184:187], v150 offset:51200
	ds_read_b128 v[204:207], v150 offset:52224
	ds_read_b128 v[208:211], v150 offset:53248
	ds_read_b128 v[212:215], v150 offset:54272
	ds_read_b128 v[216:219], v150 offset:55296
	ds_read_b128 v[226:229], v150 offset:56320
	global_load_lds_dwordx4 v134, vcc
	s_mov_b32 m0, s85
	s_nop 0
	global_load_lds_dwordx4 v132, vcc
	s_barrier
	s_waitcnt lgkmcnt(0)
	s_waitcnt lgkmcnt(0)
	v_mfma_f32_16x16x32_bf16 v[62:65], v[140:143], v[176:179], v[62:65]
	v_mfma_f32_16x16x32_bf16 v[58:61], v[168:171], v[176:179], v[58:61]
	v_mfma_f32_16x16x32_bf16 v[46:49], v[140:143], v[184:187], v[46:49]
	v_mfma_f32_16x16x32_bf16 v[42:45], v[168:171], v[184:187], v[42:45]
	v_mfma_f32_16x16x32_bf16 v[30:33], v[140:143], v[208:211], v[30:33]
	v_mfma_f32_16x16x32_bf16 v[26:29], v[168:171], v[208:211], v[26:29]
	v_mfma_f32_16x16x32_bf16 v[14:17], v[140:143], v[216:219], v[14:17]
	v_mfma_f32_16x16x32_bf16 v[10:13], v[168:171], v[216:219], v[10:13]
	v_mfma_f32_16x16x32_bf16 v[62:65], v[152:155], v[180:183], v[62:65]
	v_mfma_f32_16x16x32_bf16 v[58:61], v[172:175], v[180:183], v[58:61]
	v_mfma_f32_16x16x32_bf16 v[46:49], v[152:155], v[204:207], v[46:49]
	v_mfma_f32_16x16x32_bf16 v[42:45], v[172:175], v[204:207], v[42:45]
	v_mfma_f32_16x16x32_bf16 v[30:33], v[152:155], v[212:215], v[30:33]
	v_mfma_f32_16x16x32_bf16 v[26:29], v[172:175], v[212:215], v[26:29]
	v_mfma_f32_16x16x32_bf16 v[14:17], v[152:155], v[226:229], v[14:17]
	v_mfma_f32_16x16x32_bf16 v[10:13], v[172:175], v[226:229], v[10:13]
	s_barrier
	s_add_u32 s6, s6, 0x40080
	s_addc_u32 s7, s7, 0
	s_add_i32 s42, s42, s48
	s_mov_b32 m0, s42
	s_nop 0
	global_load_lds_dwordx4 v0, s[6:7]
	s_add_i32 m0, s42, 0x2000
	s_nop 0
	global_load_lds_dwordx4 v130, s[6:7]
	s_waitcnt vmcnt(6)
	s_barrier
	v_mfma_f32_16x16x32_bf16 v[54:57], v[230:233], v[176:179], v[54:57]
	v_mfma_f32_16x16x32_bf16 v[50:53], v[238:241], v[176:179], v[50:53]
	v_mfma_f32_16x16x32_bf16 v[38:41], v[230:233], v[184:187], v[38:41]
	v_mfma_f32_16x16x32_bf16 v[34:37], v[238:241], v[184:187], v[34:37]
	v_mfma_f32_16x16x32_bf16 v[22:25], v[230:233], v[208:211], v[22:25]
	v_mfma_f32_16x16x32_bf16 v[18:21], v[238:241], v[208:211], v[18:21]
	v_mfma_f32_16x16x32_bf16 v[6:9], v[230:233], v[216:219], v[6:9]
	v_mfma_f32_16x16x32_bf16 v[2:5], v[238:241], v[216:219], v[2:5]
	v_mfma_f32_16x16x32_bf16 v[54:57], v[234:237], v[180:183], v[54:57]
	v_mfma_f32_16x16x32_bf16 v[50:53], v[242:245], v[180:183], v[50:53]
	v_mfma_f32_16x16x32_bf16 v[38:41], v[234:237], v[204:207], v[38:41]
	v_mfma_f32_16x16x32_bf16 v[34:37], v[242:245], v[204:207], v[34:37]
	v_mfma_f32_16x16x32_bf16 v[22:25], v[234:237], v[212:215], v[22:25]
	v_mfma_f32_16x16x32_bf16 v[18:21], v[242:245], v[212:215], v[18:21]
	v_mfma_f32_16x16x32_bf16 v[6:9], v[234:237], v[226:229], v[6:9]
	v_mfma_f32_16x16x32_bf16 v[2:5], v[242:245], v[226:229], v[2:5]
	s_add_i32 s93, s93, 2
	s_add_u32 s36, s36, 0x100
	s_addc_u32 s37, s37, 0
	s_add_u32 s91, s91, 0x100
	s_addc_u32 s92, s92, 0
	s_cmp_gt_u32 s93, 13
	s_barrier
; __device__ __forceinline__ unsigned pk2(float lo, float hi) { unsigned r; asm("v_cvt_pk_bf16_f32 %0, %1, %2" : "=v"(r) : "v"(lo), "v"(hi)); return r; }
;     __device__ __forceinline__ void operator()(const f32x4 (&acc)[2][2][4][2], const Unit& u, int ui, int wr, int wc, int fr, int fq) const {
;         const int lrow0 = wr * 64 + fr, row0 = u.pm * BM + lrow0, col0 = u.pn * BM + wc * 32 + 8 * fq;
;         float rsv[2][4];
; #pragma unroll
;         for (int ai = 0; ai < 2; ++ai)
; #pragma unroll
;             for (int m = 0; m < 4; ++m) rsv[ai][m] = rstab[ui * 256 + lrow0 + ai * HALF + m * 16];
; #pragma unroll
;         for (int ai = 0; ai < 2; ++ai)
; #pragma unroll
;             for (int m = 0; m < 4; ++m) {
;                 const int row = row0 + ai * HALF + m * 16; const float rs = rsv[ai][m];
;                 bf16_t* rowp = O + (size_t)row * ldc + col0;
; #pragma unroll
;                 for (int bj = 0; bj < 2; ++bj) {
;                     f32x4 v0 = acc[ai][bj][m][0] * rs, v1 = acc[ai][bj][m][1] * rs;
;                     if (ACT == 1) {
; #pragma unroll
;                         for (int j = 0; j < 4; ++j) { const float a = fmaxf(v0[j], 0.f), b = fmaxf(v1[j], 0.f); v0[j] = a * a; v1[j] = b * b; }
;                     }
;                     u32x4 w; w.x = pk2(v0[0], v0[1]); w.y = pk2(v0[2], v0[3]); w.z = pk2(v1[0], v1[1]); w.w = pk2(v1[2], v1[3]);
;                     *(u32x4*)(rowp + bj * HALF) = w;
	v_lshl_add_u32 v140, s89, 10, v148
	ds_read2_b32 v[154:155], v140 offset1:16
	ds_read2_b32 v[156:157], v140 offset0:32 offset1:48
	ds_read2_b32 v[144:145], v140 offset0:128 offset1:144
	ds_read2_b32 v[142:143], v140 offset0:160 offset1:176
	v_lshl_add_u32 v152, s88, 8, v146
	s_waitcnt lgkmcnt(0)
	v_pk_mul_f32 v[122:123], v[122:123], v[154:155] op_sel_hi:[1,0]
	v_lshl_or_b32 v140, s87, 8, v149
	v_lshlrev_b32_e32 v250, 13, v152
	v_lshl_add_u32 v250, v140, 1, v250
	v_add_u32_e32 v250, 0x100000, v250
	v_ashrrev_i32_e32 v153, 31, v152
	v_pk_mul_f32 v[126:127], v[126:127], v[154:155] op_sel_hi:[1,0]
	v_pk_mul_f32 v[124:125], v[124:125], v[154:155] op_sel_hi:[1,0]
	v_max_f32_e32 v122, 0, v122
	v_ashrrev_i32_e32 v141, 31, v140
	v_lshlrev_b64 v[162:163], 13, v[152:153]
	v_pk_mul_f32 v[128:129], v[128:129], v[154:155] op_sel_hi:[1,0]
	v_mul_f32_e32 v151, v122, v122
	v_max_f32_e32 v122, 0, v127
	v_max_f32_e32 v123, 0, v123
	v_max_f32_e32 v124, 0, v124
	v_lshl_add_u64 v[162:163], s[4:5], 0, v[162:163]
	v_lshlrev_b64 v[168:169], 1, v[140:141]
	v_max_f32_e32 v126, 0, v126
	v_mul_f32_e32 v122, v122, v122
	v_mul_f32_e32 v127, v123, v123
	v_max_f32_e32 v123, 0, v128
	v_mul_f32_e32 v128, v124, v124
	v_max_f32_e32 v124, 0, v129
	v_max_f32_e32 v125, 0, v125
	v_pk_mul_f32 v[116:117], v[116:117], v[154:155] op_sel_hi:[1,0]
	v_pk_mul_f32 v[114:115], v[114:115], v[154:155] op_sel_hi:[1,0]
	v_lshl_add_u64 v[140:141], v[162:163], 0, v[168:169]
	v_mul_f32_e32 v126, v126, v126
	v_mul_f32_e32 v123, v123, v123
	v_mul_f32_e32 v124, v124, v124
	v_mul_f32_e32 v125, v125, v125
	v_cvt_pk_bf16_f32 v122, v126, v122
	v_pk_mul_f32 v[120:121], v[120:121], v[154:155] op_sel_hi:[1,0]
	v_pk_mul_f32 v[118:119], v[118:119], v[154:155] op_sel_hi:[1,0]
	v_max_f32_e32 v114, 0, v114
	v_max_f32_e32 v115, 0, v115
	v_max_f32_e32 v116, 0, v116
	v_cvt_pk_bf16_f32 v123, v123, v124
	v_cvt_pk_bf16_f32 v124, v151, v127
	v_cvt_pk_bf16_f32 v125, v128, v125
	global_store_dwordx4 v[140:141], v[122:125], off
	v_max_f32_e32 v117, 0, v117
	v_max_f32_e32 v118, 0, v118
	v_mul_f32_e32 v122, v114, v114
	v_max_f32_e32 v114, 0, v119
	v_mul_f32_e32 v119, v115, v115
	v_max_f32_e32 v115, 0, v120
	v_mul_f32_e32 v120, v116, v116
	v_max_f32_e32 v116, 0, v121
	v_mul_f32_e32 v115, v115, v115
	v_mul_f32_e32 v116, v116, v116
	v_mul_f32_e32 v114, v114, v114
	v_mul_f32_e32 v117, v117, v117
	v_cvt_pk_bf16_f32 v115, v115, v116
	v_cvt_pk_bf16_f32 v116, v122, v119
	v_mul_f32_e32 v118, v118, v118
	v_cvt_pk_bf16_f32 v114, v118, v114
	v_cvt_pk_bf16_f32 v117, v120, v117
	global_store_dwordx4 v[140:141], v[114:117], off offset:256
	v_pk_mul_f32 v[90:91], v[90:91], v[156:157] op_sel_hi:[1,0]
	v_pk_mul_f32 v[94:95], v[94:95], v[156:157] op_sel_hi:[1,0]
	v_mov_b32_e32 v116, v155
	v_or_b32_e32 v114, 16, v152
	v_pk_mul_f32 v[106:107], v[106:107], v[116:117] op_sel_hi:[1,0]
	v_ashrrev_i32_e32 v115, 31, v114
	v_pk_mul_f32 v[110:111], v[110:111], v[116:117] op_sel_hi:[1,0]
	v_pk_mul_f32 v[108:109], v[108:109], v[116:117] op_sel_hi:[1,0]
	v_max_f32_e32 v106, 0, v106
	v_lshlrev_b64 v[114:115], 13, v[114:115]
	v_pk_mul_f32 v[112:113], v[112:113], v[116:117] op_sel_hi:[1,0]
	v_mul_f32_e32 v117, v106, v106
	v_max_f32_e32 v106, 0, v111
	v_max_f32_e32 v107, 0, v107
	v_max_f32_e32 v108, 0, v108
	v_lshl_add_u64 v[114:115], s[4:5], 0, v[114:115]
	v_max_f32_e32 v110, 0, v110
	v_mul_f32_e32 v106, v106, v106
	v_mul_f32_e32 v111, v107, v107
	v_max_f32_e32 v107, 0, v112
	v_mul_f32_e32 v112, v108, v108
	v_max_f32_e32 v108, 0, v113
	v_max_f32_e32 v109, 0, v109
	v_pk_mul_f32 v[98:99], v[98:99], v[116:117] op_sel_hi:[1,0]
	v_lshl_add_u64 v[114:115], v[114:115], 0, v[168:169]
	v_mul_f32_e32 v110, v110, v110
	v_mul_f32_e32 v107, v107, v107
	v_mul_f32_e32 v108, v108, v108
	v_mul_f32_e32 v109, v109, v109
	v_cvt_pk_bf16_f32 v106, v110, v106
	v_pk_mul_f32 v[102:103], v[102:103], v[116:117] op_sel_hi:[1,0]
	v_pk_mul_f32 v[100:101], v[100:101], v[116:117] op_sel_hi:[1,0]
	v_max_f32_e32 v98, 0, v98
	v_cvt_pk_bf16_f32 v107, v107, v108
	v_cvt_pk_bf16_f32 v108, v117, v111
	v_cvt_pk_bf16_f32 v109, v112, v109
	global_store_dwordx4 v[114:115], v[106:109], off
	v_pk_mul_f32 v[104:105], v[104:105], v[116:117] op_sel_hi:[1,0]
	v_max_f32_e32 v99, 0, v99
	v_mul_f32_e32 v106, v98, v98
	v_max_f32_e32 v98, 0, v103
	v_max_f32_e32 v100, 0, v100
	v_max_f32_e32 v102, 0, v102
	v_mul_f32_e32 v98, v98, v98
	v_mul_f32_e32 v103, v99, v99
	v_max_f32_e32 v99, 0, v104
	v_mul_f32_e32 v104, v100, v100
	v_max_f32_e32 v100, 0, v105
	v_max_f32_e32 v101, 0, v101
	v_mul_f32_e32 v102, v102, v102
	v_mul_f32_e32 v99, v99, v99
	v_mul_f32_e32 v100, v100, v100
	v_mul_f32_e32 v101, v101, v101
	v_cvt_pk_bf16_f32 v98, v102, v98
	v_cvt_pk_bf16_f32 v99, v99, v100
	v_cvt_pk_bf16_f32 v100, v106, v103
	v_cvt_pk_bf16_f32 v101, v104, v101
	global_store_dwordx4 v[114:115], v[98:101], off offset:256
	v_pk_mul_f32 v[92:93], v[92:93], v[156:157] op_sel_hi:[1,0]
	v_max_f32_e32 v90, 0, v90
	v_or_b32_e32 v98, 32, v152
	v_ashrrev_i32_e32 v99, 31, v98
	v_lshlrev_b64 v[98:99], 13, v[98:99]
	v_pk_mul_f32 v[96:97], v[96:97], v[156:157] op_sel_hi:[1,0]
	v_mul_f32_e32 v100, v90, v90
	v_max_f32_e32 v90, 0, v95
	v_max_f32_e32 v91, 0, v91
	v_max_f32_e32 v92, 0, v92
	v_lshl_add_u64 v[98:99], s[4:5], 0, v[98:99]
	v_max_f32_e32 v94, 0, v94
	v_mul_f32_e32 v90, v90, v90
	v_mul_f32_e32 v95, v91, v91
	v_max_f32_e32 v91, 0, v96
	v_mul_f32_e32 v96, v92, v92
	v_max_f32_e32 v92, 0, v97
	v_max_f32_e32 v93, 0, v93
	v_pk_mul_f32 v[84:85], v[84:85], v[156:157] op_sel_hi:[1,0]
	v_pk_mul_f32 v[82:83], v[82:83], v[156:157] op_sel_hi:[1,0]
	v_lshl_add_u64 v[98:99], v[98:99], 0, v[168:169]
	v_mul_f32_e32 v94, v94, v94
	v_mul_f32_e32 v91, v91, v91
; __device__ __forceinline__ unsigned pk2(float lo, float hi) { unsigned r; asm("v_cvt_pk_bf16_f32 %0, %1, %2" : "=v"(r) : "v"(lo), "v"(hi)); return r; }
;     __device__ __forceinline__ void operator()(const f32x4 (&acc)[2][2][4][2], const Unit& u, int ui, int wr, int wc, int fr, int fq) const {
;     ...
;             for (int m = 0; m < 4; ++m) {
;                 const int row = row0 + ai * HALF + m * 16; const float rs = rsv[ai][m];
;                 bf16_t* rowp = O + (size_t)row * ldc + col0;
; #pragma unroll
;                 for (int bj = 0; bj < 2; ++bj) {
;                     f32x4 v0 = acc[ai][bj][m][0] * rs, v1 = acc[ai][bj][m][1] * rs;
;                     if (ACT == 1) {
; #pragma unroll
;                         for (int j = 0; j < 4; ++j) { const float a = fmaxf(v0[j], 0.f), b = fmaxf(v1[j], 0.f); v0[j] = a * a; v1[j] = b * b; }
;                     }
;                     u32x4 w; w.x = pk2(v0[0], v0[1]); w.y = pk2(v0[2], v0[3]); w.z = pk2(v1[0], v1[1]); w.w = pk2(v1[2], v1[3]);
;                     *(u32x4*)(rowp + bj * HALF) = w;
	v_mul_f32_e32 v92, v92, v92
	v_mul_f32_e32 v93, v93, v93
	v_cvt_pk_bf16_f32 v90, v94, v90
	v_pk_mul_f32 v[88:89], v[88:89], v[156:157] op_sel_hi:[1,0]
	v_pk_mul_f32 v[86:87], v[86:87], v[156:157] op_sel_hi:[1,0]
	v_max_f32_e32 v82, 0, v82
	v_max_f32_e32 v83, 0, v83
	v_max_f32_e32 v84, 0, v84
	v_cvt_pk_bf16_f32 v91, v91, v92
	v_cvt_pk_bf16_f32 v92, v100, v95
	v_cvt_pk_bf16_f32 v93, v96, v93
	global_store_dwordx4 v[98:99], v[90:93], off
	v_max_f32_e32 v85, 0, v85
	v_max_f32_e32 v86, 0, v86
	v_mul_f32_e32 v90, v82, v82
	v_max_f32_e32 v82, 0, v87
	v_mul_f32_e32 v87, v83, v83
	v_max_f32_e32 v83, 0, v88
	v_mul_f32_e32 v88, v84, v84
	v_max_f32_e32 v84, 0, v89
	v_mul_f32_e32 v83, v83, v83
	v_mul_f32_e32 v84, v84, v84
	v_mul_f32_e32 v82, v82, v82
	v_mul_f32_e32 v85, v85, v85
	v_cvt_pk_bf16_f32 v83, v83, v84
	v_cvt_pk_bf16_f32 v84, v90, v87
	v_mul_f32_e32 v86, v86, v86
	v_cvt_pk_bf16_f32 v82, v86, v82
	v_cvt_pk_bf16_f32 v85, v88, v85
	global_store_dwordx4 v[98:99], v[82:85], off offset:256
	v_pk_mul_f32 v[58:59], v[58:59], v[144:145] op_sel_hi:[1,0]
	v_pk_mul_f32 v[62:63], v[62:63], v[144:145] op_sel_hi:[1,0]
	v_mov_b32_e32 v84, v157
	v_or_b32_e32 v82, 48, v152
	v_pk_mul_f32 v[74:75], v[74:75], v[84:85] op_sel_hi:[1,0]
	v_ashrrev_i32_e32 v83, 31, v82
	v_pk_mul_f32 v[78:79], v[78:79], v[84:85] op_sel_hi:[1,0]
	v_pk_mul_f32 v[76:77], v[76:77], v[84:85] op_sel_hi:[1,0]
	v_max_f32_e32 v74, 0, v74
	v_lshlrev_b64 v[82:83], 13, v[82:83]
	v_pk_mul_f32 v[80:81], v[80:81], v[84:85] op_sel_hi:[1,0]
	v_mul_f32_e32 v85, v74, v74
	v_max_f32_e32 v74, 0, v79
	v_max_f32_e32 v75, 0, v75
	v_max_f32_e32 v76, 0, v76
	v_lshl_add_u64 v[82:83], s[4:5], 0, v[82:83]
	v_max_f32_e32 v78, 0, v78
	v_mul_f32_e32 v74, v74, v74
	v_mul_f32_e32 v79, v75, v75
	v_max_f32_e32 v75, 0, v80
	v_mul_f32_e32 v80, v76, v76
	v_max_f32_e32 v76, 0, v81
	v_max_f32_e32 v77, 0, v77
	v_pk_mul_f32 v[68:69], v[68:69], v[84:85] op_sel_hi:[1,0]
	v_pk_mul_f32 v[66:67], v[66:67], v[84:85] op_sel_hi:[1,0]
	v_lshl_add_u64 v[82:83], v[82:83], 0, v[168:169]
	v_mul_f32_e32 v78, v78, v78
	v_mul_f32_e32 v75, v75, v75
	v_mul_f32_e32 v76, v76, v76
	v_mul_f32_e32 v77, v77, v77
	v_cvt_pk_bf16_f32 v74, v78, v74
	v_pk_mul_f32 v[72:73], v[72:73], v[84:85] op_sel_hi:[1,0]
	v_pk_mul_f32 v[70:71], v[70:71], v[84:85] op_sel_hi:[1,0]
	v_max_f32_e32 v66, 0, v66
	v_max_f32_e32 v67, 0, v67
	v_max_f32_e32 v68, 0, v68
	v_cvt_pk_bf16_f32 v75, v75, v76
	v_cvt_pk_bf16_f32 v76, v85, v79
	v_cvt_pk_bf16_f32 v77, v80, v77
	global_store_dwordx4 v[82:83], v[74:77], off
	v_max_f32_e32 v69, 0, v69
	v_max_f32_e32 v70, 0, v70
	v_mul_f32_e32 v74, v66, v66
	v_max_f32_e32 v66, 0, v71
	v_mul_f32_e32 v71, v67, v67
	v_max_f32_e32 v67, 0, v72
	v_mul_f32_e32 v72, v68, v68
	v_max_f32_e32 v68, 0, v73
	v_mul_f32_e32 v67, v67, v67
	v_mul_f32_e32 v68, v68, v68
	v_mul_f32_e32 v66, v66, v66
	v_mul_f32_e32 v69, v69, v69
	v_cvt_pk_bf16_f32 v67, v67, v68
	v_cvt_pk_bf16_f32 v68, v74, v71
	v_pk_mul_f32 v[60:61], v[60:61], v[144:145] op_sel_hi:[1,0]
	v_max_f32_e32 v58, 0, v58
	v_mul_f32_e32 v70, v70, v70
	v_cvt_pk_bf16_f32 v66, v70, v66
	v_cvt_pk_bf16_f32 v69, v72, v69
	global_store_dwordx4 v[82:83], v[66:69], off offset:256
	s_mov_b64 s[6:7], 0x100000
	v_pk_mul_f32 v[64:65], v[64:65], v[144:145] op_sel_hi:[1,0]
	v_max_f32_e32 v62, 0, v62
	v_mul_f32_e32 v68, v58, v58
	v_max_f32_e32 v58, 0, v63
	v_max_f32_e32 v59, 0, v59
	v_max_f32_e32 v60, 0, v60
	v_lshl_add_u64 v[66:67], v[140:141], 0, s[6:7]
	v_mul_f32_e32 v62, v62, v62
	v_mul_f32_e32 v58, v58, v58
	v_mul_f32_e32 v63, v59, v59
	v_max_f32_e32 v59, 0, v64
	v_mul_f32_e32 v64, v60, v60
	v_max_f32_e32 v60, 0, v65
	s_mov_b32 s6, 0x100000
	v_mul_f32_e32 v59, v59, v59
	v_max_f32_e32 v61, 0, v61
	v_mul_f32_e32 v60, v60, v60
	v_cvt_pk_bf16_f32 v58, v62, v58
	v_add_co_u32_e32 v62, vcc, s6, v140
	v_pk_mul_f32 v[52:53], v[52:53], v[144:145] op_sel_hi:[1,0]
	v_pk_mul_f32 v[50:51], v[50:51], v[144:145] op_sel_hi:[1,0]
	v_mul_f32_e32 v61, v61, v61
	v_cvt_pk_bf16_f32 v59, v59, v60
	v_cvt_pk_bf16_f32 v60, v68, v63
	v_addc_co_u32_e32 v63, vcc, 0, v141, vcc
	v_pk_mul_f32 v[56:57], v[56:57], v[144:145] op_sel_hi:[1,0]
	v_pk_mul_f32 v[54:55], v[54:55], v[144:145] op_sel_hi:[1,0]
	v_max_f32_e32 v50, 0, v50
	v_max_f32_e32 v51, 0, v51
	v_max_f32_e32 v52, 0, v52
	v_cvt_pk_bf16_f32 v61, v64, v61
	v_mov_b32_e32 v158, v58
	v_mov_b32_e32 v159, v59
	v_mov_b32_e32 v160, v60
	v_mov_b32_e32 v161, v61
	v_max_f32_e32 v53, 0, v53
	v_max_f32_e32 v54, 0, v54
	v_mul_f32_e32 v58, v50, v50
	v_max_f32_e32 v50, 0, v55
	v_mul_f32_e32 v55, v51, v51
	v_max_f32_e32 v51, 0, v56
	v_mul_f32_e32 v56, v52, v52
	v_max_f32_e32 v52, 0, v57
	v_mul_f32_e32 v51, v51, v51
	v_mul_f32_e32 v52, v52, v52
	v_mul_f32_e32 v50, v50, v50
	v_mul_f32_e32 v53, v53, v53
	v_cvt_pk_bf16_f32 v51, v51, v52
	v_cvt_pk_bf16_f32 v52, v58, v55
	v_mul_f32_e32 v54, v54, v54
	v_cvt_pk_bf16_f32 v50, v54, v50
	v_cvt_pk_bf16_f32 v53, v56, v53
	v_mov_b32_e32 v164, v50
	v_mov_b32_e32 v165, v51
	v_mov_b32_e32 v166, v52
	v_mov_b32_e32 v167, v53
	s_mov_b64 s[6:7], 0x120000
	v_pk_mul_f32 v[26:27], v[26:27], v[142:143] op_sel_hi:[1,0]
	v_mov_b32_e32 v52, v145
	v_pk_mul_f32 v[42:43], v[42:43], v[52:53] op_sel_hi:[1,0]
	v_pk_mul_f32 v[46:47], v[46:47], v[52:53] op_sel_hi:[1,0]
	v_pk_mul_f32 v[44:45], v[44:45], v[52:53] op_sel_hi:[1,0]
	v_max_f32_e32 v42, 0, v42
	v_pk_mul_f32 v[48:49], v[48:49], v[52:53] op_sel_hi:[1,0]
	v_max_f32_e32 v46, 0, v46
	v_mul_f32_e32 v53, v42, v42
	v_max_f32_e32 v42, 0, v47
	v_max_f32_e32 v43, 0, v43
	v_max_f32_e32 v44, 0, v44
	v_lshl_add_u64 v[50:51], v[140:141], 0, s[6:7]
	v_mul_f32_e32 v46, v46, v46
	v_mul_f32_e32 v42, v42, v42
	v_mul_f32_e32 v47, v43, v43
	v_max_f32_e32 v43, 0, v48
; __device__ __forceinline__ unsigned pk2(float lo, float hi) { unsigned r; asm("v_cvt_pk_bf16_f32 %0, %1, %2" : "=v"(r) : "v"(lo), "v"(hi)); return r; }
; #define PG8_WAIT_V(n) asm volatile("s_waitcnt vmcnt(" #n ")" ::: "memory")
; #define PG8_BAR __builtin_amdgcn_s_barrier()
;     __device__ __forceinline__ void operator()(const f32x4 (&acc)[2][2][4][2], const Unit& u, int ui, int wr, int wc, int fr, int fq) const {
;     ...
;             for (int m = 0; m < 4; ++m) {
;                 const int row = row0 + ai * HALF + m * 16; const float rs = rsv[ai][m];
;                 bf16_t* rowp = O + (size_t)row * ldc + col0;
; #pragma unroll
;                 for (int bj = 0; bj < 2; ++bj) {
;                     f32x4 v0 = acc[ai][bj][m][0] * rs, v1 = acc[ai][bj][m][1] * rs;
;                     if (ACT == 1) {
; #pragma unroll
;                         for (int j = 0; j < 4; ++j) { const float a = fmaxf(v0[j], 0.f), b = fmaxf(v1[j], 0.f); v0[j] = a * a; v1[j] = b * b; }
;                     }
;                     u32x4 w; w.x = pk2(v0[0], v0[1]); w.y = pk2(v0[2], v0[3]); w.z = pk2(v1[0], v1[1]); w.w = pk2(v1[2], v1[3]);
;                     *(u32x4*)(rowp + bj * HALF) = w;
;                 }
;             }
;     }
; template <class Epi>
; __device__ __forceinline__ void gemm_phase(LAS unsigned char* lds, const Gemm g, const StaticOrder& S, const Epi& E) {
;     ...
;         E(acc, cur, ui, wr, wc, fr, fq);
;         if (!has_next) break;
; #pragma unroll
;         for (int a = 0; a < 2; ++a)
; #pragma unroll
;             for (int b = 0; b < 2; ++b)
; #pragma unroll
;                 for (int m = 0; m < 4; ++m)
; #pragma unroll
;                     for (int n = 0; n < 2; ++n) acc[a][b][m][n] = (f32x4){0.f, 0.f, 0.f, 0.f};
;         cur = nxt; cA = nA; cB = nB; ++ui;
;     }
;     PG8_WAIT_V(0);
;     if (wr == 0) PG8_BAR;
;     PG8_BAR;
	v_mul_f32_e32 v48, v44, v44
	v_max_f32_e32 v44, 0, v49
	s_mov_b32 s6, 0x120000
	v_mul_f32_e32 v43, v43, v43
	v_max_f32_e32 v45, 0, v45
	v_mul_f32_e32 v44, v44, v44
	v_cvt_pk_bf16_f32 v42, v46, v42
	v_add_co_u32_e32 v46, vcc, s6, v140
	v_pk_mul_f32 v[36:37], v[36:37], v[52:53] op_sel_hi:[1,0]
	v_pk_mul_f32 v[34:35], v[34:35], v[52:53] op_sel_hi:[1,0]
	v_mul_f32_e32 v45, v45, v45
	v_cvt_pk_bf16_f32 v43, v43, v44
	v_cvt_pk_bf16_f32 v44, v53, v47
	v_addc_co_u32_e32 v47, vcc, 0, v141, vcc
	v_pk_mul_f32 v[40:41], v[40:41], v[52:53] op_sel_hi:[1,0]
	v_pk_mul_f32 v[38:39], v[38:39], v[52:53] op_sel_hi:[1,0]
	v_max_f32_e32 v34, 0, v34
	v_max_f32_e32 v35, 0, v35
	v_max_f32_e32 v36, 0, v36
	v_cvt_pk_bf16_f32 v45, v48, v45
	v_mov_b32_e32 v188, v42
	v_mov_b32_e32 v189, v43
	v_mov_b32_e32 v190, v44
	v_mov_b32_e32 v191, v45
	v_max_f32_e32 v37, 0, v37
	v_max_f32_e32 v38, 0, v38
	v_mul_f32_e32 v42, v34, v34
	v_max_f32_e32 v34, 0, v39
	v_mul_f32_e32 v39, v35, v35
	v_max_f32_e32 v35, 0, v40
	v_mul_f32_e32 v40, v36, v36
	v_max_f32_e32 v36, 0, v41
	v_mul_f32_e32 v35, v35, v35
	v_mul_f32_e32 v36, v36, v36
	v_mul_f32_e32 v34, v34, v34
	v_mul_f32_e32 v37, v37, v37
	v_cvt_pk_bf16_f32 v35, v35, v36
	v_cvt_pk_bf16_f32 v36, v42, v39
	v_pk_mul_f32 v[30:31], v[30:31], v[142:143] op_sel_hi:[1,0]
	v_pk_mul_f32 v[28:29], v[28:29], v[142:143] op_sel_hi:[1,0]
	v_max_f32_e32 v26, 0, v26
	v_mul_f32_e32 v38, v38, v38
	v_cvt_pk_bf16_f32 v34, v38, v34
	v_cvt_pk_bf16_f32 v37, v40, v37
	v_mov_b32_e32 v192, v34
	v_mov_b32_e32 v193, v35
	v_mov_b32_e32 v194, v36
	v_mov_b32_e32 v195, v37
	s_mov_b64 s[6:7], 0x140000
	v_pk_mul_f32 v[32:33], v[32:33], v[142:143] op_sel_hi:[1,0]
	v_max_f32_e32 v30, 0, v30
	v_mul_f32_e32 v36, v26, v26
	v_max_f32_e32 v26, 0, v31
	v_max_f32_e32 v27, 0, v27
	v_max_f32_e32 v28, 0, v28
	v_lshl_add_u64 v[34:35], v[140:141], 0, s[6:7]
	v_mul_f32_e32 v30, v30, v30
	v_mul_f32_e32 v26, v26, v26
	v_mul_f32_e32 v31, v27, v27
	v_max_f32_e32 v27, 0, v32
	v_mul_f32_e32 v32, v28, v28
	v_max_f32_e32 v28, 0, v33
	s_mov_b32 s6, 0x140000
	v_mul_f32_e32 v27, v27, v27
	v_max_f32_e32 v29, 0, v29
	v_mul_f32_e32 v28, v28, v28
	v_cvt_pk_bf16_f32 v26, v30, v26
	v_add_co_u32_e32 v30, vcc, s6, v140
	v_pk_mul_f32 v[20:21], v[20:21], v[142:143] op_sel_hi:[1,0]
	v_pk_mul_f32 v[18:19], v[18:19], v[142:143] op_sel_hi:[1,0]
	v_mul_f32_e32 v29, v29, v29
	v_cvt_pk_bf16_f32 v27, v27, v28
	v_cvt_pk_bf16_f32 v28, v36, v31
	v_addc_co_u32_e32 v31, vcc, 0, v141, vcc
	v_pk_mul_f32 v[24:25], v[24:25], v[142:143] op_sel_hi:[1,0]
	v_pk_mul_f32 v[22:23], v[22:23], v[142:143] op_sel_hi:[1,0]
	v_max_f32_e32 v18, 0, v18
	v_max_f32_e32 v19, 0, v19
	v_max_f32_e32 v20, 0, v20
	v_cvt_pk_bf16_f32 v29, v32, v29
	v_mov_b32_e32 v196, v26
	v_mov_b32_e32 v197, v27
	v_mov_b32_e32 v198, v28
	v_mov_b32_e32 v199, v29
	v_max_f32_e32 v21, 0, v21
	v_max_f32_e32 v22, 0, v22
	v_mul_f32_e32 v26, v18, v18
	v_max_f32_e32 v18, 0, v23
	v_mul_f32_e32 v23, v19, v19
	v_max_f32_e32 v19, 0, v24
	v_mul_f32_e32 v24, v20, v20
	v_max_f32_e32 v20, 0, v25
	v_mul_f32_e32 v19, v19, v19
	v_mul_f32_e32 v20, v20, v20
	v_mul_f32_e32 v18, v18, v18
	v_mul_f32_e32 v21, v21, v21
	v_cvt_pk_bf16_f32 v19, v19, v20
	v_cvt_pk_bf16_f32 v20, v26, v23
	v_mul_f32_e32 v22, v22, v22
	v_cvt_pk_bf16_f32 v18, v22, v18
	v_cvt_pk_bf16_f32 v21, v24, v21
	v_mov_b32_e32 v200, v18
	v_mov_b32_e32 v201, v19
	v_mov_b32_e32 v202, v20
	v_mov_b32_e32 v203, v21
	s_mov_b64 s[6:7], 0x160000
	s_mov_b32 s87, s8
	v_mov_b32_e32 v20, v143
	v_pk_mul_f32 v[10:11], v[10:11], v[20:21] op_sel_hi:[1,0]
	v_pk_mul_f32 v[14:15], v[14:15], v[20:21] op_sel_hi:[1,0]
	v_pk_mul_f32 v[12:13], v[12:13], v[20:21] op_sel_hi:[1,0]
	v_max_f32_e32 v10, 0, v10
	v_pk_mul_f32 v[16:17], v[16:17], v[20:21] op_sel_hi:[1,0]
	v_max_f32_e32 v14, 0, v14
	v_mul_f32_e32 v21, v10, v10
	v_max_f32_e32 v10, 0, v15
	v_max_f32_e32 v11, 0, v11
	v_max_f32_e32 v12, 0, v12
	v_lshl_add_u64 v[18:19], v[140:141], 0, s[6:7]
	v_mul_f32_e32 v14, v14, v14
	v_mul_f32_e32 v10, v10, v10
	v_mul_f32_e32 v15, v11, v11
	v_max_f32_e32 v11, 0, v16
	v_mul_f32_e32 v16, v12, v12
	v_max_f32_e32 v12, 0, v17
	s_mov_b32 s6, 0x160000
	v_mul_f32_e32 v11, v11, v11
	v_max_f32_e32 v13, 0, v13
	v_mul_f32_e32 v12, v12, v12
	v_cvt_pk_bf16_f32 v10, v14, v10
	v_add_co_u32_e32 v14, vcc, s6, v140
	v_pk_mul_f32 v[4:5], v[4:5], v[20:21] op_sel_hi:[1,0]
	v_pk_mul_f32 v[2:3], v[2:3], v[20:21] op_sel_hi:[1,0]
	v_mul_f32_e32 v13, v13, v13
	v_cvt_pk_bf16_f32 v11, v11, v12
	v_cvt_pk_bf16_f32 v12, v21, v15
	v_addc_co_u32_e32 v15, vcc, 0, v141, vcc
	v_pk_mul_f32 v[8:9], v[8:9], v[20:21] op_sel_hi:[1,0]
	v_pk_mul_f32 v[6:7], v[6:7], v[20:21] op_sel_hi:[1,0]
	v_max_f32_e32 v2, 0, v2
	v_max_f32_e32 v3, 0, v3
	v_max_f32_e32 v4, 0, v4
	v_cvt_pk_bf16_f32 v13, v16, v13
	v_mov_b32_e32 v222, v10
	v_mov_b32_e32 v223, v11
	v_mov_b32_e32 v224, v12
	v_mov_b32_e32 v225, v13
	v_max_f32_e32 v5, 0, v5
	v_max_f32_e32 v6, 0, v6
	v_mul_f32_e32 v10, v2, v2
	v_max_f32_e32 v2, 0, v7
	v_mul_f32_e32 v7, v3, v3
	v_max_f32_e32 v3, 0, v8
	v_mul_f32_e32 v8, v4, v4
	v_max_f32_e32 v4, 0, v9
	v_mul_f32_e32 v2, v2, v2
	v_mul_f32_e32 v3, v3, v3
	v_mul_f32_e32 v4, v4, v4
	v_mul_f32_e32 v5, v5, v5
	s_and_b64 vcc, exec, s[40:41]
	s_mov_b32 s88, s10
	s_mov_b64 s[6:7], s[24:25]
	s_mov_b64 s[36:37], s[12:13]
	s_mov_b32 s89, s86
	v_mul_f32_e32 v6, v6, v6
	v_cvt_pk_bf16_f32 v2, v6, v2
	v_cvt_pk_bf16_f32 v3, v3, v4
	v_cvt_pk_bf16_f32 v4, v10, v7
	v_cvt_pk_bf16_f32 v5, v8, v5
	v_mov_b32_e32 v246, v2
	v_mov_b32_e32 v247, v3
	v_mov_b32_e32 v248, v4
	v_mov_b32_e32 v249, v5
	s_cbranch_vccz .LBB0_163
	global_store_dwordx4 v250, v[158:161], s[4:5]
	global_store_dwordx4 v250, v[164:167], s[4:5] offset:256
	s_nop 1
	v_add_u32_e32 v250, 0x20000, v250
	global_store_dwordx4 v250, v[188:191], s[4:5]
	global_store_dwordx4 v250, v[192:195], s[4:5] offset:256
	s_nop 1
	v_add_u32_e32 v250, 0x20000, v250
	global_store_dwordx4 v250, v[196:199], s[4:5]
	global_store_dwordx4 v250, v[200:203], s[4:5] offset:256
	s_nop 1
	v_add_u32_e32 v250, 0x20000, v250
	global_store_dwordx4 v250, v[222:225], s[4:5]
	global_store_dwordx4 v250, v[246:249], s[4:5] offset:256
	s_nop 1
	v_mov_b64_e32 v[164:165], 0x200
	v_mbcnt_lo_u32_b32 v193, -1, 0
	v_mbcnt_hi_u32_b32 v193, -1, v193
	v_add_u32_e32 v167, s18, v193
	v_mov_b32_e32 v188, 1
	v_mov_b32_e32 v189, 0x358637bd
	v_mov_b32_e32 v190, 0x260
	v_mov_b32_e32 v191, 0x3c0881c4
	v_mov_b32_e32 v192, 0xbab64f3b
	v_mov_b32_e32 v194, 0xf149f2ca
	v_mov_b32_e32 v195, 0xc0
	v_mov_b32_e32 v196, 0x70
	v_mov_b32_e32 v197, 0x71
	v_mov_b32_e32 v198, 5
	v_mov_b32_e32 v199, 2
	v_mov_b32_e32 v200, 3
	v_not_b32_e32 v201, 63
	v_not_b32_e32 v202, 31
	v_mov_b32_e32 v203, 0x7fc00000
	v_mov_b32_e32 v222, 0
	v_mov_b32_e32 v223, 0
	v_mov_b32_e32 v224, 0
	v_mov_b32_e32 v225, 0
	s_waitcnt vmcnt(0)
	v_readlane_b32 s70, v254, 40
	v_readlane_b32 s84, v254, 42
	s_cmpk_gt_u32 s18, 0xff
	v_readlane_b32 s71, v254, 41
	v_readlane_b32 s86, v254, 44
	v_readlane_b32 s87, v254, 45
	v_readlane_b32 s85, v254, 43
	s_cbranch_scc1 .LBB0_174
	s_barrier
; #define PG8_WAIT_V(n) asm volatile("s_waitcnt vmcnt(" #n ")" ::: "memory")
; #define PG8_BAR __builtin_amdgcn_s_barrier()
; template <class Epi>
; __device__ __forceinline__ void gemm_phase(LAS unsigned char* lds, const Gemm g, const StaticOrder& S, const Epi& E) {
;     ...
;     PG8_WAIT_V(0);
;     if (wr == 0) PG8_BAR;
;     PG8_BAR;
.LBB0_174:
	s_setprio 0
	v_readlane_b32 s84, v253, 0
	v_readlane_b32 s85, v253, 1
	s_mov_b32 s88, s96
	s_barrier

; #define PG8_STAGE(bufoff, gbase, voff) do { _Pragma("unroll") for (int _i = 0; _i < 2; ++_i) \
;         __builtin_amdgcn_global_load_lds((const unsigned*)((const char*)(gbase) + (voff)[_i]), (LAS unsigned*)(lds + (bufoff) + ldsw + _i * 8192), 16, 0, 0); } while (0)
; #define PG8_WAIT_V(n) asm volatile("s_waitcnt vmcnt(" #n ")" ::: "memory")
; #define PG8_BAR __builtin_amdgcn_s_barrier()
; template <class Epi>
; __device__ __forceinline__ void gemm_phase(LAS unsigned char* lds, const Gemm g, const StaticOrder& S, const Epi& E) {
;     ...
;     const int wid = __builtin_amdgcn_readfirstlane(tid >> 6), lane = tid & 63, wr = wid >> 2, wc = wid & 3, fr = lane & 15, fq = lane >> 4;
;     const int K = g.K, nt = K / BK;
;     unsigned voffA[2], voffB[2];
; #pragma unroll
;     for (int i = 0; i < 2; ++i) { int R, C; stage_rc(tid * 16 + i * 8192, R, C); const int Rb = Epi::PERM ? ((R & ~31) + perm32(R & 31)) : R;
;         voffA[i] = (unsigned)(R * K + C) * 2u; voffB[i] = (unsigned)(Rb * K + C) * 2u; }
;     const size_t kstep = (size_t)(BK * 2);
;     const size_t hstep = (size_t)HALF * K * 2;
;     const size_t tstep = 2 * hstep;
;     const unsigned ldsw = (unsigned)wid * 1024u;
;     const int aoff = lds_byte(wr * 64 + fr, fq * 8), boff = lds_byte(wc * 32 + fr, fq * 8);
;     ...
;     Unit cur, nxt; int ui = 0;
;     if (!S.next(0, cur)) return;
;     f32x4 acc[2][2][4][2];
; #pragma unroll
;     for (int a = 0; a < 2; ++a)
; #pragma unroll
;         for (int b = 0; b < 2; ++b)
; #pragma unroll
;             for (int m = 0; m < 4; ++m)
; #pragma unroll
;                 for (int n = 0; n < 2; ++n) acc[a][b][m][n] = (f32x4){0.f, 0.f, 0.f, 0.f};
;     bf16x8 At[4][2], B0[2][2], B1[2][2];
;     const char* cA = (const char*)g.A + (size_t)cur.pm * tstep; const char* cB = (const char*)g.Bt + (size_t)cur.pn * tstep;
;     PG8_STAGE(PG8_SB(0, 0), cB, voffB); PG8_STAGE(PG8_SA(0, 0), cA, voffA); PG8_STAGE(PG8_SB(0, 1), cB + hstep, voffB); PG8_STAGE(PG8_SA(0, 1), cA + hstep, voffA);
;     if (wr == 1) PG8_BAR;
;     PG8_WAIT_V(4); PG8_BAR;
;     PG8_STAGE(PG8_SB(1, 0), cB + kstep, voffB); PG8_STAGE(PG8_SA(1, 0), cA + kstep, voffA); PG8_STAGE(PG8_SB(1, 1), cB + hstep + kstep, voffB);
;     PG8_WAIT_V(6); PG8_BAR;
.LBB0_456:
	v_readlane_b32 s4, v254, 0
	s_waitcnt vmcnt(11)
	v_mov_b32_e32 v10, v167
	v_readlane_b32 s5, v254, 1
	s_waitcnt lgkmcnt(0)
	s_barrier
	s_andn2_b64 vcc, exec, s[4:5]
	v_readfirstlane_b32 s18, v10
	s_cbranch_vccnz .LBB0_468
	v_lshlrev_b32_e32 v0, 4, v10
	v_add_u32_e32 v2, 0x2000, v0
	v_ashrrev_i32_e32 v3, 31, v2
	v_lshrrev_b32_e32 v3, 22, v3
	v_add_u32_e32 v3, v2, v3
	v_ashrrev_i32_e32 v11, 10, v3
	v_mul_i32_i24_e32 v3, 0x400, v11
	v_sub_u32_e32 v2, v2, v3
	v_lshrrev_b32_e32 v3, 4, v2
	v_bitop3_b32 v2, v3, v2, 32 bitop3:0x6c
	v_ashrrev_i32_e32 v3, 31, v2
	v_lshrrev_b32_e32 v3, 26, v3
	v_add_u32_e32 v3, v2, v3
	v_lshlrev_b32_e32 v4, 3, v11
	s_mul_i32 s5, s22, 0x380000
	v_ashrrev_i32_e32 v12, 6, v3
	v_and_b32_e32 v4, -16, v4
	s_mul_hi_i32 s4, s22, 0x380000
	s_add_u32 s42, s94, s5
	v_add_u32_e32 v4, v12, v4
	s_addc_u32 s43, s95, s4
	v_and_b32_e32 v5, 3, v12
	s_mov_b32 s4, 0x1fffe0
	v_lshrrev_b32_e32 v6, 2, v4
	v_lshlrev_b32_e32 v7, 1, v4
	v_and_b32_e32 v3, 0xc0, v3
	v_and_or_b32 v5, v4, s4, v5
	v_and_b32_e32 v6, 4, v6
	v_and_b32_e32 v7, 24, v7
	v_sub_u32_e32 v2, v2, v3
	v_or3_b32 v5, v5, v6, v7
	v_lshlrev_b32_e32 v6, 5, v11
	v_ashrrev_i16_sdwa v2, v188, sext(v2) dst_sel:DWORD dst_unused:UNUSED_PAD src0_sel:DWORD src1_sel:BYTE_0
	v_and_b32_e32 v6, 32, v6
	v_bfe_i32 v13, v2, 0, 16
	v_add_lshl_u32 v2, v6, v13, 1
	v_lshl_add_u32 v130, v5, 11, v2
	v_lshl_add_u32 v132, v4, 11, v2
	v_bfe_i32 v2, v10, 27, 1
	v_lshrrev_b32_e32 v2, 22, v2
	v_add_u32_e32 v2, v0, v2
	v_and_b32_e32 v2, 0xfffffc00, v2
	v_sub_u32_e32 v0, v0, v2
	v_lshrrev_b32_e32 v2, 4, v0
	v_ashrrev_i32_e32 v3, 31, v10
	v_bitop3_b32 v0, v2, v0, 32 bitop3:0x6c
	v_lshrrev_b32_e32 v3, 26, v3
	v_ashrrev_i32_e32 v2, 31, v0
	v_add_u32_e32 v3, v10, v3
	v_lshrrev_b32_e32 v2, 26, v2
	v_ashrrev_i32_e32 v15, 6, v3
	v_add_u32_e32 v2, v0, v2
	v_lshlrev_b32_e32 v3, 3, v15
	v_ashrrev_i32_e32 v14, 6, v2
	v_and_b32_e32 v3, -16, v3
	s_ashr_i32 s9, s18, 6
	v_add_u32_e32 v3, v14, v3
	s_ashr_i32 s8, s18, 8
	s_lshl_b32 s44, s9, 10
	v_and_b32_e32 v4, 3, v14
	v_lshrrev_b32_e32 v5, 2, v3
	v_lshlrev_b32_e32 v6, 1, v3
	v_and_b32_e32 v2, 0xc0, v2
	s_add_u32 s45, s94, 0x5830000
	v_and_or_b32 v4, v3, s4, v4
	v_and_b32_e32 v5, 4, v5
	v_and_b32_e32 v6, 24, v6
	v_sub_u32_e32 v0, v0, v2
	s_addc_u32 s46, s95, 0
	v_or3_b32 v4, v4, v5, v6
	v_lshlrev_b32_e32 v5, 5, v15
	v_ashrrev_i16_sdwa v0, v188, sext(v0) dst_sel:DWORD dst_unused:UNUSED_PAD src0_sel:DWORD src1_sel:BYTE_0
	v_readlane_b32 s4, v254, 6
	v_and_b32_e32 v5, 32, v5
	v_bfe_i32 v16, v0, 0, 16
	v_readlane_b32 s5, v254, 7
	s_add_u32 s6, s42, s4
	v_add_lshl_u32 v2, v5, v16, 1
	s_addc_u32 s7, s43, s5
	s_add_i32 s47, s44, 0
	v_lshl_add_u32 v0, v4, 11, v2
	s_add_i32 m0, s47, 0x10000
	v_readlane_b32 s4, v254, 30
	global_load_lds_dwordx4 v0, s[6:7]
	s_add_i32 m0, s47, 0x12000
	v_readlane_b32 s5, v254, 31
	s_add_u32 s24, s45, s4
	v_lshl_add_u32 v134, v3, 11, v2
	global_load_lds_dwordx4 v130, s[6:7]
	s_addc_u32 s25, s46, s5
	s_mov_b32 m0, s47
	s_add_i32 s48, s47, 0x2000
	global_load_lds_dwordx4 v134, s[24:25]
	s_mov_b32 m0, s48
	s_add_u32 s4, s6, 0x40000
	global_load_lds_dwordx4 v132, s[24:25]
	s_addc_u32 s5, s7, 0
	s_add_i32 m0, s47, 0x14000
	v_mov_b32_e32 v131, v1
	global_load_lds_dwordx4 v0, s[4:5]
	s_add_i32 m0, s47, 0x16000
	v_mov_b32_e32 v135, v1
	global_load_lds_dwordx4 v130, s[4:5]
	s_add_u32 s4, s24, 0x40000
	s_addc_u32 s5, s25, 0
	s_add_i32 s49, s47, 0x4000
	s_mov_b32 m0, s49
	s_add_i32 s54, s47, 0x6000
	global_load_lds_dwordx4 v134, s[4:5]
	s_mov_b32 m0, s54
	v_mov_b32_e32 v133, v1
	global_load_lds_dwordx4 v132, s[4:5]
	v_lshl_add_u64 v[8:9], s[6:7], 0, v[0:1]
	v_lshl_add_u64 v[6:7], s[6:7], 0, v[130:131]
	v_lshl_add_u64 v[4:5], s[24:25], 0, v[134:135]
	s_cmp_lg_u32 s8, 1
	v_lshl_add_u64 v[2:3], s[24:25], 0, v[132:133]
	s_cbranch_scc1 .LBB0_459
	s_barrier
	s_setprio 1

; #define PG8_STAGE(bufoff, gbase, voff) do { _Pragma("unroll") for (int _i = 0; _i < 2; ++_i) \
;         __builtin_amdgcn_global_load_lds((const unsigned*)((const char*)(gbase) + (voff)[_i]), (LAS unsigned*)(lds + (bufoff) + ldsw + _i * 8192), 16, 0, 0); } while (0)
; #define PG8_LDA(dst, b, h) do { _Pragma("unroll") for (int m = 0; m < 4; ++m) _Pragma("unroll") for (int k = 0; k < 2; ++k) dst[m][k] = *(const LAS bf16x8*)(lds + PG8_SA(b, h) + aoff + m * 2048 + k * 1024); } while (0)
; #define PG8_LDB(dst, b, h) do { _Pragma("unroll") for (int n = 0; n < 2; ++n) _Pragma("unroll") for (int k = 0; k < 2; ++k) dst[n][k] = *(const LAS bf16x8*)(lds + PG8_SB(b, h) + boff + n * 2048 + k * 1024); } while (0)
; #define PG8_MMA(ai, bj, At, Bt) do { __builtin_amdgcn_s_setprio(1); _Pragma("unroll") for (int m = 0; m < 4; ++m) _Pragma("unroll") for (int n = 0; n < 2; ++n) _Pragma("unroll") for (int k = 0; k < 2; ++k) \
;         acc[ai][bj][m][n] = __builtin_amdgcn_mfma_f32_16x16x32_bf16(Bt[n][k], At[m][k], acc[ai][bj][m][n], 0, 0, 0); __builtin_amdgcn_s_setprio(0); } while (0)
; #define PG8_WAIT_V(n) asm volatile("s_waitcnt vmcnt(" #n ")" ::: "memory")
; #define PG8_WAIT_L(n) asm volatile("s_waitcnt lgkmcnt(" #n ")" ::: "memory")
; #define PG8_BAR __builtin_amdgcn_s_barrier()
; template <class Epi>
; __device__ __forceinline__ void gemm_phase(LAS unsigned char* lds, const Gemm g, const StaticOrder& S, const Epi& E) {
;     ...
;     f32x4 acc[2][2][4][2];
; #pragma unroll
;     for (int a = 0; a < 2; ++a)
; #pragma unroll
;         for (int b = 0; b < 2; ++b)
; #pragma unroll
;             for (int m = 0; m < 4; ++m)
; #pragma unroll
;                 for (int n = 0; n < 2; ++n) acc[a][b][m][n] = (f32x4){0.f, 0.f, 0.f, 0.f};
;     ...
;             PG8_LDB(B0, 0, 0); PG8_SCHED; PG8_LDA(At, 0, 0); PG8_STAGE(PG8_SA(1, 1), a1 + hstep, voffA);
;             PG8_WAIT_L(8); PG8_BAR; PG8_WAIT_L(0); PG8_MMA(0, 0, At, B0); PG8_BAR; PG8_SCHED;
;             PG8_LDB(B1, 0, 1); PG8_STAGE(PG8_SB(0, 0), b2, voffB);
;             PG8_BAR; PG8_WAIT_L(0); PG8_MMA(0, 1, At, B1); PG8_BAR;
;             PG8_LDA(At, 0, 1); PG8_STAGE(PG8_SA(0, 0), a2, voffA);
;             PG8_BAR; PG8_WAIT_L(0); PG8_MMA(1, 0, At, B0); PG8_BAR; PG8_SCHED;
;             PG8_STAGE(PG8_SB(0, 1), b2 + hstep, voffB);
;             PG8_WAIT_V(6); PG8_BAR; PG8_MMA(1, 1, At, B1); PG8_BAR;
.LBB0_463:
	s_add_u32 s6, s24, 0xfffc0080
	s_addc_u32 s7, s25, -1
	s_add_i32 s58, 0, 0x10000
	v_add_u32_e32 v153, s58, v149
	ds_read_b128 v[140:143], v153
	ds_read_b128 v[144:147], v153 offset:1024
	ds_read_b128 v[154:157], v153 offset:2048
	ds_read_b128 v[158:161], v153 offset:3072
	s_cmp_eq_u32 s91, 12
	s_cselect_b32 s37, s11, s7
	s_cselect_b32 s36, s71, s6
	s_cselect_b32 s7, s9, s90
	s_cselect_b32 s6, s88, s89
	s_add_i32 m0, s47, 0xc000
	ds_read_b128 v[168:171], v152
	ds_read_b128 v[172:175], v152 offset:1024
	ds_read_b128 v[176:179], v152 offset:2048
	ds_read_b128 v[180:183], v152 offset:3072
	ds_read_b128 v[184:187], v152 offset:4096
	ds_read_b128 v[204:207], v152 offset:5120
	ds_read_b128 v[208:211], v152 offset:6144
	ds_read_b128 v[212:215], v152 offset:7168
	global_load_lds_dwordx4 v136, s[24:25]
	s_add_i32 m0, s47, 0xe000
	s_nop 0
	global_load_lds_dwordx4 v138, s[24:25]
	s_waitcnt lgkmcnt(8)
	s_barrier
	s_waitcnt lgkmcnt(0)
	s_waitcnt lgkmcnt(0)
	v_mfma_f32_16x16x32_bf16 v[126:129], v[140:143], v[168:171], 0
	v_mfma_f32_16x16x32_bf16 v[122:125], v[154:157], v[168:171], 0
	v_mfma_f32_16x16x32_bf16 v[114:117], v[140:143], v[176:179], 0
	v_mfma_f32_16x16x32_bf16 v[106:109], v[154:157], v[176:179], 0
	v_mfma_f32_16x16x32_bf16 v[98:101], v[140:143], v[184:187], 0
	v_mfma_f32_16x16x32_bf16 v[90:93], v[154:157], v[184:187], 0
	v_mfma_f32_16x16x32_bf16 v[82:85], v[140:143], v[208:211], 0
	v_mfma_f32_16x16x32_bf16 v[74:77], v[154:157], v[208:211], 0
	v_mfma_f32_16x16x32_bf16 v[126:129], v[144:147], v[172:175], v[126:129]
	v_mfma_f32_16x16x32_bf16 v[122:125], v[158:161], v[172:175], v[122:125]
	v_mfma_f32_16x16x32_bf16 v[114:117], v[144:147], v[180:183], v[114:117]
	v_mfma_f32_16x16x32_bf16 v[106:109], v[158:161], v[180:183], v[106:109]
	v_mfma_f32_16x16x32_bf16 v[98:101], v[144:147], v[204:207], v[98:101]
	v_mfma_f32_16x16x32_bf16 v[90:93], v[158:161], v[204:207], v[90:93]
	v_mfma_f32_16x16x32_bf16 v[82:85], v[144:147], v[212:215], v[82:85]
	v_mfma_f32_16x16x32_bf16 v[74:77], v[158:161], v[212:215], v[74:77]
	s_barrier
	s_add_i32 s70, 0, 0x14000
	s_add_i32 s58, s58, s44
	v_add_u32_e32 v153, s70, v149
	s_mov_b32 m0, s58
	ds_read_b128 v[216:219], v153
	ds_read_b128 v[226:229], v153 offset:1024
	ds_read_b128 v[230:233], v153 offset:2048
	ds_read_b128 v[234:237], v153 offset:3072
	global_load_lds_dwordx4 v0, s[6:7]
	s_add_i32 m0, s58, 0x2000
	s_nop 0
	global_load_lds_dwordx4 v130, s[6:7]
	s_barrier
	s_waitcnt lgkmcnt(0)
	s_waitcnt lgkmcnt(0)
	v_mfma_f32_16x16x32_bf16 v[118:121], v[216:219], v[168:171], 0
	v_mfma_f32_16x16x32_bf16 v[110:113], v[230:233], v[168:171], 0
	v_mfma_f32_16x16x32_bf16 v[102:105], v[216:219], v[176:179], 0
	v_mfma_f32_16x16x32_bf16 v[94:97], v[230:233], v[176:179], 0
	v_mfma_f32_16x16x32_bf16 v[86:89], v[216:219], v[184:187], 0
	v_mfma_f32_16x16x32_bf16 v[78:81], v[230:233], v[184:187], 0
	v_mfma_f32_16x16x32_bf16 v[70:73], v[216:219], v[208:211], 0
	v_mfma_f32_16x16x32_bf16 v[66:69], v[230:233], v[208:211], 0
	v_mfma_f32_16x16x32_bf16 v[118:121], v[226:229], v[172:175], v[118:121]
	v_mfma_f32_16x16x32_bf16 v[110:113], v[234:237], v[172:175], v[110:113]
	v_mfma_f32_16x16x32_bf16 v[102:105], v[226:229], v[180:183], v[102:105]
	v_mfma_f32_16x16x32_bf16 v[94:97], v[234:237], v[180:183], v[94:97]
	v_mfma_f32_16x16x32_bf16 v[86:89], v[226:229], v[204:207], v[86:89]
	v_mfma_f32_16x16x32_bf16 v[78:81], v[234:237], v[204:207], v[78:81]
	v_mfma_f32_16x16x32_bf16 v[70:73], v[226:229], v[212:215], v[70:73]
	v_mfma_f32_16x16x32_bf16 v[66:69], v[234:237], v[212:215], v[66:69]
	s_mov_b32 m0, s47
	s_add_u32 vcc_lo, s36, 0x80
	s_addc_u32 vcc_hi, s37, 0
	s_barrier
	ds_read_b128 v[168:171], v152 offset:16384
	ds_read_b128 v[172:175], v152 offset:17408
	ds_read_b128 v[176:179], v152 offset:18432
	ds_read_b128 v[180:183], v152 offset:19456
	ds_read_b128 v[184:187], v152 offset:20480
	ds_read_b128 v[204:207], v152 offset:21504
	ds_read_b128 v[208:211], v152 offset:22528
	ds_read_b128 v[212:215], v152 offset:23552
	global_load_lds_dwordx4 v134, s[36:37]
	s_mov_b32 m0, s48
	s_nop 0
	global_load_lds_dwordx4 v132, s[36:37]
	s_barrier
	s_waitcnt lgkmcnt(0)
	s_waitcnt lgkmcnt(0)
	v_mfma_f32_16x16x32_bf16 v[62:65], v[140:143], v[168:171], 0
	v_mfma_f32_16x16x32_bf16 v[58:61], v[154:157], v[168:171], 0
	v_mfma_f32_16x16x32_bf16 v[50:53], v[140:143], v[176:179], 0
	v_mfma_f32_16x16x32_bf16 v[42:45], v[154:157], v[176:179], 0
	v_mfma_f32_16x16x32_bf16 v[34:37], v[140:143], v[184:187], 0
	v_mfma_f32_16x16x32_bf16 v[26:29], v[154:157], v[184:187], 0
	v_mfma_f32_16x16x32_bf16 v[18:21], v[140:143], v[208:211], 0
	v_mfma_f32_16x16x32_bf16 v[10:13], v[154:157], v[208:211], 0
	v_mfma_f32_16x16x32_bf16 v[62:65], v[144:147], v[172:175], v[62:65]
	v_mfma_f32_16x16x32_bf16 v[58:61], v[158:161], v[172:175], v[58:61]
	v_mfma_f32_16x16x32_bf16 v[50:53], v[144:147], v[180:183], v[50:53]
	v_mfma_f32_16x16x32_bf16 v[42:45], v[158:161], v[180:183], v[42:45]
	v_mfma_f32_16x16x32_bf16 v[34:37], v[144:147], v[204:207], v[34:37]
	v_mfma_f32_16x16x32_bf16 v[26:29], v[158:161], v[204:207], v[26:29]
	v_mfma_f32_16x16x32_bf16 v[18:21], v[144:147], v[212:215], v[18:21]
	v_mfma_f32_16x16x32_bf16 v[10:13], v[158:161], v[212:215], v[10:13]
	s_barrier
	s_add_u32 s60, s6, 0x40000
	s_addc_u32 s61, s7, 0
	s_add_i32 s58, s70, s44
	s_mov_b32 m0, s58
	s_nop 0
	global_load_lds_dwordx4 v0, s[60:61]
	s_add_i32 m0, s58, 0x2000
	s_nop 0
	global_load_lds_dwordx4 v130, s[60:61]
	s_waitcnt vmcnt(6)
	s_barrier
; #define PG8_STAGE(bufoff, gbase, voff) do { _Pragma("unroll") for (int _i = 0; _i < 2; ++_i) \
;         __builtin_amdgcn_global_load_lds((const unsigned*)((const char*)(gbase) + (voff)[_i]), (LAS unsigned*)(lds + (bufoff) + ldsw + _i * 8192), 16, 0, 0); } while (0)
; #define PG8_LDA(dst, b, h) do { _Pragma("unroll") for (int m = 0; m < 4; ++m) _Pragma("unroll") for (int k = 0; k < 2; ++k) dst[m][k] = *(const LAS bf16x8*)(lds + PG8_SA(b, h) + aoff + m * 2048 + k * 1024); } while (0)
; #define PG8_LDB(dst, b, h) do { _Pragma("unroll") for (int n = 0; n < 2; ++n) _Pragma("unroll") for (int k = 0; k < 2; ++k) dst[n][k] = *(const LAS bf16x8*)(lds + PG8_SB(b, h) + boff + n * 2048 + k * 1024); } while (0)
; #define PG8_WAIT_V(n) asm volatile("s_waitcnt vmcnt(" #n ")" ::: "memory")
;     __device__ __forceinline__ void operator()(const f32x4 (&acc)[2][2][4][2], const Unit& u, int ui, int wr, int wc, int fr, int fq) const {
;     ...
;                     *(u32x4*)(rowp + bj * HALF) = w;
; template <class Epi>
; __device__ __forceinline__ void gemm_phase(LAS unsigned char* lds, const Gemm g, const StaticOrder& S, const Epi& E) {
;     ...
;             PG8_LDB(B0, 0, 0); PG8_SCHED; PG8_LDA(At, 0, 0); PG8_STAGE(PG8_SA(1, 1), a1 + hstep, voffA);
;             PG8_WAIT_L(8); PG8_BAR; PG8_WAIT_L(0); PG8_MMA(0, 0, At, B0); PG8_BAR; PG8_SCHED;
;             PG8_LDB(B1, 0, 1); PG8_STAGE(PG8_SB(0, 0), b2, voffB);
;             PG8_BAR; PG8_WAIT_L(0); PG8_MMA(0, 1, At, B1); PG8_BAR;
;             PG8_LDA(At, 0, 1); PG8_STAGE(PG8_SA(0, 0), a2, voffA);
;             PG8_BAR; PG8_WAIT_L(0); PG8_MMA(1, 0, At, B0); PG8_BAR; PG8_SCHED;
;             PG8_STAGE(PG8_SB(0, 1), b2 + hstep, voffB);
;             PG8_WAIT_V(6); PG8_BAR; PG8_MMA(1, 1, At, B1); PG8_BAR;
;             PG8_LDB(B0, 1, 0); PG8_SCHED; PG8_LDA(At, 1, 0); PG8_STAGE(PG8_SA(0, 1), a2 + hstep, voffA);
;             PG8_WAIT_L(8); PG8_BAR; PG8_WAIT_L(0); PG8_MMA(0, 0, At, B0); PG8_BAR; PG8_SCHED;
;             PG8_LDB(B1, 1, 1); PG8_STAGE(PG8_SB(1, 0), b3, voffB);
;             PG8_BAR; PG8_WAIT_L(0); PG8_MMA(0, 1, At, B1); PG8_BAR;
;             PG8_LDA(At, 1, 1); PG8_STAGE(PG8_SA(1, 0), a3, voffA);
;             PG8_BAR; PG8_WAIT_L(0); PG8_MMA(1, 0, At, B0); PG8_BAR; PG8_SCHED;
;             PG8_STAGE(PG8_SB(1, 1), b3 + hstep, voffB);
;             PG8_WAIT_V(6); PG8_BAR; PG8_MMA(1, 1, At, B1); PG8_BAR;
	v_mfma_f32_16x16x32_bf16 v[54:57], v[216:219], v[168:171], 0
	v_mfma_f32_16x16x32_bf16 v[46:49], v[230:233], v[168:171], 0
	v_mfma_f32_16x16x32_bf16 v[38:41], v[216:219], v[176:179], 0
	v_mfma_f32_16x16x32_bf16 v[30:33], v[230:233], v[176:179], 0
	v_mfma_f32_16x16x32_bf16 v[22:25], v[216:219], v[184:187], 0
	v_mfma_f32_16x16x32_bf16 v[14:17], v[230:233], v[184:187], 0
	v_mfma_f32_16x16x32_bf16 v[6:9], v[216:219], v[208:211], 0
	v_mfma_f32_16x16x32_bf16 v[2:5], v[230:233], v[208:211], 0
	v_mfma_f32_16x16x32_bf16 v[54:57], v[226:229], v[172:175], v[54:57]
	v_mfma_f32_16x16x32_bf16 v[46:49], v[234:237], v[172:175], v[46:49]
	v_mfma_f32_16x16x32_bf16 v[38:41], v[226:229], v[180:183], v[38:41]
	v_mfma_f32_16x16x32_bf16 v[30:33], v[234:237], v[180:183], v[30:33]
	v_mfma_f32_16x16x32_bf16 v[22:25], v[226:229], v[204:207], v[22:25]
	v_mfma_f32_16x16x32_bf16 v[14:17], v[234:237], v[204:207], v[14:17]
	v_mfma_f32_16x16x32_bf16 v[6:9], v[226:229], v[212:215], v[6:9]
	v_mfma_f32_16x16x32_bf16 v[2:5], v[234:237], v[212:215], v[2:5]
	s_add_i32 s58, 0, 0x18000
	v_add_u32_e32 v153, s58, v149
	s_barrier
	ds_read_b128 v[140:143], v153
	ds_read_b128 v[144:147], v153 offset:1024
	ds_read_b128 v[154:157], v153 offset:2048
	ds_read_b128 v[158:161], v153 offset:3072
	s_add_u32 s36, s36, 0x40000
	s_addc_u32 s37, s37, 0
	s_mov_b32 m0, s49
	ds_read_b128 v[168:171], v152 offset:32768
	ds_read_b128 v[172:175], v152 offset:33792
	ds_read_b128 v[176:179], v152 offset:34816
	ds_read_b128 v[180:183], v152 offset:35840
	ds_read_b128 v[184:187], v152 offset:36864
	ds_read_b128 v[204:207], v152 offset:37888
	ds_read_b128 v[208:211], v152 offset:38912
	ds_read_b128 v[212:215], v152 offset:39936
	global_load_lds_dwordx4 v134, s[36:37]
	s_mov_b32 m0, s54
	s_nop 0
	global_load_lds_dwordx4 v132, s[36:37]
	s_waitcnt lgkmcnt(8)
	s_barrier
	s_waitcnt lgkmcnt(0)
	s_waitcnt lgkmcnt(0)
	v_mfma_f32_16x16x32_bf16 v[126:129], v[140:143], v[168:171], v[126:129]
	v_mfma_f32_16x16x32_bf16 v[122:125], v[154:157], v[168:171], v[122:125]
	s_cmp_eq_u32 s87, 0
	s_cbranch_scc1 .LdsA_skip_0
	global_store_dwordx4 v166, v[162:165], s[4:5]
.LdsA_skip_0:
	v_mfma_f32_16x16x32_bf16 v[114:117], v[140:143], v[176:179], v[114:117]
	v_mfma_f32_16x16x32_bf16 v[106:109], v[154:157], v[176:179], v[106:109]
	v_mfma_f32_16x16x32_bf16 v[98:101], v[140:143], v[184:187], v[98:101]
	v_mfma_f32_16x16x32_bf16 v[90:93], v[154:157], v[184:187], v[90:93]
	v_mfma_f32_16x16x32_bf16 v[82:85], v[140:143], v[208:211], v[82:85]
	v_mfma_f32_16x16x32_bf16 v[74:77], v[154:157], v[208:211], v[74:77]
	v_mfma_f32_16x16x32_bf16 v[126:129], v[144:147], v[172:175], v[126:129]
	v_mfma_f32_16x16x32_bf16 v[122:125], v[158:161], v[172:175], v[122:125]
	v_mfma_f32_16x16x32_bf16 v[114:117], v[144:147], v[180:183], v[114:117]
	v_mfma_f32_16x16x32_bf16 v[106:109], v[158:161], v[180:183], v[106:109]
	v_mfma_f32_16x16x32_bf16 v[98:101], v[144:147], v[204:207], v[98:101]
	v_mfma_f32_16x16x32_bf16 v[90:93], v[158:161], v[204:207], v[90:93]
	v_mfma_f32_16x16x32_bf16 v[82:85], v[144:147], v[212:215], v[82:85]
	v_mfma_f32_16x16x32_bf16 v[74:77], v[158:161], v[212:215], v[74:77]
	s_barrier
	s_add_i32 s36, 0, 0x1c000
	s_add_i32 s37, s58, s44
	v_add_u32_e32 v153, s36, v149
	s_add_u32 s60, s6, 0x80
	s_addc_u32 s61, s7, 0
	s_mov_b32 m0, s37
	ds_read_b128 v[216:219], v153
	ds_read_b128 v[226:229], v153 offset:1024
	ds_read_b128 v[230:233], v153 offset:2048
	ds_read_b128 v[234:237], v153 offset:3072
	global_load_lds_dwordx4 v0, s[60:61]
	s_add_i32 m0, s37, 0x2000
	s_nop 0
	global_load_lds_dwordx4 v130, s[60:61]
	s_barrier
	s_waitcnt lgkmcnt(0)
	s_waitcnt lgkmcnt(0)
	v_mfma_f32_16x16x32_bf16 v[118:121], v[216:219], v[168:171], v[118:121]
	v_mfma_f32_16x16x32_bf16 v[110:113], v[230:233], v[168:171], v[110:113]
	v_mfma_f32_16x16x32_bf16 v[102:105], v[216:219], v[176:179], v[102:105]
	v_mfma_f32_16x16x32_bf16 v[94:97], v[230:233], v[176:179], v[94:97]
	v_mfma_f32_16x16x32_bf16 v[86:89], v[216:219], v[184:187], v[86:89]
	v_mfma_f32_16x16x32_bf16 v[78:81], v[230:233], v[184:187], v[78:81]
	v_mfma_f32_16x16x32_bf16 v[70:73], v[216:219], v[208:211], v[70:73]
	v_mfma_f32_16x16x32_bf16 v[66:69], v[230:233], v[208:211], v[66:69]
	v_mfma_f32_16x16x32_bf16 v[118:121], v[226:229], v[172:175], v[118:121]
	v_mfma_f32_16x16x32_bf16 v[110:113], v[234:237], v[172:175], v[110:113]
	v_mfma_f32_16x16x32_bf16 v[102:105], v[226:229], v[180:183], v[102:105]
	v_mfma_f32_16x16x32_bf16 v[94:97], v[234:237], v[180:183], v[94:97]
	v_mfma_f32_16x16x32_bf16 v[86:89], v[226:229], v[204:207], v[86:89]
	v_mfma_f32_16x16x32_bf16 v[78:81], v[234:237], v[204:207], v[78:81]
	v_mfma_f32_16x16x32_bf16 v[70:73], v[226:229], v[212:215], v[70:73]
	v_mfma_f32_16x16x32_bf16 v[66:69], v[234:237], v[212:215], v[66:69]
	s_mov_b32 m0, s55
	s_barrier
	ds_read_b128 v[168:171], v152 offset:49152
	ds_read_b128 v[172:175], v152 offset:50176
	ds_read_b128 v[176:179], v152 offset:51200
	ds_read_b128 v[180:183], v152 offset:52224
	ds_read_b128 v[184:187], v152 offset:53248
	ds_read_b128 v[204:207], v152 offset:54272
	ds_read_b128 v[208:211], v152 offset:55296
	ds_read_b128 v[212:215], v152 offset:56320
	global_load_lds_dwordx4 v134, vcc
	s_mov_b32 m0, s83
	s_nop 0
	global_load_lds_dwordx4 v132, vcc
	s_barrier
; template <class Epi>
; __device__ __forceinline__ void gemm_phase(LAS unsigned char* lds, const Gemm g, const StaticOrder& S, const Epi& E) {
;     ...
;         for (int t = 0; t < nt; t += 2) {
;             if constexpr (Epi::MIDSCALE) {
;                 if (t == 4 || t == 8) {
;                     float f[2][4];
; #pragma unroll
;                     for (int ai = 0; ai < 2; ++ai)
; #pragma unroll
;                         for (int m = 0; m < 4; ++m) f[ai][m] = E.rstab[ui * 256 + wr * 64 + fr + ai * HALF + m * 16];
;                     asm volatile("s_waitcnt lgkmcnt(0)" ::: "memory");
; #pragma unroll
;                     for (int ai = 0; ai < 2; ++ai)
; #pragma unroll
;                         for (int m = 0; m < 4; ++m) { const float ff = (t == 4) ? __builtin_amdgcn_rcpf(f[ai][m]) : f[ai][m];
; #pragma unroll
;                             for (int bj = 0; bj < 2; ++bj)
; #pragma unroll
;                                 for (int n = 0; n < 2; ++n) acc[ai][bj][m][n] = acc[ai][bj][m][n] * ff; }
;                 }
;             }
;             const bool last = (t == nt - 2);
;             const char* a1 = cA + (size_t)(t + 1) * kstep;
;             const char* a2 = last ? nA : cA + (size_t)(t + 2) * kstep; const char* b2 = last ? nB : cB + (size_t)(t + 2) * kstep;
;             const char* a3 = a2 + kstep; const char* b3 = b2 + kstep;
;             PG8_LDB(B0, 0, 0); PG8_SCHED; PG8_LDA(At, 0, 0); PG8_STAGE(PG8_SA(1, 1), a1 + hstep, voffA);
;             PG8_WAIT_L(8); PG8_BAR; PG8_WAIT_L(0); PG8_MMA(0, 0, At, B0); PG8_BAR; PG8_SCHED;
;             PG8_LDB(B1, 0, 1); PG8_STAGE(PG8_SB(0, 0), b2, voffB);
;             PG8_BAR; PG8_WAIT_L(0); PG8_MMA(0, 1, At, B1); PG8_BAR;
;             PG8_LDA(At, 0, 1); PG8_STAGE(PG8_SA(0, 0), a2, voffA);
;             PG8_BAR; PG8_WAIT_L(0); PG8_MMA(1, 0, At, B0); PG8_BAR; PG8_SCHED;
;             PG8_STAGE(PG8_SB(0, 1), b2 + hstep, voffB);
;             PG8_WAIT_V(6); PG8_BAR; PG8_MMA(1, 1, At, B1); PG8_BAR;
;             PG8_LDB(B0, 1, 0); PG8_SCHED; PG8_LDA(At, 1, 0); PG8_STAGE(PG8_SA(0, 1), a2 + hstep, voffA);
;             PG8_WAIT_L(8); PG8_BAR; PG8_WAIT_L(0); PG8_MMA(0, 0, At, B0); PG8_BAR; PG8_SCHED;
;             PG8_LDB(B1, 1, 1); PG8_STAGE(PG8_SB(1, 0), b3, voffB);
;             PG8_BAR; PG8_WAIT_L(0); PG8_MMA(0, 1, At, B1); PG8_BAR;
;             PG8_LDA(At, 1, 1); PG8_STAGE(PG8_SA(1, 0), a3, voffA);
	s_waitcnt lgkmcnt(0)
	s_waitcnt lgkmcnt(0)
	v_mfma_f32_16x16x32_bf16 v[62:65], v[140:143], v[168:171], v[62:65]
	v_mfma_f32_16x16x32_bf16 v[58:61], v[154:157], v[168:171], v[58:61]
	v_mfma_f32_16x16x32_bf16 v[50:53], v[140:143], v[176:179], v[50:53]
	v_mfma_f32_16x16x32_bf16 v[42:45], v[154:157], v[176:179], v[42:45]
	v_mfma_f32_16x16x32_bf16 v[34:37], v[140:143], v[184:187], v[34:37]
	v_mfma_f32_16x16x32_bf16 v[26:29], v[154:157], v[184:187], v[26:29]
	v_mfma_f32_16x16x32_bf16 v[18:21], v[140:143], v[208:211], v[18:21]
	v_mfma_f32_16x16x32_bf16 v[10:13], v[154:157], v[208:211], v[10:13]
	v_mfma_f32_16x16x32_bf16 v[62:65], v[144:147], v[172:175], v[62:65]
	v_mfma_f32_16x16x32_bf16 v[58:61], v[158:161], v[172:175], v[58:61]
	v_mfma_f32_16x16x32_bf16 v[50:53], v[144:147], v[180:183], v[50:53]
	v_mfma_f32_16x16x32_bf16 v[42:45], v[158:161], v[180:183], v[42:45]
	v_mfma_f32_16x16x32_bf16 v[34:37], v[144:147], v[204:207], v[34:37]
	v_mfma_f32_16x16x32_bf16 v[26:29], v[158:161], v[204:207], v[26:29]
	v_mfma_f32_16x16x32_bf16 v[18:21], v[144:147], v[212:215], v[18:21]
	v_mfma_f32_16x16x32_bf16 v[10:13], v[158:161], v[212:215], v[10:13]
	s_barrier
	s_add_u32 s6, s6, 0x40080
	s_addc_u32 s7, s7, 0
	s_add_i32 s36, s36, s44
	s_mov_b32 m0, s36
	s_nop 0
	global_load_lds_dwordx4 v0, s[6:7]
	s_add_i32 m0, s36, 0x2000
	s_nop 0
	global_load_lds_dwordx4 v130, s[6:7]
	s_waitcnt vmcnt(6)
	s_barrier
	v_mfma_f32_16x16x32_bf16 v[54:57], v[216:219], v[168:171], v[54:57]
	v_mfma_f32_16x16x32_bf16 v[46:49], v[230:233], v[168:171], v[46:49]
	v_mfma_f32_16x16x32_bf16 v[38:41], v[216:219], v[176:179], v[38:41]
	v_mfma_f32_16x16x32_bf16 v[30:33], v[230:233], v[176:179], v[30:33]
	v_mfma_f32_16x16x32_bf16 v[22:25], v[216:219], v[184:187], v[22:25]
	v_mfma_f32_16x16x32_bf16 v[14:17], v[230:233], v[184:187], v[14:17]
	v_mfma_f32_16x16x32_bf16 v[6:9], v[216:219], v[208:211], v[6:9]
	v_mfma_f32_16x16x32_bf16 v[2:5], v[230:233], v[208:211], v[2:5]
	v_mfma_f32_16x16x32_bf16 v[54:57], v[226:229], v[172:175], v[54:57]
	v_mfma_f32_16x16x32_bf16 v[46:49], v[234:237], v[172:175], v[46:49]
	v_mfma_f32_16x16x32_bf16 v[38:41], v[226:229], v[180:183], v[38:41]
	v_mfma_f32_16x16x32_bf16 v[30:33], v[234:237], v[180:183], v[30:33]
	v_mfma_f32_16x16x32_bf16 v[22:25], v[226:229], v[204:207], v[22:25]
	v_mfma_f32_16x16x32_bf16 v[14:17], v[234:237], v[204:207], v[14:17]
	v_mfma_f32_16x16x32_bf16 v[6:9], v[226:229], v[212:215], v[6:9]
	v_mfma_f32_16x16x32_bf16 v[2:5], v[234:237], v[212:215], v[2:5]
	s_add_i32 s91, s91, 2
	s_add_u32 s24, s24, 0x100
	s_addc_u32 s25, s25, 0
	s_add_u32 s89, s89, 0x100
	s_addc_u32 s90, s90, 0
	s_cmp_gt_u32 s91, 13
	s_barrier
	s_add_u32 s6, s24, 0xfffc0080
	s_addc_u32 s7, s25, -1
	s_add_i32 s58, 0, 0x10000
	v_add_u32_e32 v153, s58, v149
	ds_read_b128 v[140:143], v153
	ds_read_b128 v[144:147], v153 offset:1024
	ds_read_b128 v[154:157], v153 offset:2048
	ds_read_b128 v[158:161], v153 offset:3072
	s_cmp_eq_u32 s91, 12
	s_cselect_b32 s37, s11, s7
	s_cselect_b32 s36, s71, s6
	s_cselect_b32 s7, s9, s90
	s_cselect_b32 s6, s88, s89
	s_add_i32 m0, s47, 0xc000
	ds_read_b128 v[168:171], v152
	ds_read_b128 v[172:175], v152 offset:1024
	ds_read_b128 v[176:179], v152 offset:2048
	ds_read_b128 v[180:183], v152 offset:3072
	ds_read_b128 v[184:187], v152 offset:4096
	ds_read_b128 v[204:207], v152 offset:5120
	ds_read_b128 v[208:211], v152 offset:6144
	ds_read_b128 v[212:215], v152 offset:7168
	global_load_lds_dwordx4 v136, s[24:25]
	s_add_i32 m0, s47, 0xe000
	s_nop 0
	global_load_lds_dwordx4 v138, s[24:25]
	s_waitcnt lgkmcnt(8)
	s_barrier
	s_waitcnt lgkmcnt(0)
	s_waitcnt lgkmcnt(0)
	v_mfma_f32_16x16x32_bf16 v[126:129], v[140:143], v[168:171], v[126:129]
	v_mfma_f32_16x16x32_bf16 v[122:125], v[154:157], v[168:171], v[122:125]
	v_mfma_f32_16x16x32_bf16 v[114:117], v[140:143], v[176:179], v[114:117]
	v_mfma_f32_16x16x32_bf16 v[106:109], v[154:157], v[176:179], v[106:109]
	v_mfma_f32_16x16x32_bf16 v[98:101], v[140:143], v[184:187], v[98:101]
	v_mfma_f32_16x16x32_bf16 v[90:93], v[154:157], v[184:187], v[90:93]
	v_mfma_f32_16x16x32_bf16 v[82:85], v[140:143], v[208:211], v[82:85]
	v_mfma_f32_16x16x32_bf16 v[74:77], v[154:157], v[208:211], v[74:77]
	v_mfma_f32_16x16x32_bf16 v[126:129], v[144:147], v[172:175], v[126:129]
	v_mfma_f32_16x16x32_bf16 v[122:125], v[158:161], v[172:175], v[122:125]
	v_mfma_f32_16x16x32_bf16 v[114:117], v[144:147], v[180:183], v[114:117]
	v_mfma_f32_16x16x32_bf16 v[106:109], v[158:161], v[180:183], v[106:109]
	v_mfma_f32_16x16x32_bf16 v[98:101], v[144:147], v[204:207], v[98:101]
	v_mfma_f32_16x16x32_bf16 v[90:93], v[158:161], v[204:207], v[90:93]
	v_mfma_f32_16x16x32_bf16 v[82:85], v[144:147], v[212:215], v[82:85]
	v_mfma_f32_16x16x32_bf16 v[74:77], v[158:161], v[212:215], v[74:77]
	s_barrier
	s_add_i32 s70, 0, 0x14000
	s_add_i32 s58, s58, s44
	v_add_u32_e32 v153, s70, v149
	s_mov_b32 m0, s58
	ds_read_b128 v[216:219], v153
	ds_read_b128 v[226:229], v153 offset:1024
	ds_read_b128 v[230:233], v153 offset:2048
	ds_read_b128 v[234:237], v153 offset:3072
	global_load_lds_dwordx4 v0, s[6:7]
	s_add_i32 m0, s58, 0x2000
	s_nop 0
	global_load_lds_dwordx4 v130, s[6:7]
	s_barrier
; #define PG8_STAGE(bufoff, gbase, voff) do { _Pragma("unroll") for (int _i = 0; _i < 2; ++_i) \
;         __builtin_amdgcn_global_load_lds((const unsigned*)((const char*)(gbase) + (voff)[_i]), (LAS unsigned*)(lds + (bufoff) + ldsw + _i * 8192), 16, 0, 0); } while (0)
; #define PG8_LDA(dst, b, h) do { _Pragma("unroll") for (int m = 0; m < 4; ++m) _Pragma("unroll") for (int k = 0; k < 2; ++k) dst[m][k] = *(const LAS bf16x8*)(lds + PG8_SA(b, h) + aoff + m * 2048 + k * 1024); } while (0)
; #define PG8_LDB(dst, b, h) do { _Pragma("unroll") for (int n = 0; n < 2; ++n) _Pragma("unroll") for (int k = 0; k < 2; ++k) dst[n][k] = *(const LAS bf16x8*)(lds + PG8_SB(b, h) + boff + n * 2048 + k * 1024); } while (0)
; #define PG8_WAIT_V(n) asm volatile("s_waitcnt vmcnt(" #n ")" ::: "memory")
;     __device__ __forceinline__ void operator()(const f32x4 (&acc)[2][2][4][2], const Unit& u, int ui, int wr, int wc, int fr, int fq) const {
;     ...
;                     *(u32x4*)(rowp + bj * HALF) = w;
; template <class Epi>
; __device__ __forceinline__ void gemm_phase(LAS unsigned char* lds, const Gemm g, const StaticOrder& S, const Epi& E) {
;     ...
;             PG8_LDB(B0, 0, 0); PG8_SCHED; PG8_LDA(At, 0, 0); PG8_STAGE(PG8_SA(1, 1), a1 + hstep, voffA);
;             PG8_WAIT_L(8); PG8_BAR; PG8_WAIT_L(0); PG8_MMA(0, 0, At, B0); PG8_BAR; PG8_SCHED;
;             PG8_LDB(B1, 0, 1); PG8_STAGE(PG8_SB(0, 0), b2, voffB);
;             PG8_BAR; PG8_WAIT_L(0); PG8_MMA(0, 1, At, B1); PG8_BAR;
;             PG8_LDA(At, 0, 1); PG8_STAGE(PG8_SA(0, 0), a2, voffA);
;             PG8_BAR; PG8_WAIT_L(0); PG8_MMA(1, 0, At, B0); PG8_BAR; PG8_SCHED;
;             PG8_STAGE(PG8_SB(0, 1), b2 + hstep, voffB);
;             PG8_WAIT_V(6); PG8_BAR; PG8_MMA(1, 1, At, B1); PG8_BAR;
;             PG8_LDB(B0, 1, 0); PG8_SCHED; PG8_LDA(At, 1, 0); PG8_STAGE(PG8_SA(0, 1), a2 + hstep, voffA);
;             PG8_WAIT_L(8); PG8_BAR; PG8_WAIT_L(0); PG8_MMA(0, 0, At, B0); PG8_BAR; PG8_SCHED;
;             PG8_LDB(B1, 1, 1); PG8_STAGE(PG8_SB(1, 0), b3, voffB);
;             PG8_BAR; PG8_WAIT_L(0); PG8_MMA(0, 1, At, B1); PG8_BAR;
;             PG8_LDA(At, 1, 1); PG8_STAGE(PG8_SA(1, 0), a3, voffA);
;             PG8_BAR; PG8_WAIT_L(0); PG8_MMA(1, 0, At, B0); PG8_BAR; PG8_SCHED;
;             PG8_STAGE(PG8_SB(1, 1), b3 + hstep, voffB);
;             PG8_WAIT_V(6); PG8_BAR; PG8_MMA(1, 1, At, B1); PG8_BAR;
	s_waitcnt lgkmcnt(0)
	s_waitcnt lgkmcnt(0)
	v_mfma_f32_16x16x32_bf16 v[118:121], v[216:219], v[168:171], v[118:121]
	v_mfma_f32_16x16x32_bf16 v[110:113], v[230:233], v[168:171], v[110:113]
	v_mfma_f32_16x16x32_bf16 v[102:105], v[216:219], v[176:179], v[102:105]
	v_mfma_f32_16x16x32_bf16 v[94:97], v[230:233], v[176:179], v[94:97]
	v_mfma_f32_16x16x32_bf16 v[86:89], v[216:219], v[184:187], v[86:89]
	v_mfma_f32_16x16x32_bf16 v[78:81], v[230:233], v[184:187], v[78:81]
	v_mfma_f32_16x16x32_bf16 v[70:73], v[216:219], v[208:211], v[70:73]
	v_mfma_f32_16x16x32_bf16 v[66:69], v[230:233], v[208:211], v[66:69]
	v_mfma_f32_16x16x32_bf16 v[118:121], v[226:229], v[172:175], v[118:121]
	v_mfma_f32_16x16x32_bf16 v[110:113], v[234:237], v[172:175], v[110:113]
	v_mfma_f32_16x16x32_bf16 v[102:105], v[226:229], v[180:183], v[102:105]
	v_mfma_f32_16x16x32_bf16 v[94:97], v[234:237], v[180:183], v[94:97]
	v_mfma_f32_16x16x32_bf16 v[86:89], v[226:229], v[204:207], v[86:89]
	v_mfma_f32_16x16x32_bf16 v[78:81], v[234:237], v[204:207], v[78:81]
	v_mfma_f32_16x16x32_bf16 v[70:73], v[226:229], v[212:215], v[70:73]
	v_mfma_f32_16x16x32_bf16 v[66:69], v[234:237], v[212:215], v[66:69]
	s_mov_b32 m0, s47
	s_add_u32 vcc_lo, s36, 0x80
	s_addc_u32 vcc_hi, s37, 0
	s_barrier
	ds_read_b128 v[168:171], v152 offset:16384
	ds_read_b128 v[172:175], v152 offset:17408
	ds_read_b128 v[176:179], v152 offset:18432
	ds_read_b128 v[180:183], v152 offset:19456
	ds_read_b128 v[184:187], v152 offset:20480
	ds_read_b128 v[204:207], v152 offset:21504
	ds_read_b128 v[208:211], v152 offset:22528
	ds_read_b128 v[212:215], v152 offset:23552
	global_load_lds_dwordx4 v134, s[36:37]
	s_mov_b32 m0, s48
	s_nop 0
	global_load_lds_dwordx4 v132, s[36:37]
	s_barrier
	s_waitcnt lgkmcnt(0)
	s_waitcnt lgkmcnt(0)
	v_mfma_f32_16x16x32_bf16 v[62:65], v[140:143], v[168:171], v[62:65]
	v_mfma_f32_16x16x32_bf16 v[58:61], v[154:157], v[168:171], v[58:61]
	v_mfma_f32_16x16x32_bf16 v[50:53], v[140:143], v[176:179], v[50:53]
	v_mfma_f32_16x16x32_bf16 v[42:45], v[154:157], v[176:179], v[42:45]
	v_mfma_f32_16x16x32_bf16 v[34:37], v[140:143], v[184:187], v[34:37]
	v_mfma_f32_16x16x32_bf16 v[26:29], v[154:157], v[184:187], v[26:29]
	v_mfma_f32_16x16x32_bf16 v[18:21], v[140:143], v[208:211], v[18:21]
	v_mfma_f32_16x16x32_bf16 v[10:13], v[154:157], v[208:211], v[10:13]
	v_mfma_f32_16x16x32_bf16 v[62:65], v[144:147], v[172:175], v[62:65]
	v_mfma_f32_16x16x32_bf16 v[58:61], v[158:161], v[172:175], v[58:61]
	v_mfma_f32_16x16x32_bf16 v[50:53], v[144:147], v[180:183], v[50:53]
	v_mfma_f32_16x16x32_bf16 v[42:45], v[158:161], v[180:183], v[42:45]
	v_mfma_f32_16x16x32_bf16 v[34:37], v[144:147], v[204:207], v[34:37]
	v_mfma_f32_16x16x32_bf16 v[26:29], v[158:161], v[204:207], v[26:29]
	v_mfma_f32_16x16x32_bf16 v[18:21], v[144:147], v[212:215], v[18:21]
	v_mfma_f32_16x16x32_bf16 v[10:13], v[158:161], v[212:215], v[10:13]
	s_barrier
	s_add_u32 s60, s6, 0x40000
	s_addc_u32 s61, s7, 0
	s_add_i32 s58, s70, s44
	s_mov_b32 m0, s58
	s_nop 0
	global_load_lds_dwordx4 v0, s[60:61]
	s_add_i32 m0, s58, 0x2000
	s_nop 0
	global_load_lds_dwordx4 v130, s[60:61]
	s_waitcnt vmcnt(6)
	s_barrier
	v_mfma_f32_16x16x32_bf16 v[54:57], v[216:219], v[168:171], v[54:57]
	v_mfma_f32_16x16x32_bf16 v[46:49], v[230:233], v[168:171], v[46:49]
	v_mfma_f32_16x16x32_bf16 v[38:41], v[216:219], v[176:179], v[38:41]
	v_mfma_f32_16x16x32_bf16 v[30:33], v[230:233], v[176:179], v[30:33]
	v_mfma_f32_16x16x32_bf16 v[22:25], v[216:219], v[184:187], v[22:25]
	v_mfma_f32_16x16x32_bf16 v[14:17], v[230:233], v[184:187], v[14:17]
	v_mfma_f32_16x16x32_bf16 v[6:9], v[216:219], v[208:211], v[6:9]
	v_mfma_f32_16x16x32_bf16 v[2:5], v[230:233], v[208:211], v[2:5]
	v_mfma_f32_16x16x32_bf16 v[54:57], v[226:229], v[172:175], v[54:57]
	v_mfma_f32_16x16x32_bf16 v[46:49], v[234:237], v[172:175], v[46:49]
	v_mfma_f32_16x16x32_bf16 v[38:41], v[226:229], v[180:183], v[38:41]
	v_mfma_f32_16x16x32_bf16 v[30:33], v[234:237], v[180:183], v[30:33]
	v_mfma_f32_16x16x32_bf16 v[22:25], v[226:229], v[204:207], v[22:25]
	v_mfma_f32_16x16x32_bf16 v[14:17], v[234:237], v[204:207], v[14:17]
	v_mfma_f32_16x16x32_bf16 v[6:9], v[226:229], v[212:215], v[6:9]
	v_mfma_f32_16x16x32_bf16 v[2:5], v[234:237], v[212:215], v[2:5]
	s_add_i32 s58, 0, 0x18000
	v_add_u32_e32 v153, s58, v149
	s_barrier
	ds_read_b128 v[140:143], v153
	ds_read_b128 v[144:147], v153 offset:1024
	ds_read_b128 v[154:157], v153 offset:2048
	ds_read_b128 v[158:161], v153 offset:3072
	s_add_u32 s36, s36, 0x40000
	s_addc_u32 s37, s37, 0
	s_mov_b32 m0, s49
	ds_read_b128 v[168:171], v152 offset:32768
	ds_read_b128 v[172:175], v152 offset:33792
	ds_read_b128 v[176:179], v152 offset:34816
	ds_read_b128 v[180:183], v152 offset:35840
	ds_read_b128 v[184:187], v152 offset:36864
	ds_read_b128 v[204:207], v152 offset:37888
	ds_read_b128 v[208:211], v152 offset:38912
	ds_read_b128 v[212:215], v152 offset:39936
	global_load_lds_dwordx4 v134, s[36:37]
	s_mov_b32 m0, s54
	s_nop 0
	global_load_lds_dwordx4 v132, s[36:37]
	s_waitcnt lgkmcnt(8)
	s_barrier
	s_waitcnt lgkmcnt(0)
	s_waitcnt lgkmcnt(0)
	v_mfma_f32_16x16x32_bf16 v[126:129], v[140:143], v[168:171], v[126:129]
	v_mfma_f32_16x16x32_bf16 v[122:125], v[154:157], v[168:171], v[122:125]
	s_cmp_eq_u32 s87, 0
	s_cbranch_scc1 .LdsA_skip_1
	global_store_dwordx4 v166, v[188:191], s[4:5] offset:256
	s_nop 1
	v_add_u32_e32 v166, 0xe000, v166
; #define PG8_STAGE(bufoff, gbase, voff) do { _Pragma("unroll") for (int _i = 0; _i < 2; ++_i) \
;         __builtin_amdgcn_global_load_lds((const unsigned*)((const char*)(gbase) + (voff)[_i]), (LAS unsigned*)(lds + (bufoff) + ldsw + _i * 8192), 16, 0, 0); } while (0)
; #define PG8_LDA(dst, b, h) do { _Pragma("unroll") for (int m = 0; m < 4; ++m) _Pragma("unroll") for (int k = 0; k < 2; ++k) dst[m][k] = *(const LAS bf16x8*)(lds + PG8_SA(b, h) + aoff + m * 2048 + k * 1024); } while (0)
; #define PG8_LDB(dst, b, h) do { _Pragma("unroll") for (int n = 0; n < 2; ++n) _Pragma("unroll") for (int k = 0; k < 2; ++k) dst[n][k] = *(const LAS bf16x8*)(lds + PG8_SB(b, h) + boff + n * 2048 + k * 1024); } while (0)
; #define PG8_WAIT_V(n) asm volatile("s_waitcnt vmcnt(" #n ")" ::: "memory")
; #define PG8_WAIT_L(n) asm volatile("s_waitcnt lgkmcnt(" #n ")" ::: "memory")
; #define PG8_BAR __builtin_amdgcn_s_barrier()
; #define PG8_SCHED __builtin_amdgcn_sched_barrier(0)
; template <class Epi>
; __device__ __forceinline__ void gemm_phase(LAS unsigned char* lds, const Gemm g, const StaticOrder& S, const Epi& E) {
;     ...
;         for (int t = 0; t < nt; t += 2) {
;     ...
;             PG8_LDB(B0, 0, 0); PG8_SCHED; PG8_LDA(At, 0, 0); PG8_STAGE(PG8_SA(1, 1), a1 + hstep, voffA);
;             PG8_WAIT_L(8); PG8_BAR; PG8_WAIT_L(0); PG8_MMA(0, 0, At, B0); PG8_BAR; PG8_SCHED;
;             PG8_LDB(B1, 0, 1); PG8_STAGE(PG8_SB(0, 0), b2, voffB);
;             PG8_BAR; PG8_WAIT_L(0); PG8_MMA(0, 1, At, B1); PG8_BAR;
;             PG8_LDA(At, 0, 1); PG8_STAGE(PG8_SA(0, 0), a2, voffA);
;             PG8_BAR; PG8_WAIT_L(0); PG8_MMA(1, 0, At, B0); PG8_BAR; PG8_SCHED;
;             PG8_STAGE(PG8_SB(0, 1), b2 + hstep, voffB);
;             PG8_WAIT_V(6); PG8_BAR; PG8_MMA(1, 1, At, B1); PG8_BAR;
;             PG8_LDB(B0, 1, 0); PG8_SCHED; PG8_LDA(At, 1, 0); PG8_STAGE(PG8_SA(0, 1), a2 + hstep, voffA);
;             PG8_WAIT_L(8); PG8_BAR; PG8_WAIT_L(0); PG8_MMA(0, 0, At, B0); PG8_BAR; PG8_SCHED;
;             PG8_LDB(B1, 1, 1); PG8_STAGE(PG8_SB(1, 0), b3, voffB);
;             PG8_BAR; PG8_WAIT_L(0); PG8_MMA(0, 1, At, B1); PG8_BAR;
;             PG8_LDA(At, 1, 1); PG8_STAGE(PG8_SA(1, 0), a3, voffA);
;             PG8_BAR; PG8_WAIT_L(0); PG8_MMA(1, 0, At, B0); PG8_BAR; PG8_SCHED;
;             PG8_STAGE(PG8_SB(1, 1), b3 + hstep, voffB);
;             PG8_WAIT_V(6); PG8_BAR; PG8_MMA(1, 1, At, B1); PG8_BAR;
.LdsA_skip_1:
	v_mfma_f32_16x16x32_bf16 v[114:117], v[140:143], v[176:179], v[114:117]
	v_mfma_f32_16x16x32_bf16 v[106:109], v[154:157], v[176:179], v[106:109]
	v_mfma_f32_16x16x32_bf16 v[98:101], v[140:143], v[184:187], v[98:101]
	v_mfma_f32_16x16x32_bf16 v[90:93], v[154:157], v[184:187], v[90:93]
	v_mfma_f32_16x16x32_bf16 v[82:85], v[140:143], v[208:211], v[82:85]
	v_mfma_f32_16x16x32_bf16 v[74:77], v[154:157], v[208:211], v[74:77]
	v_mfma_f32_16x16x32_bf16 v[126:129], v[144:147], v[172:175], v[126:129]
	v_mfma_f32_16x16x32_bf16 v[122:125], v[158:161], v[172:175], v[122:125]
	v_mfma_f32_16x16x32_bf16 v[114:117], v[144:147], v[180:183], v[114:117]
	v_mfma_f32_16x16x32_bf16 v[106:109], v[158:161], v[180:183], v[106:109]
	v_mfma_f32_16x16x32_bf16 v[98:101], v[144:147], v[204:207], v[98:101]
	v_mfma_f32_16x16x32_bf16 v[90:93], v[158:161], v[204:207], v[90:93]
	v_mfma_f32_16x16x32_bf16 v[82:85], v[144:147], v[212:215], v[82:85]
	v_mfma_f32_16x16x32_bf16 v[74:77], v[158:161], v[212:215], v[74:77]
	s_barrier
	s_add_i32 s36, 0, 0x1c000
	s_add_i32 s37, s58, s44
	v_add_u32_e32 v153, s36, v149
	s_add_u32 s60, s6, 0x80
	s_addc_u32 s61, s7, 0
	s_mov_b32 m0, s37
	ds_read_b128 v[216:219], v153
	ds_read_b128 v[226:229], v153 offset:1024
	ds_read_b128 v[230:233], v153 offset:2048
	ds_read_b128 v[234:237], v153 offset:3072
	global_load_lds_dwordx4 v0, s[60:61]
	s_add_i32 m0, s37, 0x2000
	s_nop 0
	global_load_lds_dwordx4 v130, s[60:61]
	s_barrier
	s_waitcnt lgkmcnt(0)
	s_waitcnt lgkmcnt(0)
	v_mfma_f32_16x16x32_bf16 v[118:121], v[216:219], v[168:171], v[118:121]
	v_mfma_f32_16x16x32_bf16 v[110:113], v[230:233], v[168:171], v[110:113]
	v_mfma_f32_16x16x32_bf16 v[102:105], v[216:219], v[176:179], v[102:105]
	v_mfma_f32_16x16x32_bf16 v[94:97], v[230:233], v[176:179], v[94:97]
	v_mfma_f32_16x16x32_bf16 v[86:89], v[216:219], v[184:187], v[86:89]
	v_mfma_f32_16x16x32_bf16 v[78:81], v[230:233], v[184:187], v[78:81]
	v_mfma_f32_16x16x32_bf16 v[70:73], v[216:219], v[208:211], v[70:73]
	v_mfma_f32_16x16x32_bf16 v[66:69], v[230:233], v[208:211], v[66:69]
	v_mfma_f32_16x16x32_bf16 v[118:121], v[226:229], v[172:175], v[118:121]
	v_mfma_f32_16x16x32_bf16 v[110:113], v[234:237], v[172:175], v[110:113]
	v_mfma_f32_16x16x32_bf16 v[102:105], v[226:229], v[180:183], v[102:105]
	v_mfma_f32_16x16x32_bf16 v[94:97], v[234:237], v[180:183], v[94:97]
	v_mfma_f32_16x16x32_bf16 v[86:89], v[226:229], v[204:207], v[86:89]
	v_mfma_f32_16x16x32_bf16 v[78:81], v[234:237], v[204:207], v[78:81]
	v_mfma_f32_16x16x32_bf16 v[70:73], v[226:229], v[212:215], v[70:73]
	v_mfma_f32_16x16x32_bf16 v[66:69], v[234:237], v[212:215], v[66:69]
	s_mov_b32 m0, s55
	s_barrier
	ds_read_b128 v[168:171], v152 offset:49152
	ds_read_b128 v[172:175], v152 offset:50176
	ds_read_b128 v[176:179], v152 offset:51200
	ds_read_b128 v[180:183], v152 offset:52224
	ds_read_b128 v[184:187], v152 offset:53248
	ds_read_b128 v[204:207], v152 offset:54272
	ds_read_b128 v[208:211], v152 offset:55296
	ds_read_b128 v[212:215], v152 offset:56320
	global_load_lds_dwordx4 v134, vcc
	s_mov_b32 m0, s83
	s_nop 0
	global_load_lds_dwordx4 v132, vcc
	s_barrier
	s_waitcnt lgkmcnt(0)
	s_waitcnt lgkmcnt(0)
	v_mfma_f32_16x16x32_bf16 v[62:65], v[140:143], v[168:171], v[62:65]
	v_mfma_f32_16x16x32_bf16 v[58:61], v[154:157], v[168:171], v[58:61]
	v_mfma_f32_16x16x32_bf16 v[50:53], v[140:143], v[176:179], v[50:53]
	v_mfma_f32_16x16x32_bf16 v[42:45], v[154:157], v[176:179], v[42:45]
	v_mfma_f32_16x16x32_bf16 v[34:37], v[140:143], v[184:187], v[34:37]
	v_mfma_f32_16x16x32_bf16 v[26:29], v[154:157], v[184:187], v[26:29]
	v_mfma_f32_16x16x32_bf16 v[18:21], v[140:143], v[208:211], v[18:21]
	v_mfma_f32_16x16x32_bf16 v[10:13], v[154:157], v[208:211], v[10:13]
	v_mfma_f32_16x16x32_bf16 v[62:65], v[144:147], v[172:175], v[62:65]
	v_mfma_f32_16x16x32_bf16 v[58:61], v[158:161], v[172:175], v[58:61]
	v_mfma_f32_16x16x32_bf16 v[50:53], v[144:147], v[180:183], v[50:53]
	v_mfma_f32_16x16x32_bf16 v[42:45], v[158:161], v[180:183], v[42:45]
	v_mfma_f32_16x16x32_bf16 v[34:37], v[144:147], v[204:207], v[34:37]
	v_mfma_f32_16x16x32_bf16 v[26:29], v[158:161], v[204:207], v[26:29]
	v_mfma_f32_16x16x32_bf16 v[18:21], v[144:147], v[212:215], v[18:21]
	v_mfma_f32_16x16x32_bf16 v[10:13], v[158:161], v[212:215], v[10:13]
	s_barrier
	s_add_u32 s6, s6, 0x40080
	s_addc_u32 s7, s7, 0
	s_add_i32 s36, s36, s44
	s_mov_b32 m0, s36
	s_nop 0
	global_load_lds_dwordx4 v0, s[6:7]
	s_add_i32 m0, s36, 0x2000
	s_nop 0
	global_load_lds_dwordx4 v130, s[6:7]
	s_waitcnt vmcnt(6)
	s_barrier
	v_mfma_f32_16x16x32_bf16 v[54:57], v[216:219], v[168:171], v[54:57]
	v_mfma_f32_16x16x32_bf16 v[46:49], v[230:233], v[168:171], v[46:49]
	v_mfma_f32_16x16x32_bf16 v[38:41], v[216:219], v[176:179], v[38:41]
	v_mfma_f32_16x16x32_bf16 v[30:33], v[230:233], v[176:179], v[30:33]
	v_mfma_f32_16x16x32_bf16 v[22:25], v[216:219], v[184:187], v[22:25]
	v_mfma_f32_16x16x32_bf16 v[14:17], v[230:233], v[184:187], v[14:17]
	v_mfma_f32_16x16x32_bf16 v[6:9], v[216:219], v[208:211], v[6:9]
	v_mfma_f32_16x16x32_bf16 v[2:5], v[230:233], v[208:211], v[2:5]
	v_mfma_f32_16x16x32_bf16 v[54:57], v[226:229], v[172:175], v[54:57]
	v_mfma_f32_16x16x32_bf16 v[46:49], v[234:237], v[172:175], v[46:49]
	v_mfma_f32_16x16x32_bf16 v[38:41], v[226:229], v[180:183], v[38:41]
	v_mfma_f32_16x16x32_bf16 v[30:33], v[234:237], v[180:183], v[30:33]
	v_mfma_f32_16x16x32_bf16 v[22:25], v[226:229], v[204:207], v[22:25]
	v_mfma_f32_16x16x32_bf16 v[14:17], v[234:237], v[204:207], v[14:17]
	v_mfma_f32_16x16x32_bf16 v[6:9], v[226:229], v[212:215], v[6:9]
	v_mfma_f32_16x16x32_bf16 v[2:5], v[234:237], v[212:215], v[2:5]
	s_add_i32 s91, s91, 2
	s_add_u32 s24, s24, 0x100
	s_addc_u32 s25, s25, 0
	s_add_u32 s89, s89, 0x100
	s_addc_u32 s90, s90, 0
	s_cmp_gt_u32 s91, 13
	s_barrier
; #define PG8_STAGE(bufoff, gbase, voff) do { _Pragma("unroll") for (int _i = 0; _i < 2; ++_i) \
;         __builtin_amdgcn_global_load_lds((const unsigned*)((const char*)(gbase) + (voff)[_i]), (LAS unsigned*)(lds + (bufoff) + ldsw + _i * 8192), 16, 0, 0); } while (0)
; #define PG8_LDA(dst, b, h) do { _Pragma("unroll") for (int m = 0; m < 4; ++m) _Pragma("unroll") for (int k = 0; k < 2; ++k) dst[m][k] = *(const LAS bf16x8*)(lds + PG8_SA(b, h) + aoff + m * 2048 + k * 1024); } while (0)
; #define PG8_LDB(dst, b, h) do { _Pragma("unroll") for (int n = 0; n < 2; ++n) _Pragma("unroll") for (int k = 0; k < 2; ++k) dst[n][k] = *(const LAS bf16x8*)(lds + PG8_SB(b, h) + boff + n * 2048 + k * 1024); } while (0)
; #define PG8_WAIT_V(n) asm volatile("s_waitcnt vmcnt(" #n ")" ::: "memory")
; #define PG8_WAIT_L(n) asm volatile("s_waitcnt lgkmcnt(" #n ")" ::: "memory")
; #define PG8_BAR __builtin_amdgcn_s_barrier()
; #define PG8_SCHED __builtin_amdgcn_sched_barrier(0)
; template <class Epi>
; __device__ __forceinline__ void gemm_phase(LAS unsigned char* lds, const Gemm g, const StaticOrder& S, const Epi& E) {
;     ...
;             PG8_LDB(B0, 0, 0); PG8_SCHED; PG8_LDA(At, 0, 0); PG8_STAGE(PG8_SA(1, 1), a1 + hstep, voffA);
;             PG8_WAIT_L(8); PG8_BAR; PG8_WAIT_L(0); PG8_MMA(0, 0, At, B0); PG8_BAR; PG8_SCHED;
;             PG8_LDB(B1, 0, 1); PG8_STAGE(PG8_SB(0, 0), b2, voffB);
;             PG8_BAR; PG8_WAIT_L(0); PG8_MMA(0, 1, At, B1); PG8_BAR;
;             PG8_LDA(At, 0, 1); PG8_STAGE(PG8_SA(0, 0), a2, voffA);
;             PG8_BAR; PG8_WAIT_L(0); PG8_MMA(1, 0, At, B0); PG8_BAR; PG8_SCHED;
;             PG8_STAGE(PG8_SB(0, 1), b2 + hstep, voffB);
;             PG8_WAIT_V(6); PG8_BAR; PG8_MMA(1, 1, At, B1); PG8_BAR;
;             PG8_LDB(B0, 1, 0); PG8_SCHED; PG8_LDA(At, 1, 0); PG8_STAGE(PG8_SA(0, 1), a2 + hstep, voffA);
;             PG8_WAIT_L(8); PG8_BAR; PG8_WAIT_L(0); PG8_MMA(0, 0, At, B0); PG8_BAR; PG8_SCHED;
;             PG8_LDB(B1, 1, 1); PG8_STAGE(PG8_SB(1, 0), b3, voffB);
;             PG8_BAR; PG8_WAIT_L(0); PG8_MMA(0, 1, At, B1); PG8_BAR;
;             PG8_LDA(At, 1, 1); PG8_STAGE(PG8_SA(1, 0), a3, voffA);
;             PG8_BAR; PG8_WAIT_L(0); PG8_MMA(1, 0, At, B0); PG8_BAR; PG8_SCHED;
;             PG8_STAGE(PG8_SB(1, 1), b3 + hstep, voffB);
;             PG8_WAIT_V(6); PG8_BAR; PG8_MMA(1, 1, At, B1); PG8_BAR;
	s_add_u32 s6, s24, 0xfffc0080
	s_addc_u32 s7, s25, -1
	s_add_i32 s58, 0, 0x10000
	v_add_u32_e32 v153, s58, v149
	ds_read_b128 v[140:143], v153
	ds_read_b128 v[144:147], v153 offset:1024
	ds_read_b128 v[154:157], v153 offset:2048
	ds_read_b128 v[158:161], v153 offset:3072
	s_cmp_eq_u32 s91, 12
	s_cselect_b32 s37, s11, s7
	s_cselect_b32 s36, s71, s6
	s_cselect_b32 s7, s9, s90
	s_cselect_b32 s6, s88, s89
	s_add_i32 m0, s47, 0xc000
	ds_read_b128 v[168:171], v152
	ds_read_b128 v[172:175], v152 offset:1024
	ds_read_b128 v[176:179], v152 offset:2048
	ds_read_b128 v[180:183], v152 offset:3072
	ds_read_b128 v[184:187], v152 offset:4096
	ds_read_b128 v[204:207], v152 offset:5120
	ds_read_b128 v[208:211], v152 offset:6144
	ds_read_b128 v[212:215], v152 offset:7168
	global_load_lds_dwordx4 v136, s[24:25]
	s_add_i32 m0, s47, 0xe000
	s_nop 0
	global_load_lds_dwordx4 v138, s[24:25]
	s_waitcnt lgkmcnt(8)
	s_barrier
	s_waitcnt lgkmcnt(0)
	s_waitcnt lgkmcnt(0)
	v_mfma_f32_16x16x32_bf16 v[126:129], v[140:143], v[168:171], v[126:129]
	v_mfma_f32_16x16x32_bf16 v[122:125], v[154:157], v[168:171], v[122:125]
	v_mfma_f32_16x16x32_bf16 v[114:117], v[140:143], v[176:179], v[114:117]
	v_mfma_f32_16x16x32_bf16 v[106:109], v[154:157], v[176:179], v[106:109]
	v_mfma_f32_16x16x32_bf16 v[98:101], v[140:143], v[184:187], v[98:101]
	v_mfma_f32_16x16x32_bf16 v[90:93], v[154:157], v[184:187], v[90:93]
	v_mfma_f32_16x16x32_bf16 v[82:85], v[140:143], v[208:211], v[82:85]
	v_mfma_f32_16x16x32_bf16 v[74:77], v[154:157], v[208:211], v[74:77]
	v_mfma_f32_16x16x32_bf16 v[126:129], v[144:147], v[172:175], v[126:129]
	v_mfma_f32_16x16x32_bf16 v[122:125], v[158:161], v[172:175], v[122:125]
	v_mfma_f32_16x16x32_bf16 v[114:117], v[144:147], v[180:183], v[114:117]
	v_mfma_f32_16x16x32_bf16 v[106:109], v[158:161], v[180:183], v[106:109]
	v_mfma_f32_16x16x32_bf16 v[98:101], v[144:147], v[204:207], v[98:101]
	v_mfma_f32_16x16x32_bf16 v[90:93], v[158:161], v[204:207], v[90:93]
	v_mfma_f32_16x16x32_bf16 v[82:85], v[144:147], v[212:215], v[82:85]
	v_mfma_f32_16x16x32_bf16 v[74:77], v[158:161], v[212:215], v[74:77]
	s_barrier
	s_add_i32 s70, 0, 0x14000
	s_add_i32 s58, s58, s44
	v_add_u32_e32 v153, s70, v149
	s_mov_b32 m0, s58
	ds_read_b128 v[216:219], v153
	ds_read_b128 v[226:229], v153 offset:1024
	ds_read_b128 v[230:233], v153 offset:2048
	ds_read_b128 v[234:237], v153 offset:3072
	global_load_lds_dwordx4 v0, s[6:7]
	s_add_i32 m0, s58, 0x2000
	s_nop 0
	global_load_lds_dwordx4 v130, s[6:7]
	s_barrier
	s_waitcnt lgkmcnt(0)
	s_waitcnt lgkmcnt(0)
	v_mfma_f32_16x16x32_bf16 v[118:121], v[216:219], v[168:171], v[118:121]
	v_mfma_f32_16x16x32_bf16 v[110:113], v[230:233], v[168:171], v[110:113]
	v_mfma_f32_16x16x32_bf16 v[102:105], v[216:219], v[176:179], v[102:105]
	v_mfma_f32_16x16x32_bf16 v[94:97], v[230:233], v[176:179], v[94:97]
	v_mfma_f32_16x16x32_bf16 v[86:89], v[216:219], v[184:187], v[86:89]
	v_mfma_f32_16x16x32_bf16 v[78:81], v[230:233], v[184:187], v[78:81]
	v_mfma_f32_16x16x32_bf16 v[70:73], v[216:219], v[208:211], v[70:73]
	v_mfma_f32_16x16x32_bf16 v[66:69], v[230:233], v[208:211], v[66:69]
	v_mfma_f32_16x16x32_bf16 v[118:121], v[226:229], v[172:175], v[118:121]
	v_mfma_f32_16x16x32_bf16 v[110:113], v[234:237], v[172:175], v[110:113]
	v_mfma_f32_16x16x32_bf16 v[102:105], v[226:229], v[180:183], v[102:105]
	v_mfma_f32_16x16x32_bf16 v[94:97], v[234:237], v[180:183], v[94:97]
	v_mfma_f32_16x16x32_bf16 v[86:89], v[226:229], v[204:207], v[86:89]
	v_mfma_f32_16x16x32_bf16 v[78:81], v[234:237], v[204:207], v[78:81]
	v_mfma_f32_16x16x32_bf16 v[70:73], v[226:229], v[212:215], v[70:73]
	v_mfma_f32_16x16x32_bf16 v[66:69], v[234:237], v[212:215], v[66:69]
	s_mov_b32 m0, s47
	s_add_u32 vcc_lo, s36, 0x80
	s_addc_u32 vcc_hi, s37, 0
	s_barrier
	ds_read_b128 v[168:171], v152 offset:16384
	ds_read_b128 v[172:175], v152 offset:17408
	ds_read_b128 v[176:179], v152 offset:18432
	ds_read_b128 v[180:183], v152 offset:19456
	ds_read_b128 v[184:187], v152 offset:20480
	ds_read_b128 v[204:207], v152 offset:21504
	ds_read_b128 v[208:211], v152 offset:22528
	ds_read_b128 v[212:215], v152 offset:23552
	global_load_lds_dwordx4 v134, s[36:37]
	s_mov_b32 m0, s48
	s_nop 0
	global_load_lds_dwordx4 v132, s[36:37]
	s_barrier
	s_waitcnt lgkmcnt(0)
	s_waitcnt lgkmcnt(0)
	v_mfma_f32_16x16x32_bf16 v[62:65], v[140:143], v[168:171], v[62:65]
	v_mfma_f32_16x16x32_bf16 v[58:61], v[154:157], v[168:171], v[58:61]
	v_mfma_f32_16x16x32_bf16 v[50:53], v[140:143], v[176:179], v[50:53]
	v_mfma_f32_16x16x32_bf16 v[42:45], v[154:157], v[176:179], v[42:45]
	v_mfma_f32_16x16x32_bf16 v[34:37], v[140:143], v[184:187], v[34:37]
	v_mfma_f32_16x16x32_bf16 v[26:29], v[154:157], v[184:187], v[26:29]
	v_mfma_f32_16x16x32_bf16 v[18:21], v[140:143], v[208:211], v[18:21]
	v_mfma_f32_16x16x32_bf16 v[10:13], v[154:157], v[208:211], v[10:13]
	v_mfma_f32_16x16x32_bf16 v[62:65], v[144:147], v[172:175], v[62:65]
	v_mfma_f32_16x16x32_bf16 v[58:61], v[158:161], v[172:175], v[58:61]
	v_mfma_f32_16x16x32_bf16 v[50:53], v[144:147], v[180:183], v[50:53]
	v_mfma_f32_16x16x32_bf16 v[42:45], v[158:161], v[180:183], v[42:45]
	v_mfma_f32_16x16x32_bf16 v[34:37], v[144:147], v[204:207], v[34:37]
	v_mfma_f32_16x16x32_bf16 v[26:29], v[158:161], v[204:207], v[26:29]
	v_mfma_f32_16x16x32_bf16 v[18:21], v[144:147], v[212:215], v[18:21]
	v_mfma_f32_16x16x32_bf16 v[10:13], v[158:161], v[212:215], v[10:13]
	s_barrier
	s_add_u32 s60, s6, 0x40000
	s_addc_u32 s61, s7, 0
	s_add_i32 s58, s70, s44
	s_mov_b32 m0, s58
	s_nop 0
	global_load_lds_dwordx4 v0, s[60:61]
	s_add_i32 m0, s58, 0x2000
	s_nop 0
	global_load_lds_dwordx4 v130, s[60:61]
	s_waitcnt vmcnt(6)
	s_barrier
; #define PG8_STAGE(bufoff, gbase, voff) do { _Pragma("unroll") for (int _i = 0; _i < 2; ++_i) \
;         __builtin_amdgcn_global_load_lds((const unsigned*)((const char*)(gbase) + (voff)[_i]), (LAS unsigned*)(lds + (bufoff) + ldsw + _i * 8192), 16, 0, 0); } while (0)
; #define PG8_LDA(dst, b, h) do { _Pragma("unroll") for (int m = 0; m < 4; ++m) _Pragma("unroll") for (int k = 0; k < 2; ++k) dst[m][k] = *(const LAS bf16x8*)(lds + PG8_SA(b, h) + aoff + m * 2048 + k * 1024); } while (0)
; #define PG8_LDB(dst, b, h) do { _Pragma("unroll") for (int n = 0; n < 2; ++n) _Pragma("unroll") for (int k = 0; k < 2; ++k) dst[n][k] = *(const LAS bf16x8*)(lds + PG8_SB(b, h) + boff + n * 2048 + k * 1024); } while (0)
; #define PG8_WAIT_V(n) asm volatile("s_waitcnt vmcnt(" #n ")" ::: "memory")
; #define PG8_WAIT_L(n) asm volatile("s_waitcnt lgkmcnt(" #n ")" ::: "memory")
; #define PG8_BAR __builtin_amdgcn_s_barrier()
; #define PG8_SCHED __builtin_amdgcn_sched_barrier(0)
; template <class Epi>
; __device__ __forceinline__ void gemm_phase(LAS unsigned char* lds, const Gemm g, const StaticOrder& S, const Epi& E) {
;     ...
;             PG8_LDB(B0, 0, 0); PG8_SCHED; PG8_LDA(At, 0, 0); PG8_STAGE(PG8_SA(1, 1), a1 + hstep, voffA);
;             PG8_WAIT_L(8); PG8_BAR; PG8_WAIT_L(0); PG8_MMA(0, 0, At, B0); PG8_BAR; PG8_SCHED;
;             PG8_LDB(B1, 0, 1); PG8_STAGE(PG8_SB(0, 0), b2, voffB);
;             PG8_BAR; PG8_WAIT_L(0); PG8_MMA(0, 1, At, B1); PG8_BAR;
;             PG8_LDA(At, 0, 1); PG8_STAGE(PG8_SA(0, 0), a2, voffA);
;             PG8_BAR; PG8_WAIT_L(0); PG8_MMA(1, 0, At, B0); PG8_BAR; PG8_SCHED;
;             PG8_STAGE(PG8_SB(0, 1), b2 + hstep, voffB);
;             PG8_WAIT_V(6); PG8_BAR; PG8_MMA(1, 1, At, B1); PG8_BAR;
;             PG8_LDB(B0, 1, 0); PG8_SCHED; PG8_LDA(At, 1, 0); PG8_STAGE(PG8_SA(0, 1), a2 + hstep, voffA);
;             PG8_WAIT_L(8); PG8_BAR; PG8_WAIT_L(0); PG8_MMA(0, 0, At, B0); PG8_BAR; PG8_SCHED;
;             PG8_LDB(B1, 1, 1); PG8_STAGE(PG8_SB(1, 0), b3, voffB);
;             PG8_BAR; PG8_WAIT_L(0); PG8_MMA(0, 1, At, B1); PG8_BAR;
;             PG8_LDA(At, 1, 1); PG8_STAGE(PG8_SA(1, 0), a3, voffA);
;             PG8_BAR; PG8_WAIT_L(0); PG8_MMA(1, 0, At, B0); PG8_BAR; PG8_SCHED;
;             PG8_STAGE(PG8_SB(1, 1), b3 + hstep, voffB);
;             PG8_WAIT_V(6); PG8_BAR; PG8_MMA(1, 1, At, B1); PG8_BAR;
	v_mfma_f32_16x16x32_bf16 v[54:57], v[216:219], v[168:171], v[54:57]
	v_mfma_f32_16x16x32_bf16 v[46:49], v[230:233], v[168:171], v[46:49]
	v_mfma_f32_16x16x32_bf16 v[38:41], v[216:219], v[176:179], v[38:41]
	v_mfma_f32_16x16x32_bf16 v[30:33], v[230:233], v[176:179], v[30:33]
	v_mfma_f32_16x16x32_bf16 v[22:25], v[216:219], v[184:187], v[22:25]
	v_mfma_f32_16x16x32_bf16 v[14:17], v[230:233], v[184:187], v[14:17]
	v_mfma_f32_16x16x32_bf16 v[6:9], v[216:219], v[208:211], v[6:9]
	v_mfma_f32_16x16x32_bf16 v[2:5], v[230:233], v[208:211], v[2:5]
	v_mfma_f32_16x16x32_bf16 v[54:57], v[226:229], v[172:175], v[54:57]
	v_mfma_f32_16x16x32_bf16 v[46:49], v[234:237], v[172:175], v[46:49]
	v_mfma_f32_16x16x32_bf16 v[38:41], v[226:229], v[180:183], v[38:41]
	v_mfma_f32_16x16x32_bf16 v[30:33], v[234:237], v[180:183], v[30:33]
	v_mfma_f32_16x16x32_bf16 v[22:25], v[226:229], v[204:207], v[22:25]
	v_mfma_f32_16x16x32_bf16 v[14:17], v[234:237], v[204:207], v[14:17]
	v_mfma_f32_16x16x32_bf16 v[6:9], v[226:229], v[212:215], v[6:9]
	v_mfma_f32_16x16x32_bf16 v[2:5], v[234:237], v[212:215], v[2:5]
	s_add_i32 s58, 0, 0x18000
	v_add_u32_e32 v153, s58, v149
	s_barrier
	ds_read_b128 v[140:143], v153
	ds_read_b128 v[144:147], v153 offset:1024
	ds_read_b128 v[154:157], v153 offset:2048
	ds_read_b128 v[158:161], v153 offset:3072
	s_add_u32 s36, s36, 0x40000
	s_addc_u32 s37, s37, 0
	s_mov_b32 m0, s49
	ds_read_b128 v[168:171], v152 offset:32768
	ds_read_b128 v[172:175], v152 offset:33792
	ds_read_b128 v[176:179], v152 offset:34816
	ds_read_b128 v[180:183], v152 offset:35840
	ds_read_b128 v[184:187], v152 offset:36864
	ds_read_b128 v[204:207], v152 offset:37888
	ds_read_b128 v[208:211], v152 offset:38912
	ds_read_b128 v[212:215], v152 offset:39936
	global_load_lds_dwordx4 v134, s[36:37]
	s_mov_b32 m0, s54
	s_nop 0
	global_load_lds_dwordx4 v132, s[36:37]
	s_waitcnt lgkmcnt(8)
	s_barrier
	s_waitcnt lgkmcnt(0)
	s_waitcnt lgkmcnt(0)
	v_mfma_f32_16x16x32_bf16 v[126:129], v[140:143], v[168:171], v[126:129]
	v_mfma_f32_16x16x32_bf16 v[122:125], v[154:157], v[168:171], v[122:125]
	s_cmp_eq_u32 s87, 0
	s_cbranch_scc1 .LdsA_skip_2
	global_store_dwordx4 v166, v[192:195], s[4:5]
.LdsA_skip_2:
	v_mfma_f32_16x16x32_bf16 v[114:117], v[140:143], v[176:179], v[114:117]
	v_mfma_f32_16x16x32_bf16 v[106:109], v[154:157], v[176:179], v[106:109]
	v_mfma_f32_16x16x32_bf16 v[98:101], v[140:143], v[184:187], v[98:101]
	v_mfma_f32_16x16x32_bf16 v[90:93], v[154:157], v[184:187], v[90:93]
	v_mfma_f32_16x16x32_bf16 v[82:85], v[140:143], v[208:211], v[82:85]
	v_mfma_f32_16x16x32_bf16 v[74:77], v[154:157], v[208:211], v[74:77]
	v_mfma_f32_16x16x32_bf16 v[126:129], v[144:147], v[172:175], v[126:129]
	v_mfma_f32_16x16x32_bf16 v[122:125], v[158:161], v[172:175], v[122:125]
	v_mfma_f32_16x16x32_bf16 v[114:117], v[144:147], v[180:183], v[114:117]
	v_mfma_f32_16x16x32_bf16 v[106:109], v[158:161], v[180:183], v[106:109]
	v_mfma_f32_16x16x32_bf16 v[98:101], v[144:147], v[204:207], v[98:101]
	v_mfma_f32_16x16x32_bf16 v[90:93], v[158:161], v[204:207], v[90:93]
	v_mfma_f32_16x16x32_bf16 v[82:85], v[144:147], v[212:215], v[82:85]
	v_mfma_f32_16x16x32_bf16 v[74:77], v[158:161], v[212:215], v[74:77]
	s_barrier
	s_add_i32 s36, 0, 0x1c000
	s_add_i32 s37, s58, s44
	v_add_u32_e32 v153, s36, v149
	s_add_u32 s60, s6, 0x80
	s_addc_u32 s61, s7, 0
	s_mov_b32 m0, s37
	ds_read_b128 v[216:219], v153
	ds_read_b128 v[226:229], v153 offset:1024
	ds_read_b128 v[230:233], v153 offset:2048
	ds_read_b128 v[234:237], v153 offset:3072
	global_load_lds_dwordx4 v0, s[60:61]
	s_add_i32 m0, s37, 0x2000
	s_nop 0
	global_load_lds_dwordx4 v130, s[60:61]
	s_barrier
	s_waitcnt lgkmcnt(0)
	s_waitcnt lgkmcnt(0)
	v_mfma_f32_16x16x32_bf16 v[118:121], v[216:219], v[168:171], v[118:121]
	v_mfma_f32_16x16x32_bf16 v[110:113], v[230:233], v[168:171], v[110:113]
	v_mfma_f32_16x16x32_bf16 v[102:105], v[216:219], v[176:179], v[102:105]
	v_mfma_f32_16x16x32_bf16 v[94:97], v[230:233], v[176:179], v[94:97]
	v_mfma_f32_16x16x32_bf16 v[86:89], v[216:219], v[184:187], v[86:89]
	v_mfma_f32_16x16x32_bf16 v[78:81], v[230:233], v[184:187], v[78:81]
	v_mfma_f32_16x16x32_bf16 v[70:73], v[216:219], v[208:211], v[70:73]
	v_mfma_f32_16x16x32_bf16 v[66:69], v[230:233], v[208:211], v[66:69]
	v_mfma_f32_16x16x32_bf16 v[118:121], v[226:229], v[172:175], v[118:121]
	v_mfma_f32_16x16x32_bf16 v[110:113], v[234:237], v[172:175], v[110:113]
	v_mfma_f32_16x16x32_bf16 v[102:105], v[226:229], v[180:183], v[102:105]
	v_mfma_f32_16x16x32_bf16 v[94:97], v[234:237], v[180:183], v[94:97]
	v_mfma_f32_16x16x32_bf16 v[86:89], v[226:229], v[204:207], v[86:89]
	v_mfma_f32_16x16x32_bf16 v[78:81], v[234:237], v[204:207], v[78:81]
	v_mfma_f32_16x16x32_bf16 v[70:73], v[226:229], v[212:215], v[70:73]
	v_mfma_f32_16x16x32_bf16 v[66:69], v[234:237], v[212:215], v[66:69]
	s_mov_b32 m0, s55
	s_barrier
	ds_read_b128 v[168:171], v152 offset:49152
	ds_read_b128 v[172:175], v152 offset:50176
	ds_read_b128 v[176:179], v152 offset:51200
	ds_read_b128 v[180:183], v152 offset:52224
	ds_read_b128 v[184:187], v152 offset:53248
	ds_read_b128 v[204:207], v152 offset:54272
	ds_read_b128 v[208:211], v152 offset:55296
	ds_read_b128 v[212:215], v152 offset:56320
	global_load_lds_dwordx4 v134, vcc
	s_mov_b32 m0, s83
	s_nop 0
	global_load_lds_dwordx4 v132, vcc
	s_barrier
; #define PG8_STAGE(bufoff, gbase, voff) do { _Pragma("unroll") for (int _i = 0; _i < 2; ++_i) \
;         __builtin_amdgcn_global_load_lds((const unsigned*)((const char*)(gbase) + (voff)[_i]), (LAS unsigned*)(lds + (bufoff) + ldsw + _i * 8192), 16, 0, 0); } while (0)
; #define PG8_LDA(dst, b, h) do { _Pragma("unroll") for (int m = 0; m < 4; ++m) _Pragma("unroll") for (int k = 0; k < 2; ++k) dst[m][k] = *(const LAS bf16x8*)(lds + PG8_SA(b, h) + aoff + m * 2048 + k * 1024); } while (0)
; #define PG8_LDB(dst, b, h) do { _Pragma("unroll") for (int n = 0; n < 2; ++n) _Pragma("unroll") for (int k = 0; k < 2; ++k) dst[n][k] = *(const LAS bf16x8*)(lds + PG8_SB(b, h) + boff + n * 2048 + k * 1024); } while (0)
; #define PG8_WAIT_V(n) asm volatile("s_waitcnt vmcnt(" #n ")" ::: "memory")
; #define PG8_WAIT_L(n) asm volatile("s_waitcnt lgkmcnt(" #n ")" ::: "memory")
; #define PG8_BAR __builtin_amdgcn_s_barrier()
; #define PG8_SCHED __builtin_amdgcn_sched_barrier(0)
; template <class Epi>
; __device__ __forceinline__ void gemm_phase(LAS unsigned char* lds, const Gemm g, const StaticOrder& S, const Epi& E) {
;     ...
;             PG8_LDB(B0, 0, 0); PG8_SCHED; PG8_LDA(At, 0, 0); PG8_STAGE(PG8_SA(1, 1), a1 + hstep, voffA);
;             PG8_WAIT_L(8); PG8_BAR; PG8_WAIT_L(0); PG8_MMA(0, 0, At, B0); PG8_BAR; PG8_SCHED;
;             PG8_LDB(B1, 0, 1); PG8_STAGE(PG8_SB(0, 0), b2, voffB);
;             PG8_BAR; PG8_WAIT_L(0); PG8_MMA(0, 1, At, B1); PG8_BAR;
;             PG8_LDA(At, 0, 1); PG8_STAGE(PG8_SA(0, 0), a2, voffA);
;             PG8_BAR; PG8_WAIT_L(0); PG8_MMA(1, 0, At, B0); PG8_BAR; PG8_SCHED;
;             PG8_STAGE(PG8_SB(0, 1), b2 + hstep, voffB);
;             PG8_WAIT_V(6); PG8_BAR; PG8_MMA(1, 1, At, B1); PG8_BAR;
;             PG8_LDB(B0, 1, 0); PG8_SCHED; PG8_LDA(At, 1, 0); PG8_STAGE(PG8_SA(0, 1), a2 + hstep, voffA);
;             PG8_WAIT_L(8); PG8_BAR; PG8_WAIT_L(0); PG8_MMA(0, 0, At, B0); PG8_BAR; PG8_SCHED;
;             PG8_LDB(B1, 1, 1); PG8_STAGE(PG8_SB(1, 0), b3, voffB);
;             PG8_BAR; PG8_WAIT_L(0); PG8_MMA(0, 1, At, B1); PG8_BAR;
;             PG8_LDA(At, 1, 1); PG8_STAGE(PG8_SA(1, 0), a3, voffA);
;             PG8_BAR; PG8_WAIT_L(0); PG8_MMA(1, 0, At, B0); PG8_BAR; PG8_SCHED;
;             PG8_STAGE(PG8_SB(1, 1), b3 + hstep, voffB);
;             PG8_WAIT_V(6); PG8_BAR; PG8_MMA(1, 1, At, B1); PG8_BAR;
	s_waitcnt lgkmcnt(0)
	s_waitcnt lgkmcnt(0)
	v_mfma_f32_16x16x32_bf16 v[62:65], v[140:143], v[168:171], v[62:65]
	v_mfma_f32_16x16x32_bf16 v[58:61], v[154:157], v[168:171], v[58:61]
	v_mfma_f32_16x16x32_bf16 v[50:53], v[140:143], v[176:179], v[50:53]
	v_mfma_f32_16x16x32_bf16 v[42:45], v[154:157], v[176:179], v[42:45]
	v_mfma_f32_16x16x32_bf16 v[34:37], v[140:143], v[184:187], v[34:37]
	v_mfma_f32_16x16x32_bf16 v[26:29], v[154:157], v[184:187], v[26:29]
	v_mfma_f32_16x16x32_bf16 v[18:21], v[140:143], v[208:211], v[18:21]
	v_mfma_f32_16x16x32_bf16 v[10:13], v[154:157], v[208:211], v[10:13]
	v_mfma_f32_16x16x32_bf16 v[62:65], v[144:147], v[172:175], v[62:65]
	v_mfma_f32_16x16x32_bf16 v[58:61], v[158:161], v[172:175], v[58:61]
	v_mfma_f32_16x16x32_bf16 v[50:53], v[144:147], v[180:183], v[50:53]
	v_mfma_f32_16x16x32_bf16 v[42:45], v[158:161], v[180:183], v[42:45]
	v_mfma_f32_16x16x32_bf16 v[34:37], v[144:147], v[204:207], v[34:37]
	v_mfma_f32_16x16x32_bf16 v[26:29], v[158:161], v[204:207], v[26:29]
	v_mfma_f32_16x16x32_bf16 v[18:21], v[144:147], v[212:215], v[18:21]
	v_mfma_f32_16x16x32_bf16 v[10:13], v[158:161], v[212:215], v[10:13]
	s_barrier
	s_add_u32 s6, s6, 0x40080
	s_addc_u32 s7, s7, 0
	s_add_i32 s36, s36, s44
	s_mov_b32 m0, s36
	s_nop 0
	global_load_lds_dwordx4 v0, s[6:7]
	s_add_i32 m0, s36, 0x2000
	s_nop 0
	global_load_lds_dwordx4 v130, s[6:7]
	s_waitcnt vmcnt(6)
	s_barrier
	v_mfma_f32_16x16x32_bf16 v[54:57], v[216:219], v[168:171], v[54:57]
	v_mfma_f32_16x16x32_bf16 v[46:49], v[230:233], v[168:171], v[46:49]
	v_mfma_f32_16x16x32_bf16 v[38:41], v[216:219], v[176:179], v[38:41]
	v_mfma_f32_16x16x32_bf16 v[30:33], v[230:233], v[176:179], v[30:33]
	v_mfma_f32_16x16x32_bf16 v[22:25], v[216:219], v[184:187], v[22:25]
	v_mfma_f32_16x16x32_bf16 v[14:17], v[230:233], v[184:187], v[14:17]
	v_mfma_f32_16x16x32_bf16 v[6:9], v[216:219], v[208:211], v[6:9]
	v_mfma_f32_16x16x32_bf16 v[2:5], v[230:233], v[208:211], v[2:5]
	v_mfma_f32_16x16x32_bf16 v[54:57], v[226:229], v[172:175], v[54:57]
	v_mfma_f32_16x16x32_bf16 v[46:49], v[234:237], v[172:175], v[46:49]
	v_mfma_f32_16x16x32_bf16 v[38:41], v[226:229], v[180:183], v[38:41]
	v_mfma_f32_16x16x32_bf16 v[30:33], v[234:237], v[180:183], v[30:33]
	v_mfma_f32_16x16x32_bf16 v[22:25], v[226:229], v[204:207], v[22:25]
	v_mfma_f32_16x16x32_bf16 v[14:17], v[234:237], v[204:207], v[14:17]
	v_mfma_f32_16x16x32_bf16 v[6:9], v[226:229], v[212:215], v[6:9]
	v_mfma_f32_16x16x32_bf16 v[2:5], v[234:237], v[212:215], v[2:5]
	s_add_i32 s91, s91, 2
	s_add_u32 s24, s24, 0x100
	s_addc_u32 s25, s25, 0
	s_add_u32 s89, s89, 0x100
	s_addc_u32 s90, s90, 0
	s_cmp_gt_u32 s91, 13
	s_barrier
	s_add_u32 s6, s24, 0xfffc0080
	s_addc_u32 s7, s25, -1
	s_add_i32 s58, 0, 0x10000
	v_add_u32_e32 v153, s58, v149
	ds_read_b128 v[140:143], v153
	ds_read_b128 v[144:147], v153 offset:1024
	ds_read_b128 v[154:157], v153 offset:2048
	ds_read_b128 v[158:161], v153 offset:3072
	s_cmp_eq_u32 s91, 12
	s_cselect_b32 s37, s11, s7
	s_cselect_b32 s36, s71, s6
	s_cselect_b32 s7, s9, s90
	s_cselect_b32 s6, s88, s89
	s_add_i32 m0, s47, 0xc000
	ds_read_b128 v[168:171], v152
	ds_read_b128 v[172:175], v152 offset:1024
	ds_read_b128 v[176:179], v152 offset:2048
	ds_read_b128 v[180:183], v152 offset:3072
	ds_read_b128 v[184:187], v152 offset:4096
	ds_read_b128 v[204:207], v152 offset:5120
	ds_read_b128 v[208:211], v152 offset:6144
	ds_read_b128 v[212:215], v152 offset:7168
	global_load_lds_dwordx4 v136, s[24:25]
	s_add_i32 m0, s47, 0xe000
	s_nop 0
	global_load_lds_dwordx4 v138, s[24:25]
	s_waitcnt lgkmcnt(8)
	s_barrier
	s_waitcnt lgkmcnt(0)
	s_waitcnt lgkmcnt(0)
	v_mfma_f32_16x16x32_bf16 v[126:129], v[140:143], v[168:171], v[126:129]
	v_mfma_f32_16x16x32_bf16 v[122:125], v[154:157], v[168:171], v[122:125]
	v_mfma_f32_16x16x32_bf16 v[114:117], v[140:143], v[176:179], v[114:117]
	v_mfma_f32_16x16x32_bf16 v[106:109], v[154:157], v[176:179], v[106:109]
	v_mfma_f32_16x16x32_bf16 v[98:101], v[140:143], v[184:187], v[98:101]
	v_mfma_f32_16x16x32_bf16 v[90:93], v[154:157], v[184:187], v[90:93]
	v_mfma_f32_16x16x32_bf16 v[82:85], v[140:143], v[208:211], v[82:85]
	v_mfma_f32_16x16x32_bf16 v[74:77], v[154:157], v[208:211], v[74:77]
	v_mfma_f32_16x16x32_bf16 v[126:129], v[144:147], v[172:175], v[126:129]
	v_mfma_f32_16x16x32_bf16 v[122:125], v[158:161], v[172:175], v[122:125]
	v_mfma_f32_16x16x32_bf16 v[114:117], v[144:147], v[180:183], v[114:117]
	v_mfma_f32_16x16x32_bf16 v[106:109], v[158:161], v[180:183], v[106:109]
	v_mfma_f32_16x16x32_bf16 v[98:101], v[144:147], v[204:207], v[98:101]
	v_mfma_f32_16x16x32_bf16 v[90:93], v[158:161], v[204:207], v[90:93]
	v_mfma_f32_16x16x32_bf16 v[82:85], v[144:147], v[212:215], v[82:85]
	v_mfma_f32_16x16x32_bf16 v[74:77], v[158:161], v[212:215], v[74:77]
	s_barrier
	s_add_i32 s70, 0, 0x14000
	s_add_i32 s58, s58, s44
	v_add_u32_e32 v153, s70, v149
	s_mov_b32 m0, s58
	ds_read_b128 v[216:219], v153
	ds_read_b128 v[226:229], v153 offset:1024
	ds_read_b128 v[230:233], v153 offset:2048
	ds_read_b128 v[234:237], v153 offset:3072
	global_load_lds_dwordx4 v0, s[6:7]
	s_add_i32 m0, s58, 0x2000
	s_nop 0
	global_load_lds_dwordx4 v130, s[6:7]
	s_barrier
; #define PG8_STAGE(bufoff, gbase, voff) do { _Pragma("unroll") for (int _i = 0; _i < 2; ++_i) \
;         __builtin_amdgcn_global_load_lds((const unsigned*)((const char*)(gbase) + (voff)[_i]), (LAS unsigned*)(lds + (bufoff) + ldsw + _i * 8192), 16, 0, 0); } while (0)
; #define PG8_LDA(dst, b, h) do { _Pragma("unroll") for (int m = 0; m < 4; ++m) _Pragma("unroll") for (int k = 0; k < 2; ++k) dst[m][k] = *(const LAS bf16x8*)(lds + PG8_SA(b, h) + aoff + m * 2048 + k * 1024); } while (0)
; #define PG8_LDB(dst, b, h) do { _Pragma("unroll") for (int n = 0; n < 2; ++n) _Pragma("unroll") for (int k = 0; k < 2; ++k) dst[n][k] = *(const LAS bf16x8*)(lds + PG8_SB(b, h) + boff + n * 2048 + k * 1024); } while (0)
; #define PG8_WAIT_V(n) asm volatile("s_waitcnt vmcnt(" #n ")" ::: "memory")
; #define PG8_WAIT_L(n) asm volatile("s_waitcnt lgkmcnt(" #n ")" ::: "memory")
; #define PG8_BAR __builtin_amdgcn_s_barrier()
; #define PG8_SCHED __builtin_amdgcn_sched_barrier(0)
; template <class Epi>
; __device__ __forceinline__ void gemm_phase(LAS unsigned char* lds, const Gemm g, const StaticOrder& S, const Epi& E) {
;     ...
;             PG8_LDB(B0, 0, 0); PG8_SCHED; PG8_LDA(At, 0, 0); PG8_STAGE(PG8_SA(1, 1), a1 + hstep, voffA);
;             PG8_WAIT_L(8); PG8_BAR; PG8_WAIT_L(0); PG8_MMA(0, 0, At, B0); PG8_BAR; PG8_SCHED;
;             PG8_LDB(B1, 0, 1); PG8_STAGE(PG8_SB(0, 0), b2, voffB);
;             PG8_BAR; PG8_WAIT_L(0); PG8_MMA(0, 1, At, B1); PG8_BAR;
;             PG8_LDA(At, 0, 1); PG8_STAGE(PG8_SA(0, 0), a2, voffA);
;             PG8_BAR; PG8_WAIT_L(0); PG8_MMA(1, 0, At, B0); PG8_BAR; PG8_SCHED;
;             PG8_STAGE(PG8_SB(0, 1), b2 + hstep, voffB);
;             PG8_WAIT_V(6); PG8_BAR; PG8_MMA(1, 1, At, B1); PG8_BAR;
;             PG8_LDB(B0, 1, 0); PG8_SCHED; PG8_LDA(At, 1, 0); PG8_STAGE(PG8_SA(0, 1), a2 + hstep, voffA);
;             PG8_WAIT_L(8); PG8_BAR; PG8_WAIT_L(0); PG8_MMA(0, 0, At, B0); PG8_BAR; PG8_SCHED;
;             PG8_LDB(B1, 1, 1); PG8_STAGE(PG8_SB(1, 0), b3, voffB);
;             PG8_BAR; PG8_WAIT_L(0); PG8_MMA(0, 1, At, B1); PG8_BAR;
;             PG8_LDA(At, 1, 1); PG8_STAGE(PG8_SA(1, 0), a3, voffA);
;             PG8_BAR; PG8_WAIT_L(0); PG8_MMA(1, 0, At, B0); PG8_BAR; PG8_SCHED;
;             PG8_STAGE(PG8_SB(1, 1), b3 + hstep, voffB);
;             PG8_WAIT_V(6); PG8_BAR; PG8_MMA(1, 1, At, B1); PG8_BAR;
	s_waitcnt lgkmcnt(0)
	s_waitcnt lgkmcnt(0)
	v_mfma_f32_16x16x32_bf16 v[118:121], v[216:219], v[168:171], v[118:121]
	v_mfma_f32_16x16x32_bf16 v[110:113], v[230:233], v[168:171], v[110:113]
	v_mfma_f32_16x16x32_bf16 v[102:105], v[216:219], v[176:179], v[102:105]
	v_mfma_f32_16x16x32_bf16 v[94:97], v[230:233], v[176:179], v[94:97]
	v_mfma_f32_16x16x32_bf16 v[86:89], v[216:219], v[184:187], v[86:89]
	v_mfma_f32_16x16x32_bf16 v[78:81], v[230:233], v[184:187], v[78:81]
	v_mfma_f32_16x16x32_bf16 v[70:73], v[216:219], v[208:211], v[70:73]
	v_mfma_f32_16x16x32_bf16 v[66:69], v[230:233], v[208:211], v[66:69]
	v_mfma_f32_16x16x32_bf16 v[118:121], v[226:229], v[172:175], v[118:121]
	v_mfma_f32_16x16x32_bf16 v[110:113], v[234:237], v[172:175], v[110:113]
	v_mfma_f32_16x16x32_bf16 v[102:105], v[226:229], v[180:183], v[102:105]
	v_mfma_f32_16x16x32_bf16 v[94:97], v[234:237], v[180:183], v[94:97]
	v_mfma_f32_16x16x32_bf16 v[86:89], v[226:229], v[204:207], v[86:89]
	v_mfma_f32_16x16x32_bf16 v[78:81], v[234:237], v[204:207], v[78:81]
	v_mfma_f32_16x16x32_bf16 v[70:73], v[226:229], v[212:215], v[70:73]
	v_mfma_f32_16x16x32_bf16 v[66:69], v[234:237], v[212:215], v[66:69]
	s_mov_b32 m0, s47
	s_add_u32 vcc_lo, s36, 0x80
	s_addc_u32 vcc_hi, s37, 0
	s_barrier
	ds_read_b128 v[168:171], v152 offset:16384
	ds_read_b128 v[172:175], v152 offset:17408
	ds_read_b128 v[176:179], v152 offset:18432
	ds_read_b128 v[180:183], v152 offset:19456
	ds_read_b128 v[184:187], v152 offset:20480
	ds_read_b128 v[204:207], v152 offset:21504
	ds_read_b128 v[208:211], v152 offset:22528
	ds_read_b128 v[212:215], v152 offset:23552
	global_load_lds_dwordx4 v134, s[36:37]
	s_mov_b32 m0, s48
	s_nop 0
	global_load_lds_dwordx4 v132, s[36:37]
	s_barrier
	s_waitcnt lgkmcnt(0)
	s_waitcnt lgkmcnt(0)
	v_mfma_f32_16x16x32_bf16 v[62:65], v[140:143], v[168:171], v[62:65]
	v_mfma_f32_16x16x32_bf16 v[58:61], v[154:157], v[168:171], v[58:61]
	v_mfma_f32_16x16x32_bf16 v[50:53], v[140:143], v[176:179], v[50:53]
	v_mfma_f32_16x16x32_bf16 v[42:45], v[154:157], v[176:179], v[42:45]
	v_mfma_f32_16x16x32_bf16 v[34:37], v[140:143], v[184:187], v[34:37]
	v_mfma_f32_16x16x32_bf16 v[26:29], v[154:157], v[184:187], v[26:29]
	v_mfma_f32_16x16x32_bf16 v[18:21], v[140:143], v[208:211], v[18:21]
	v_mfma_f32_16x16x32_bf16 v[10:13], v[154:157], v[208:211], v[10:13]
	v_mfma_f32_16x16x32_bf16 v[62:65], v[144:147], v[172:175], v[62:65]
	v_mfma_f32_16x16x32_bf16 v[58:61], v[158:161], v[172:175], v[58:61]
	v_mfma_f32_16x16x32_bf16 v[50:53], v[144:147], v[180:183], v[50:53]
	v_mfma_f32_16x16x32_bf16 v[42:45], v[158:161], v[180:183], v[42:45]
	v_mfma_f32_16x16x32_bf16 v[34:37], v[144:147], v[204:207], v[34:37]
	v_mfma_f32_16x16x32_bf16 v[26:29], v[158:161], v[204:207], v[26:29]
	v_mfma_f32_16x16x32_bf16 v[18:21], v[144:147], v[212:215], v[18:21]
	v_mfma_f32_16x16x32_bf16 v[10:13], v[158:161], v[212:215], v[10:13]
	s_barrier
	s_add_u32 s60, s6, 0x40000
	s_addc_u32 s61, s7, 0
	s_add_i32 s58, s70, s44
	s_mov_b32 m0, s58
	s_nop 0
	global_load_lds_dwordx4 v0, s[60:61]
	s_add_i32 m0, s58, 0x2000
	s_nop 0
	global_load_lds_dwordx4 v130, s[60:61]
	s_waitcnt vmcnt(6)
	s_barrier
	v_mfma_f32_16x16x32_bf16 v[54:57], v[216:219], v[168:171], v[54:57]
	v_mfma_f32_16x16x32_bf16 v[46:49], v[230:233], v[168:171], v[46:49]
	v_mfma_f32_16x16x32_bf16 v[38:41], v[216:219], v[176:179], v[38:41]
	v_mfma_f32_16x16x32_bf16 v[30:33], v[230:233], v[176:179], v[30:33]
	v_mfma_f32_16x16x32_bf16 v[22:25], v[216:219], v[184:187], v[22:25]
	v_mfma_f32_16x16x32_bf16 v[14:17], v[230:233], v[184:187], v[14:17]
	v_mfma_f32_16x16x32_bf16 v[6:9], v[216:219], v[208:211], v[6:9]
	v_mfma_f32_16x16x32_bf16 v[2:5], v[230:233], v[208:211], v[2:5]
	v_mfma_f32_16x16x32_bf16 v[54:57], v[226:229], v[172:175], v[54:57]
	v_mfma_f32_16x16x32_bf16 v[46:49], v[234:237], v[172:175], v[46:49]
	v_mfma_f32_16x16x32_bf16 v[38:41], v[226:229], v[180:183], v[38:41]
	v_mfma_f32_16x16x32_bf16 v[30:33], v[234:237], v[180:183], v[30:33]
	v_mfma_f32_16x16x32_bf16 v[22:25], v[226:229], v[204:207], v[22:25]
	v_mfma_f32_16x16x32_bf16 v[14:17], v[234:237], v[204:207], v[14:17]
	v_mfma_f32_16x16x32_bf16 v[6:9], v[226:229], v[212:215], v[6:9]
	v_mfma_f32_16x16x32_bf16 v[2:5], v[234:237], v[212:215], v[2:5]
	s_add_i32 s58, 0, 0x18000
	v_add_u32_e32 v153, s58, v149
	s_barrier
	ds_read_b128 v[140:143], v153
	ds_read_b128 v[144:147], v153 offset:1024
	ds_read_b128 v[154:157], v153 offset:2048
	ds_read_b128 v[158:161], v153 offset:3072
	s_add_u32 s36, s36, 0x40000
	s_addc_u32 s37, s37, 0
	s_mov_b32 m0, s49
	ds_read_b128 v[168:171], v152 offset:32768
	ds_read_b128 v[172:175], v152 offset:33792
	ds_read_b128 v[176:179], v152 offset:34816
	ds_read_b128 v[180:183], v152 offset:35840
	ds_read_b128 v[184:187], v152 offset:36864
	ds_read_b128 v[204:207], v152 offset:37888
	ds_read_b128 v[208:211], v152 offset:38912
	ds_read_b128 v[212:215], v152 offset:39936
	global_load_lds_dwordx4 v134, s[36:37]
	s_mov_b32 m0, s54
	s_nop 0
	global_load_lds_dwordx4 v132, s[36:37]
	s_waitcnt lgkmcnt(8)
	s_barrier
	s_waitcnt lgkmcnt(0)
	s_waitcnt lgkmcnt(0)
	v_mfma_f32_16x16x32_bf16 v[126:129], v[140:143], v[168:171], v[126:129]
	v_mfma_f32_16x16x32_bf16 v[122:125], v[154:157], v[168:171], v[122:125]
	s_cmp_eq_u32 s87, 0
	s_cbranch_scc1 .LdsA_skip_3
	global_store_dwordx4 v166, v[196:199], s[4:5] offset:256
	s_nop 1
	v_add_u32_e32 v166, 0xe000, v166
; #define PG8_STAGE(bufoff, gbase, voff) do { _Pragma("unroll") for (int _i = 0; _i < 2; ++_i) \
;         __builtin_amdgcn_global_load_lds((const unsigned*)((const char*)(gbase) + (voff)[_i]), (LAS unsigned*)(lds + (bufoff) + ldsw + _i * 8192), 16, 0, 0); } while (0)
; #define PG8_LDA(dst, b, h) do { _Pragma("unroll") for (int m = 0; m < 4; ++m) _Pragma("unroll") for (int k = 0; k < 2; ++k) dst[m][k] = *(const LAS bf16x8*)(lds + PG8_SA(b, h) + aoff + m * 2048 + k * 1024); } while (0)
; #define PG8_LDB(dst, b, h) do { _Pragma("unroll") for (int n = 0; n < 2; ++n) _Pragma("unroll") for (int k = 0; k < 2; ++k) dst[n][k] = *(const LAS bf16x8*)(lds + PG8_SB(b, h) + boff + n * 2048 + k * 1024); } while (0)
; #define PG8_WAIT_V(n) asm volatile("s_waitcnt vmcnt(" #n ")" ::: "memory")
; #define PG8_WAIT_L(n) asm volatile("s_waitcnt lgkmcnt(" #n ")" ::: "memory")
; #define PG8_BAR __builtin_amdgcn_s_barrier()
; #define PG8_SCHED __builtin_amdgcn_sched_barrier(0)
; template <class Epi>
; __device__ __forceinline__ void gemm_phase(LAS unsigned char* lds, const Gemm g, const StaticOrder& S, const Epi& E) {
;     ...
;             PG8_LDB(B0, 0, 0); PG8_SCHED; PG8_LDA(At, 0, 0); PG8_STAGE(PG8_SA(1, 1), a1 + hstep, voffA);
;             PG8_WAIT_L(8); PG8_BAR; PG8_WAIT_L(0); PG8_MMA(0, 0, At, B0); PG8_BAR; PG8_SCHED;
;             PG8_LDB(B1, 0, 1); PG8_STAGE(PG8_SB(0, 0), b2, voffB);
;             PG8_BAR; PG8_WAIT_L(0); PG8_MMA(0, 1, At, B1); PG8_BAR;
;             PG8_LDA(At, 0, 1); PG8_STAGE(PG8_SA(0, 0), a2, voffA);
;             PG8_BAR; PG8_WAIT_L(0); PG8_MMA(1, 0, At, B0); PG8_BAR; PG8_SCHED;
;             PG8_STAGE(PG8_SB(0, 1), b2 + hstep, voffB);
;             PG8_WAIT_V(6); PG8_BAR; PG8_MMA(1, 1, At, B1); PG8_BAR;
;             PG8_LDB(B0, 1, 0); PG8_SCHED; PG8_LDA(At, 1, 0); PG8_STAGE(PG8_SA(0, 1), a2 + hstep, voffA);
;             PG8_WAIT_L(8); PG8_BAR; PG8_WAIT_L(0); PG8_MMA(0, 0, At, B0); PG8_BAR; PG8_SCHED;
;             PG8_LDB(B1, 1, 1); PG8_STAGE(PG8_SB(1, 0), b3, voffB);
;             PG8_BAR; PG8_WAIT_L(0); PG8_MMA(0, 1, At, B1); PG8_BAR;
;             PG8_LDA(At, 1, 1); PG8_STAGE(PG8_SA(1, 0), a3, voffA);
;             PG8_BAR; PG8_WAIT_L(0); PG8_MMA(1, 0, At, B0); PG8_BAR; PG8_SCHED;
;             PG8_STAGE(PG8_SB(1, 1), b3 + hstep, voffB);
;             PG8_WAIT_V(6); PG8_BAR; PG8_MMA(1, 1, At, B1); PG8_BAR;
.LdsA_skip_3:
	v_mfma_f32_16x16x32_bf16 v[114:117], v[140:143], v[176:179], v[114:117]
	v_mfma_f32_16x16x32_bf16 v[106:109], v[154:157], v[176:179], v[106:109]
	v_mfma_f32_16x16x32_bf16 v[98:101], v[140:143], v[184:187], v[98:101]
	v_mfma_f32_16x16x32_bf16 v[90:93], v[154:157], v[184:187], v[90:93]
	v_mfma_f32_16x16x32_bf16 v[82:85], v[140:143], v[208:211], v[82:85]
	v_mfma_f32_16x16x32_bf16 v[74:77], v[154:157], v[208:211], v[74:77]
	v_mfma_f32_16x16x32_bf16 v[126:129], v[144:147], v[172:175], v[126:129]
	v_mfma_f32_16x16x32_bf16 v[122:125], v[158:161], v[172:175], v[122:125]
	v_mfma_f32_16x16x32_bf16 v[114:117], v[144:147], v[180:183], v[114:117]
	v_mfma_f32_16x16x32_bf16 v[106:109], v[158:161], v[180:183], v[106:109]
	v_mfma_f32_16x16x32_bf16 v[98:101], v[144:147], v[204:207], v[98:101]
	v_mfma_f32_16x16x32_bf16 v[90:93], v[158:161], v[204:207], v[90:93]
	v_mfma_f32_16x16x32_bf16 v[82:85], v[144:147], v[212:215], v[82:85]
	v_mfma_f32_16x16x32_bf16 v[74:77], v[158:161], v[212:215], v[74:77]
	s_barrier
	s_add_i32 s36, 0, 0x1c000
	s_add_i32 s37, s58, s44
	v_add_u32_e32 v153, s36, v149
	s_add_u32 s60, s6, 0x80
	s_addc_u32 s61, s7, 0
	s_mov_b32 m0, s37
	ds_read_b128 v[216:219], v153
	ds_read_b128 v[226:229], v153 offset:1024
	ds_read_b128 v[230:233], v153 offset:2048
	ds_read_b128 v[234:237], v153 offset:3072
	global_load_lds_dwordx4 v0, s[60:61]
	s_add_i32 m0, s37, 0x2000
	s_nop 0
	global_load_lds_dwordx4 v130, s[60:61]
	s_barrier
	s_waitcnt lgkmcnt(0)
	s_waitcnt lgkmcnt(0)
	v_mfma_f32_16x16x32_bf16 v[118:121], v[216:219], v[168:171], v[118:121]
	v_mfma_f32_16x16x32_bf16 v[110:113], v[230:233], v[168:171], v[110:113]
	v_mfma_f32_16x16x32_bf16 v[102:105], v[216:219], v[176:179], v[102:105]
	v_mfma_f32_16x16x32_bf16 v[94:97], v[230:233], v[176:179], v[94:97]
	v_mfma_f32_16x16x32_bf16 v[86:89], v[216:219], v[184:187], v[86:89]
	v_mfma_f32_16x16x32_bf16 v[78:81], v[230:233], v[184:187], v[78:81]
	v_mfma_f32_16x16x32_bf16 v[70:73], v[216:219], v[208:211], v[70:73]
	v_mfma_f32_16x16x32_bf16 v[66:69], v[230:233], v[208:211], v[66:69]
	v_mfma_f32_16x16x32_bf16 v[118:121], v[226:229], v[172:175], v[118:121]
	v_mfma_f32_16x16x32_bf16 v[110:113], v[234:237], v[172:175], v[110:113]
	v_mfma_f32_16x16x32_bf16 v[102:105], v[226:229], v[180:183], v[102:105]
	v_mfma_f32_16x16x32_bf16 v[94:97], v[234:237], v[180:183], v[94:97]
	v_mfma_f32_16x16x32_bf16 v[86:89], v[226:229], v[204:207], v[86:89]
	v_mfma_f32_16x16x32_bf16 v[78:81], v[234:237], v[204:207], v[78:81]
	v_mfma_f32_16x16x32_bf16 v[70:73], v[226:229], v[212:215], v[70:73]
	v_mfma_f32_16x16x32_bf16 v[66:69], v[234:237], v[212:215], v[66:69]
	s_mov_b32 m0, s55
	s_barrier
	ds_read_b128 v[168:171], v152 offset:49152
	ds_read_b128 v[172:175], v152 offset:50176
	ds_read_b128 v[176:179], v152 offset:51200
	ds_read_b128 v[180:183], v152 offset:52224
	ds_read_b128 v[184:187], v152 offset:53248
	ds_read_b128 v[204:207], v152 offset:54272
	ds_read_b128 v[208:211], v152 offset:55296
	ds_read_b128 v[212:215], v152 offset:56320
	global_load_lds_dwordx4 v134, vcc
	s_mov_b32 m0, s83
	s_nop 0
	global_load_lds_dwordx4 v132, vcc
	s_barrier
	s_waitcnt lgkmcnt(0)
	s_waitcnt lgkmcnt(0)
	v_mfma_f32_16x16x32_bf16 v[62:65], v[140:143], v[168:171], v[62:65]
	v_mfma_f32_16x16x32_bf16 v[58:61], v[154:157], v[168:171], v[58:61]
	v_mfma_f32_16x16x32_bf16 v[50:53], v[140:143], v[176:179], v[50:53]
	v_mfma_f32_16x16x32_bf16 v[42:45], v[154:157], v[176:179], v[42:45]
	v_mfma_f32_16x16x32_bf16 v[34:37], v[140:143], v[184:187], v[34:37]
	v_mfma_f32_16x16x32_bf16 v[26:29], v[154:157], v[184:187], v[26:29]
	v_mfma_f32_16x16x32_bf16 v[18:21], v[140:143], v[208:211], v[18:21]
	v_mfma_f32_16x16x32_bf16 v[10:13], v[154:157], v[208:211], v[10:13]
	v_mfma_f32_16x16x32_bf16 v[62:65], v[144:147], v[172:175], v[62:65]
	v_mfma_f32_16x16x32_bf16 v[58:61], v[158:161], v[172:175], v[58:61]
	v_mfma_f32_16x16x32_bf16 v[50:53], v[144:147], v[180:183], v[50:53]
	v_mfma_f32_16x16x32_bf16 v[42:45], v[158:161], v[180:183], v[42:45]
	v_mfma_f32_16x16x32_bf16 v[34:37], v[144:147], v[204:207], v[34:37]
	v_mfma_f32_16x16x32_bf16 v[26:29], v[158:161], v[204:207], v[26:29]
	v_mfma_f32_16x16x32_bf16 v[18:21], v[144:147], v[212:215], v[18:21]
	v_mfma_f32_16x16x32_bf16 v[10:13], v[158:161], v[212:215], v[10:13]
	s_barrier
	s_add_u32 s6, s6, 0x40080
	s_addc_u32 s7, s7, 0
	s_add_i32 s36, s36, s44
	s_mov_b32 m0, s36
	s_nop 0
	global_load_lds_dwordx4 v0, s[6:7]
	s_add_i32 m0, s36, 0x2000
	s_nop 0
	global_load_lds_dwordx4 v130, s[6:7]
	s_waitcnt vmcnt(6)
	s_barrier
	v_mfma_f32_16x16x32_bf16 v[54:57], v[216:219], v[168:171], v[54:57]
	v_mfma_f32_16x16x32_bf16 v[46:49], v[230:233], v[168:171], v[46:49]
	v_mfma_f32_16x16x32_bf16 v[38:41], v[216:219], v[176:179], v[38:41]
	v_mfma_f32_16x16x32_bf16 v[30:33], v[230:233], v[176:179], v[30:33]
	v_mfma_f32_16x16x32_bf16 v[22:25], v[216:219], v[184:187], v[22:25]
	v_mfma_f32_16x16x32_bf16 v[14:17], v[230:233], v[184:187], v[14:17]
	v_mfma_f32_16x16x32_bf16 v[6:9], v[216:219], v[208:211], v[6:9]
	v_mfma_f32_16x16x32_bf16 v[2:5], v[230:233], v[208:211], v[2:5]
	v_mfma_f32_16x16x32_bf16 v[54:57], v[226:229], v[172:175], v[54:57]
	v_mfma_f32_16x16x32_bf16 v[46:49], v[234:237], v[172:175], v[46:49]
	v_mfma_f32_16x16x32_bf16 v[38:41], v[226:229], v[180:183], v[38:41]
	v_mfma_f32_16x16x32_bf16 v[30:33], v[234:237], v[180:183], v[30:33]
	v_mfma_f32_16x16x32_bf16 v[22:25], v[226:229], v[204:207], v[22:25]
	v_mfma_f32_16x16x32_bf16 v[14:17], v[234:237], v[204:207], v[14:17]
	v_mfma_f32_16x16x32_bf16 v[6:9], v[226:229], v[212:215], v[6:9]
	v_mfma_f32_16x16x32_bf16 v[2:5], v[234:237], v[212:215], v[2:5]
	s_add_i32 s91, s91, 2
	s_add_u32 s24, s24, 0x100
	s_addc_u32 s25, s25, 0
	s_add_u32 s89, s89, 0x100
	s_addc_u32 s90, s90, 0
	s_cmp_gt_u32 s91, 13
	s_barrier
; #define PG8_STAGE(bufoff, gbase, voff) do { _Pragma("unroll") for (int _i = 0; _i < 2; ++_i) \
;         __builtin_amdgcn_global_load_lds((const unsigned*)((const char*)(gbase) + (voff)[_i]), (LAS unsigned*)(lds + (bufoff) + ldsw + _i * 8192), 16, 0, 0); } while (0)
; #define PG8_LDA(dst, b, h) do { _Pragma("unroll") for (int m = 0; m < 4; ++m) _Pragma("unroll") for (int k = 0; k < 2; ++k) dst[m][k] = *(const LAS bf16x8*)(lds + PG8_SA(b, h) + aoff + m * 2048 + k * 1024); } while (0)
; #define PG8_LDB(dst, b, h) do { _Pragma("unroll") for (int n = 0; n < 2; ++n) _Pragma("unroll") for (int k = 0; k < 2; ++k) dst[n][k] = *(const LAS bf16x8*)(lds + PG8_SB(b, h) + boff + n * 2048 + k * 1024); } while (0)
; #define PG8_WAIT_V(n) asm volatile("s_waitcnt vmcnt(" #n ")" ::: "memory")
; #define PG8_WAIT_L(n) asm volatile("s_waitcnt lgkmcnt(" #n ")" ::: "memory")
; #define PG8_BAR __builtin_amdgcn_s_barrier()
; #define PG8_SCHED __builtin_amdgcn_sched_barrier(0)
; template <class Epi>
; __device__ __forceinline__ void gemm_phase(LAS unsigned char* lds, const Gemm g, const StaticOrder& S, const Epi& E) {
;     ...
;             PG8_LDB(B0, 0, 0); PG8_SCHED; PG8_LDA(At, 0, 0); PG8_STAGE(PG8_SA(1, 1), a1 + hstep, voffA);
;             PG8_WAIT_L(8); PG8_BAR; PG8_WAIT_L(0); PG8_MMA(0, 0, At, B0); PG8_BAR; PG8_SCHED;
;             PG8_LDB(B1, 0, 1); PG8_STAGE(PG8_SB(0, 0), b2, voffB);
;             PG8_BAR; PG8_WAIT_L(0); PG8_MMA(0, 1, At, B1); PG8_BAR;
;             PG8_LDA(At, 0, 1); PG8_STAGE(PG8_SA(0, 0), a2, voffA);
;             PG8_BAR; PG8_WAIT_L(0); PG8_MMA(1, 0, At, B0); PG8_BAR; PG8_SCHED;
;             PG8_STAGE(PG8_SB(0, 1), b2 + hstep, voffB);
;             PG8_WAIT_V(6); PG8_BAR; PG8_MMA(1, 1, At, B1); PG8_BAR;
;             PG8_LDB(B0, 1, 0); PG8_SCHED; PG8_LDA(At, 1, 0); PG8_STAGE(PG8_SA(0, 1), a2 + hstep, voffA);
;             PG8_WAIT_L(8); PG8_BAR; PG8_WAIT_L(0); PG8_MMA(0, 0, At, B0); PG8_BAR; PG8_SCHED;
;             PG8_LDB(B1, 1, 1); PG8_STAGE(PG8_SB(1, 0), b3, voffB);
;             PG8_BAR; PG8_WAIT_L(0); PG8_MMA(0, 1, At, B1); PG8_BAR;
;             PG8_LDA(At, 1, 1); PG8_STAGE(PG8_SA(1, 0), a3, voffA);
;             PG8_BAR; PG8_WAIT_L(0); PG8_MMA(1, 0, At, B0); PG8_BAR; PG8_SCHED;
;             PG8_STAGE(PG8_SB(1, 1), b3 + hstep, voffB);
;             PG8_WAIT_V(6); PG8_BAR; PG8_MMA(1, 1, At, B1); PG8_BAR;
	s_add_u32 s6, s24, 0xfffc0080
	s_addc_u32 s7, s25, -1
	s_add_i32 s58, 0, 0x10000
	v_add_u32_e32 v153, s58, v149
	ds_read_b128 v[140:143], v153
	ds_read_b128 v[144:147], v153 offset:1024
	ds_read_b128 v[154:157], v153 offset:2048
	ds_read_b128 v[158:161], v153 offset:3072
	s_cmp_eq_u32 s91, 12
	s_cselect_b32 s37, s11, s7
	s_cselect_b32 s36, s71, s6
	s_cselect_b32 s7, s9, s90
	s_cselect_b32 s6, s88, s89
	s_add_i32 m0, s47, 0xc000
	ds_read_b128 v[168:171], v152
	ds_read_b128 v[172:175], v152 offset:1024
	ds_read_b128 v[176:179], v152 offset:2048
	ds_read_b128 v[180:183], v152 offset:3072
	ds_read_b128 v[184:187], v152 offset:4096
	ds_read_b128 v[204:207], v152 offset:5120
	ds_read_b128 v[208:211], v152 offset:6144
	ds_read_b128 v[212:215], v152 offset:7168
	global_load_lds_dwordx4 v136, s[24:25]
	s_add_i32 m0, s47, 0xe000
	s_nop 0
	global_load_lds_dwordx4 v138, s[24:25]
	s_waitcnt lgkmcnt(8)
	s_barrier
	s_waitcnt lgkmcnt(0)
	s_waitcnt lgkmcnt(0)
	v_mfma_f32_16x16x32_bf16 v[126:129], v[140:143], v[168:171], v[126:129]
	v_mfma_f32_16x16x32_bf16 v[122:125], v[154:157], v[168:171], v[122:125]
	v_mfma_f32_16x16x32_bf16 v[114:117], v[140:143], v[176:179], v[114:117]
	v_mfma_f32_16x16x32_bf16 v[106:109], v[154:157], v[176:179], v[106:109]
	v_mfma_f32_16x16x32_bf16 v[98:101], v[140:143], v[184:187], v[98:101]
	v_mfma_f32_16x16x32_bf16 v[90:93], v[154:157], v[184:187], v[90:93]
	v_mfma_f32_16x16x32_bf16 v[82:85], v[140:143], v[208:211], v[82:85]
	v_mfma_f32_16x16x32_bf16 v[74:77], v[154:157], v[208:211], v[74:77]
	v_mfma_f32_16x16x32_bf16 v[126:129], v[144:147], v[172:175], v[126:129]
	v_mfma_f32_16x16x32_bf16 v[122:125], v[158:161], v[172:175], v[122:125]
	v_mfma_f32_16x16x32_bf16 v[114:117], v[144:147], v[180:183], v[114:117]
	v_mfma_f32_16x16x32_bf16 v[106:109], v[158:161], v[180:183], v[106:109]
	v_mfma_f32_16x16x32_bf16 v[98:101], v[144:147], v[204:207], v[98:101]
	v_mfma_f32_16x16x32_bf16 v[90:93], v[158:161], v[204:207], v[90:93]
	v_mfma_f32_16x16x32_bf16 v[82:85], v[144:147], v[212:215], v[82:85]
	v_mfma_f32_16x16x32_bf16 v[74:77], v[158:161], v[212:215], v[74:77]
	s_barrier
	s_add_i32 s70, 0, 0x14000
	s_add_i32 s58, s58, s44
	v_add_u32_e32 v153, s70, v149
	s_mov_b32 m0, s58
	ds_read_b128 v[216:219], v153
	ds_read_b128 v[226:229], v153 offset:1024
	ds_read_b128 v[230:233], v153 offset:2048
	ds_read_b128 v[234:237], v153 offset:3072
	global_load_lds_dwordx4 v0, s[6:7]
	s_add_i32 m0, s58, 0x2000
	s_nop 0
	global_load_lds_dwordx4 v130, s[6:7]
	s_barrier
	s_waitcnt lgkmcnt(0)
	s_waitcnt lgkmcnt(0)
	v_mfma_f32_16x16x32_bf16 v[118:121], v[216:219], v[168:171], v[118:121]
	v_mfma_f32_16x16x32_bf16 v[110:113], v[230:233], v[168:171], v[110:113]
	v_mfma_f32_16x16x32_bf16 v[102:105], v[216:219], v[176:179], v[102:105]
	v_mfma_f32_16x16x32_bf16 v[94:97], v[230:233], v[176:179], v[94:97]
	v_mfma_f32_16x16x32_bf16 v[86:89], v[216:219], v[184:187], v[86:89]
	v_mfma_f32_16x16x32_bf16 v[78:81], v[230:233], v[184:187], v[78:81]
	v_mfma_f32_16x16x32_bf16 v[70:73], v[216:219], v[208:211], v[70:73]
	v_mfma_f32_16x16x32_bf16 v[66:69], v[230:233], v[208:211], v[66:69]
	v_mfma_f32_16x16x32_bf16 v[118:121], v[226:229], v[172:175], v[118:121]
	v_mfma_f32_16x16x32_bf16 v[110:113], v[234:237], v[172:175], v[110:113]
	v_mfma_f32_16x16x32_bf16 v[102:105], v[226:229], v[180:183], v[102:105]
	v_mfma_f32_16x16x32_bf16 v[94:97], v[234:237], v[180:183], v[94:97]
	v_mfma_f32_16x16x32_bf16 v[86:89], v[226:229], v[204:207], v[86:89]
	v_mfma_f32_16x16x32_bf16 v[78:81], v[234:237], v[204:207], v[78:81]
	v_mfma_f32_16x16x32_bf16 v[70:73], v[226:229], v[212:215], v[70:73]
	v_mfma_f32_16x16x32_bf16 v[66:69], v[234:237], v[212:215], v[66:69]
	s_mov_b32 m0, s47
	s_add_u32 vcc_lo, s36, 0x80
	s_addc_u32 vcc_hi, s37, 0
	s_barrier
	ds_read_b128 v[168:171], v152 offset:16384
	ds_read_b128 v[172:175], v152 offset:17408
	ds_read_b128 v[176:179], v152 offset:18432
	ds_read_b128 v[180:183], v152 offset:19456
	ds_read_b128 v[184:187], v152 offset:20480
	ds_read_b128 v[204:207], v152 offset:21504
	ds_read_b128 v[208:211], v152 offset:22528
	ds_read_b128 v[212:215], v152 offset:23552
	global_load_lds_dwordx4 v134, s[36:37]
	s_mov_b32 m0, s48
	s_nop 0
	global_load_lds_dwordx4 v132, s[36:37]
	s_barrier
	s_waitcnt lgkmcnt(0)
	s_waitcnt lgkmcnt(0)
	v_mfma_f32_16x16x32_bf16 v[62:65], v[140:143], v[168:171], v[62:65]
	v_mfma_f32_16x16x32_bf16 v[58:61], v[154:157], v[168:171], v[58:61]
	v_mfma_f32_16x16x32_bf16 v[50:53], v[140:143], v[176:179], v[50:53]
	v_mfma_f32_16x16x32_bf16 v[42:45], v[154:157], v[176:179], v[42:45]
	v_mfma_f32_16x16x32_bf16 v[34:37], v[140:143], v[184:187], v[34:37]
	v_mfma_f32_16x16x32_bf16 v[26:29], v[154:157], v[184:187], v[26:29]
	v_mfma_f32_16x16x32_bf16 v[18:21], v[140:143], v[208:211], v[18:21]
	v_mfma_f32_16x16x32_bf16 v[10:13], v[154:157], v[208:211], v[10:13]
	v_mfma_f32_16x16x32_bf16 v[62:65], v[144:147], v[172:175], v[62:65]
	v_mfma_f32_16x16x32_bf16 v[58:61], v[158:161], v[172:175], v[58:61]
	v_mfma_f32_16x16x32_bf16 v[50:53], v[144:147], v[180:183], v[50:53]
	v_mfma_f32_16x16x32_bf16 v[42:45], v[158:161], v[180:183], v[42:45]
	v_mfma_f32_16x16x32_bf16 v[34:37], v[144:147], v[204:207], v[34:37]
	v_mfma_f32_16x16x32_bf16 v[26:29], v[158:161], v[204:207], v[26:29]
	v_mfma_f32_16x16x32_bf16 v[18:21], v[144:147], v[212:215], v[18:21]
	v_mfma_f32_16x16x32_bf16 v[10:13], v[158:161], v[212:215], v[10:13]
	s_barrier
	s_add_u32 s60, s6, 0x40000
	s_addc_u32 s61, s7, 0
	s_add_i32 s58, s70, s44
	s_mov_b32 m0, s58
	s_nop 0
	global_load_lds_dwordx4 v0, s[60:61]
	s_add_i32 m0, s58, 0x2000
	s_nop 0
	global_load_lds_dwordx4 v130, s[60:61]
	s_waitcnt vmcnt(6)
	s_barrier
; #define PG8_STAGE(bufoff, gbase, voff) do { _Pragma("unroll") for (int _i = 0; _i < 2; ++_i) \
;         __builtin_amdgcn_global_load_lds((const unsigned*)((const char*)(gbase) + (voff)[_i]), (LAS unsigned*)(lds + (bufoff) + ldsw + _i * 8192), 16, 0, 0); } while (0)
; #define PG8_LDA(dst, b, h) do { _Pragma("unroll") for (int m = 0; m < 4; ++m) _Pragma("unroll") for (int k = 0; k < 2; ++k) dst[m][k] = *(const LAS bf16x8*)(lds + PG8_SA(b, h) + aoff + m * 2048 + k * 1024); } while (0)
; #define PG8_LDB(dst, b, h) do { _Pragma("unroll") for (int n = 0; n < 2; ++n) _Pragma("unroll") for (int k = 0; k < 2; ++k) dst[n][k] = *(const LAS bf16x8*)(lds + PG8_SB(b, h) + boff + n * 2048 + k * 1024); } while (0)
; #define PG8_WAIT_V(n) asm volatile("s_waitcnt vmcnt(" #n ")" ::: "memory")
; #define PG8_WAIT_L(n) asm volatile("s_waitcnt lgkmcnt(" #n ")" ::: "memory")
; #define PG8_BAR __builtin_amdgcn_s_barrier()
; #define PG8_SCHED __builtin_amdgcn_sched_barrier(0)
; template <class Epi>
; __device__ __forceinline__ void gemm_phase(LAS unsigned char* lds, const Gemm g, const StaticOrder& S, const Epi& E) {
;     ...
;             PG8_LDB(B0, 0, 0); PG8_SCHED; PG8_LDA(At, 0, 0); PG8_STAGE(PG8_SA(1, 1), a1 + hstep, voffA);
;             PG8_WAIT_L(8); PG8_BAR; PG8_WAIT_L(0); PG8_MMA(0, 0, At, B0); PG8_BAR; PG8_SCHED;
;             PG8_LDB(B1, 0, 1); PG8_STAGE(PG8_SB(0, 0), b2, voffB);
;             PG8_BAR; PG8_WAIT_L(0); PG8_MMA(0, 1, At, B1); PG8_BAR;
;             PG8_LDA(At, 0, 1); PG8_STAGE(PG8_SA(0, 0), a2, voffA);
;             PG8_BAR; PG8_WAIT_L(0); PG8_MMA(1, 0, At, B0); PG8_BAR; PG8_SCHED;
;             PG8_STAGE(PG8_SB(0, 1), b2 + hstep, voffB);
;             PG8_WAIT_V(6); PG8_BAR; PG8_MMA(1, 1, At, B1); PG8_BAR;
;             PG8_LDB(B0, 1, 0); PG8_SCHED; PG8_LDA(At, 1, 0); PG8_STAGE(PG8_SA(0, 1), a2 + hstep, voffA);
;             PG8_WAIT_L(8); PG8_BAR; PG8_WAIT_L(0); PG8_MMA(0, 0, At, B0); PG8_BAR; PG8_SCHED;
;             PG8_LDB(B1, 1, 1); PG8_STAGE(PG8_SB(1, 0), b3, voffB);
;             PG8_BAR; PG8_WAIT_L(0); PG8_MMA(0, 1, At, B1); PG8_BAR;
;             PG8_LDA(At, 1, 1); PG8_STAGE(PG8_SA(1, 0), a3, voffA);
;             PG8_BAR; PG8_WAIT_L(0); PG8_MMA(1, 0, At, B0); PG8_BAR; PG8_SCHED;
;             PG8_STAGE(PG8_SB(1, 1), b3 + hstep, voffB);
;             PG8_WAIT_V(6); PG8_BAR; PG8_MMA(1, 1, At, B1); PG8_BAR;
	v_mfma_f32_16x16x32_bf16 v[54:57], v[216:219], v[168:171], v[54:57]
	v_mfma_f32_16x16x32_bf16 v[46:49], v[230:233], v[168:171], v[46:49]
	v_mfma_f32_16x16x32_bf16 v[38:41], v[216:219], v[176:179], v[38:41]
	v_mfma_f32_16x16x32_bf16 v[30:33], v[230:233], v[176:179], v[30:33]
	v_mfma_f32_16x16x32_bf16 v[22:25], v[216:219], v[184:187], v[22:25]
	v_mfma_f32_16x16x32_bf16 v[14:17], v[230:233], v[184:187], v[14:17]
	v_mfma_f32_16x16x32_bf16 v[6:9], v[216:219], v[208:211], v[6:9]
	v_mfma_f32_16x16x32_bf16 v[2:5], v[230:233], v[208:211], v[2:5]
	v_mfma_f32_16x16x32_bf16 v[54:57], v[226:229], v[172:175], v[54:57]
	v_mfma_f32_16x16x32_bf16 v[46:49], v[234:237], v[172:175], v[46:49]
	v_mfma_f32_16x16x32_bf16 v[38:41], v[226:229], v[180:183], v[38:41]
	v_mfma_f32_16x16x32_bf16 v[30:33], v[234:237], v[180:183], v[30:33]
	v_mfma_f32_16x16x32_bf16 v[22:25], v[226:229], v[204:207], v[22:25]
	v_mfma_f32_16x16x32_bf16 v[14:17], v[234:237], v[204:207], v[14:17]
	v_mfma_f32_16x16x32_bf16 v[6:9], v[226:229], v[212:215], v[6:9]
	v_mfma_f32_16x16x32_bf16 v[2:5], v[234:237], v[212:215], v[2:5]
	s_add_i32 s58, 0, 0x18000
	v_add_u32_e32 v153, s58, v149
	s_barrier
	ds_read_b128 v[140:143], v153
	ds_read_b128 v[144:147], v153 offset:1024
	ds_read_b128 v[154:157], v153 offset:2048
	ds_read_b128 v[158:161], v153 offset:3072
	s_add_u32 s36, s36, 0x40000
	s_addc_u32 s37, s37, 0
	s_mov_b32 m0, s49
	ds_read_b128 v[168:171], v152 offset:32768
	ds_read_b128 v[172:175], v152 offset:33792
	ds_read_b128 v[176:179], v152 offset:34816
	ds_read_b128 v[180:183], v152 offset:35840
	ds_read_b128 v[184:187], v152 offset:36864
	ds_read_b128 v[204:207], v152 offset:37888
	ds_read_b128 v[208:211], v152 offset:38912
	ds_read_b128 v[212:215], v152 offset:39936
	global_load_lds_dwordx4 v134, s[36:37]
	s_mov_b32 m0, s54
	s_nop 0
	global_load_lds_dwordx4 v132, s[36:37]
	s_waitcnt lgkmcnt(8)
	s_barrier
	s_waitcnt lgkmcnt(0)
	s_waitcnt lgkmcnt(0)
	v_mfma_f32_16x16x32_bf16 v[126:129], v[140:143], v[168:171], v[126:129]
	v_mfma_f32_16x16x32_bf16 v[122:125], v[154:157], v[168:171], v[122:125]
	s_cmp_eq_u32 s87, 0
	s_cbranch_scc1 .LdsA_skip_4
	global_store_dwordx4 v166, v[200:203], s[4:5]
.LdsA_skip_4:
	v_mfma_f32_16x16x32_bf16 v[114:117], v[140:143], v[176:179], v[114:117]
	v_mfma_f32_16x16x32_bf16 v[106:109], v[154:157], v[176:179], v[106:109]
	v_mfma_f32_16x16x32_bf16 v[98:101], v[140:143], v[184:187], v[98:101]
	v_mfma_f32_16x16x32_bf16 v[90:93], v[154:157], v[184:187], v[90:93]
	v_mfma_f32_16x16x32_bf16 v[82:85], v[140:143], v[208:211], v[82:85]
	v_mfma_f32_16x16x32_bf16 v[74:77], v[154:157], v[208:211], v[74:77]
	v_mfma_f32_16x16x32_bf16 v[126:129], v[144:147], v[172:175], v[126:129]
	v_mfma_f32_16x16x32_bf16 v[122:125], v[158:161], v[172:175], v[122:125]
	v_mfma_f32_16x16x32_bf16 v[114:117], v[144:147], v[180:183], v[114:117]
	v_mfma_f32_16x16x32_bf16 v[106:109], v[158:161], v[180:183], v[106:109]
	v_mfma_f32_16x16x32_bf16 v[98:101], v[144:147], v[204:207], v[98:101]
	v_mfma_f32_16x16x32_bf16 v[90:93], v[158:161], v[204:207], v[90:93]
	v_mfma_f32_16x16x32_bf16 v[82:85], v[144:147], v[212:215], v[82:85]
	v_mfma_f32_16x16x32_bf16 v[74:77], v[158:161], v[212:215], v[74:77]
	s_barrier
	s_add_i32 s36, 0, 0x1c000
	s_add_i32 s37, s58, s44
	v_add_u32_e32 v153, s36, v149
	s_add_u32 s60, s6, 0x80
	s_addc_u32 s61, s7, 0
	s_mov_b32 m0, s37
	ds_read_b128 v[216:219], v153
	ds_read_b128 v[226:229], v153 offset:1024
	ds_read_b128 v[230:233], v153 offset:2048
	ds_read_b128 v[234:237], v153 offset:3072
	global_load_lds_dwordx4 v0, s[60:61]
	s_add_i32 m0, s37, 0x2000
	s_nop 0
	global_load_lds_dwordx4 v130, s[60:61]
	s_barrier
	s_waitcnt lgkmcnt(0)
	s_waitcnt lgkmcnt(0)
	v_mfma_f32_16x16x32_bf16 v[118:121], v[216:219], v[168:171], v[118:121]
	v_mfma_f32_16x16x32_bf16 v[110:113], v[230:233], v[168:171], v[110:113]
	v_mfma_f32_16x16x32_bf16 v[102:105], v[216:219], v[176:179], v[102:105]
	v_mfma_f32_16x16x32_bf16 v[94:97], v[230:233], v[176:179], v[94:97]
	v_mfma_f32_16x16x32_bf16 v[86:89], v[216:219], v[184:187], v[86:89]
	v_mfma_f32_16x16x32_bf16 v[78:81], v[230:233], v[184:187], v[78:81]
	v_mfma_f32_16x16x32_bf16 v[70:73], v[216:219], v[208:211], v[70:73]
	v_mfma_f32_16x16x32_bf16 v[66:69], v[230:233], v[208:211], v[66:69]
	v_mfma_f32_16x16x32_bf16 v[118:121], v[226:229], v[172:175], v[118:121]
	v_mfma_f32_16x16x32_bf16 v[110:113], v[234:237], v[172:175], v[110:113]
	v_mfma_f32_16x16x32_bf16 v[102:105], v[226:229], v[180:183], v[102:105]
	v_mfma_f32_16x16x32_bf16 v[94:97], v[234:237], v[180:183], v[94:97]
	v_mfma_f32_16x16x32_bf16 v[86:89], v[226:229], v[204:207], v[86:89]
	v_mfma_f32_16x16x32_bf16 v[78:81], v[234:237], v[204:207], v[78:81]
	v_mfma_f32_16x16x32_bf16 v[70:73], v[226:229], v[212:215], v[70:73]
	v_mfma_f32_16x16x32_bf16 v[66:69], v[234:237], v[212:215], v[66:69]
	s_mov_b32 m0, s55
	s_barrier
	ds_read_b128 v[168:171], v152 offset:49152
	ds_read_b128 v[172:175], v152 offset:50176
	ds_read_b128 v[176:179], v152 offset:51200
	ds_read_b128 v[180:183], v152 offset:52224
	ds_read_b128 v[184:187], v152 offset:53248
	ds_read_b128 v[204:207], v152 offset:54272
	ds_read_b128 v[208:211], v152 offset:55296
	ds_read_b128 v[212:215], v152 offset:56320
	global_load_lds_dwordx4 v134, vcc
	s_mov_b32 m0, s83
	s_nop 0
	global_load_lds_dwordx4 v132, vcc
	s_barrier
; #define PG8_STAGE(bufoff, gbase, voff) do { _Pragma("unroll") for (int _i = 0; _i < 2; ++_i) \
;         __builtin_amdgcn_global_load_lds((const unsigned*)((const char*)(gbase) + (voff)[_i]), (LAS unsigned*)(lds + (bufoff) + ldsw + _i * 8192), 16, 0, 0); } while (0)
; #define PG8_LDA(dst, b, h) do { _Pragma("unroll") for (int m = 0; m < 4; ++m) _Pragma("unroll") for (int k = 0; k < 2; ++k) dst[m][k] = *(const LAS bf16x8*)(lds + PG8_SA(b, h) + aoff + m * 2048 + k * 1024); } while (0)
; #define PG8_LDB(dst, b, h) do { _Pragma("unroll") for (int n = 0; n < 2; ++n) _Pragma("unroll") for (int k = 0; k < 2; ++k) dst[n][k] = *(const LAS bf16x8*)(lds + PG8_SB(b, h) + boff + n * 2048 + k * 1024); } while (0)
; #define PG8_WAIT_V(n) asm volatile("s_waitcnt vmcnt(" #n ")" ::: "memory")
; #define PG8_WAIT_L(n) asm volatile("s_waitcnt lgkmcnt(" #n ")" ::: "memory")
; #define PG8_BAR __builtin_amdgcn_s_barrier()
; #define PG8_SCHED __builtin_amdgcn_sched_barrier(0)
; template <class Epi>
; __device__ __forceinline__ void gemm_phase(LAS unsigned char* lds, const Gemm g, const StaticOrder& S, const Epi& E) {
;     ...
;             PG8_LDB(B0, 0, 0); PG8_SCHED; PG8_LDA(At, 0, 0); PG8_STAGE(PG8_SA(1, 1), a1 + hstep, voffA);
;             PG8_WAIT_L(8); PG8_BAR; PG8_WAIT_L(0); PG8_MMA(0, 0, At, B0); PG8_BAR; PG8_SCHED;
;             PG8_LDB(B1, 0, 1); PG8_STAGE(PG8_SB(0, 0), b2, voffB);
;             PG8_BAR; PG8_WAIT_L(0); PG8_MMA(0, 1, At, B1); PG8_BAR;
;             PG8_LDA(At, 0, 1); PG8_STAGE(PG8_SA(0, 0), a2, voffA);
;             PG8_BAR; PG8_WAIT_L(0); PG8_MMA(1, 0, At, B0); PG8_BAR; PG8_SCHED;
;             PG8_STAGE(PG8_SB(0, 1), b2 + hstep, voffB);
;             PG8_WAIT_V(6); PG8_BAR; PG8_MMA(1, 1, At, B1); PG8_BAR;
;             PG8_LDB(B0, 1, 0); PG8_SCHED; PG8_LDA(At, 1, 0); PG8_STAGE(PG8_SA(0, 1), a2 + hstep, voffA);
;             PG8_WAIT_L(8); PG8_BAR; PG8_WAIT_L(0); PG8_MMA(0, 0, At, B0); PG8_BAR; PG8_SCHED;
;             PG8_LDB(B1, 1, 1); PG8_STAGE(PG8_SB(1, 0), b3, voffB);
;             PG8_BAR; PG8_WAIT_L(0); PG8_MMA(0, 1, At, B1); PG8_BAR;
;             PG8_LDA(At, 1, 1); PG8_STAGE(PG8_SA(1, 0), a3, voffA);
;             PG8_BAR; PG8_WAIT_L(0); PG8_MMA(1, 0, At, B0); PG8_BAR; PG8_SCHED;
;             PG8_STAGE(PG8_SB(1, 1), b3 + hstep, voffB);
;             PG8_WAIT_V(6); PG8_BAR; PG8_MMA(1, 1, At, B1); PG8_BAR;
	s_waitcnt lgkmcnt(0)
	s_waitcnt lgkmcnt(0)
	v_mfma_f32_16x16x32_bf16 v[62:65], v[140:143], v[168:171], v[62:65]
	v_mfma_f32_16x16x32_bf16 v[58:61], v[154:157], v[168:171], v[58:61]
	v_mfma_f32_16x16x32_bf16 v[50:53], v[140:143], v[176:179], v[50:53]
	v_mfma_f32_16x16x32_bf16 v[42:45], v[154:157], v[176:179], v[42:45]
	v_mfma_f32_16x16x32_bf16 v[34:37], v[140:143], v[184:187], v[34:37]
	v_mfma_f32_16x16x32_bf16 v[26:29], v[154:157], v[184:187], v[26:29]
	v_mfma_f32_16x16x32_bf16 v[18:21], v[140:143], v[208:211], v[18:21]
	v_mfma_f32_16x16x32_bf16 v[10:13], v[154:157], v[208:211], v[10:13]
	v_mfma_f32_16x16x32_bf16 v[62:65], v[144:147], v[172:175], v[62:65]
	v_mfma_f32_16x16x32_bf16 v[58:61], v[158:161], v[172:175], v[58:61]
	v_mfma_f32_16x16x32_bf16 v[50:53], v[144:147], v[180:183], v[50:53]
	v_mfma_f32_16x16x32_bf16 v[42:45], v[158:161], v[180:183], v[42:45]
	v_mfma_f32_16x16x32_bf16 v[34:37], v[144:147], v[204:207], v[34:37]
	v_mfma_f32_16x16x32_bf16 v[26:29], v[158:161], v[204:207], v[26:29]
	v_mfma_f32_16x16x32_bf16 v[18:21], v[144:147], v[212:215], v[18:21]
	v_mfma_f32_16x16x32_bf16 v[10:13], v[158:161], v[212:215], v[10:13]
	s_barrier
	s_add_u32 s6, s6, 0x40080
	s_addc_u32 s7, s7, 0
	s_add_i32 s36, s36, s44
	s_mov_b32 m0, s36
	s_nop 0
	global_load_lds_dwordx4 v0, s[6:7]
	s_add_i32 m0, s36, 0x2000
	s_nop 0
	global_load_lds_dwordx4 v130, s[6:7]
	s_waitcnt vmcnt(6)
	s_barrier
	v_mfma_f32_16x16x32_bf16 v[54:57], v[216:219], v[168:171], v[54:57]
	v_mfma_f32_16x16x32_bf16 v[46:49], v[230:233], v[168:171], v[46:49]
	v_mfma_f32_16x16x32_bf16 v[38:41], v[216:219], v[176:179], v[38:41]
	v_mfma_f32_16x16x32_bf16 v[30:33], v[230:233], v[176:179], v[30:33]
	v_mfma_f32_16x16x32_bf16 v[22:25], v[216:219], v[184:187], v[22:25]
	v_mfma_f32_16x16x32_bf16 v[14:17], v[230:233], v[184:187], v[14:17]
	v_mfma_f32_16x16x32_bf16 v[6:9], v[216:219], v[208:211], v[6:9]
	v_mfma_f32_16x16x32_bf16 v[2:5], v[230:233], v[208:211], v[2:5]
	v_mfma_f32_16x16x32_bf16 v[54:57], v[226:229], v[172:175], v[54:57]
	v_mfma_f32_16x16x32_bf16 v[46:49], v[234:237], v[172:175], v[46:49]
	v_mfma_f32_16x16x32_bf16 v[38:41], v[226:229], v[180:183], v[38:41]
	v_mfma_f32_16x16x32_bf16 v[30:33], v[234:237], v[180:183], v[30:33]
	v_mfma_f32_16x16x32_bf16 v[22:25], v[226:229], v[204:207], v[22:25]
	v_mfma_f32_16x16x32_bf16 v[14:17], v[234:237], v[204:207], v[14:17]
	v_mfma_f32_16x16x32_bf16 v[6:9], v[226:229], v[212:215], v[6:9]
	v_mfma_f32_16x16x32_bf16 v[2:5], v[234:237], v[212:215], v[2:5]
	s_add_i32 s91, s91, 2
	s_add_u32 s24, s24, 0x100
	s_addc_u32 s25, s25, 0
	s_add_u32 s89, s89, 0x100
	s_addc_u32 s90, s90, 0
	s_cmp_gt_u32 s91, 13
	s_barrier
	s_add_u32 s6, s24, 0xfffc0080
	s_addc_u32 s7, s25, -1
	s_add_i32 s58, 0, 0x10000
	v_add_u32_e32 v153, s58, v149
	ds_read_b128 v[140:143], v153
	ds_read_b128 v[144:147], v153 offset:1024
	ds_read_b128 v[154:157], v153 offset:2048
	ds_read_b128 v[158:161], v153 offset:3072
	s_cmp_eq_u32 s91, 12
	s_cselect_b32 s37, s11, s7
	s_cselect_b32 s36, s71, s6
	s_cselect_b32 s7, s9, s90
	s_cselect_b32 s6, s88, s89
	s_add_i32 m0, s47, 0xc000
	ds_read_b128 v[168:171], v152
	ds_read_b128 v[172:175], v152 offset:1024
	ds_read_b128 v[176:179], v152 offset:2048
	ds_read_b128 v[180:183], v152 offset:3072
	ds_read_b128 v[184:187], v152 offset:4096
	ds_read_b128 v[204:207], v152 offset:5120
	ds_read_b128 v[208:211], v152 offset:6144
	ds_read_b128 v[212:215], v152 offset:7168
	global_load_lds_dwordx4 v136, s[24:25]
	s_add_i32 m0, s47, 0xe000
	s_nop 0
	global_load_lds_dwordx4 v138, s[24:25]
	s_waitcnt lgkmcnt(8)
	s_barrier
	s_waitcnt lgkmcnt(0)
	s_waitcnt lgkmcnt(0)
	v_mfma_f32_16x16x32_bf16 v[126:129], v[140:143], v[168:171], v[126:129]
	v_mfma_f32_16x16x32_bf16 v[122:125], v[154:157], v[168:171], v[122:125]
	v_mfma_f32_16x16x32_bf16 v[114:117], v[140:143], v[176:179], v[114:117]
	v_mfma_f32_16x16x32_bf16 v[106:109], v[154:157], v[176:179], v[106:109]
	v_mfma_f32_16x16x32_bf16 v[98:101], v[140:143], v[184:187], v[98:101]
	v_mfma_f32_16x16x32_bf16 v[90:93], v[154:157], v[184:187], v[90:93]
	v_mfma_f32_16x16x32_bf16 v[82:85], v[140:143], v[208:211], v[82:85]
	v_mfma_f32_16x16x32_bf16 v[74:77], v[154:157], v[208:211], v[74:77]
	v_mfma_f32_16x16x32_bf16 v[126:129], v[144:147], v[172:175], v[126:129]
	v_mfma_f32_16x16x32_bf16 v[122:125], v[158:161], v[172:175], v[122:125]
	v_mfma_f32_16x16x32_bf16 v[114:117], v[144:147], v[180:183], v[114:117]
	v_mfma_f32_16x16x32_bf16 v[106:109], v[158:161], v[180:183], v[106:109]
	v_mfma_f32_16x16x32_bf16 v[98:101], v[144:147], v[204:207], v[98:101]
	v_mfma_f32_16x16x32_bf16 v[90:93], v[158:161], v[204:207], v[90:93]
	v_mfma_f32_16x16x32_bf16 v[82:85], v[144:147], v[212:215], v[82:85]
	v_mfma_f32_16x16x32_bf16 v[74:77], v[158:161], v[212:215], v[74:77]
	s_barrier
	s_add_i32 s70, 0, 0x14000
	s_add_i32 s58, s58, s44
	v_add_u32_e32 v153, s70, v149
	s_mov_b32 m0, s58
	ds_read_b128 v[216:219], v153
	ds_read_b128 v[226:229], v153 offset:1024
	ds_read_b128 v[230:233], v153 offset:2048
	ds_read_b128 v[234:237], v153 offset:3072
	global_load_lds_dwordx4 v0, s[6:7]
	s_add_i32 m0, s58, 0x2000
	s_nop 0
	global_load_lds_dwordx4 v130, s[6:7]
	s_barrier
; #define PG8_STAGE(bufoff, gbase, voff) do { _Pragma("unroll") for (int _i = 0; _i < 2; ++_i) \
;         __builtin_amdgcn_global_load_lds((const unsigned*)((const char*)(gbase) + (voff)[_i]), (LAS unsigned*)(lds + (bufoff) + ldsw + _i * 8192), 16, 0, 0); } while (0)
; #define PG8_LDA(dst, b, h) do { _Pragma("unroll") for (int m = 0; m < 4; ++m) _Pragma("unroll") for (int k = 0; k < 2; ++k) dst[m][k] = *(const LAS bf16x8*)(lds + PG8_SA(b, h) + aoff + m * 2048 + k * 1024); } while (0)
; #define PG8_LDB(dst, b, h) do { _Pragma("unroll") for (int n = 0; n < 2; ++n) _Pragma("unroll") for (int k = 0; k < 2; ++k) dst[n][k] = *(const LAS bf16x8*)(lds + PG8_SB(b, h) + boff + n * 2048 + k * 1024); } while (0)
; #define PG8_WAIT_V(n) asm volatile("s_waitcnt vmcnt(" #n ")" ::: "memory")
; #define PG8_WAIT_L(n) asm volatile("s_waitcnt lgkmcnt(" #n ")" ::: "memory")
; #define PG8_BAR __builtin_amdgcn_s_barrier()
; #define PG8_SCHED __builtin_amdgcn_sched_barrier(0)
; template <class Epi>
; __device__ __forceinline__ void gemm_phase(LAS unsigned char* lds, const Gemm g, const StaticOrder& S, const Epi& E) {
;     ...
;             PG8_LDB(B0, 0, 0); PG8_SCHED; PG8_LDA(At, 0, 0); PG8_STAGE(PG8_SA(1, 1), a1 + hstep, voffA);
;             PG8_WAIT_L(8); PG8_BAR; PG8_WAIT_L(0); PG8_MMA(0, 0, At, B0); PG8_BAR; PG8_SCHED;
;             PG8_LDB(B1, 0, 1); PG8_STAGE(PG8_SB(0, 0), b2, voffB);
;             PG8_BAR; PG8_WAIT_L(0); PG8_MMA(0, 1, At, B1); PG8_BAR;
;             PG8_LDA(At, 0, 1); PG8_STAGE(PG8_SA(0, 0), a2, voffA);
;             PG8_BAR; PG8_WAIT_L(0); PG8_MMA(1, 0, At, B0); PG8_BAR; PG8_SCHED;
;             PG8_STAGE(PG8_SB(0, 1), b2 + hstep, voffB);
;             PG8_WAIT_V(6); PG8_BAR; PG8_MMA(1, 1, At, B1); PG8_BAR;
;             PG8_LDB(B0, 1, 0); PG8_SCHED; PG8_LDA(At, 1, 0); PG8_STAGE(PG8_SA(0, 1), a2 + hstep, voffA);
;             PG8_WAIT_L(8); PG8_BAR; PG8_WAIT_L(0); PG8_MMA(0, 0, At, B0); PG8_BAR; PG8_SCHED;
;             PG8_LDB(B1, 1, 1); PG8_STAGE(PG8_SB(1, 0), b3, voffB);
;             PG8_BAR; PG8_WAIT_L(0); PG8_MMA(0, 1, At, B1); PG8_BAR;
;             PG8_LDA(At, 1, 1); PG8_STAGE(PG8_SA(1, 0), a3, voffA);
;             PG8_BAR; PG8_WAIT_L(0); PG8_MMA(1, 0, At, B0); PG8_BAR; PG8_SCHED;
;             PG8_STAGE(PG8_SB(1, 1), b3 + hstep, voffB);
;             PG8_WAIT_V(6); PG8_BAR; PG8_MMA(1, 1, At, B1); PG8_BAR;
	s_waitcnt lgkmcnt(0)
	s_waitcnt lgkmcnt(0)
	v_mfma_f32_16x16x32_bf16 v[118:121], v[216:219], v[168:171], v[118:121]
	v_mfma_f32_16x16x32_bf16 v[110:113], v[230:233], v[168:171], v[110:113]
	v_mfma_f32_16x16x32_bf16 v[102:105], v[216:219], v[176:179], v[102:105]
	v_mfma_f32_16x16x32_bf16 v[94:97], v[230:233], v[176:179], v[94:97]
	v_mfma_f32_16x16x32_bf16 v[86:89], v[216:219], v[184:187], v[86:89]
	v_mfma_f32_16x16x32_bf16 v[78:81], v[230:233], v[184:187], v[78:81]
	v_mfma_f32_16x16x32_bf16 v[70:73], v[216:219], v[208:211], v[70:73]
	v_mfma_f32_16x16x32_bf16 v[66:69], v[230:233], v[208:211], v[66:69]
	v_mfma_f32_16x16x32_bf16 v[118:121], v[226:229], v[172:175], v[118:121]
	v_mfma_f32_16x16x32_bf16 v[110:113], v[234:237], v[172:175], v[110:113]
	v_mfma_f32_16x16x32_bf16 v[102:105], v[226:229], v[180:183], v[102:105]
	v_mfma_f32_16x16x32_bf16 v[94:97], v[234:237], v[180:183], v[94:97]
	v_mfma_f32_16x16x32_bf16 v[86:89], v[226:229], v[204:207], v[86:89]
	v_mfma_f32_16x16x32_bf16 v[78:81], v[234:237], v[204:207], v[78:81]
	v_mfma_f32_16x16x32_bf16 v[70:73], v[226:229], v[212:215], v[70:73]
	v_mfma_f32_16x16x32_bf16 v[66:69], v[234:237], v[212:215], v[66:69]
	s_mov_b32 m0, s47
	s_add_u32 vcc_lo, s36, 0x80
	s_addc_u32 vcc_hi, s37, 0
	s_barrier
	ds_read_b128 v[168:171], v152 offset:16384
	ds_read_b128 v[172:175], v152 offset:17408
	ds_read_b128 v[176:179], v152 offset:18432
	ds_read_b128 v[180:183], v152 offset:19456
	ds_read_b128 v[184:187], v152 offset:20480
	ds_read_b128 v[204:207], v152 offset:21504
	ds_read_b128 v[208:211], v152 offset:22528
	ds_read_b128 v[212:215], v152 offset:23552
	global_load_lds_dwordx4 v134, s[36:37]
	s_mov_b32 m0, s48
	s_nop 0
	global_load_lds_dwordx4 v132, s[36:37]
	s_barrier
	s_waitcnt lgkmcnt(0)
	s_waitcnt lgkmcnt(0)
	v_mfma_f32_16x16x32_bf16 v[62:65], v[140:143], v[168:171], v[62:65]
	v_mfma_f32_16x16x32_bf16 v[58:61], v[154:157], v[168:171], v[58:61]
	v_mfma_f32_16x16x32_bf16 v[50:53], v[140:143], v[176:179], v[50:53]
	v_mfma_f32_16x16x32_bf16 v[42:45], v[154:157], v[176:179], v[42:45]
	v_mfma_f32_16x16x32_bf16 v[34:37], v[140:143], v[184:187], v[34:37]
	v_mfma_f32_16x16x32_bf16 v[26:29], v[154:157], v[184:187], v[26:29]
	v_mfma_f32_16x16x32_bf16 v[18:21], v[140:143], v[208:211], v[18:21]
	v_mfma_f32_16x16x32_bf16 v[10:13], v[154:157], v[208:211], v[10:13]
	v_mfma_f32_16x16x32_bf16 v[62:65], v[144:147], v[172:175], v[62:65]
	v_mfma_f32_16x16x32_bf16 v[58:61], v[158:161], v[172:175], v[58:61]
	v_mfma_f32_16x16x32_bf16 v[50:53], v[144:147], v[180:183], v[50:53]
	v_mfma_f32_16x16x32_bf16 v[42:45], v[158:161], v[180:183], v[42:45]
	v_mfma_f32_16x16x32_bf16 v[34:37], v[144:147], v[204:207], v[34:37]
	v_mfma_f32_16x16x32_bf16 v[26:29], v[158:161], v[204:207], v[26:29]
	v_mfma_f32_16x16x32_bf16 v[18:21], v[144:147], v[212:215], v[18:21]
	v_mfma_f32_16x16x32_bf16 v[10:13], v[158:161], v[212:215], v[10:13]
	s_barrier
	s_add_u32 s60, s6, 0x40000
	s_addc_u32 s61, s7, 0
	s_add_i32 s58, s70, s44
	s_mov_b32 m0, s58
	s_nop 0
	global_load_lds_dwordx4 v0, s[60:61]
	s_add_i32 m0, s58, 0x2000
	s_nop 0
	global_load_lds_dwordx4 v130, s[60:61]
	s_waitcnt vmcnt(6)
	s_barrier
	v_mfma_f32_16x16x32_bf16 v[54:57], v[216:219], v[168:171], v[54:57]
	v_mfma_f32_16x16x32_bf16 v[46:49], v[230:233], v[168:171], v[46:49]
	v_mfma_f32_16x16x32_bf16 v[38:41], v[216:219], v[176:179], v[38:41]
	v_mfma_f32_16x16x32_bf16 v[30:33], v[230:233], v[176:179], v[30:33]
	v_mfma_f32_16x16x32_bf16 v[22:25], v[216:219], v[184:187], v[22:25]
	v_mfma_f32_16x16x32_bf16 v[14:17], v[230:233], v[184:187], v[14:17]
	v_mfma_f32_16x16x32_bf16 v[6:9], v[216:219], v[208:211], v[6:9]
	v_mfma_f32_16x16x32_bf16 v[2:5], v[230:233], v[208:211], v[2:5]
	v_mfma_f32_16x16x32_bf16 v[54:57], v[226:229], v[172:175], v[54:57]
	v_mfma_f32_16x16x32_bf16 v[46:49], v[234:237], v[172:175], v[46:49]
	v_mfma_f32_16x16x32_bf16 v[38:41], v[226:229], v[180:183], v[38:41]
	v_mfma_f32_16x16x32_bf16 v[30:33], v[234:237], v[180:183], v[30:33]
	v_mfma_f32_16x16x32_bf16 v[22:25], v[226:229], v[204:207], v[22:25]
	v_mfma_f32_16x16x32_bf16 v[14:17], v[234:237], v[204:207], v[14:17]
	v_mfma_f32_16x16x32_bf16 v[6:9], v[226:229], v[212:215], v[6:9]
	v_mfma_f32_16x16x32_bf16 v[2:5], v[234:237], v[212:215], v[2:5]
	s_add_i32 s58, 0, 0x18000
	v_add_u32_e32 v153, s58, v149
	s_barrier
	ds_read_b128 v[140:143], v153
	ds_read_b128 v[144:147], v153 offset:1024
	ds_read_b128 v[154:157], v153 offset:2048
	ds_read_b128 v[158:161], v153 offset:3072
	s_add_u32 s36, s36, 0x40000
	s_addc_u32 s37, s37, 0
	s_mov_b32 m0, s49
	ds_read_b128 v[168:171], v152 offset:32768
	ds_read_b128 v[172:175], v152 offset:33792
	ds_read_b128 v[176:179], v152 offset:34816
	ds_read_b128 v[180:183], v152 offset:35840
	ds_read_b128 v[184:187], v152 offset:36864
	ds_read_b128 v[204:207], v152 offset:37888
	ds_read_b128 v[208:211], v152 offset:38912
	ds_read_b128 v[212:215], v152 offset:39936
	global_load_lds_dwordx4 v134, s[36:37]
	s_mov_b32 m0, s54
	s_nop 0
	global_load_lds_dwordx4 v132, s[36:37]
	s_waitcnt lgkmcnt(8)
	s_barrier
	s_waitcnt lgkmcnt(0)
	s_waitcnt lgkmcnt(0)
	v_mfma_f32_16x16x32_bf16 v[126:129], v[140:143], v[168:171], v[126:129]
	v_mfma_f32_16x16x32_bf16 v[122:125], v[154:157], v[168:171], v[122:125]
	s_cmp_eq_u32 s87, 0
	s_cbranch_scc1 .LdsA_skip_5
	global_store_dwordx4 v166, v[222:225], s[4:5] offset:256
	s_nop 1
	v_add_u32_e32 v166, 0xe000, v166
; #define PG8_STAGE(bufoff, gbase, voff) do { _Pragma("unroll") for (int _i = 0; _i < 2; ++_i) \
;         __builtin_amdgcn_global_load_lds((const unsigned*)((const char*)(gbase) + (voff)[_i]), (LAS unsigned*)(lds + (bufoff) + ldsw + _i * 8192), 16, 0, 0); } while (0)
; #define PG8_LDA(dst, b, h) do { _Pragma("unroll") for (int m = 0; m < 4; ++m) _Pragma("unroll") for (int k = 0; k < 2; ++k) dst[m][k] = *(const LAS bf16x8*)(lds + PG8_SA(b, h) + aoff + m * 2048 + k * 1024); } while (0)
; #define PG8_LDB(dst, b, h) do { _Pragma("unroll") for (int n = 0; n < 2; ++n) _Pragma("unroll") for (int k = 0; k < 2; ++k) dst[n][k] = *(const LAS bf16x8*)(lds + PG8_SB(b, h) + boff + n * 2048 + k * 1024); } while (0)
; #define PG8_WAIT_V(n) asm volatile("s_waitcnt vmcnt(" #n ")" ::: "memory")
; #define PG8_WAIT_L(n) asm volatile("s_waitcnt lgkmcnt(" #n ")" ::: "memory")
; #define PG8_BAR __builtin_amdgcn_s_barrier()
; #define PG8_SCHED __builtin_amdgcn_sched_barrier(0)
; template <class Epi>
; __device__ __forceinline__ void gemm_phase(LAS unsigned char* lds, const Gemm g, const StaticOrder& S, const Epi& E) {
;     ...
;             PG8_LDB(B0, 0, 0); PG8_SCHED; PG8_LDA(At, 0, 0); PG8_STAGE(PG8_SA(1, 1), a1 + hstep, voffA);
;             PG8_WAIT_L(8); PG8_BAR; PG8_WAIT_L(0); PG8_MMA(0, 0, At, B0); PG8_BAR; PG8_SCHED;
;             PG8_LDB(B1, 0, 1); PG8_STAGE(PG8_SB(0, 0), b2, voffB);
;             PG8_BAR; PG8_WAIT_L(0); PG8_MMA(0, 1, At, B1); PG8_BAR;
;             PG8_LDA(At, 0, 1); PG8_STAGE(PG8_SA(0, 0), a2, voffA);
;             PG8_BAR; PG8_WAIT_L(0); PG8_MMA(1, 0, At, B0); PG8_BAR; PG8_SCHED;
;             PG8_STAGE(PG8_SB(0, 1), b2 + hstep, voffB);
;             PG8_WAIT_V(6); PG8_BAR; PG8_MMA(1, 1, At, B1); PG8_BAR;
;             PG8_LDB(B0, 1, 0); PG8_SCHED; PG8_LDA(At, 1, 0); PG8_STAGE(PG8_SA(0, 1), a2 + hstep, voffA);
;             PG8_WAIT_L(8); PG8_BAR; PG8_WAIT_L(0); PG8_MMA(0, 0, At, B0); PG8_BAR; PG8_SCHED;
;             PG8_LDB(B1, 1, 1); PG8_STAGE(PG8_SB(1, 0), b3, voffB);
;             PG8_BAR; PG8_WAIT_L(0); PG8_MMA(0, 1, At, B1); PG8_BAR;
;             PG8_LDA(At, 1, 1); PG8_STAGE(PG8_SA(1, 0), a3, voffA);
;             PG8_BAR; PG8_WAIT_L(0); PG8_MMA(1, 0, At, B0); PG8_BAR; PG8_SCHED;
;             PG8_STAGE(PG8_SB(1, 1), b3 + hstep, voffB);
;             PG8_WAIT_V(6); PG8_BAR; PG8_MMA(1, 1, At, B1); PG8_BAR;
.LdsA_skip_5:
	v_mfma_f32_16x16x32_bf16 v[114:117], v[140:143], v[176:179], v[114:117]
	v_mfma_f32_16x16x32_bf16 v[106:109], v[154:157], v[176:179], v[106:109]
	v_mfma_f32_16x16x32_bf16 v[98:101], v[140:143], v[184:187], v[98:101]
	v_mfma_f32_16x16x32_bf16 v[90:93], v[154:157], v[184:187], v[90:93]
	v_mfma_f32_16x16x32_bf16 v[82:85], v[140:143], v[208:211], v[82:85]
	v_mfma_f32_16x16x32_bf16 v[74:77], v[154:157], v[208:211], v[74:77]
	v_mfma_f32_16x16x32_bf16 v[126:129], v[144:147], v[172:175], v[126:129]
	v_mfma_f32_16x16x32_bf16 v[122:125], v[158:161], v[172:175], v[122:125]
	v_mfma_f32_16x16x32_bf16 v[114:117], v[144:147], v[180:183], v[114:117]
	v_mfma_f32_16x16x32_bf16 v[106:109], v[158:161], v[180:183], v[106:109]
	v_mfma_f32_16x16x32_bf16 v[98:101], v[144:147], v[204:207], v[98:101]
	v_mfma_f32_16x16x32_bf16 v[90:93], v[158:161], v[204:207], v[90:93]
	v_mfma_f32_16x16x32_bf16 v[82:85], v[144:147], v[212:215], v[82:85]
	v_mfma_f32_16x16x32_bf16 v[74:77], v[158:161], v[212:215], v[74:77]
	s_barrier
	s_add_i32 s36, 0, 0x1c000
	s_add_i32 s37, s58, s44
	v_add_u32_e32 v153, s36, v149
	s_add_u32 s60, s6, 0x80
	s_addc_u32 s61, s7, 0
	s_mov_b32 m0, s37
	ds_read_b128 v[216:219], v153
	ds_read_b128 v[226:229], v153 offset:1024
	ds_read_b128 v[230:233], v153 offset:2048
	ds_read_b128 v[234:237], v153 offset:3072
	global_load_lds_dwordx4 v0, s[60:61]
	s_add_i32 m0, s37, 0x2000
	s_nop 0
	global_load_lds_dwordx4 v130, s[60:61]
	s_barrier
	s_waitcnt lgkmcnt(0)
	s_waitcnt lgkmcnt(0)
	v_mfma_f32_16x16x32_bf16 v[118:121], v[216:219], v[168:171], v[118:121]
	v_mfma_f32_16x16x32_bf16 v[110:113], v[230:233], v[168:171], v[110:113]
	v_mfma_f32_16x16x32_bf16 v[102:105], v[216:219], v[176:179], v[102:105]
	v_mfma_f32_16x16x32_bf16 v[94:97], v[230:233], v[176:179], v[94:97]
	v_mfma_f32_16x16x32_bf16 v[86:89], v[216:219], v[184:187], v[86:89]
	v_mfma_f32_16x16x32_bf16 v[78:81], v[230:233], v[184:187], v[78:81]
	v_mfma_f32_16x16x32_bf16 v[70:73], v[216:219], v[208:211], v[70:73]
	v_mfma_f32_16x16x32_bf16 v[66:69], v[230:233], v[208:211], v[66:69]
	v_mfma_f32_16x16x32_bf16 v[118:121], v[226:229], v[172:175], v[118:121]
	v_mfma_f32_16x16x32_bf16 v[110:113], v[234:237], v[172:175], v[110:113]
	v_mfma_f32_16x16x32_bf16 v[102:105], v[226:229], v[180:183], v[102:105]
	v_mfma_f32_16x16x32_bf16 v[94:97], v[234:237], v[180:183], v[94:97]
	v_mfma_f32_16x16x32_bf16 v[86:89], v[226:229], v[204:207], v[86:89]
	v_mfma_f32_16x16x32_bf16 v[78:81], v[234:237], v[204:207], v[78:81]
	v_mfma_f32_16x16x32_bf16 v[70:73], v[226:229], v[212:215], v[70:73]
	v_mfma_f32_16x16x32_bf16 v[66:69], v[234:237], v[212:215], v[66:69]
	s_mov_b32 m0, s55
	s_barrier
	ds_read_b128 v[168:171], v152 offset:49152
	ds_read_b128 v[172:175], v152 offset:50176
	ds_read_b128 v[176:179], v152 offset:51200
	ds_read_b128 v[180:183], v152 offset:52224
	ds_read_b128 v[184:187], v152 offset:53248
	ds_read_b128 v[204:207], v152 offset:54272
	ds_read_b128 v[208:211], v152 offset:55296
	ds_read_b128 v[212:215], v152 offset:56320
	global_load_lds_dwordx4 v134, vcc
	s_mov_b32 m0, s83
	s_nop 0
	global_load_lds_dwordx4 v132, vcc
	s_barrier
	s_waitcnt lgkmcnt(0)
	s_waitcnt lgkmcnt(0)
	v_mfma_f32_16x16x32_bf16 v[62:65], v[140:143], v[168:171], v[62:65]
	v_mfma_f32_16x16x32_bf16 v[58:61], v[154:157], v[168:171], v[58:61]
	v_mfma_f32_16x16x32_bf16 v[50:53], v[140:143], v[176:179], v[50:53]
	v_mfma_f32_16x16x32_bf16 v[42:45], v[154:157], v[176:179], v[42:45]
	v_mfma_f32_16x16x32_bf16 v[34:37], v[140:143], v[184:187], v[34:37]
	v_mfma_f32_16x16x32_bf16 v[26:29], v[154:157], v[184:187], v[26:29]
	v_mfma_f32_16x16x32_bf16 v[18:21], v[140:143], v[208:211], v[18:21]
	v_mfma_f32_16x16x32_bf16 v[10:13], v[154:157], v[208:211], v[10:13]
	v_mfma_f32_16x16x32_bf16 v[62:65], v[144:147], v[172:175], v[62:65]
	v_mfma_f32_16x16x32_bf16 v[58:61], v[158:161], v[172:175], v[58:61]
	v_mfma_f32_16x16x32_bf16 v[50:53], v[144:147], v[180:183], v[50:53]
	v_mfma_f32_16x16x32_bf16 v[42:45], v[158:161], v[180:183], v[42:45]
	v_mfma_f32_16x16x32_bf16 v[34:37], v[144:147], v[204:207], v[34:37]
	v_mfma_f32_16x16x32_bf16 v[26:29], v[158:161], v[204:207], v[26:29]
	v_mfma_f32_16x16x32_bf16 v[18:21], v[144:147], v[212:215], v[18:21]
	v_mfma_f32_16x16x32_bf16 v[10:13], v[158:161], v[212:215], v[10:13]
	s_barrier
	s_add_u32 s6, s6, 0x40080
	s_addc_u32 s7, s7, 0
	s_add_i32 s36, s36, s44
	s_mov_b32 m0, s36
	s_nop 0
	global_load_lds_dwordx4 v0, s[6:7]
	s_add_i32 m0, s36, 0x2000
	s_nop 0
	global_load_lds_dwordx4 v130, s[6:7]
	s_waitcnt vmcnt(6)
	s_barrier
	v_mfma_f32_16x16x32_bf16 v[54:57], v[216:219], v[168:171], v[54:57]
	v_mfma_f32_16x16x32_bf16 v[46:49], v[230:233], v[168:171], v[46:49]
	v_mfma_f32_16x16x32_bf16 v[38:41], v[216:219], v[176:179], v[38:41]
	v_mfma_f32_16x16x32_bf16 v[30:33], v[230:233], v[176:179], v[30:33]
	v_mfma_f32_16x16x32_bf16 v[22:25], v[216:219], v[184:187], v[22:25]
	v_mfma_f32_16x16x32_bf16 v[14:17], v[230:233], v[184:187], v[14:17]
	v_mfma_f32_16x16x32_bf16 v[6:9], v[216:219], v[208:211], v[6:9]
	v_mfma_f32_16x16x32_bf16 v[2:5], v[230:233], v[208:211], v[2:5]
	v_mfma_f32_16x16x32_bf16 v[54:57], v[226:229], v[172:175], v[54:57]
	v_mfma_f32_16x16x32_bf16 v[46:49], v[234:237], v[172:175], v[46:49]
	v_mfma_f32_16x16x32_bf16 v[38:41], v[226:229], v[180:183], v[38:41]
	v_mfma_f32_16x16x32_bf16 v[30:33], v[234:237], v[180:183], v[30:33]
	v_mfma_f32_16x16x32_bf16 v[22:25], v[226:229], v[204:207], v[22:25]
	v_mfma_f32_16x16x32_bf16 v[14:17], v[234:237], v[204:207], v[14:17]
	v_mfma_f32_16x16x32_bf16 v[6:9], v[226:229], v[212:215], v[6:9]
	v_mfma_f32_16x16x32_bf16 v[2:5], v[234:237], v[212:215], v[2:5]
	s_add_i32 s91, s91, 2
	s_add_u32 s24, s24, 0x100
	s_addc_u32 s25, s25, 0
	s_add_u32 s89, s89, 0x100
	s_addc_u32 s90, s90, 0
	s_cmp_gt_u32 s91, 13
	s_barrier
; #define PG8_STAGE(bufoff, gbase, voff) do { _Pragma("unroll") for (int _i = 0; _i < 2; ++_i) \
;         __builtin_amdgcn_global_load_lds((const unsigned*)((const char*)(gbase) + (voff)[_i]), (LAS unsigned*)(lds + (bufoff) + ldsw + _i * 8192), 16, 0, 0); } while (0)
; #define PG8_LDA(dst, b, h) do { _Pragma("unroll") for (int m = 0; m < 4; ++m) _Pragma("unroll") for (int k = 0; k < 2; ++k) dst[m][k] = *(const LAS bf16x8*)(lds + PG8_SA(b, h) + aoff + m * 2048 + k * 1024); } while (0)
; #define PG8_LDB(dst, b, h) do { _Pragma("unroll") for (int n = 0; n < 2; ++n) _Pragma("unroll") for (int k = 0; k < 2; ++k) dst[n][k] = *(const LAS bf16x8*)(lds + PG8_SB(b, h) + boff + n * 2048 + k * 1024); } while (0)
; #define PG8_WAIT_V(n) asm volatile("s_waitcnt vmcnt(" #n ")" ::: "memory")
; #define PG8_WAIT_L(n) asm volatile("s_waitcnt lgkmcnt(" #n ")" ::: "memory")
; #define PG8_BAR __builtin_amdgcn_s_barrier()
; #define PG8_SCHED __builtin_amdgcn_sched_barrier(0)
; template <class Epi>
; __device__ __forceinline__ void gemm_phase(LAS unsigned char* lds, const Gemm g, const StaticOrder& S, const Epi& E) {
;     ...
;             PG8_LDB(B0, 0, 0); PG8_SCHED; PG8_LDA(At, 0, 0); PG8_STAGE(PG8_SA(1, 1), a1 + hstep, voffA);
;             PG8_WAIT_L(8); PG8_BAR; PG8_WAIT_L(0); PG8_MMA(0, 0, At, B0); PG8_BAR; PG8_SCHED;
;             PG8_LDB(B1, 0, 1); PG8_STAGE(PG8_SB(0, 0), b2, voffB);
;             PG8_BAR; PG8_WAIT_L(0); PG8_MMA(0, 1, At, B1); PG8_BAR;
;             PG8_LDA(At, 0, 1); PG8_STAGE(PG8_SA(0, 0), a2, voffA);
;             PG8_BAR; PG8_WAIT_L(0); PG8_MMA(1, 0, At, B0); PG8_BAR; PG8_SCHED;
;             PG8_STAGE(PG8_SB(0, 1), b2 + hstep, voffB);
;             PG8_WAIT_V(6); PG8_BAR; PG8_MMA(1, 1, At, B1); PG8_BAR;
;             PG8_LDB(B0, 1, 0); PG8_SCHED; PG8_LDA(At, 1, 0); PG8_STAGE(PG8_SA(0, 1), a2 + hstep, voffA);
;             PG8_WAIT_L(8); PG8_BAR; PG8_WAIT_L(0); PG8_MMA(0, 0, At, B0); PG8_BAR; PG8_SCHED;
;             PG8_LDB(B1, 1, 1); PG8_STAGE(PG8_SB(1, 0), b3, voffB);
;             PG8_BAR; PG8_WAIT_L(0); PG8_MMA(0, 1, At, B1); PG8_BAR;
;             PG8_LDA(At, 1, 1); PG8_STAGE(PG8_SA(1, 0), a3, voffA);
;             PG8_BAR; PG8_WAIT_L(0); PG8_MMA(1, 0, At, B0); PG8_BAR; PG8_SCHED;
;             PG8_STAGE(PG8_SB(1, 1), b3 + hstep, voffB);
;             PG8_WAIT_V(6); PG8_BAR; PG8_MMA(1, 1, At, B1); PG8_BAR;
	s_add_u32 s6, s24, 0xfffc0080
	s_addc_u32 s7, s25, -1
	s_add_i32 s58, 0, 0x10000
	v_add_u32_e32 v153, s58, v149
	ds_read_b128 v[140:143], v153
	ds_read_b128 v[144:147], v153 offset:1024
	ds_read_b128 v[154:157], v153 offset:2048
	ds_read_b128 v[158:161], v153 offset:3072
	s_cmp_eq_u32 s91, 12
	s_cselect_b32 s37, s11, s7
	s_cselect_b32 s36, s71, s6
	s_cselect_b32 s7, s9, s90
	s_cselect_b32 s6, s88, s89
	s_add_i32 m0, s47, 0xc000
	ds_read_b128 v[168:171], v152
	ds_read_b128 v[172:175], v152 offset:1024
	ds_read_b128 v[176:179], v152 offset:2048
	ds_read_b128 v[180:183], v152 offset:3072
	ds_read_b128 v[184:187], v152 offset:4096
	ds_read_b128 v[204:207], v152 offset:5120
	ds_read_b128 v[208:211], v152 offset:6144
	ds_read_b128 v[212:215], v152 offset:7168
	global_load_lds_dwordx4 v136, s[24:25]
	s_add_i32 m0, s47, 0xe000
	s_nop 0
	global_load_lds_dwordx4 v138, s[24:25]
	s_waitcnt lgkmcnt(8)
	s_barrier
	s_waitcnt lgkmcnt(0)
	s_waitcnt lgkmcnt(0)
	v_mfma_f32_16x16x32_bf16 v[126:129], v[140:143], v[168:171], v[126:129]
	v_mfma_f32_16x16x32_bf16 v[122:125], v[154:157], v[168:171], v[122:125]
	v_mfma_f32_16x16x32_bf16 v[114:117], v[140:143], v[176:179], v[114:117]
	v_mfma_f32_16x16x32_bf16 v[106:109], v[154:157], v[176:179], v[106:109]
	v_mfma_f32_16x16x32_bf16 v[98:101], v[140:143], v[184:187], v[98:101]
	v_mfma_f32_16x16x32_bf16 v[90:93], v[154:157], v[184:187], v[90:93]
	v_mfma_f32_16x16x32_bf16 v[82:85], v[140:143], v[208:211], v[82:85]
	v_mfma_f32_16x16x32_bf16 v[74:77], v[154:157], v[208:211], v[74:77]
	v_mfma_f32_16x16x32_bf16 v[126:129], v[144:147], v[172:175], v[126:129]
	v_mfma_f32_16x16x32_bf16 v[122:125], v[158:161], v[172:175], v[122:125]
	v_mfma_f32_16x16x32_bf16 v[114:117], v[144:147], v[180:183], v[114:117]
	v_mfma_f32_16x16x32_bf16 v[106:109], v[158:161], v[180:183], v[106:109]
	v_mfma_f32_16x16x32_bf16 v[98:101], v[144:147], v[204:207], v[98:101]
	v_mfma_f32_16x16x32_bf16 v[90:93], v[158:161], v[204:207], v[90:93]
	v_mfma_f32_16x16x32_bf16 v[82:85], v[144:147], v[212:215], v[82:85]
	v_mfma_f32_16x16x32_bf16 v[74:77], v[158:161], v[212:215], v[74:77]
	s_barrier
	s_add_i32 s70, 0, 0x14000
	s_add_i32 s58, s58, s44
	v_add_u32_e32 v153, s70, v149
	s_mov_b32 m0, s58
	ds_read_b128 v[216:219], v153
	ds_read_b128 v[226:229], v153 offset:1024
	ds_read_b128 v[230:233], v153 offset:2048
	ds_read_b128 v[234:237], v153 offset:3072
	global_load_lds_dwordx4 v0, s[6:7]
	s_add_i32 m0, s58, 0x2000
	s_nop 0
	global_load_lds_dwordx4 v130, s[6:7]
	s_barrier
	s_waitcnt lgkmcnt(0)
	s_waitcnt lgkmcnt(0)
	v_mfma_f32_16x16x32_bf16 v[118:121], v[216:219], v[168:171], v[118:121]
	v_mfma_f32_16x16x32_bf16 v[110:113], v[230:233], v[168:171], v[110:113]
	v_mfma_f32_16x16x32_bf16 v[102:105], v[216:219], v[176:179], v[102:105]
	v_mfma_f32_16x16x32_bf16 v[94:97], v[230:233], v[176:179], v[94:97]
	v_mfma_f32_16x16x32_bf16 v[86:89], v[216:219], v[184:187], v[86:89]
	v_mfma_f32_16x16x32_bf16 v[78:81], v[230:233], v[184:187], v[78:81]
	v_mfma_f32_16x16x32_bf16 v[70:73], v[216:219], v[208:211], v[70:73]
	v_mfma_f32_16x16x32_bf16 v[66:69], v[230:233], v[208:211], v[66:69]
	v_mfma_f32_16x16x32_bf16 v[118:121], v[226:229], v[172:175], v[118:121]
	v_mfma_f32_16x16x32_bf16 v[110:113], v[234:237], v[172:175], v[110:113]
	v_mfma_f32_16x16x32_bf16 v[102:105], v[226:229], v[180:183], v[102:105]
	v_mfma_f32_16x16x32_bf16 v[94:97], v[234:237], v[180:183], v[94:97]
	v_mfma_f32_16x16x32_bf16 v[86:89], v[226:229], v[204:207], v[86:89]
	v_mfma_f32_16x16x32_bf16 v[78:81], v[234:237], v[204:207], v[78:81]
	v_mfma_f32_16x16x32_bf16 v[70:73], v[226:229], v[212:215], v[70:73]
	v_mfma_f32_16x16x32_bf16 v[66:69], v[234:237], v[212:215], v[66:69]
	s_mov_b32 m0, s47
	s_add_u32 vcc_lo, s36, 0x80
	s_addc_u32 vcc_hi, s37, 0
	s_barrier
	ds_read_b128 v[168:171], v152 offset:16384
	ds_read_b128 v[172:175], v152 offset:17408
	ds_read_b128 v[176:179], v152 offset:18432
	ds_read_b128 v[180:183], v152 offset:19456
	ds_read_b128 v[184:187], v152 offset:20480
	ds_read_b128 v[204:207], v152 offset:21504
	ds_read_b128 v[208:211], v152 offset:22528
	ds_read_b128 v[212:215], v152 offset:23552
	global_load_lds_dwordx4 v134, s[36:37]
	s_mov_b32 m0, s48
	s_nop 0
	global_load_lds_dwordx4 v132, s[36:37]
	s_barrier
	s_waitcnt lgkmcnt(0)
	s_waitcnt lgkmcnt(0)
	v_mfma_f32_16x16x32_bf16 v[62:65], v[140:143], v[168:171], v[62:65]
	v_mfma_f32_16x16x32_bf16 v[58:61], v[154:157], v[168:171], v[58:61]
	v_mfma_f32_16x16x32_bf16 v[50:53], v[140:143], v[176:179], v[50:53]
	v_mfma_f32_16x16x32_bf16 v[42:45], v[154:157], v[176:179], v[42:45]
	v_mfma_f32_16x16x32_bf16 v[34:37], v[140:143], v[184:187], v[34:37]
	v_mfma_f32_16x16x32_bf16 v[26:29], v[154:157], v[184:187], v[26:29]
	v_mfma_f32_16x16x32_bf16 v[18:21], v[140:143], v[208:211], v[18:21]
	v_mfma_f32_16x16x32_bf16 v[10:13], v[154:157], v[208:211], v[10:13]
	v_mfma_f32_16x16x32_bf16 v[62:65], v[144:147], v[172:175], v[62:65]
	v_mfma_f32_16x16x32_bf16 v[58:61], v[158:161], v[172:175], v[58:61]
	v_mfma_f32_16x16x32_bf16 v[50:53], v[144:147], v[180:183], v[50:53]
	v_mfma_f32_16x16x32_bf16 v[42:45], v[158:161], v[180:183], v[42:45]
	v_mfma_f32_16x16x32_bf16 v[34:37], v[144:147], v[204:207], v[34:37]
	v_mfma_f32_16x16x32_bf16 v[26:29], v[158:161], v[204:207], v[26:29]
	v_mfma_f32_16x16x32_bf16 v[18:21], v[144:147], v[212:215], v[18:21]
	v_mfma_f32_16x16x32_bf16 v[10:13], v[158:161], v[212:215], v[10:13]
	s_barrier
	s_add_u32 s60, s6, 0x40000
	s_addc_u32 s61, s7, 0
	s_add_i32 s58, s70, s44
	s_mov_b32 m0, s58
	s_nop 0
	global_load_lds_dwordx4 v0, s[60:61]
	s_add_i32 m0, s58, 0x2000
	s_nop 0
	global_load_lds_dwordx4 v130, s[60:61]
	s_waitcnt vmcnt(6)
	s_barrier
; #define PG8_STAGE(bufoff, gbase, voff) do { _Pragma("unroll") for (int _i = 0; _i < 2; ++_i) \
;         __builtin_amdgcn_global_load_lds((const unsigned*)((const char*)(gbase) + (voff)[_i]), (LAS unsigned*)(lds + (bufoff) + ldsw + _i * 8192), 16, 0, 0); } while (0)
; #define PG8_LDA(dst, b, h) do { _Pragma("unroll") for (int m = 0; m < 4; ++m) _Pragma("unroll") for (int k = 0; k < 2; ++k) dst[m][k] = *(const LAS bf16x8*)(lds + PG8_SA(b, h) + aoff + m * 2048 + k * 1024); } while (0)
; #define PG8_LDB(dst, b, h) do { _Pragma("unroll") for (int n = 0; n < 2; ++n) _Pragma("unroll") for (int k = 0; k < 2; ++k) dst[n][k] = *(const LAS bf16x8*)(lds + PG8_SB(b, h) + boff + n * 2048 + k * 1024); } while (0)
; #define PG8_WAIT_V(n) asm volatile("s_waitcnt vmcnt(" #n ")" ::: "memory")
; #define PG8_WAIT_L(n) asm volatile("s_waitcnt lgkmcnt(" #n ")" ::: "memory")
; #define PG8_BAR __builtin_amdgcn_s_barrier()
; #define PG8_SCHED __builtin_amdgcn_sched_barrier(0)
; template <class Epi>
; __device__ __forceinline__ void gemm_phase(LAS unsigned char* lds, const Gemm g, const StaticOrder& S, const Epi& E) {
;     ...
;             PG8_LDB(B0, 0, 0); PG8_SCHED; PG8_LDA(At, 0, 0); PG8_STAGE(PG8_SA(1, 1), a1 + hstep, voffA);
;             PG8_WAIT_L(8); PG8_BAR; PG8_WAIT_L(0); PG8_MMA(0, 0, At, B0); PG8_BAR; PG8_SCHED;
;             PG8_LDB(B1, 0, 1); PG8_STAGE(PG8_SB(0, 0), b2, voffB);
;             PG8_BAR; PG8_WAIT_L(0); PG8_MMA(0, 1, At, B1); PG8_BAR;
;             PG8_LDA(At, 0, 1); PG8_STAGE(PG8_SA(0, 0), a2, voffA);
;             PG8_BAR; PG8_WAIT_L(0); PG8_MMA(1, 0, At, B0); PG8_BAR; PG8_SCHED;
;             PG8_STAGE(PG8_SB(0, 1), b2 + hstep, voffB);
;             PG8_WAIT_V(6); PG8_BAR; PG8_MMA(1, 1, At, B1); PG8_BAR;
;             PG8_LDB(B0, 1, 0); PG8_SCHED; PG8_LDA(At, 1, 0); PG8_STAGE(PG8_SA(0, 1), a2 + hstep, voffA);
;             PG8_WAIT_L(8); PG8_BAR; PG8_WAIT_L(0); PG8_MMA(0, 0, At, B0); PG8_BAR; PG8_SCHED;
;             PG8_LDB(B1, 1, 1); PG8_STAGE(PG8_SB(1, 0), b3, voffB);
;             PG8_BAR; PG8_WAIT_L(0); PG8_MMA(0, 1, At, B1); PG8_BAR;
;             PG8_LDA(At, 1, 1); PG8_STAGE(PG8_SA(1, 0), a3, voffA);
;             PG8_BAR; PG8_WAIT_L(0); PG8_MMA(1, 0, At, B0); PG8_BAR; PG8_SCHED;
;             PG8_STAGE(PG8_SB(1, 1), b3 + hstep, voffB);
;             PG8_WAIT_V(6); PG8_BAR; PG8_MMA(1, 1, At, B1); PG8_BAR;
	v_mfma_f32_16x16x32_bf16 v[54:57], v[216:219], v[168:171], v[54:57]
	v_mfma_f32_16x16x32_bf16 v[46:49], v[230:233], v[168:171], v[46:49]
	v_mfma_f32_16x16x32_bf16 v[38:41], v[216:219], v[176:179], v[38:41]
	v_mfma_f32_16x16x32_bf16 v[30:33], v[230:233], v[176:179], v[30:33]
	v_mfma_f32_16x16x32_bf16 v[22:25], v[216:219], v[184:187], v[22:25]
	v_mfma_f32_16x16x32_bf16 v[14:17], v[230:233], v[184:187], v[14:17]
	v_mfma_f32_16x16x32_bf16 v[6:9], v[216:219], v[208:211], v[6:9]
	v_mfma_f32_16x16x32_bf16 v[2:5], v[230:233], v[208:211], v[2:5]
	v_mfma_f32_16x16x32_bf16 v[54:57], v[226:229], v[172:175], v[54:57]
	v_mfma_f32_16x16x32_bf16 v[46:49], v[234:237], v[172:175], v[46:49]
	v_mfma_f32_16x16x32_bf16 v[38:41], v[226:229], v[180:183], v[38:41]
	v_mfma_f32_16x16x32_bf16 v[30:33], v[234:237], v[180:183], v[30:33]
	v_mfma_f32_16x16x32_bf16 v[22:25], v[226:229], v[204:207], v[22:25]
	v_mfma_f32_16x16x32_bf16 v[14:17], v[234:237], v[204:207], v[14:17]
	v_mfma_f32_16x16x32_bf16 v[6:9], v[226:229], v[212:215], v[6:9]
	v_mfma_f32_16x16x32_bf16 v[2:5], v[234:237], v[212:215], v[2:5]
	s_add_i32 s58, 0, 0x18000
	v_add_u32_e32 v153, s58, v149
	s_barrier
	ds_read_b128 v[140:143], v153
	ds_read_b128 v[144:147], v153 offset:1024
	ds_read_b128 v[154:157], v153 offset:2048
	ds_read_b128 v[158:161], v153 offset:3072
	s_add_u32 s36, s36, 0x40000
	s_addc_u32 s37, s37, 0
	s_mov_b32 m0, s49
	ds_read_b128 v[168:171], v152 offset:32768
	ds_read_b128 v[172:175], v152 offset:33792
	ds_read_b128 v[176:179], v152 offset:34816
	ds_read_b128 v[180:183], v152 offset:35840
	ds_read_b128 v[184:187], v152 offset:36864
	ds_read_b128 v[204:207], v152 offset:37888
	ds_read_b128 v[208:211], v152 offset:38912
	ds_read_b128 v[212:215], v152 offset:39936
	global_load_lds_dwordx4 v134, s[36:37]
	s_mov_b32 m0, s54
	s_nop 0
	global_load_lds_dwordx4 v132, s[36:37]
	s_waitcnt lgkmcnt(8)
	s_barrier
	s_waitcnt lgkmcnt(0)
	s_waitcnt lgkmcnt(0)
	v_mfma_f32_16x16x32_bf16 v[126:129], v[140:143], v[168:171], v[126:129]
	v_mfma_f32_16x16x32_bf16 v[122:125], v[154:157], v[168:171], v[122:125]
	s_cmp_eq_u32 s87, 0
	s_cbranch_scc1 .LdsA_skip_6
	global_store_dwordx4 v166, v[244:247], s[4:5]
.LdsA_skip_6:
	v_mfma_f32_16x16x32_bf16 v[114:117], v[140:143], v[176:179], v[114:117]
	v_mfma_f32_16x16x32_bf16 v[106:109], v[154:157], v[176:179], v[106:109]
	v_mfma_f32_16x16x32_bf16 v[98:101], v[140:143], v[184:187], v[98:101]
	v_mfma_f32_16x16x32_bf16 v[90:93], v[154:157], v[184:187], v[90:93]
	v_mfma_f32_16x16x32_bf16 v[82:85], v[140:143], v[208:211], v[82:85]
	v_mfma_f32_16x16x32_bf16 v[74:77], v[154:157], v[208:211], v[74:77]
	v_mfma_f32_16x16x32_bf16 v[126:129], v[144:147], v[172:175], v[126:129]
	v_mfma_f32_16x16x32_bf16 v[122:125], v[158:161], v[172:175], v[122:125]
	v_mfma_f32_16x16x32_bf16 v[114:117], v[144:147], v[180:183], v[114:117]
	v_mfma_f32_16x16x32_bf16 v[106:109], v[158:161], v[180:183], v[106:109]
	v_mfma_f32_16x16x32_bf16 v[98:101], v[144:147], v[204:207], v[98:101]
	v_mfma_f32_16x16x32_bf16 v[90:93], v[158:161], v[204:207], v[90:93]
	v_mfma_f32_16x16x32_bf16 v[82:85], v[144:147], v[212:215], v[82:85]
	v_mfma_f32_16x16x32_bf16 v[74:77], v[158:161], v[212:215], v[74:77]
	s_barrier
	s_add_i32 s36, 0, 0x1c000
	s_add_i32 s37, s58, s44
	v_add_u32_e32 v153, s36, v149
	s_add_u32 s60, s6, 0x80
	s_addc_u32 s61, s7, 0
	s_mov_b32 m0, s37
	ds_read_b128 v[216:219], v153
	ds_read_b128 v[226:229], v153 offset:1024
	ds_read_b128 v[230:233], v153 offset:2048
	ds_read_b128 v[234:237], v153 offset:3072
	global_load_lds_dwordx4 v0, s[60:61]
	s_add_i32 m0, s37, 0x2000
	s_nop 0
	global_load_lds_dwordx4 v130, s[60:61]
	s_barrier
	s_waitcnt lgkmcnt(0)
	s_waitcnt lgkmcnt(0)
	v_mfma_f32_16x16x32_bf16 v[118:121], v[216:219], v[168:171], v[118:121]
	v_mfma_f32_16x16x32_bf16 v[110:113], v[230:233], v[168:171], v[110:113]
	v_mfma_f32_16x16x32_bf16 v[102:105], v[216:219], v[176:179], v[102:105]
	v_mfma_f32_16x16x32_bf16 v[94:97], v[230:233], v[176:179], v[94:97]
	v_mfma_f32_16x16x32_bf16 v[86:89], v[216:219], v[184:187], v[86:89]
	v_mfma_f32_16x16x32_bf16 v[78:81], v[230:233], v[184:187], v[78:81]
	v_mfma_f32_16x16x32_bf16 v[70:73], v[216:219], v[208:211], v[70:73]
	v_mfma_f32_16x16x32_bf16 v[66:69], v[230:233], v[208:211], v[66:69]
	v_mfma_f32_16x16x32_bf16 v[118:121], v[226:229], v[172:175], v[118:121]
	v_mfma_f32_16x16x32_bf16 v[110:113], v[234:237], v[172:175], v[110:113]
	v_mfma_f32_16x16x32_bf16 v[102:105], v[226:229], v[180:183], v[102:105]
	v_mfma_f32_16x16x32_bf16 v[94:97], v[234:237], v[180:183], v[94:97]
	v_mfma_f32_16x16x32_bf16 v[86:89], v[226:229], v[204:207], v[86:89]
	v_mfma_f32_16x16x32_bf16 v[78:81], v[234:237], v[204:207], v[78:81]
	v_mfma_f32_16x16x32_bf16 v[70:73], v[226:229], v[212:215], v[70:73]
	v_mfma_f32_16x16x32_bf16 v[66:69], v[234:237], v[212:215], v[66:69]
	s_mov_b32 m0, s55
	s_barrier
	ds_read_b128 v[168:171], v152 offset:49152
	ds_read_b128 v[172:175], v152 offset:50176
	ds_read_b128 v[176:179], v152 offset:51200
	ds_read_b128 v[180:183], v152 offset:52224
	ds_read_b128 v[184:187], v152 offset:53248
	ds_read_b128 v[204:207], v152 offset:54272
	ds_read_b128 v[208:211], v152 offset:55296
	ds_read_b128 v[212:215], v152 offset:56320
	global_load_lds_dwordx4 v134, vcc
	s_mov_b32 m0, s83
	s_nop 0
	global_load_lds_dwordx4 v132, vcc
	s_barrier
; #define PG8_STAGE(bufoff, gbase, voff) do { _Pragma("unroll") for (int _i = 0; _i < 2; ++_i) \
;         __builtin_amdgcn_global_load_lds((const unsigned*)((const char*)(gbase) + (voff)[_i]), (LAS unsigned*)(lds + (bufoff) + ldsw + _i * 8192), 16, 0, 0); } while (0)
; #define PG8_LDA(dst, b, h) do { _Pragma("unroll") for (int m = 0; m < 4; ++m) _Pragma("unroll") for (int k = 0; k < 2; ++k) dst[m][k] = *(const LAS bf16x8*)(lds + PG8_SA(b, h) + aoff + m * 2048 + k * 1024); } while (0)
; #define PG8_LDB(dst, b, h) do { _Pragma("unroll") for (int n = 0; n < 2; ++n) _Pragma("unroll") for (int k = 0; k < 2; ++k) dst[n][k] = *(const LAS bf16x8*)(lds + PG8_SB(b, h) + boff + n * 2048 + k * 1024); } while (0)
; #define PG8_WAIT_V(n) asm volatile("s_waitcnt vmcnt(" #n ")" ::: "memory")
; #define PG8_WAIT_L(n) asm volatile("s_waitcnt lgkmcnt(" #n ")" ::: "memory")
; #define PG8_BAR __builtin_amdgcn_s_barrier()
; #define PG8_SCHED __builtin_amdgcn_sched_barrier(0)
; template <class Epi>
; __device__ __forceinline__ void gemm_phase(LAS unsigned char* lds, const Gemm g, const StaticOrder& S, const Epi& E) {
;     ...
;             PG8_LDB(B0, 0, 0); PG8_SCHED; PG8_LDA(At, 0, 0); PG8_STAGE(PG8_SA(1, 1), a1 + hstep, voffA);
;             PG8_WAIT_L(8); PG8_BAR; PG8_WAIT_L(0); PG8_MMA(0, 0, At, B0); PG8_BAR; PG8_SCHED;
;             PG8_LDB(B1, 0, 1); PG8_STAGE(PG8_SB(0, 0), b2, voffB);
;             PG8_BAR; PG8_WAIT_L(0); PG8_MMA(0, 1, At, B1); PG8_BAR;
;             PG8_LDA(At, 0, 1); PG8_STAGE(PG8_SA(0, 0), a2, voffA);
;             PG8_BAR; PG8_WAIT_L(0); PG8_MMA(1, 0, At, B0); PG8_BAR; PG8_SCHED;
;             PG8_STAGE(PG8_SB(0, 1), b2 + hstep, voffB);
;             PG8_WAIT_V(6); PG8_BAR; PG8_MMA(1, 1, At, B1); PG8_BAR;
;             PG8_LDB(B0, 1, 0); PG8_SCHED; PG8_LDA(At, 1, 0); PG8_STAGE(PG8_SA(0, 1), a2 + hstep, voffA);
;             PG8_WAIT_L(8); PG8_BAR; PG8_WAIT_L(0); PG8_MMA(0, 0, At, B0); PG8_BAR; PG8_SCHED;
;             PG8_LDB(B1, 1, 1); PG8_STAGE(PG8_SB(1, 0), b3, voffB);
;             PG8_BAR; PG8_WAIT_L(0); PG8_MMA(0, 1, At, B1); PG8_BAR;
;             PG8_LDA(At, 1, 1); PG8_STAGE(PG8_SA(1, 0), a3, voffA);
;             PG8_BAR; PG8_WAIT_L(0); PG8_MMA(1, 0, At, B0); PG8_BAR; PG8_SCHED;
;             PG8_STAGE(PG8_SB(1, 1), b3 + hstep, voffB);
;             PG8_WAIT_V(6); PG8_BAR; PG8_MMA(1, 1, At, B1); PG8_BAR;
	s_waitcnt lgkmcnt(0)
	s_waitcnt lgkmcnt(0)
	v_mfma_f32_16x16x32_bf16 v[62:65], v[140:143], v[168:171], v[62:65]
	v_mfma_f32_16x16x32_bf16 v[58:61], v[154:157], v[168:171], v[58:61]
	v_mfma_f32_16x16x32_bf16 v[50:53], v[140:143], v[176:179], v[50:53]
	v_mfma_f32_16x16x32_bf16 v[42:45], v[154:157], v[176:179], v[42:45]
	v_mfma_f32_16x16x32_bf16 v[34:37], v[140:143], v[184:187], v[34:37]
	v_mfma_f32_16x16x32_bf16 v[26:29], v[154:157], v[184:187], v[26:29]
	v_mfma_f32_16x16x32_bf16 v[18:21], v[140:143], v[208:211], v[18:21]
	v_mfma_f32_16x16x32_bf16 v[10:13], v[154:157], v[208:211], v[10:13]
	v_mfma_f32_16x16x32_bf16 v[62:65], v[144:147], v[172:175], v[62:65]
	v_mfma_f32_16x16x32_bf16 v[58:61], v[158:161], v[172:175], v[58:61]
	v_mfma_f32_16x16x32_bf16 v[50:53], v[144:147], v[180:183], v[50:53]
	v_mfma_f32_16x16x32_bf16 v[42:45], v[158:161], v[180:183], v[42:45]
	v_mfma_f32_16x16x32_bf16 v[34:37], v[144:147], v[204:207], v[34:37]
	v_mfma_f32_16x16x32_bf16 v[26:29], v[158:161], v[204:207], v[26:29]
	v_mfma_f32_16x16x32_bf16 v[18:21], v[144:147], v[212:215], v[18:21]
	v_mfma_f32_16x16x32_bf16 v[10:13], v[158:161], v[212:215], v[10:13]
	s_barrier
	s_add_u32 s6, s6, 0x40080
	s_addc_u32 s7, s7, 0
	s_add_i32 s36, s36, s44
	s_mov_b32 m0, s36
	s_nop 0
	global_load_lds_dwordx4 v0, s[6:7]
	s_add_i32 m0, s36, 0x2000
	s_nop 0
	global_load_lds_dwordx4 v130, s[6:7]
	s_waitcnt vmcnt(6)
	s_barrier
	v_mfma_f32_16x16x32_bf16 v[54:57], v[216:219], v[168:171], v[54:57]
	v_mfma_f32_16x16x32_bf16 v[46:49], v[230:233], v[168:171], v[46:49]
	v_mfma_f32_16x16x32_bf16 v[38:41], v[216:219], v[176:179], v[38:41]
	v_mfma_f32_16x16x32_bf16 v[30:33], v[230:233], v[176:179], v[30:33]
	v_mfma_f32_16x16x32_bf16 v[22:25], v[216:219], v[184:187], v[22:25]
	v_mfma_f32_16x16x32_bf16 v[14:17], v[230:233], v[184:187], v[14:17]
	v_mfma_f32_16x16x32_bf16 v[6:9], v[216:219], v[208:211], v[6:9]
	v_mfma_f32_16x16x32_bf16 v[2:5], v[230:233], v[208:211], v[2:5]
	v_mfma_f32_16x16x32_bf16 v[54:57], v[226:229], v[172:175], v[54:57]
	v_mfma_f32_16x16x32_bf16 v[46:49], v[234:237], v[172:175], v[46:49]
	v_mfma_f32_16x16x32_bf16 v[38:41], v[226:229], v[180:183], v[38:41]
	v_mfma_f32_16x16x32_bf16 v[30:33], v[234:237], v[180:183], v[30:33]
	v_mfma_f32_16x16x32_bf16 v[22:25], v[226:229], v[204:207], v[22:25]
	v_mfma_f32_16x16x32_bf16 v[14:17], v[234:237], v[204:207], v[14:17]
	v_mfma_f32_16x16x32_bf16 v[6:9], v[226:229], v[212:215], v[6:9]
	v_mfma_f32_16x16x32_bf16 v[2:5], v[234:237], v[212:215], v[2:5]
	s_add_i32 s91, s91, 2
	s_add_u32 s24, s24, 0x100
	s_addc_u32 s25, s25, 0
	s_add_u32 s89, s89, 0x100
	s_addc_u32 s90, s90, 0
	s_cmp_gt_u32 s91, 13
	s_barrier
	s_add_u32 s6, s24, 0xfffc0080
	s_addc_u32 s7, s25, -1
	s_add_i32 s58, 0, 0x10000
	v_add_u32_e32 v153, s58, v149
	ds_read_b128 v[140:143], v153
	ds_read_b128 v[144:147], v153 offset:1024
	ds_read_b128 v[154:157], v153 offset:2048
	ds_read_b128 v[158:161], v153 offset:3072
	s_cmp_eq_u32 s91, 12
	s_cselect_b32 s37, s11, s7
	s_cselect_b32 s36, s71, s6
	s_cselect_b32 s7, s9, s90
	s_cselect_b32 s6, s88, s89
	s_add_i32 m0, s47, 0xc000
	ds_read_b128 v[168:171], v152
	ds_read_b128 v[172:175], v152 offset:1024
	ds_read_b128 v[176:179], v152 offset:2048
	ds_read_b128 v[180:183], v152 offset:3072
	ds_read_b128 v[184:187], v152 offset:4096
	ds_read_b128 v[204:207], v152 offset:5120
	ds_read_b128 v[208:211], v152 offset:6144
	ds_read_b128 v[212:215], v152 offset:7168
	global_load_lds_dwordx4 v136, s[24:25]
	s_add_i32 m0, s47, 0xe000
	s_nop 0
	global_load_lds_dwordx4 v138, s[24:25]
	s_waitcnt lgkmcnt(8)
	s_barrier
	s_waitcnt lgkmcnt(0)
	s_waitcnt lgkmcnt(0)
	v_mfma_f32_16x16x32_bf16 v[126:129], v[140:143], v[168:171], v[126:129]
	v_mfma_f32_16x16x32_bf16 v[122:125], v[154:157], v[168:171], v[122:125]
	v_mfma_f32_16x16x32_bf16 v[114:117], v[140:143], v[176:179], v[114:117]
	v_mfma_f32_16x16x32_bf16 v[106:109], v[154:157], v[176:179], v[106:109]
	v_mfma_f32_16x16x32_bf16 v[98:101], v[140:143], v[184:187], v[98:101]
	v_mfma_f32_16x16x32_bf16 v[90:93], v[154:157], v[184:187], v[90:93]
	v_mfma_f32_16x16x32_bf16 v[82:85], v[140:143], v[208:211], v[82:85]
	v_mfma_f32_16x16x32_bf16 v[74:77], v[154:157], v[208:211], v[74:77]
	v_mfma_f32_16x16x32_bf16 v[126:129], v[144:147], v[172:175], v[126:129]
	v_mfma_f32_16x16x32_bf16 v[122:125], v[158:161], v[172:175], v[122:125]
	v_mfma_f32_16x16x32_bf16 v[114:117], v[144:147], v[180:183], v[114:117]
	v_mfma_f32_16x16x32_bf16 v[106:109], v[158:161], v[180:183], v[106:109]
	v_mfma_f32_16x16x32_bf16 v[98:101], v[144:147], v[204:207], v[98:101]
	v_mfma_f32_16x16x32_bf16 v[90:93], v[158:161], v[204:207], v[90:93]
	v_mfma_f32_16x16x32_bf16 v[82:85], v[144:147], v[212:215], v[82:85]
	v_mfma_f32_16x16x32_bf16 v[74:77], v[158:161], v[212:215], v[74:77]
	s_barrier
	s_add_i32 s70, 0, 0x14000
	s_add_i32 s58, s58, s44
	v_add_u32_e32 v153, s70, v149
	s_mov_b32 m0, s58
	ds_read_b128 v[216:219], v153
	ds_read_b128 v[226:229], v153 offset:1024
	ds_read_b128 v[230:233], v153 offset:2048
	ds_read_b128 v[234:237], v153 offset:3072
	global_load_lds_dwordx4 v0, s[6:7]
	s_add_i32 m0, s58, 0x2000
	s_nop 0
	global_load_lds_dwordx4 v130, s[6:7]
	s_barrier
; #define PG8_STAGE(bufoff, gbase, voff) do { _Pragma("unroll") for (int _i = 0; _i < 2; ++_i) \
;         __builtin_amdgcn_global_load_lds((const unsigned*)((const char*)(gbase) + (voff)[_i]), (LAS unsigned*)(lds + (bufoff) + ldsw + _i * 8192), 16, 0, 0); } while (0)
; #define PG8_LDA(dst, b, h) do { _Pragma("unroll") for (int m = 0; m < 4; ++m) _Pragma("unroll") for (int k = 0; k < 2; ++k) dst[m][k] = *(const LAS bf16x8*)(lds + PG8_SA(b, h) + aoff + m * 2048 + k * 1024); } while (0)
; #define PG8_LDB(dst, b, h) do { _Pragma("unroll") for (int n = 0; n < 2; ++n) _Pragma("unroll") for (int k = 0; k < 2; ++k) dst[n][k] = *(const LAS bf16x8*)(lds + PG8_SB(b, h) + boff + n * 2048 + k * 1024); } while (0)
; #define PG8_WAIT_V(n) asm volatile("s_waitcnt vmcnt(" #n ")" ::: "memory")
; #define PG8_WAIT_L(n) asm volatile("s_waitcnt lgkmcnt(" #n ")" ::: "memory")
; #define PG8_BAR __builtin_amdgcn_s_barrier()
; #define PG8_SCHED __builtin_amdgcn_sched_barrier(0)
; template <class Epi>
; __device__ __forceinline__ void gemm_phase(LAS unsigned char* lds, const Gemm g, const StaticOrder& S, const Epi& E) {
;     ...
;             PG8_LDB(B0, 0, 0); PG8_SCHED; PG8_LDA(At, 0, 0); PG8_STAGE(PG8_SA(1, 1), a1 + hstep, voffA);
;             PG8_WAIT_L(8); PG8_BAR; PG8_WAIT_L(0); PG8_MMA(0, 0, At, B0); PG8_BAR; PG8_SCHED;
;             PG8_LDB(B1, 0, 1); PG8_STAGE(PG8_SB(0, 0), b2, voffB);
;             PG8_BAR; PG8_WAIT_L(0); PG8_MMA(0, 1, At, B1); PG8_BAR;
;             PG8_LDA(At, 0, 1); PG8_STAGE(PG8_SA(0, 0), a2, voffA);
;             PG8_BAR; PG8_WAIT_L(0); PG8_MMA(1, 0, At, B0); PG8_BAR; PG8_SCHED;
;             PG8_STAGE(PG8_SB(0, 1), b2 + hstep, voffB);
;             PG8_WAIT_V(6); PG8_BAR; PG8_MMA(1, 1, At, B1); PG8_BAR;
;             PG8_LDB(B0, 1, 0); PG8_SCHED; PG8_LDA(At, 1, 0); PG8_STAGE(PG8_SA(0, 1), a2 + hstep, voffA);
;             PG8_WAIT_L(8); PG8_BAR; PG8_WAIT_L(0); PG8_MMA(0, 0, At, B0); PG8_BAR; PG8_SCHED;
;             PG8_LDB(B1, 1, 1); PG8_STAGE(PG8_SB(1, 0), b3, voffB);
;             PG8_BAR; PG8_WAIT_L(0); PG8_MMA(0, 1, At, B1); PG8_BAR;
;             PG8_LDA(At, 1, 1); PG8_STAGE(PG8_SA(1, 0), a3, voffA);
;             PG8_BAR; PG8_WAIT_L(0); PG8_MMA(1, 0, At, B0); PG8_BAR; PG8_SCHED;
;             PG8_STAGE(PG8_SB(1, 1), b3 + hstep, voffB);
;             PG8_WAIT_V(6); PG8_BAR; PG8_MMA(1, 1, At, B1); PG8_BAR;
	s_waitcnt lgkmcnt(0)
	s_waitcnt lgkmcnt(0)
	v_mfma_f32_16x16x32_bf16 v[118:121], v[216:219], v[168:171], v[118:121]
	v_mfma_f32_16x16x32_bf16 v[110:113], v[230:233], v[168:171], v[110:113]
	v_mfma_f32_16x16x32_bf16 v[102:105], v[216:219], v[176:179], v[102:105]
	v_mfma_f32_16x16x32_bf16 v[94:97], v[230:233], v[176:179], v[94:97]
	v_mfma_f32_16x16x32_bf16 v[86:89], v[216:219], v[184:187], v[86:89]
	v_mfma_f32_16x16x32_bf16 v[78:81], v[230:233], v[184:187], v[78:81]
	v_mfma_f32_16x16x32_bf16 v[70:73], v[216:219], v[208:211], v[70:73]
	v_mfma_f32_16x16x32_bf16 v[66:69], v[230:233], v[208:211], v[66:69]
	v_mfma_f32_16x16x32_bf16 v[118:121], v[226:229], v[172:175], v[118:121]
	v_mfma_f32_16x16x32_bf16 v[110:113], v[234:237], v[172:175], v[110:113]
	v_mfma_f32_16x16x32_bf16 v[102:105], v[226:229], v[180:183], v[102:105]
	v_mfma_f32_16x16x32_bf16 v[94:97], v[234:237], v[180:183], v[94:97]
	v_mfma_f32_16x16x32_bf16 v[86:89], v[226:229], v[204:207], v[86:89]
	v_mfma_f32_16x16x32_bf16 v[78:81], v[234:237], v[204:207], v[78:81]
	v_mfma_f32_16x16x32_bf16 v[70:73], v[226:229], v[212:215], v[70:73]
	v_mfma_f32_16x16x32_bf16 v[66:69], v[234:237], v[212:215], v[66:69]
	s_mov_b32 m0, s47
	s_add_u32 vcc_lo, s36, 0x80
	s_addc_u32 vcc_hi, s37, 0
	s_barrier
	ds_read_b128 v[168:171], v152 offset:16384
	ds_read_b128 v[172:175], v152 offset:17408
	ds_read_b128 v[176:179], v152 offset:18432
	ds_read_b128 v[180:183], v152 offset:19456
	ds_read_b128 v[184:187], v152 offset:20480
	ds_read_b128 v[204:207], v152 offset:21504
	ds_read_b128 v[208:211], v152 offset:22528
	ds_read_b128 v[212:215], v152 offset:23552
	global_load_lds_dwordx4 v134, s[36:37]
	s_mov_b32 m0, s48
	s_nop 0
	global_load_lds_dwordx4 v132, s[36:37]
	s_barrier
	s_waitcnt lgkmcnt(0)
	s_waitcnt lgkmcnt(0)
	v_mfma_f32_16x16x32_bf16 v[62:65], v[140:143], v[168:171], v[62:65]
	v_mfma_f32_16x16x32_bf16 v[58:61], v[154:157], v[168:171], v[58:61]
	v_mfma_f32_16x16x32_bf16 v[50:53], v[140:143], v[176:179], v[50:53]
	v_mfma_f32_16x16x32_bf16 v[42:45], v[154:157], v[176:179], v[42:45]
	v_mfma_f32_16x16x32_bf16 v[34:37], v[140:143], v[184:187], v[34:37]
	v_mfma_f32_16x16x32_bf16 v[26:29], v[154:157], v[184:187], v[26:29]
	v_mfma_f32_16x16x32_bf16 v[18:21], v[140:143], v[208:211], v[18:21]
	v_mfma_f32_16x16x32_bf16 v[10:13], v[154:157], v[208:211], v[10:13]
	v_mfma_f32_16x16x32_bf16 v[62:65], v[144:147], v[172:175], v[62:65]
	v_mfma_f32_16x16x32_bf16 v[58:61], v[158:161], v[172:175], v[58:61]
	v_mfma_f32_16x16x32_bf16 v[50:53], v[144:147], v[180:183], v[50:53]
	v_mfma_f32_16x16x32_bf16 v[42:45], v[158:161], v[180:183], v[42:45]
	v_mfma_f32_16x16x32_bf16 v[34:37], v[144:147], v[204:207], v[34:37]
	v_mfma_f32_16x16x32_bf16 v[26:29], v[158:161], v[204:207], v[26:29]
	v_mfma_f32_16x16x32_bf16 v[18:21], v[144:147], v[212:215], v[18:21]
	v_mfma_f32_16x16x32_bf16 v[10:13], v[158:161], v[212:215], v[10:13]
	s_barrier
	s_add_u32 s60, s6, 0x40000
	s_addc_u32 s61, s7, 0
	s_add_i32 s58, s70, s44
	s_mov_b32 m0, s58
	s_nop 0
	global_load_lds_dwordx4 v0, s[60:61]
	s_add_i32 m0, s58, 0x2000
	s_nop 0
	global_load_lds_dwordx4 v130, s[60:61]
	s_waitcnt vmcnt(6)
	s_barrier
	v_mfma_f32_16x16x32_bf16 v[54:57], v[216:219], v[168:171], v[54:57]
	v_mfma_f32_16x16x32_bf16 v[46:49], v[230:233], v[168:171], v[46:49]
	v_mfma_f32_16x16x32_bf16 v[38:41], v[216:219], v[176:179], v[38:41]
	v_mfma_f32_16x16x32_bf16 v[30:33], v[230:233], v[176:179], v[30:33]
	v_mfma_f32_16x16x32_bf16 v[22:25], v[216:219], v[184:187], v[22:25]
	v_mfma_f32_16x16x32_bf16 v[14:17], v[230:233], v[184:187], v[14:17]
	v_mfma_f32_16x16x32_bf16 v[6:9], v[216:219], v[208:211], v[6:9]
	v_mfma_f32_16x16x32_bf16 v[2:5], v[230:233], v[208:211], v[2:5]
	v_mfma_f32_16x16x32_bf16 v[54:57], v[226:229], v[172:175], v[54:57]
	v_mfma_f32_16x16x32_bf16 v[46:49], v[234:237], v[172:175], v[46:49]
	v_mfma_f32_16x16x32_bf16 v[38:41], v[226:229], v[180:183], v[38:41]
	v_mfma_f32_16x16x32_bf16 v[30:33], v[234:237], v[180:183], v[30:33]
	v_mfma_f32_16x16x32_bf16 v[22:25], v[226:229], v[204:207], v[22:25]
	v_mfma_f32_16x16x32_bf16 v[14:17], v[234:237], v[204:207], v[14:17]
	v_mfma_f32_16x16x32_bf16 v[6:9], v[226:229], v[212:215], v[6:9]
	v_mfma_f32_16x16x32_bf16 v[2:5], v[234:237], v[212:215], v[2:5]
	s_add_i32 s58, 0, 0x18000
	v_add_u32_e32 v153, s58, v149
	s_barrier
	ds_read_b128 v[140:143], v153
	ds_read_b128 v[144:147], v153 offset:1024
	ds_read_b128 v[154:157], v153 offset:2048
	ds_read_b128 v[158:161], v153 offset:3072
	s_add_u32 s36, s36, 0x40000
	s_addc_u32 s37, s37, 0
	s_mov_b32 m0, s49
	ds_read_b128 v[168:171], v152 offset:32768
	ds_read_b128 v[172:175], v152 offset:33792
	ds_read_b128 v[176:179], v152 offset:34816
	ds_read_b128 v[180:183], v152 offset:35840
	ds_read_b128 v[184:187], v152 offset:36864
	ds_read_b128 v[204:207], v152 offset:37888
	ds_read_b128 v[208:211], v152 offset:38912
	ds_read_b128 v[212:215], v152 offset:39936
	global_load_lds_dwordx4 v134, s[36:37]
	s_mov_b32 m0, s54
	s_nop 0
	global_load_lds_dwordx4 v132, s[36:37]
	s_waitcnt lgkmcnt(8)
	s_barrier
	s_waitcnt lgkmcnt(0)
	s_waitcnt lgkmcnt(0)
	v_mfma_f32_16x16x32_bf16 v[126:129], v[140:143], v[168:171], v[126:129]
	v_mfma_f32_16x16x32_bf16 v[122:125], v[154:157], v[168:171], v[122:125]
	s_cmp_eq_u32 s87, 0
	s_cbranch_scc1 .LdsA_skip_7
	global_store_dwordx4 v166, v[248:251], s[4:5] offset:256
; #define PG8_STAGE(bufoff, gbase, voff) do { _Pragma("unroll") for (int _i = 0; _i < 2; ++_i) \
;         __builtin_amdgcn_global_load_lds((const unsigned*)((const char*)(gbase) + (voff)[_i]), (LAS unsigned*)(lds + (bufoff) + ldsw + _i * 8192), 16, 0, 0); } while (0)
; #define PG8_LDA(dst, b, h) do { _Pragma("unroll") for (int m = 0; m < 4; ++m) _Pragma("unroll") for (int k = 0; k < 2; ++k) dst[m][k] = *(const LAS bf16x8*)(lds + PG8_SA(b, h) + aoff + m * 2048 + k * 1024); } while (0)
; #define PG8_LDB(dst, b, h) do { _Pragma("unroll") for (int n = 0; n < 2; ++n) _Pragma("unroll") for (int k = 0; k < 2; ++k) dst[n][k] = *(const LAS bf16x8*)(lds + PG8_SB(b, h) + boff + n * 2048 + k * 1024); } while (0)
; #define PG8_WAIT_V(n) asm volatile("s_waitcnt vmcnt(" #n ")" ::: "memory")
; #define PG8_WAIT_L(n) asm volatile("s_waitcnt lgkmcnt(" #n ")" ::: "memory")
; #define PG8_BAR __builtin_amdgcn_s_barrier()
; #define PG8_SCHED __builtin_amdgcn_sched_barrier(0)
; template <class Epi>
; __device__ __forceinline__ void gemm_phase(LAS unsigned char* lds, const Gemm g, const StaticOrder& S, const Epi& E) {
;     ...
;             PG8_LDB(B0, 0, 0); PG8_SCHED; PG8_LDA(At, 0, 0); PG8_STAGE(PG8_SA(1, 1), a1 + hstep, voffA);
;             PG8_WAIT_L(8); PG8_BAR; PG8_WAIT_L(0); PG8_MMA(0, 0, At, B0); PG8_BAR; PG8_SCHED;
;             PG8_LDB(B1, 0, 1); PG8_STAGE(PG8_SB(0, 0), b2, voffB);
;             PG8_BAR; PG8_WAIT_L(0); PG8_MMA(0, 1, At, B1); PG8_BAR;
;             PG8_LDA(At, 0, 1); PG8_STAGE(PG8_SA(0, 0), a2, voffA);
;             PG8_BAR; PG8_WAIT_L(0); PG8_MMA(1, 0, At, B0); PG8_BAR; PG8_SCHED;
;             PG8_STAGE(PG8_SB(0, 1), b2 + hstep, voffB);
;             PG8_WAIT_V(6); PG8_BAR; PG8_MMA(1, 1, At, B1); PG8_BAR;
;             PG8_LDB(B0, 1, 0); PG8_SCHED; PG8_LDA(At, 1, 0); PG8_STAGE(PG8_SA(0, 1), a2 + hstep, voffA);
;             PG8_WAIT_L(8); PG8_BAR; PG8_WAIT_L(0); PG8_MMA(0, 0, At, B0); PG8_BAR; PG8_SCHED;
;             PG8_LDB(B1, 1, 1); PG8_STAGE(PG8_SB(1, 0), b3, voffB);
;             PG8_BAR; PG8_WAIT_L(0); PG8_MMA(0, 1, At, B1); PG8_BAR;
;             PG8_LDA(At, 1, 1); PG8_STAGE(PG8_SA(1, 0), a3, voffA);
;             PG8_BAR; PG8_WAIT_L(0); PG8_MMA(1, 0, At, B0); PG8_BAR; PG8_SCHED;
;             PG8_STAGE(PG8_SB(1, 1), b3 + hstep, voffB);
;             PG8_WAIT_V(6); PG8_BAR; PG8_MMA(1, 1, At, B1); PG8_BAR;
.LdsA_skip_7:
	v_mfma_f32_16x16x32_bf16 v[114:117], v[140:143], v[176:179], v[114:117]
	v_mfma_f32_16x16x32_bf16 v[106:109], v[154:157], v[176:179], v[106:109]
	v_mfma_f32_16x16x32_bf16 v[98:101], v[140:143], v[184:187], v[98:101]
	v_mfma_f32_16x16x32_bf16 v[90:93], v[154:157], v[184:187], v[90:93]
	v_mfma_f32_16x16x32_bf16 v[82:85], v[140:143], v[208:211], v[82:85]
	v_mfma_f32_16x16x32_bf16 v[74:77], v[154:157], v[208:211], v[74:77]
	v_mfma_f32_16x16x32_bf16 v[126:129], v[144:147], v[172:175], v[126:129]
	v_mfma_f32_16x16x32_bf16 v[122:125], v[158:161], v[172:175], v[122:125]
	v_mfma_f32_16x16x32_bf16 v[114:117], v[144:147], v[180:183], v[114:117]
	v_mfma_f32_16x16x32_bf16 v[106:109], v[158:161], v[180:183], v[106:109]
	v_mfma_f32_16x16x32_bf16 v[98:101], v[144:147], v[204:207], v[98:101]
	v_mfma_f32_16x16x32_bf16 v[90:93], v[158:161], v[204:207], v[90:93]
	v_mfma_f32_16x16x32_bf16 v[82:85], v[144:147], v[212:215], v[82:85]
	v_mfma_f32_16x16x32_bf16 v[74:77], v[158:161], v[212:215], v[74:77]
	s_barrier
	s_add_i32 s36, 0, 0x1c000
	s_add_i32 s37, s58, s44
	v_add_u32_e32 v153, s36, v149
	s_add_u32 s60, s6, 0x80
	s_addc_u32 s61, s7, 0
	s_mov_b32 m0, s37
	ds_read_b128 v[216:219], v153
	ds_read_b128 v[226:229], v153 offset:1024
	ds_read_b128 v[230:233], v153 offset:2048
	ds_read_b128 v[234:237], v153 offset:3072
	global_load_lds_dwordx4 v0, s[60:61]
	s_add_i32 m0, s37, 0x2000
	s_nop 0
	global_load_lds_dwordx4 v130, s[60:61]
	s_barrier
	s_waitcnt lgkmcnt(0)
	s_waitcnt lgkmcnt(0)
	v_mfma_f32_16x16x32_bf16 v[118:121], v[216:219], v[168:171], v[118:121]
	v_mfma_f32_16x16x32_bf16 v[110:113], v[230:233], v[168:171], v[110:113]
	v_mfma_f32_16x16x32_bf16 v[102:105], v[216:219], v[176:179], v[102:105]
	v_mfma_f32_16x16x32_bf16 v[94:97], v[230:233], v[176:179], v[94:97]
	v_mfma_f32_16x16x32_bf16 v[86:89], v[216:219], v[184:187], v[86:89]
	v_mfma_f32_16x16x32_bf16 v[78:81], v[230:233], v[184:187], v[78:81]
	v_mfma_f32_16x16x32_bf16 v[70:73], v[216:219], v[208:211], v[70:73]
	v_mfma_f32_16x16x32_bf16 v[66:69], v[230:233], v[208:211], v[66:69]
	v_mfma_f32_16x16x32_bf16 v[118:121], v[226:229], v[172:175], v[118:121]
	v_mfma_f32_16x16x32_bf16 v[110:113], v[234:237], v[172:175], v[110:113]
	v_mfma_f32_16x16x32_bf16 v[102:105], v[226:229], v[180:183], v[102:105]
	v_mfma_f32_16x16x32_bf16 v[94:97], v[234:237], v[180:183], v[94:97]
	v_mfma_f32_16x16x32_bf16 v[86:89], v[226:229], v[204:207], v[86:89]
	v_mfma_f32_16x16x32_bf16 v[78:81], v[234:237], v[204:207], v[78:81]
	v_mfma_f32_16x16x32_bf16 v[70:73], v[226:229], v[212:215], v[70:73]
	v_mfma_f32_16x16x32_bf16 v[66:69], v[234:237], v[212:215], v[66:69]
	s_mov_b32 m0, s55
	s_barrier
	ds_read_b128 v[168:171], v152 offset:49152
	ds_read_b128 v[172:175], v152 offset:50176
	ds_read_b128 v[176:179], v152 offset:51200
	ds_read_b128 v[180:183], v152 offset:52224
	ds_read_b128 v[184:187], v152 offset:53248
	ds_read_b128 v[204:207], v152 offset:54272
	ds_read_b128 v[208:211], v152 offset:55296
	ds_read_b128 v[212:215], v152 offset:56320
	global_load_lds_dwordx4 v134, vcc
	s_mov_b32 m0, s83
	s_nop 0
	global_load_lds_dwordx4 v132, vcc
	s_barrier
	s_waitcnt lgkmcnt(0)
	s_waitcnt lgkmcnt(0)
	v_mfma_f32_16x16x32_bf16 v[62:65], v[140:143], v[168:171], v[62:65]
	v_mfma_f32_16x16x32_bf16 v[58:61], v[154:157], v[168:171], v[58:61]
	v_mfma_f32_16x16x32_bf16 v[50:53], v[140:143], v[176:179], v[50:53]
	v_mfma_f32_16x16x32_bf16 v[42:45], v[154:157], v[176:179], v[42:45]
	v_mfma_f32_16x16x32_bf16 v[34:37], v[140:143], v[184:187], v[34:37]
	v_mfma_f32_16x16x32_bf16 v[26:29], v[154:157], v[184:187], v[26:29]
	v_mfma_f32_16x16x32_bf16 v[18:21], v[140:143], v[208:211], v[18:21]
	v_mfma_f32_16x16x32_bf16 v[10:13], v[154:157], v[208:211], v[10:13]
	v_mfma_f32_16x16x32_bf16 v[62:65], v[144:147], v[172:175], v[62:65]
	v_mfma_f32_16x16x32_bf16 v[58:61], v[158:161], v[172:175], v[58:61]
	v_mfma_f32_16x16x32_bf16 v[50:53], v[144:147], v[180:183], v[50:53]
	v_mfma_f32_16x16x32_bf16 v[42:45], v[158:161], v[180:183], v[42:45]
	v_mfma_f32_16x16x32_bf16 v[34:37], v[144:147], v[204:207], v[34:37]
	v_mfma_f32_16x16x32_bf16 v[26:29], v[158:161], v[204:207], v[26:29]
	v_mfma_f32_16x16x32_bf16 v[18:21], v[144:147], v[212:215], v[18:21]
	v_mfma_f32_16x16x32_bf16 v[10:13], v[158:161], v[212:215], v[10:13]
	s_barrier
	s_add_u32 s6, s6, 0x40080
	s_addc_u32 s7, s7, 0
	s_add_i32 s36, s36, s44
	s_mov_b32 m0, s36
	s_nop 0
	global_load_lds_dwordx4 v0, s[6:7]
	s_add_i32 m0, s36, 0x2000
	s_nop 0
	global_load_lds_dwordx4 v130, s[6:7]
	s_waitcnt vmcnt(6)
	s_barrier
	v_mfma_f32_16x16x32_bf16 v[54:57], v[216:219], v[168:171], v[54:57]
	v_mfma_f32_16x16x32_bf16 v[46:49], v[230:233], v[168:171], v[46:49]
	v_mfma_f32_16x16x32_bf16 v[38:41], v[216:219], v[176:179], v[38:41]
	v_mfma_f32_16x16x32_bf16 v[30:33], v[230:233], v[176:179], v[30:33]
	v_mfma_f32_16x16x32_bf16 v[22:25], v[216:219], v[184:187], v[22:25]
	v_mfma_f32_16x16x32_bf16 v[14:17], v[230:233], v[184:187], v[14:17]
	v_mfma_f32_16x16x32_bf16 v[6:9], v[216:219], v[208:211], v[6:9]
	v_mfma_f32_16x16x32_bf16 v[2:5], v[230:233], v[208:211], v[2:5]
	v_mfma_f32_16x16x32_bf16 v[54:57], v[226:229], v[172:175], v[54:57]
	v_mfma_f32_16x16x32_bf16 v[46:49], v[234:237], v[172:175], v[46:49]
	v_mfma_f32_16x16x32_bf16 v[38:41], v[226:229], v[180:183], v[38:41]
	v_mfma_f32_16x16x32_bf16 v[30:33], v[234:237], v[180:183], v[30:33]
	v_mfma_f32_16x16x32_bf16 v[22:25], v[226:229], v[204:207], v[22:25]
	v_mfma_f32_16x16x32_bf16 v[14:17], v[234:237], v[204:207], v[14:17]
	v_mfma_f32_16x16x32_bf16 v[6:9], v[226:229], v[212:215], v[6:9]
	v_mfma_f32_16x16x32_bf16 v[2:5], v[234:237], v[212:215], v[2:5]
	s_add_i32 s91, s91, 2
	s_add_u32 s24, s24, 0x100
	s_addc_u32 s25, s25, 0
	s_add_u32 s89, s89, 0x100
	s_addc_u32 s90, s90, 0
	s_cmp_gt_u32 s91, 13
	s_barrier
; __device__ __forceinline__ unsigned pk2(float lo, float hi) { unsigned r; asm("v_cvt_pk_bf16_f32 %0, %1, %2" : "=v"(r) : "v"(lo), "v"(hi)); return r; }
;     __device__ __forceinline__ void operator()(const f32x4 (&acc)[2][2][4][2], const Unit& u, int ui, int wr, int wc, int fr, int fq) const {
;         const int lrow0 = wr * 64 + fr, row0 = u.pm * BM + lrow0, col0 = u.pn * BM + wc * 32 + 8 * fq;
;         float rsv[2][4];
; #pragma unroll
;         for (int ai = 0; ai < 2; ++ai)
; #pragma unroll
;             for (int m = 0; m < 4; ++m) rsv[ai][m] = rstab[ui * 256 + lrow0 + ai * HALF + m * 16];
; #pragma unroll
;         for (int ai = 0; ai < 2; ++ai)
; #pragma unroll
;             for (int m = 0; m < 4; ++m) {
;                 const int row = row0 + ai * HALF + m * 16; const float rs = rsv[ai][m];
;                 bf16_t* rowp = O + (size_t)row * ldc + col0;
; #pragma unroll
;                 for (int bj = 0; bj < 2; ++bj) {
;                     f32x4 v0 = acc[ai][bj][m][0] * rs, v1 = acc[ai][bj][m][1] * rs;
;                     if (ACT == 1) {
; #pragma unroll
;                         for (int j = 0; j < 4; ++j) { const float a = fmaxf(v0[j], 0.f), b = fmaxf(v1[j], 0.f); v0[j] = a * a; v1[j] = b * b; }
;                     }
;                     u32x4 w; w.x = pk2(v0[0], v0[1]); w.y = pk2(v0[2], v0[3]); w.z = pk2(v1[0], v1[1]); w.w = pk2(v1[2], v1[3]);
;                     *(u32x4*)(rowp + bj * HALF) = w;
	v_lshl_add_u32 v140, s87, 10, v150
	v_lshl_or_b32 v144, s85, 8, v151
	v_lshl_add_u32 v153, s86, 8, v148
	v_mul_u32_u24_e32 v166, 0xe00, v153
	v_lshl_add_u32 v166, v144, 1, v166
	v_add_u32_e32 v166, 0x70000, v166
	ds_read2_b32 v[154:155], v140 offset1:16
	ds_read2_b32 v[156:157], v140 offset0:32 offset1:48
	ds_read2_b32 v[146:147], v140 offset0:128 offset1:144
	ds_read2_b32 v[140:141], v140 offset0:160 offset1:176
	v_ashrrev_i32_e32 v145, 31, v144
	v_mov_b64_e32 v[142:143], s[4:5]
	v_mad_i64_i32 v[158:159], s[6:7], v153, s65, v[142:143]
	v_lshlrev_b64 v[144:145], 1, v[144:145]
	v_lshl_add_u64 v[158:159], v[158:159], 0, v[144:145]
	s_waitcnt lgkmcnt(0)
	v_pk_mul_f32 v[128:129], v[128:129], v[154:155] op_sel_hi:[1,0]
	v_pk_mul_f32 v[126:127], v[126:127], v[154:155] op_sel_hi:[1,0]
	v_pk_mul_f32 v[160:161], v[124:125], v[154:155] op_sel_hi:[1,0]
	v_pk_mul_f32 v[124:125], v[122:123], v[154:155] op_sel_hi:[1,0]
	v_cvt_pk_bf16_f32 v122, v126, v127
	v_cvt_pk_bf16_f32 v123, v128, v129
	v_pk_mul_f32 v[118:119], v[118:119], v[154:155] op_sel_hi:[1,0]
	v_cvt_pk_bf16_f32 v124, v124, v125
	v_cvt_pk_bf16_f32 v125, v160, v161
	global_store_dwordx4 v[158:159], v[122:125], off
	v_pk_mul_f32 v[120:121], v[120:121], v[154:155] op_sel_hi:[1,0]
	v_pk_mul_f32 v[98:99], v[98:99], v[156:157] op_sel_hi:[1,0]
	v_pk_mul_f32 v[122:123], v[112:113], v[154:155] op_sel_hi:[1,0]
	v_pk_mul_f32 v[112:113], v[110:111], v[154:155] op_sel_hi:[1,0]
	v_cvt_pk_bf16_f32 v110, v118, v119
	v_cvt_pk_bf16_f32 v111, v120, v121
	v_pk_mul_f32 v[86:87], v[86:87], v[156:157] op_sel_hi:[1,0]
	v_cvt_pk_bf16_f32 v112, v112, v113
	v_cvt_pk_bf16_f32 v113, v122, v123
	global_store_dwordx4 v[158:159], v[110:113], off offset:256
	v_pk_mul_f32 v[88:89], v[88:89], v[156:157] op_sel_hi:[1,0]
	v_pk_mul_f32 v[64:65], v[64:65], v[146:147] op_sel_hi:[1,0]
	v_or_b32_e32 v110, 16, v153
	v_mad_i64_i32 v[110:111], s[6:7], v110, s65, v[142:143]
	v_mov_b32_e32 v112, v155
	v_lshl_add_u64 v[110:111], v[110:111], 0, v[144:145]
	v_pk_mul_f32 v[116:117], v[116:117], v[112:113] op_sel_hi:[1,0]
	v_pk_mul_f32 v[114:115], v[114:115], v[112:113] op_sel_hi:[1,0]
	v_pk_mul_f32 v[118:119], v[108:109], v[112:113] op_sel_hi:[1,0]
	v_pk_mul_f32 v[108:109], v[106:107], v[112:113] op_sel_hi:[1,0]
	v_cvt_pk_bf16_f32 v106, v114, v115
	v_cvt_pk_bf16_f32 v107, v116, v117
	v_pk_mul_f32 v[102:103], v[102:103], v[112:113] op_sel_hi:[1,0]
	v_cvt_pk_bf16_f32 v108, v108, v109
	v_cvt_pk_bf16_f32 v109, v118, v119
	global_store_dwordx4 v[110:111], v[106:109], off
	v_pk_mul_f32 v[104:105], v[104:105], v[112:113] op_sel_hi:[1,0]
	v_pk_mul_f32 v[62:63], v[62:63], v[146:147] op_sel_hi:[1,0]
	v_pk_mul_f32 v[106:107], v[96:97], v[112:113] op_sel_hi:[1,0]
	v_pk_mul_f32 v[96:97], v[94:95], v[112:113] op_sel_hi:[1,0]
	v_cvt_pk_bf16_f32 v94, v102, v103
	v_cvt_pk_bf16_f32 v95, v104, v105
	v_pk_mul_f32 v[54:55], v[54:55], v[146:147] op_sel_hi:[1,0]
	v_cvt_pk_bf16_f32 v96, v96, v97
	v_cvt_pk_bf16_f32 v97, v106, v107
	global_store_dwordx4 v[110:111], v[94:97], off offset:256
	v_pk_mul_f32 v[56:57], v[56:57], v[146:147] op_sel_hi:[1,0]
	v_pk_mul_f32 v[34:35], v[34:35], v[140:141] op_sel_hi:[1,0]
	v_or_b32_e32 v94, 32, v153
	v_mad_i64_i32 v[94:95], s[6:7], v94, s65, v[142:143]
	v_lshl_add_u64 v[94:95], v[94:95], 0, v[144:145]
	v_pk_mul_f32 v[96:97], v[100:101], v[156:157] op_sel_hi:[1,0]
	v_pk_mul_f32 v[100:101], v[92:93], v[156:157] op_sel_hi:[1,0]
	v_pk_mul_f32 v[92:93], v[90:91], v[156:157] op_sel_hi:[1,0]
	v_cvt_pk_bf16_f32 v90, v98, v99
	v_cvt_pk_bf16_f32 v91, v96, v97
	v_pk_mul_f32 v[22:23], v[22:23], v[140:141] op_sel_hi:[1,0]
	v_cvt_pk_bf16_f32 v92, v92, v93
	v_cvt_pk_bf16_f32 v93, v100, v101
	global_store_dwordx4 v[94:95], v[90:93], off
	v_pk_mul_f32 v[24:25], v[24:25], v[140:141] op_sel_hi:[1,0]
	s_and_b64 vcc, exec, s[40:41]
	v_pk_mul_f32 v[90:91], v[80:81], v[156:157] op_sel_hi:[1,0]
	v_pk_mul_f32 v[80:81], v[78:79], v[156:157] op_sel_hi:[1,0]
	v_cvt_pk_bf16_f32 v78, v86, v87
	v_cvt_pk_bf16_f32 v79, v88, v89
	s_mov_b32 s85, s8
	v_cvt_pk_bf16_f32 v80, v80, v81
	v_cvt_pk_bf16_f32 v81, v90, v91
	global_store_dwordx4 v[94:95], v[78:81], off offset:256
	s_mov_b32 s86, s10
	s_mov_b64 s[24:25], s[12:13]
	v_or_b32_e32 v78, 48, v153
	v_mad_i64_i32 v[78:79], s[6:7], v78, s65, v[142:143]
	v_mov_b32_e32 v80, v157
	v_lshl_add_u64 v[78:79], v[78:79], 0, v[144:145]
	v_pk_mul_f32 v[84:85], v[84:85], v[80:81] op_sel_hi:[1,0]
	v_pk_mul_f32 v[82:83], v[82:83], v[80:81] op_sel_hi:[1,0]
	v_pk_mul_f32 v[86:87], v[76:77], v[80:81] op_sel_hi:[1,0]
	v_pk_mul_f32 v[76:77], v[74:75], v[80:81] op_sel_hi:[1,0]
	v_cvt_pk_bf16_f32 v74, v82, v83
	v_cvt_pk_bf16_f32 v75, v84, v85
	v_pk_mul_f32 v[70:71], v[70:71], v[80:81] op_sel_hi:[1,0]
	v_cvt_pk_bf16_f32 v76, v76, v77
	v_cvt_pk_bf16_f32 v77, v86, v87
	global_store_dwordx4 v[78:79], v[74:77], off
	v_pk_mul_f32 v[72:73], v[72:73], v[80:81] op_sel_hi:[1,0]
	s_mov_b32 s87, s84
	v_pk_mul_f32 v[74:75], v[68:69], v[80:81] op_sel_hi:[1,0]
	v_pk_mul_f32 v[68:69], v[66:67], v[80:81] op_sel_hi:[1,0]
	v_cvt_pk_bf16_f32 v66, v70, v71
	v_cvt_pk_bf16_f32 v67, v72, v73
	s_nop 0
	v_cvt_pk_bf16_f32 v68, v68, v69
	v_cvt_pk_bf16_f32 v69, v74, v75
	global_store_dwordx4 v[78:79], v[66:69], off offset:256
	s_nop 1
	v_add_u32_e32 v66, 0x80, v153
	v_mad_i64_i32 v[66:67], s[6:7], v66, s65, v[142:143]
	v_lshl_add_u64 v[66:67], v[66:67], 0, v[144:145]
	v_pk_mul_f32 v[68:69], v[60:61], v[146:147] op_sel_hi:[1,0]
; __device__ __forceinline__ unsigned pk2(float lo, float hi) { unsigned r; asm("v_cvt_pk_bf16_f32 %0, %1, %2" : "=v"(r) : "v"(lo), "v"(hi)); return r; }
; #define PG8_WAIT_V(n) asm volatile("s_waitcnt vmcnt(" #n ")" ::: "memory")
; #define PG8_BAR __builtin_amdgcn_s_barrier()
;     __device__ __forceinline__ void operator()(const f32x4 (&acc)[2][2][4][2], const Unit& u, int ui, int wr, int wc, int fr, int fq) const {
;     ...
;                     f32x4 v0 = acc[ai][bj][m][0] * rs, v1 = acc[ai][bj][m][1] * rs;
;                     if (ACT == 1) {
; #pragma unroll
;                         for (int j = 0; j < 4; ++j) { const float a = fmaxf(v0[j], 0.f), b = fmaxf(v1[j], 0.f); v0[j] = a * a; v1[j] = b * b; }
;                     }
;                     u32x4 w; w.x = pk2(v0[0], v0[1]); w.y = pk2(v0[2], v0[3]); w.z = pk2(v1[0], v1[1]); w.w = pk2(v1[2], v1[3]);
;                     *(u32x4*)(rowp + bj * HALF) = w;
; template <class Epi>
; __device__ __forceinline__ void gemm_phase(LAS unsigned char* lds, const Gemm g, const StaticOrder& S, const Epi& E) {
;     ...
;         if (!has_next) break;
; #pragma unroll
;         for (int a = 0; a < 2; ++a)
; #pragma unroll
;             for (int b = 0; b < 2; ++b)
; #pragma unroll
;                 for (int m = 0; m < 4; ++m)
; #pragma unroll
;                     for (int n = 0; n < 2; ++n) acc[a][b][m][n] = (f32x4){0.f, 0.f, 0.f, 0.f};
;         cur = nxt; cA = nA; cB = nB; ++ui;
;     }
;     PG8_WAIT_V(0);
;     if (wr == 0) PG8_BAR;
;     PG8_BAR;
	v_pk_mul_f32 v[60:61], v[58:59], v[146:147] op_sel_hi:[1,0]
	v_cvt_pk_bf16_f32 v58, v62, v63
	v_cvt_pk_bf16_f32 v59, v64, v65
	s_nop 0
	v_cvt_pk_bf16_f32 v60, v60, v61
	v_cvt_pk_bf16_f32 v61, v68, v69
	v_mov_b32_e32 v162, v58
	v_mov_b32_e32 v163, v59
	v_mov_b32_e32 v164, v60
	v_mov_b32_e32 v165, v61
	s_nop 1
	v_pk_mul_f32 v[58:59], v[48:49], v[146:147] op_sel_hi:[1,0]
	v_pk_mul_f32 v[48:49], v[46:47], v[146:147] op_sel_hi:[1,0]
	v_cvt_pk_bf16_f32 v46, v54, v55
	v_cvt_pk_bf16_f32 v47, v56, v57
	s_nop 0
	v_cvt_pk_bf16_f32 v48, v48, v49
	v_cvt_pk_bf16_f32 v49, v58, v59
	v_mov_b32_e32 v188, v46
	v_mov_b32_e32 v189, v47
	v_mov_b32_e32 v190, v48
	v_mov_b32_e32 v191, v49
	s_nop 1
	v_add_u32_e32 v46, 0x90, v153
	v_mad_i64_i32 v[46:47], s[6:7], v46, s65, v[142:143]
	v_mov_b32_e32 v48, v147
	v_lshl_add_u64 v[46:47], v[46:47], 0, v[144:145]
	v_pk_mul_f32 v[52:53], v[52:53], v[48:49] op_sel_hi:[1,0]
	v_pk_mul_f32 v[50:51], v[50:51], v[48:49] op_sel_hi:[1,0]
	v_pk_mul_f32 v[54:55], v[44:45], v[48:49] op_sel_hi:[1,0]
	v_pk_mul_f32 v[44:45], v[42:43], v[48:49] op_sel_hi:[1,0]
	v_cvt_pk_bf16_f32 v42, v50, v51
	v_cvt_pk_bf16_f32 v43, v52, v53
	v_pk_mul_f32 v[38:39], v[38:39], v[48:49] op_sel_hi:[1,0]
	v_cvt_pk_bf16_f32 v44, v44, v45
	v_cvt_pk_bf16_f32 v45, v54, v55
	v_mov_b32_e32 v192, v42
	v_mov_b32_e32 v193, v43
	v_mov_b32_e32 v194, v44
	v_mov_b32_e32 v195, v45
	v_pk_mul_f32 v[40:41], v[40:41], v[48:49] op_sel_hi:[1,0]
	s_nop 0
	v_pk_mul_f32 v[42:43], v[32:33], v[48:49] op_sel_hi:[1,0]
	v_pk_mul_f32 v[32:33], v[30:31], v[48:49] op_sel_hi:[1,0]
	v_cvt_pk_bf16_f32 v30, v38, v39
	v_cvt_pk_bf16_f32 v31, v40, v41
	s_nop 0
	v_cvt_pk_bf16_f32 v32, v32, v33
	v_cvt_pk_bf16_f32 v33, v42, v43
	v_mov_b32_e32 v196, v30
	v_mov_b32_e32 v197, v31
	v_mov_b32_e32 v198, v32
	v_mov_b32_e32 v199, v33
	s_nop 1
	v_add_u32_e32 v30, 0xa0, v153
	v_mad_i64_i32 v[30:31], s[6:7], v30, s65, v[142:143]
	v_lshl_add_u64 v[30:31], v[30:31], 0, v[144:145]
	v_pk_mul_f32 v[32:33], v[36:37], v[140:141] op_sel_hi:[1,0]
	v_pk_mul_f32 v[36:37], v[28:29], v[140:141] op_sel_hi:[1,0]
	v_pk_mul_f32 v[28:29], v[26:27], v[140:141] op_sel_hi:[1,0]
	v_cvt_pk_bf16_f32 v26, v34, v35
	v_cvt_pk_bf16_f32 v27, v32, v33
	s_nop 0
	v_cvt_pk_bf16_f32 v28, v28, v29
	v_cvt_pk_bf16_f32 v29, v36, v37
	v_mov_b32_e32 v200, v26
	v_mov_b32_e32 v201, v27
	v_mov_b32_e32 v202, v28
	v_mov_b32_e32 v203, v29
	s_nop 1
	v_pk_mul_f32 v[26:27], v[16:17], v[140:141] op_sel_hi:[1,0]
	v_pk_mul_f32 v[16:17], v[14:15], v[140:141] op_sel_hi:[1,0]
	v_cvt_pk_bf16_f32 v14, v22, v23
	v_cvt_pk_bf16_f32 v15, v24, v25
	s_nop 0
	v_cvt_pk_bf16_f32 v16, v16, v17
	v_cvt_pk_bf16_f32 v17, v26, v27
	v_mov_b32_e32 v222, v14
	v_mov_b32_e32 v223, v15
	v_mov_b32_e32 v224, v16
	v_mov_b32_e32 v225, v17
	s_nop 1
	v_add_u32_e32 v14, 0xb0, v153
	v_mad_i64_i32 v[14:15], s[6:7], v14, s65, v[142:143]
	v_mov_b32_e32 v16, v141
	v_lshl_add_u64 v[14:15], v[14:15], 0, v[144:145]
	v_pk_mul_f32 v[20:21], v[20:21], v[16:17] op_sel_hi:[1,0]
	v_pk_mul_f32 v[18:19], v[18:19], v[16:17] op_sel_hi:[1,0]
	v_pk_mul_f32 v[22:23], v[12:13], v[16:17] op_sel_hi:[1,0]
	v_pk_mul_f32 v[12:13], v[10:11], v[16:17] op_sel_hi:[1,0]
	v_cvt_pk_bf16_f32 v10, v18, v19
	v_cvt_pk_bf16_f32 v11, v20, v21
	s_mov_b64 s[6:7], s[22:23]
	v_cvt_pk_bf16_f32 v12, v12, v13
	v_cvt_pk_bf16_f32 v13, v22, v23
	v_mov_b32_e32 v244, v10
	v_mov_b32_e32 v245, v11
	v_mov_b32_e32 v246, v12
	v_mov_b32_e32 v247, v13
	v_pk_mul_f32 v[8:9], v[8:9], v[16:17] op_sel_hi:[1,0]
	v_pk_mul_f32 v[6:7], v[6:7], v[16:17] op_sel_hi:[1,0]
	v_pk_mul_f32 v[10:11], v[4:5], v[16:17] op_sel_hi:[1,0]
	v_pk_mul_f32 v[4:5], v[2:3], v[16:17] op_sel_hi:[1,0]
	v_cvt_pk_bf16_f32 v2, v6, v7
	v_cvt_pk_bf16_f32 v3, v8, v9
	s_nop 0
	v_cvt_pk_bf16_f32 v4, v4, v5
	v_cvt_pk_bf16_f32 v5, v10, v11
	v_mov_b32_e32 v248, v2
	v_mov_b32_e32 v249, v3
	v_mov_b32_e32 v250, v4
	v_mov_b32_e32 v251, v5
	s_cbranch_vccz .LBB0_460
	global_store_dwordx4 v166, v[162:165], s[4:5]
	global_store_dwordx4 v166, v[188:191], s[4:5] offset:256
	s_nop 1
	v_add_u32_e32 v166, 0xe000, v166
	global_store_dwordx4 v166, v[192:195], s[4:5]
	global_store_dwordx4 v166, v[196:199], s[4:5] offset:256
	s_nop 1
	v_add_u32_e32 v166, 0xe000, v166
	global_store_dwordx4 v166, v[200:203], s[4:5]
	global_store_dwordx4 v166, v[222:225], s[4:5] offset:256
	s_nop 1
	v_add_u32_e32 v166, 0xe000, v166
	global_store_dwordx4 v166, v[244:247], s[4:5]
	global_store_dwordx4 v166, v[248:251], s[4:5] offset:256
	s_nop 1
	v_mov_b64_e32 v[164:165], 0x200
	v_mbcnt_lo_u32_b32 v193, -1, 0
	v_mbcnt_hi_u32_b32 v193, -1, v193
	v_mov_b32_e32 v188, 1
	v_mov_b32_e32 v189, 0x358637bd
	v_mov_b32_e32 v190, 0x260
	v_mov_b32_e32 v191, 0x3c0881c4
	v_mov_b32_e32 v192, 0xbab64f3b
	v_mov_b32_e32 v194, 0xf149f2ca
	v_mov_b32_e32 v195, 0xc0
	v_mov_b32_e32 v196, 0x70
	v_mov_b32_e32 v197, 0x71
	v_mov_b32_e32 v198, 5
	v_mov_b32_e32 v199, 2
	v_mov_b32_e32 v200, 3
	v_not_b32_e32 v201, 63
	v_not_b32_e32 v202, 31
	v_mov_b32_e32 v203, 0x7fc00000
	v_mov_b32_e32 v222, 0
	v_mov_b32_e32 v223, 0
	v_mov_b32_e32 v224, 0
	v_mov_b32_e32 v225, 0
	s_waitcnt vmcnt(0)
	v_readlane_b32 s70, v254, 40
	v_readlane_b32 s84, v254, 42
	s_cmpk_gt_u32 s18, 0xff
	v_readlane_b32 s71, v254, 41
	v_readlane_b32 s86, v254, 44
	v_readlane_b32 s87, v254, 45
	v_readlane_b32 s85, v254, 43
	s_cbranch_scc1 .LBB0_467
	s_barrier
.LBB0_467:
	s_setprio 0
	v_readlane_b32 s84, v253, 0
	v_readlane_b32 s85, v253, 1
	s_barrier
